# GEMM loops without s_setprio flips
# speedup vs baseline: 1.0030x; 1.0030x over previous
.LBB0_111:
	s_mul_i32 s10, s1, 0x6000
	s_add_i32 s55, s10, 0xffffa000
	s_cmp_lg_u32 s1, 0
	s_cselect_b32 s55, s55, 0xc000
	v_add_u32_e32 v159, s55, v132
	v_lshl_add_u64 v[160:161], v[154:155], 0, s[4:5]
	v_readfirstlane_b32 s55, v159
	v_add_u32_e32 v164, 0x1000, v159
	v_lshl_add_u64 v[162:163], v[160:161], 0, s[26:27]
	s_mov_b32 m0, s55
	v_readfirstlane_b32 s55, v164
	v_add_u32_e32 v164, 0x2000, v159
	s_waitcnt vmcnt(6)
	s_barrier
	global_load_lds_dwordx4 v[162:163], off
	v_lshl_add_u64 v[162:163], v[160:161], 0, s[28:29]
	s_mov_b32 m0, s55
	v_readfirstlane_b32 s55, v164
	global_load_lds_dwordx4 v[162:163], off
	v_lshl_add_u64 v[162:163], v[160:161], 0, s[30:31]
	s_mov_b32 m0, s55
	v_lshl_add_u64 v[160:161], v[160:161], 0, s[34:35]
	global_load_lds_dwordx4 v[162:163], off
	v_add_u32_e32 v162, 0x3000, v159
	v_add_u32_e32 v164, 0x4000, v159
	v_readfirstlane_b32 s55, v162
	s_mov_b32 m0, s55
	v_readfirstlane_b32 s55, v164
	global_load_lds_dwordx4 v[160:161], off
	v_lshl_add_u64 v[160:161], v[152:153], 0, s[4:5]
	v_add_u32_e32 v159, 0x5000, v159
	v_lshl_add_u64 v[162:163], v[160:161], 0, s[44:45]
	s_mov_b32 m0, s55
	v_readfirstlane_b32 s55, v159
	global_load_lds_dwordx4 v[162:163], off
	v_lshl_add_u64 v[160:161], v[160:161], 0, s[46:47]
	s_mov_b32 m0, s55
	s_add_i32 s10, s10, 0
	global_load_lds_dwordx4 v[160:161], off
	v_add3_u32 v159, s10, v156, v158
	ds_read_b128 v[160:163], v159 offset:16384
	ds_read_b128 v[168:171], v159 offset:17408
	ds_read_b128 v[172:175], v159 offset:18432
	ds_read_b128 v[176:179], v159 offset:19456
	v_add3_u32 v159, s10, v157, v158
	ds_read_b128 v[180:183], v159
	ds_read_b128 v[184:187], v159 offset:1024
	ds_read_b128 v[188:191], v159 offset:2048
	ds_read_b128 v[192:195], v159 offset:3072
	s_waitcnt lgkmcnt(0)
	v_mfma_f32_16x16x32_bf16 v[126:129], v[160:163], v[180:183], v[126:129]
	v_mfma_f32_16x16x32_bf16 v[122:125], v[168:171], v[180:183], v[122:125]
	v_mfma_f32_16x16x32_bf16 v[118:121], v[172:175], v[180:183], v[118:121]
	v_mfma_f32_16x16x32_bf16 v[114:117], v[176:179], v[180:183], v[114:117]
	v_mfma_f32_16x16x32_bf16 v[110:113], v[160:163], v[184:187], v[110:113]
	v_mfma_f32_16x16x32_bf16 v[106:109], v[168:171], v[184:187], v[106:109]
	v_mfma_f32_16x16x32_bf16 v[102:105], v[172:175], v[184:187], v[102:105]
	v_mfma_f32_16x16x32_bf16 v[98:101], v[176:179], v[184:187], v[98:101]
	v_mfma_f32_16x16x32_bf16 v[94:97], v[160:163], v[188:191], v[94:97]
	v_mfma_f32_16x16x32_bf16 v[90:93], v[168:171], v[188:191], v[90:93]
	v_mfma_f32_16x16x32_bf16 v[86:89], v[172:175], v[188:191], v[86:89]
	v_mfma_f32_16x16x32_bf16 v[82:85], v[176:179], v[188:191], v[82:85]
	v_mfma_f32_16x16x32_bf16 v[78:81], v[160:163], v[192:195], v[78:81]
	v_mfma_f32_16x16x32_bf16 v[74:77], v[168:171], v[192:195], v[74:77]
	v_mfma_f32_16x16x32_bf16 v[70:73], v[172:175], v[192:195], v[70:73]
	v_mfma_f32_16x16x32_bf16 v[66:69], v[176:179], v[192:195], v[66:69]
	ds_read_b128 v[180:183], v159 offset:4096
	ds_read_b128 v[184:187], v159 offset:5120
	ds_read_b128 v[188:191], v159 offset:6144
	ds_read_b128 v[192:195], v159 offset:7168
	s_waitcnt lgkmcnt(0)
	v_mfma_f32_16x16x32_bf16 v[62:65], v[160:163], v[180:183], v[62:65]
	v_mfma_f32_16x16x32_bf16 v[58:61], v[168:171], v[180:183], v[58:61]
	v_mfma_f32_16x16x32_bf16 v[54:57], v[172:175], v[180:183], v[54:57]
	v_mfma_f32_16x16x32_bf16 v[50:53], v[176:179], v[180:183], v[50:53]
	v_mfma_f32_16x16x32_bf16 v[46:49], v[160:163], v[184:187], v[46:49]
	v_mfma_f32_16x16x32_bf16 v[42:45], v[168:171], v[184:187], v[42:45]
	v_mfma_f32_16x16x32_bf16 v[38:41], v[172:175], v[184:187], v[38:41]
	v_mfma_f32_16x16x32_bf16 v[34:37], v[176:179], v[184:187], v[34:37]
	v_mfma_f32_16x16x32_bf16 v[30:33], v[160:163], v[188:191], v[30:33]
	v_mfma_f32_16x16x32_bf16 v[26:29], v[168:171], v[188:191], v[26:29]
	v_mfma_f32_16x16x32_bf16 v[22:25], v[172:175], v[188:191], v[22:25]
	v_mfma_f32_16x16x32_bf16 v[18:21], v[176:179], v[188:191], v[18:21]
	v_mfma_f32_16x16x32_bf16 v[14:17], v[160:163], v[192:195], v[14:17]
	v_mfma_f32_16x16x32_bf16 v[10:13], v[168:171], v[192:195], v[10:13]
	v_mfma_f32_16x16x32_bf16 v[6:9], v[172:175], v[192:195], v[6:9]
	v_mfma_f32_16x16x32_bf16 v[2:5], v[176:179], v[192:195], v[2:5]
	s_add_i32 s10, s1, 1
	s_cmp_lg_u32 s1, 2
	s_cselect_b32 s1, s10, 0
	s_add_u32 s4, s4, 64
	s_addc_u32 s5, s5, 0
	s_cmpk_eq_i32 s4, 0x780
	s_cbranch_scc0 .LBB0_111
	v_add3_u32 v132, 0, v156, v158
	v_add3_u32 v164, 0, v157, v158
	s_waitcnt vmcnt(6)
	s_barrier
	ds_read_b128 v[152:155], v132 offset:16384
	ds_read_b128 v[160:163], v132 offset:17408
	ds_read_b128 v[168:171], v132 offset:18432
	ds_read_b128 v[172:175], v132 offset:19456
	ds_read_b128 v[156:159], v164
	ds_read_b128 v[176:179], v164 offset:1024
	ds_read_b128 v[180:183], v164 offset:2048
	ds_read_b128 v[184:187], v164 offset:3072
	s_waitcnt lgkmcnt(0)
	v_mfma_f32_16x16x32_bf16 v[126:129], v[152:155], v[156:159], v[126:129]
	v_mfma_f32_16x16x32_bf16 v[122:125], v[160:163], v[156:159], v[122:125]
	v_mfma_f32_16x16x32_bf16 v[118:121], v[168:171], v[156:159], v[118:121]
	v_mfma_f32_16x16x32_bf16 v[114:117], v[172:175], v[156:159], v[114:117]
	v_mfma_f32_16x16x32_bf16 v[110:113], v[152:155], v[176:179], v[110:113]
	v_mfma_f32_16x16x32_bf16 v[106:109], v[160:163], v[176:179], v[106:109]
	v_mfma_f32_16x16x32_bf16 v[102:105], v[168:171], v[176:179], v[102:105]
	v_mfma_f32_16x16x32_bf16 v[98:101], v[172:175], v[176:179], v[98:101]
	v_mfma_f32_16x16x32_bf16 v[94:97], v[152:155], v[180:183], v[94:97]
	v_mfma_f32_16x16x32_bf16 v[90:93], v[160:163], v[180:183], v[90:93]
	v_mfma_f32_16x16x32_bf16 v[86:89], v[168:171], v[180:183], v[86:89]
	v_mfma_f32_16x16x32_bf16 v[82:85], v[172:175], v[180:183], v[82:85]
	v_mfma_f32_16x16x32_bf16 v[78:81], v[152:155], v[184:187], v[78:81]
	v_mfma_f32_16x16x32_bf16 v[74:77], v[160:163], v[184:187], v[74:77]
	v_mfma_f32_16x16x32_bf16 v[70:73], v[168:171], v[184:187], v[70:73]
	v_mfma_f32_16x16x32_bf16 v[66:69], v[172:175], v[184:187], v[66:69]
	ds_read_b128 v[156:159], v164 offset:4096
	ds_read_b128 v[176:179], v164 offset:5120
	ds_read_b128 v[180:183], v164 offset:6144
	ds_read_b128 v[184:187], v164 offset:7168
	s_waitcnt lgkmcnt(0)
	v_mfma_f32_16x16x32_bf16 v[62:65], v[152:155], v[156:159], v[62:65]
	v_mfma_f32_16x16x32_bf16 v[58:61], v[160:163], v[156:159], v[58:61]
	v_mfma_f32_16x16x32_bf16 v[54:57], v[168:171], v[156:159], v[54:57]
	v_mfma_f32_16x16x32_bf16 v[50:53], v[172:175], v[156:159], v[50:53]
	v_mfma_f32_16x16x32_bf16 v[46:49], v[152:155], v[176:179], v[46:49]
	v_mfma_f32_16x16x32_bf16 v[42:45], v[160:163], v[176:179], v[42:45]
	v_mfma_f32_16x16x32_bf16 v[38:41], v[168:171], v[176:179], v[38:41]
	v_mfma_f32_16x16x32_bf16 v[34:37], v[172:175], v[176:179], v[34:37]
	v_mfma_f32_16x16x32_bf16 v[30:33], v[152:155], v[180:183], v[30:33]
	v_mfma_f32_16x16x32_bf16 v[26:29], v[160:163], v[180:183], v[26:29]
	v_mfma_f32_16x16x32_bf16 v[22:25], v[168:171], v[180:183], v[22:25]
	v_mfma_f32_16x16x32_bf16 v[18:21], v[172:175], v[180:183], v[18:21]
	v_mfma_f32_16x16x32_bf16 v[14:17], v[152:155], v[184:187], v[14:17]
	v_mfma_f32_16x16x32_bf16 v[10:13], v[160:163], v[184:187], v[10:13]
	v_mfma_f32_16x16x32_bf16 v[6:9], v[168:171], v[184:187], v[6:9]
	v_mfma_f32_16x16x32_bf16 v[2:5], v[172:175], v[184:187], v[2:5]
	s_waitcnt vmcnt(0)
	s_barrier
	ds_read_b128 v[152:155], v132 offset:40960
	ds_read_b128 v[156:159], v132 offset:41984
	ds_read_b128 v[160:163], v132 offset:43008
	ds_read_b128 v[168:171], v132 offset:44032
	ds_read_b128 v[172:175], v164 offset:24576
	ds_read_b128 v[176:179], v164 offset:25600
	ds_read_b128 v[180:183], v164 offset:26624
	ds_read_b128 v[184:187], v164 offset:27648
	s_lshl_b64 s[58:59], s[56:57], 8
	s_waitcnt lgkmcnt(0)
	v_mfma_f32_16x16x32_bf16 v[126:129], v[152:155], v[172:175], v[126:129]
	v_mfma_f32_16x16x32_bf16 v[122:125], v[156:159], v[172:175], v[122:125]
	v_mfma_f32_16x16x32_bf16 v[118:121], v[160:163], v[172:175], v[118:121]
	v_mfma_f32_16x16x32_bf16 v[114:117], v[168:171], v[172:175], v[114:117]
	v_mfma_f32_16x16x32_bf16 v[110:113], v[152:155], v[176:179], v[110:113]
	v_mfma_f32_16x16x32_bf16 v[106:109], v[156:159], v[176:179], v[106:109]
	v_mfma_f32_16x16x32_bf16 v[102:105], v[160:163], v[176:179], v[102:105]
	v_mfma_f32_16x16x32_bf16 v[98:101], v[168:171], v[176:179], v[98:101]
	v_mfma_f32_16x16x32_bf16 v[94:97], v[152:155], v[180:183], v[94:97]
	v_mfma_f32_16x16x32_bf16 v[90:93], v[156:159], v[180:183], v[90:93]
	v_mfma_f32_16x16x32_bf16 v[86:89], v[160:163], v[180:183], v[86:89]
	v_mfma_f32_16x16x32_bf16 v[82:85], v[168:171], v[180:183], v[82:85]
	v_mfma_f32_16x16x32_bf16 v[78:81], v[152:155], v[184:187], v[78:81]
	v_mfma_f32_16x16x32_bf16 v[74:77], v[156:159], v[184:187], v[74:77]
	v_mfma_f32_16x16x32_bf16 v[70:73], v[160:163], v[184:187], v[70:73]
	v_mfma_f32_16x16x32_bf16 v[66:69], v[168:171], v[184:187], v[66:69]
	ds_read_b128 v[172:175], v164 offset:28672
	ds_read_b128 v[176:179], v164 offset:29696
	ds_read_b128 v[180:183], v164 offset:30720
	ds_read_b128 v[184:187], v164 offset:31744
	s_waitcnt lgkmcnt(0)
	v_mfma_f32_16x16x32_bf16 v[62:65], v[152:155], v[172:175], v[62:65]
	v_mfma_f32_16x16x32_bf16 v[58:61], v[156:159], v[172:175], v[58:61]
	v_mfma_f32_16x16x32_bf16 v[54:57], v[160:163], v[172:175], v[54:57]
	v_mfma_f32_16x16x32_bf16 v[50:53], v[168:171], v[172:175], v[50:53]
	v_mfma_f32_16x16x32_bf16 v[46:49], v[152:155], v[176:179], v[46:49]
	v_mfma_f32_16x16x32_bf16 v[42:45], v[156:159], v[176:179], v[42:45]
	v_mfma_f32_16x16x32_bf16 v[38:41], v[160:163], v[176:179], v[38:41]
	v_mfma_f32_16x16x32_bf16 v[34:37], v[168:171], v[176:179], v[34:37]
	v_mfma_f32_16x16x32_bf16 v[30:33], v[152:155], v[180:183], v[30:33]
	v_mfma_f32_16x16x32_bf16 v[26:29], v[156:159], v[180:183], v[26:29]
	v_mfma_f32_16x16x32_bf16 v[22:25], v[160:163], v[180:183], v[22:25]
	v_mfma_f32_16x16x32_bf16 v[18:21], v[168:171], v[180:183], v[18:21]
	v_mfma_f32_16x16x32_bf16 v[14:17], v[152:155], v[184:187], v[14:17]
	v_mfma_f32_16x16x32_bf16 v[10:13], v[156:159], v[184:187], v[10:13]
	v_mfma_f32_16x16x32_bf16 v[6:9], v[160:163], v[184:187], v[6:9]
	v_mfma_f32_16x16x32_bf16 v[2:5], v[168:171], v[184:187], v[2:5]
	s_cmp_eq_u32 s68, 2
	s_mov_b64 s[4:5], -1
	s_waitcnt vmcnt(0)
	s_barrier
	s_cbranch_scc1 .LBB0_146
	v_lshl_add_u64 v[152:153], s[58:59], 0, v[134:135]
	v_lshl_add_u64 v[154:155], v[152:153], 2, s[50:51]
	flat_load_dword v157, v[154:155]
	s_lshl_b32 s0, s0, 7
	s_cmp_lg_u32 s68, 3
	s_cselect_b64 s[4:5], -1, 0
	s_ashr_i32 s1, s0, 31
	v_lshl_add_u64 v[154:155], s[0:1], 1, v[146:147]
	v_mad_u64_u32 v[154:155], s[0:1], v152, s62, v[154:155]
	v_mov_b32_e32 v156, v155
	s_mov_b64 s[60:61], -1
	v_lshlrev_b32_e32 v132, 1, v136
	s_and_b64 vcc, exec, s[4:5]
	s_waitcnt vmcnt(0) lgkmcnt(0)
	v_fmamk_f32 v155, v157, 0x3a800000, v139
	v_mul_f32_e32 v157, 0x4b800000, v155
	v_cmp_gt_f32_e64 s[0:1], s43, v155
	s_nop 1
	v_cndmask_b32_e64 v155, v155, v157, s[0:1]
	v_rsq_f32_e32 v158, v155
	v_mad_u64_u32 v[156:157], s[68:69], v153, s62, v[156:157]
	v_mov_b32_e32 v155, v156
	v_mul_f32_e32 v156, 0x45800000, v158
	v_cndmask_b32_e64 v156, v158, v156, s[0:1]
	v_pk_mul_f32 v[158:159], v[128:129], v[156:157] op_sel_hi:[1,0]
	v_pk_mul_f32 v[160:161], v[126:127], v[156:157] op_sel_hi:[1,0]
	s_cbranch_vccz .LBB0_148
	v_cvt_pk_bf16_f32 v162, v160, v161
	v_cvt_pk_bf16_f32 v163, v158, v159
	v_lshl_add_u64 v[164:165], v[154:155], 0, v[132:133]
	flat_store_dwordx2 v[164:165], v[162:163]
	v_cmp_gt_u32_e64 s[0:1], s67, v136
	s_cbranch_execz .LBB0_149

.LBB0_531:
	s_mul_i32 s43, s1, 0x6000
	s_add_i32 s50, s43, 0xffffa000
	s_cmp_lg_u32 s1, 0
	s_cselect_b32 s50, s50, 0xc000
	v_add_u32_e32 v150, s50, v143
	v_lshl_add_u64 v[146:147], v[138:139], 0, s[48:49]
	v_readfirstlane_b32 s50, v150
	v_add_u32_e32 v151, 0x1000, v150
	v_lshl_add_u64 v[148:149], v[146:147], 0, s[24:25]
	s_mov_b32 m0, s50
	v_readfirstlane_b32 s50, v151
	v_add_u32_e32 v151, 0x2000, v150
	s_waitcnt vmcnt(6)
	s_barrier
	global_load_lds_dwordx4 v[148:149], off
	v_lshl_add_u64 v[148:149], v[146:147], 0, s[26:27]
	s_mov_b32 m0, s50
	v_readfirstlane_b32 s50, v151
	global_load_lds_dwordx4 v[148:149], off
	v_lshl_add_u64 v[148:149], v[146:147], 0, s[28:29]
	s_mov_b32 m0, s50
	v_lshl_add_u64 v[146:147], v[146:147], 0, s[30:31]
	global_load_lds_dwordx4 v[148:149], off
	v_add_u32_e32 v148, 0x3000, v150
	v_add_u32_e32 v151, 0x4000, v150
	v_readfirstlane_b32 s50, v148
	s_mov_b32 m0, s50
	v_readfirstlane_b32 s50, v151
	global_load_lds_dwordx4 v[146:147], off
	v_lshl_add_u64 v[146:147], v[136:137], 0, s[48:49]
	v_lshl_add_u64 v[148:149], v[146:147], 0, s[34:35]
	s_mov_b32 m0, s50
	v_lshl_add_u64 v[146:147], v[146:147], 0, s[44:45]
	global_load_lds_dwordx4 v[148:149], off
	v_add_u32_e32 v148, 0x5000, v150
	s_add_i32 s43, s43, 0
	v_readfirstlane_b32 s50, v148
	s_mov_b32 m0, s50
	v_add3_u32 v158, s43, v142, v145
	global_load_lds_dwordx4 v[146:147], off
	v_add3_u32 v178, s43, v144, v145
	ds_read_b128 v[146:149], v158 offset:16384
	ds_read_b128 v[150:153], v158 offset:17408
	ds_read_b128 v[154:157], v158 offset:18432
	ds_read_b128 v[158:161], v158 offset:19456
	ds_read_b128 v[162:165], v178
	ds_read_b128 v[166:169], v178 offset:1024
	ds_read_b128 v[170:173], v178 offset:2048
	ds_read_b128 v[174:177], v178 offset:3072
	s_waitcnt lgkmcnt(0)
	v_mfma_f32_16x16x32_bf16 v[126:129], v[146:149], v[162:165], v[126:129]
	v_mfma_f32_16x16x32_bf16 v[122:125], v[150:153], v[162:165], v[122:125]
	v_mfma_f32_16x16x32_bf16 v[118:121], v[154:157], v[162:165], v[118:121]
	v_mfma_f32_16x16x32_bf16 v[114:117], v[158:161], v[162:165], v[114:117]
	v_mfma_f32_16x16x32_bf16 v[110:113], v[146:149], v[166:169], v[110:113]
	v_mfma_f32_16x16x32_bf16 v[106:109], v[150:153], v[166:169], v[106:109]
	v_mfma_f32_16x16x32_bf16 v[102:105], v[154:157], v[166:169], v[102:105]
	v_mfma_f32_16x16x32_bf16 v[98:101], v[158:161], v[166:169], v[98:101]
	v_mfma_f32_16x16x32_bf16 v[94:97], v[146:149], v[170:173], v[94:97]
	v_mfma_f32_16x16x32_bf16 v[90:93], v[150:153], v[170:173], v[90:93]
	v_mfma_f32_16x16x32_bf16 v[86:89], v[154:157], v[170:173], v[86:89]
	v_mfma_f32_16x16x32_bf16 v[82:85], v[158:161], v[170:173], v[82:85]
	v_mfma_f32_16x16x32_bf16 v[78:81], v[146:149], v[174:177], v[78:81]
	v_mfma_f32_16x16x32_bf16 v[74:77], v[150:153], v[174:177], v[74:77]
	v_mfma_f32_16x16x32_bf16 v[70:73], v[154:157], v[174:177], v[70:73]
	v_mfma_f32_16x16x32_bf16 v[66:69], v[158:161], v[174:177], v[66:69]
	ds_read_b128 v[162:165], v178 offset:4096
	ds_read_b128 v[166:169], v178 offset:5120
	ds_read_b128 v[170:173], v178 offset:6144
	ds_read_b128 v[174:177], v178 offset:7168
	s_waitcnt lgkmcnt(0)
	v_mfma_f32_16x16x32_bf16 v[62:65], v[146:149], v[162:165], v[62:65]
	v_mfma_f32_16x16x32_bf16 v[58:61], v[150:153], v[162:165], v[58:61]
	v_mfma_f32_16x16x32_bf16 v[54:57], v[154:157], v[162:165], v[54:57]
	v_mfma_f32_16x16x32_bf16 v[50:53], v[158:161], v[162:165], v[50:53]
	v_mfma_f32_16x16x32_bf16 v[46:49], v[146:149], v[166:169], v[46:49]
	v_mfma_f32_16x16x32_bf16 v[42:45], v[150:153], v[166:169], v[42:45]
	v_mfma_f32_16x16x32_bf16 v[38:41], v[154:157], v[166:169], v[38:41]
	v_mfma_f32_16x16x32_bf16 v[34:37], v[158:161], v[166:169], v[34:37]
	v_mfma_f32_16x16x32_bf16 v[30:33], v[146:149], v[170:173], v[30:33]
	v_mfma_f32_16x16x32_bf16 v[26:29], v[150:153], v[170:173], v[26:29]
	v_mfma_f32_16x16x32_bf16 v[22:25], v[154:157], v[170:173], v[22:25]
	v_mfma_f32_16x16x32_bf16 v[18:21], v[158:161], v[170:173], v[18:21]
	v_mfma_f32_16x16x32_bf16 v[14:17], v[146:149], v[174:177], v[14:17]
	v_mfma_f32_16x16x32_bf16 v[10:13], v[150:153], v[174:177], v[10:13]
	v_mfma_f32_16x16x32_bf16 v[6:9], v[154:157], v[174:177], v[6:9]
	v_mfma_f32_16x16x32_bf16 v[2:5], v[158:161], v[174:177], v[2:5]
	s_add_i32 s43, s1, 1
	s_cmp_lg_u32 s1, 2
	s_cselect_b32 s1, s43, 0
	s_add_u32 s48, s48, 64
	s_addc_u32 s49, s49, 0
	s_cmpk_eq_i32 s48, 0x780
	s_cbranch_scc0 .LBB0_531
	v_add3_u32 v170, 0, v142, v145
	v_add3_u32 v174, 0, v144, v145
	s_waitcnt vmcnt(6)
	s_barrier
	ds_read_b128 v[136:139], v170 offset:16384
	ds_read_b128 v[146:149], v170 offset:17408
	ds_read_b128 v[150:153], v170 offset:18432
	ds_read_b128 v[154:157], v170 offset:19456
	ds_read_b128 v[142:145], v174
	ds_read_b128 v[158:161], v174 offset:1024
	ds_read_b128 v[162:165], v174 offset:2048
	ds_read_b128 v[166:169], v174 offset:3072
	s_lshl_b64 s[46:47], s[46:47], 8
	s_waitcnt lgkmcnt(0)
	v_mfma_f32_16x16x32_bf16 v[122:125], v[146:149], v[142:145], v[122:125]
	v_mfma_f32_16x16x32_bf16 v[118:121], v[150:153], v[142:145], v[118:121]
	v_mfma_f32_16x16x32_bf16 v[114:117], v[154:157], v[142:145], v[114:117]
	v_mfma_f32_16x16x32_bf16 v[110:113], v[136:139], v[158:161], v[110:113]
	v_mfma_f32_16x16x32_bf16 v[106:109], v[146:149], v[158:161], v[106:109]
	v_mfma_f32_16x16x32_bf16 v[102:105], v[150:153], v[158:161], v[102:105]
	v_mfma_f32_16x16x32_bf16 v[98:101], v[154:157], v[158:161], v[98:101]
	v_mfma_f32_16x16x32_bf16 v[94:97], v[136:139], v[162:165], v[94:97]
	v_mfma_f32_16x16x32_bf16 v[90:93], v[146:149], v[162:165], v[90:93]
	v_mfma_f32_16x16x32_bf16 v[86:89], v[150:153], v[162:165], v[86:89]
	v_mfma_f32_16x16x32_bf16 v[82:85], v[154:157], v[162:165], v[82:85]
	v_mfma_f32_16x16x32_bf16 v[78:81], v[136:139], v[166:169], v[78:81]
	v_mfma_f32_16x16x32_bf16 v[74:77], v[146:149], v[166:169], v[74:77]
	v_mfma_f32_16x16x32_bf16 v[70:73], v[150:153], v[166:169], v[70:73]
	v_mfma_f32_16x16x32_bf16 v[66:69], v[154:157], v[166:169], v[66:69]
	v_mfma_f32_16x16x32_bf16 v[126:129], v[136:139], v[142:145], v[126:129]
	ds_read_b128 v[142:145], v174 offset:4096
	ds_read_b128 v[158:161], v174 offset:5120
	ds_read_b128 v[162:165], v174 offset:6144
	ds_read_b128 v[166:169], v174 offset:7168
	s_waitcnt lgkmcnt(0)
	v_mfma_f32_16x16x32_bf16 v[62:65], v[136:139], v[142:145], v[62:65]
	v_mfma_f32_16x16x32_bf16 v[58:61], v[146:149], v[142:145], v[58:61]
	v_mfma_f32_16x16x32_bf16 v[54:57], v[150:153], v[142:145], v[54:57]
	v_mfma_f32_16x16x32_bf16 v[50:53], v[154:157], v[142:145], v[50:53]
	v_mfma_f32_16x16x32_bf16 v[46:49], v[136:139], v[158:161], v[46:49]
	v_mfma_f32_16x16x32_bf16 v[42:45], v[146:149], v[158:161], v[42:45]
	v_mfma_f32_16x16x32_bf16 v[38:41], v[150:153], v[158:161], v[38:41]
	v_mfma_f32_16x16x32_bf16 v[34:37], v[154:157], v[158:161], v[34:37]
	v_mfma_f32_16x16x32_bf16 v[30:33], v[136:139], v[162:165], v[30:33]
	v_mfma_f32_16x16x32_bf16 v[26:29], v[146:149], v[162:165], v[26:29]
	v_mfma_f32_16x16x32_bf16 v[22:25], v[150:153], v[162:165], v[22:25]
	v_mfma_f32_16x16x32_bf16 v[18:21], v[154:157], v[162:165], v[18:21]
	v_mfma_f32_16x16x32_bf16 v[14:17], v[136:139], v[166:169], v[14:17]
	v_mfma_f32_16x16x32_bf16 v[10:13], v[146:149], v[166:169], v[10:13]
	v_mfma_f32_16x16x32_bf16 v[6:9], v[150:153], v[166:169], v[6:9]
	v_mfma_f32_16x16x32_bf16 v[2:5], v[154:157], v[166:169], v[2:5]
	s_waitcnt vmcnt(0)
	s_barrier
	ds_read_b128 v[136:139], v170 offset:40960
	ds_read_b128 v[142:145], v170 offset:41984
	ds_read_b128 v[146:149], v170 offset:43008
	ds_read_b128 v[150:153], v170 offset:44032
	ds_read_b128 v[154:157], v174 offset:24576
	ds_read_b128 v[158:161], v174 offset:25600
	ds_read_b128 v[162:165], v174 offset:26624
	ds_read_b128 v[166:169], v174 offset:27648
	s_waitcnt lgkmcnt(0)
	v_mfma_f32_16x16x32_bf16 v[122:125], v[142:145], v[154:157], v[122:125]
	v_mfma_f32_16x16x32_bf16 v[110:113], v[136:139], v[158:161], v[110:113]
	v_mfma_f32_16x16x32_bf16 v[106:109], v[142:145], v[158:161], v[106:109]
	v_mfma_f32_16x16x32_bf16 v[102:105], v[146:149], v[158:161], v[102:105]
	v_mfma_f32_16x16x32_bf16 v[98:101], v[150:153], v[158:161], v[98:101]
	v_mfma_f32_16x16x32_bf16 v[94:97], v[136:139], v[162:165], v[94:97]
	v_mfma_f32_16x16x32_bf16 v[90:93], v[142:145], v[162:165], v[90:93]
	v_mfma_f32_16x16x32_bf16 v[86:89], v[146:149], v[162:165], v[86:89]
	v_mfma_f32_16x16x32_bf16 v[82:85], v[150:153], v[162:165], v[82:85]
	v_mfma_f32_16x16x32_bf16 v[78:81], v[136:139], v[166:169], v[78:81]
	v_mfma_f32_16x16x32_bf16 v[74:77], v[142:145], v[166:169], v[74:77]
	v_mfma_f32_16x16x32_bf16 v[70:73], v[146:149], v[166:169], v[70:73]
	v_mfma_f32_16x16x32_bf16 v[66:69], v[150:153], v[166:169], v[66:69]
	v_mfma_f32_16x16x32_bf16 v[126:129], v[136:139], v[154:157], v[126:129]
	v_mfma_f32_16x16x32_bf16 v[170:173], v[146:149], v[154:157], v[118:121]
	v_mfma_f32_16x16x32_bf16 v[154:157], v[150:153], v[154:157], v[114:117]
	s_nop 1
	ds_read_b128 v[114:117], v174 offset:28672
	ds_read_b128 v[118:121], v174 offset:29696
	ds_read_b128 v[158:161], v174 offset:30720
	ds_read_b128 v[162:165], v174 offset:31744
	s_waitcnt lgkmcnt(0)
	v_mfma_f32_16x16x32_bf16 v[62:65], v[136:139], v[114:117], v[62:65]
	v_mfma_f32_16x16x32_bf16 v[58:61], v[142:145], v[114:117], v[58:61]
	v_mfma_f32_16x16x32_bf16 v[54:57], v[146:149], v[114:117], v[54:57]
	v_mfma_f32_16x16x32_bf16 v[50:53], v[150:153], v[114:117], v[50:53]
	v_mfma_f32_16x16x32_bf16 v[46:49], v[136:139], v[118:121], v[46:49]
	v_mfma_f32_16x16x32_bf16 v[42:45], v[142:145], v[118:121], v[42:45]
	v_mfma_f32_16x16x32_bf16 v[38:41], v[146:149], v[118:121], v[38:41]
	v_mfma_f32_16x16x32_bf16 v[34:37], v[150:153], v[118:121], v[34:37]
	v_mfma_f32_16x16x32_bf16 v[30:33], v[136:139], v[158:161], v[30:33]
	v_mfma_f32_16x16x32_bf16 v[26:29], v[142:145], v[158:161], v[26:29]
	v_mfma_f32_16x16x32_bf16 v[22:25], v[146:149], v[158:161], v[22:25]
	v_mfma_f32_16x16x32_bf16 v[18:21], v[150:153], v[158:161], v[18:21]
	v_mfma_f32_16x16x32_bf16 v[14:17], v[136:139], v[162:165], v[14:17]
	v_mfma_f32_16x16x32_bf16 v[10:13], v[142:145], v[162:165], v[10:13]
	v_mfma_f32_16x16x32_bf16 v[6:9], v[146:149], v[162:165], v[6:9]
	v_mfma_f32_16x16x32_bf16 v[2:5], v[150:153], v[162:165], v[2:5]
	v_lshl_add_u64 v[114:115], s[46:47], 0, v[134:135]
	v_lshl_or_b32 v116, s0, 7, v140
	v_lshlrev_b64 v[120:121], 12, v[114:115]
	v_ashrrev_i32_e32 v117, 31, v116
	v_lshl_add_u64 v[136:137], v[132:133], 0, v[120:121]
	v_lshlrev_b64 v[118:119], 2, v[116:117]
	v_lshl_add_u64 v[146:147], v[136:137], 0, v[118:119]
	s_waitcnt vmcnt(0)
	s_barrier
	flat_load_dwordx4 v[136:139], v[146:147]
	v_lshlrev_b64 v[142:143], 11, v[114:115]
	v_lshl_add_u64 v[120:121], v[130:131], 0, v[120:121]
	v_lshl_add_u64 v[142:143], s[8:9], 0, v[142:143]
	v_lshl_add_u64 v[150:151], v[120:121], 0, v[118:119]
	v_lshl_add_u64 v[152:153], v[116:117], 1, v[142:143]
	s_waitcnt vmcnt(0) lgkmcnt(0)
	v_pk_add_f32 v[126:127], v[126:127], v[136:137]
	v_pk_add_f32 v[128:129], v[128:129], v[138:139]
	v_cvt_pk_bf16_f32 v120, v126, v127
	v_cvt_pk_bf16_f32 v121, v128, v129
	flat_store_dwordx4 v[150:151], v[126:129]
	flat_store_dwordx2 v[152:153], v[120:121]
	flat_load_dwordx4 v[136:139], v[146:147] offset:64
	s_waitcnt vmcnt(0) lgkmcnt(0)
	v_pk_add_f32 v[136:137], v[122:123], v[136:137]
	v_pk_add_f32 v[138:139], v[124:125], v[138:139]
	v_cvt_pk_bf16_f32 v120, v136, v137
	v_cvt_pk_bf16_f32 v121, v138, v139
	flat_store_dwordx4 v[150:151], v[136:139] offset:64
	flat_store_dwordx2 v[152:153], v[120:121] offset:32
	flat_load_dwordx4 v[120:123], v[146:147] offset:128
	v_pk_mul_f32 v[124:125], v[128:129], v[128:129]
	s_waitcnt vmcnt(0) lgkmcnt(0)
	v_pk_add_f32 v[142:143], v[170:171], v[120:121]
	v_pk_add_f32 v[144:145], v[172:173], v[122:123]
	v_cvt_pk_bf16_f32 v120, v142, v143
	v_cvt_pk_bf16_f32 v121, v144, v145
	flat_store_dwordx4 v[150:151], v[142:145] offset:128
	flat_store_dwordx2 v[152:153], v[120:121] offset:64
	flat_load_dwordx4 v[146:149], v[146:147] offset:192
	v_and_b32_e32 v121, 64, v141
	v_xor_b32_e32 v120, 16, v141
	v_add_u32_e32 v123, 64, v121
	v_cmp_lt_i32_e64 s[0:1], v120, v123
	s_nop 1
	v_cndmask_b32_e64 v120, v141, v120, s[0:1]
	v_lshlrev_b32_e32 v122, 2, v120
	v_pk_mul_f32 v[120:121], v[126:127], v[126:127]
	s_nop 0
	v_add_f32_e32 v120, v120, v121
	v_add_f32_e32 v120, v120, v124
	v_add_f32_e32 v126, v120, v125
	v_pk_mul_f32 v[120:121], v[136:137], v[136:137]
	v_pk_mul_f32 v[124:125], v[138:139], v[138:139]
	v_add_f32_e32 v120, v120, v121
	v_add_f32_e32 v120, v120, v124
	v_add_f32_e32 v120, v120, v125
	v_add_f32_e32 v136, v126, v120
	v_pk_mul_f32 v[120:121], v[142:143], v[142:143]
	v_pk_mul_f32 v[124:125], v[144:145], v[144:145]
	v_add_f32_e32 v120, v120, v121
	v_add_f32_e32 v120, v120, v124
	v_add_f32_e32 v137, v120, v125
	v_add_f32_e32 v136, v136, v137
	s_waitcnt vmcnt(0) lgkmcnt(0)
	v_pk_add_f32 v[124:125], v[154:155], v[146:147]
	v_pk_add_f32 v[126:127], v[156:157], v[148:149]
	v_pk_mul_f32 v[120:121], v[124:125], v[124:125]
	v_pk_mul_f32 v[128:129], v[126:127], v[126:127]
	v_add_f32_e32 v120, v120, v121
	v_add_f32_e32 v120, v120, v128
	v_add_f32_e32 v120, v120, v129
	v_add_f32_e32 v120, v136, v120
	ds_bpermute_b32 v121, v122, v120
	v_xor_b32_e32 v128, 32, v141
	v_cmp_lt_i32_e64 s[0:1], v128, v123
	flat_store_dwordx4 v[150:151], v[124:127] offset:192
	s_waitcnt lgkmcnt(0)
	v_add_f32_e32 v120, v120, v121
	v_cndmask_b32_e64 v123, v141, v128, s[0:1]
	v_lshlrev_b32_e32 v123, 2, v123
	ds_bpermute_b32 v121, v123, v120
	v_cvt_pk_bf16_f32 v124, v124, v125
	v_cvt_pk_bf16_f32 v125, v126, v127
	flat_store_dwordx2 v[152:153], v[124:125] offset:96
	s_and_saveexec_b64 s[0:1], vcc
	s_cbranch_execz .LBB0_534
	s_waitcnt lgkmcnt(0)
	v_add_f32_e32 v124, v120, v121
	v_lshl_add_u64 v[120:121], v[114:115], 2, s[10:11]
	flat_atomic_add_f32 v[120:121], v124

.LBB0_564:
	s_mul_i32 s51, s45, 0x6000
	s_add_i32 s52, s51, 0xffffa000
	s_cmp_lg_u32 s45, 0
	s_cselect_b32 s52, s52, 0xc000
	v_add_u32_e32 v146, s52, v138
	v_lshl_add_u64 v[142:143], v[134:135], 0, s[48:49]
	v_readfirstlane_b32 s52, v146
	v_add_u32_e32 v147, 0x1000, v146
	v_lshl_add_u64 v[144:145], v[142:143], 0, s[22:23]
	s_mov_b32 m0, s52
	v_readfirstlane_b32 s52, v147
	v_add_u32_e32 v147, 0x2000, v146
	s_waitcnt vmcnt(6)
	s_barrier
	global_load_lds_dwordx4 v[144:145], off
	v_lshl_add_u64 v[144:145], v[142:143], 0, s[24:25]
	s_mov_b32 m0, s52
	v_readfirstlane_b32 s52, v147
	global_load_lds_dwordx4 v[144:145], off
	v_lshl_add_u64 v[144:145], v[142:143], 0, s[26:27]
	s_mov_b32 m0, s52
	v_lshl_add_u64 v[142:143], v[142:143], 0, s[28:29]
	global_load_lds_dwordx4 v[144:145], off
	v_add_u32_e32 v144, 0x3000, v146
	v_add_u32_e32 v147, 0x4000, v146
	v_readfirstlane_b32 s52, v144
	s_mov_b32 m0, s52
	v_readfirstlane_b32 s52, v147
	global_load_lds_dwordx4 v[142:143], off
	v_lshl_add_u64 v[142:143], v[132:133], 0, s[48:49]
	v_lshl_add_u64 v[144:145], v[142:143], 0, s[30:31]
	s_mov_b32 m0, s52
	v_lshl_add_u64 v[142:143], v[142:143], 0, s[34:35]
	global_load_lds_dwordx4 v[144:145], off
	v_add_u32_e32 v144, 0x5000, v146
	s_add_i32 s51, s51, 0
	v_readfirstlane_b32 s52, v144
	s_mov_b32 m0, s52
	v_add3_u32 v154, s51, v139, v141
	global_load_lds_dwordx4 v[142:143], off
	v_add3_u32 v174, s51, v140, v141
	ds_read_b128 v[142:145], v154 offset:16384
	ds_read_b128 v[146:149], v154 offset:17408
	ds_read_b128 v[150:153], v154 offset:18432
	ds_read_b128 v[154:157], v154 offset:19456
	ds_read_b128 v[158:161], v174
	ds_read_b128 v[162:165], v174 offset:1024
	ds_read_b128 v[166:169], v174 offset:2048
	ds_read_b128 v[170:173], v174 offset:3072
	s_waitcnt lgkmcnt(0)
	v_mfma_f32_16x16x32_bf16 v[126:129], v[142:145], v[158:161], v[126:129]
	v_mfma_f32_16x16x32_bf16 v[122:125], v[146:149], v[158:161], v[122:125]
	v_mfma_f32_16x16x32_bf16 v[118:121], v[150:153], v[158:161], v[118:121]
	v_mfma_f32_16x16x32_bf16 v[114:117], v[154:157], v[158:161], v[114:117]
	v_mfma_f32_16x16x32_bf16 v[110:113], v[142:145], v[162:165], v[110:113]
	v_mfma_f32_16x16x32_bf16 v[106:109], v[146:149], v[162:165], v[106:109]
	v_mfma_f32_16x16x32_bf16 v[102:105], v[150:153], v[162:165], v[102:105]
	v_mfma_f32_16x16x32_bf16 v[98:101], v[154:157], v[162:165], v[98:101]
	v_mfma_f32_16x16x32_bf16 v[94:97], v[142:145], v[166:169], v[94:97]
	v_mfma_f32_16x16x32_bf16 v[90:93], v[146:149], v[166:169], v[90:93]
	v_mfma_f32_16x16x32_bf16 v[86:89], v[150:153], v[166:169], v[86:89]
	v_mfma_f32_16x16x32_bf16 v[82:85], v[154:157], v[166:169], v[82:85]
	v_mfma_f32_16x16x32_bf16 v[78:81], v[142:145], v[170:173], v[78:81]
	v_mfma_f32_16x16x32_bf16 v[74:77], v[146:149], v[170:173], v[74:77]
	v_mfma_f32_16x16x32_bf16 v[70:73], v[150:153], v[170:173], v[70:73]
	v_mfma_f32_16x16x32_bf16 v[66:69], v[154:157], v[170:173], v[66:69]
	ds_read_b128 v[158:161], v174 offset:4096
	ds_read_b128 v[162:165], v174 offset:5120
	ds_read_b128 v[166:169], v174 offset:6144
	ds_read_b128 v[170:173], v174 offset:7168
	s_waitcnt lgkmcnt(0)
	v_mfma_f32_16x16x32_bf16 v[62:65], v[142:145], v[158:161], v[62:65]
	v_mfma_f32_16x16x32_bf16 v[58:61], v[146:149], v[158:161], v[58:61]
	v_mfma_f32_16x16x32_bf16 v[54:57], v[150:153], v[158:161], v[54:57]
	v_mfma_f32_16x16x32_bf16 v[50:53], v[154:157], v[158:161], v[50:53]
	v_mfma_f32_16x16x32_bf16 v[46:49], v[142:145], v[162:165], v[46:49]
	v_mfma_f32_16x16x32_bf16 v[42:45], v[146:149], v[162:165], v[42:45]
	v_mfma_f32_16x16x32_bf16 v[38:41], v[150:153], v[162:165], v[38:41]
	v_mfma_f32_16x16x32_bf16 v[34:37], v[154:157], v[162:165], v[34:37]
	v_mfma_f32_16x16x32_bf16 v[30:33], v[142:145], v[166:169], v[30:33]
	v_mfma_f32_16x16x32_bf16 v[26:29], v[146:149], v[166:169], v[26:29]
	v_mfma_f32_16x16x32_bf16 v[22:25], v[150:153], v[166:169], v[22:25]
	v_mfma_f32_16x16x32_bf16 v[18:21], v[154:157], v[166:169], v[18:21]
	v_mfma_f32_16x16x32_bf16 v[14:17], v[142:145], v[170:173], v[14:17]
	v_mfma_f32_16x16x32_bf16 v[10:13], v[146:149], v[170:173], v[10:13]
	v_mfma_f32_16x16x32_bf16 v[6:9], v[150:153], v[170:173], v[6:9]
	v_mfma_f32_16x16x32_bf16 v[2:5], v[154:157], v[170:173], v[2:5]
	s_add_i32 s51, s45, 1
	s_cmp_lg_u32 s45, 2
	s_cselect_b32 s45, s51, 0
	s_add_u32 s48, s48, 64
	s_addc_u32 s49, s49, 0
	s_cmpk_eq_i32 s48, 0x780
	s_cbranch_scc0 .LBB0_564
	v_add3_u32 v166, 0, v139, v141
	v_add3_u32 v167, 0, v140, v141
	s_waitcnt vmcnt(6)
	s_barrier
	ds_read_b128 v[132:135], v166 offset:16384
	ds_read_b128 v[142:145], v166 offset:17408
	ds_read_b128 v[146:149], v166 offset:18432
	ds_read_b128 v[150:153], v166 offset:19456
	ds_read_b128 v[138:141], v167
	ds_read_b128 v[154:157], v167 offset:1024
	ds_read_b128 v[158:161], v167 offset:2048
	ds_read_b128 v[162:165], v167 offset:3072
	s_waitcnt lgkmcnt(0)
	v_mfma_f32_16x16x32_bf16 v[126:129], v[132:135], v[138:141], v[126:129]
	v_mfma_f32_16x16x32_bf16 v[122:125], v[142:145], v[138:141], v[122:125]
	v_mfma_f32_16x16x32_bf16 v[118:121], v[146:149], v[138:141], v[118:121]
	v_mfma_f32_16x16x32_bf16 v[114:117], v[150:153], v[138:141], v[114:117]
	v_mfma_f32_16x16x32_bf16 v[110:113], v[132:135], v[154:157], v[110:113]
	v_mfma_f32_16x16x32_bf16 v[106:109], v[142:145], v[154:157], v[106:109]
	v_mfma_f32_16x16x32_bf16 v[102:105], v[146:149], v[154:157], v[102:105]
	v_mfma_f32_16x16x32_bf16 v[98:101], v[150:153], v[154:157], v[98:101]
	v_mfma_f32_16x16x32_bf16 v[94:97], v[132:135], v[158:161], v[94:97]
	v_mfma_f32_16x16x32_bf16 v[90:93], v[142:145], v[158:161], v[90:93]
	v_mfma_f32_16x16x32_bf16 v[86:89], v[146:149], v[158:161], v[86:89]
	v_mfma_f32_16x16x32_bf16 v[82:85], v[150:153], v[158:161], v[82:85]
	v_mfma_f32_16x16x32_bf16 v[78:81], v[132:135], v[162:165], v[78:81]
	v_mfma_f32_16x16x32_bf16 v[74:77], v[142:145], v[162:165], v[74:77]
	v_mfma_f32_16x16x32_bf16 v[70:73], v[146:149], v[162:165], v[70:73]
	v_mfma_f32_16x16x32_bf16 v[66:69], v[150:153], v[162:165], v[66:69]
	ds_read_b128 v[138:141], v167 offset:4096
	ds_read_b128 v[154:157], v167 offset:5120
	ds_read_b128 v[158:161], v167 offset:6144
	ds_read_b128 v[162:165], v167 offset:7168
	s_waitcnt lgkmcnt(0)
	v_mfma_f32_16x16x32_bf16 v[62:65], v[132:135], v[138:141], v[62:65]
	v_mfma_f32_16x16x32_bf16 v[58:61], v[142:145], v[138:141], v[58:61]
	v_mfma_f32_16x16x32_bf16 v[54:57], v[146:149], v[138:141], v[54:57]
	v_mfma_f32_16x16x32_bf16 v[50:53], v[150:153], v[138:141], v[50:53]
	v_mfma_f32_16x16x32_bf16 v[46:49], v[132:135], v[154:157], v[46:49]
	v_mfma_f32_16x16x32_bf16 v[42:45], v[142:145], v[154:157], v[42:45]
	v_mfma_f32_16x16x32_bf16 v[38:41], v[146:149], v[154:157], v[38:41]
	v_mfma_f32_16x16x32_bf16 v[34:37], v[150:153], v[154:157], v[34:37]
	v_mfma_f32_16x16x32_bf16 v[30:33], v[132:135], v[158:161], v[30:33]
	v_mfma_f32_16x16x32_bf16 v[26:29], v[142:145], v[158:161], v[26:29]
	v_mfma_f32_16x16x32_bf16 v[22:25], v[146:149], v[158:161], v[22:25]
	v_mfma_f32_16x16x32_bf16 v[18:21], v[150:153], v[158:161], v[18:21]
	v_mfma_f32_16x16x32_bf16 v[14:17], v[132:135], v[162:165], v[14:17]
	v_mfma_f32_16x16x32_bf16 v[10:13], v[142:145], v[162:165], v[10:13]
	v_mfma_f32_16x16x32_bf16 v[6:9], v[146:149], v[162:165], v[6:9]
	v_mfma_f32_16x16x32_bf16 v[2:5], v[150:153], v[162:165], v[2:5]
	s_waitcnt vmcnt(0)
	s_barrier
	ds_read_b128 v[132:135], v166 offset:40960
	ds_read_b128 v[138:141], v166 offset:41984
	ds_read_b128 v[142:145], v166 offset:43008
	ds_read_b128 v[146:149], v166 offset:44032
	ds_read_b128 v[150:153], v167 offset:24576
	ds_read_b128 v[154:157], v167 offset:25600
	ds_read_b128 v[158:161], v167 offset:26624
	ds_read_b128 v[162:165], v167 offset:27648
	s_lshl_b64 s[46:47], s[46:47], 8
	s_waitcnt lgkmcnt(0)
	v_mfma_f32_16x16x32_bf16 v[126:129], v[132:135], v[150:153], v[126:129]
	v_mfma_f32_16x16x32_bf16 v[122:125], v[138:141], v[150:153], v[122:125]
	v_mfma_f32_16x16x32_bf16 v[118:121], v[142:145], v[150:153], v[118:121]
	v_mfma_f32_16x16x32_bf16 v[114:117], v[146:149], v[150:153], v[114:117]
	v_mfma_f32_16x16x32_bf16 v[110:113], v[132:135], v[154:157], v[110:113]
	v_mfma_f32_16x16x32_bf16 v[150:153], v[138:141], v[154:157], v[106:109]
	v_mfma_f32_16x16x32_bf16 v[102:105], v[142:145], v[154:157], v[102:105]
	v_mfma_f32_16x16x32_bf16 v[98:101], v[146:149], v[154:157], v[98:101]
	v_mfma_f32_16x16x32_bf16 v[94:97], v[132:135], v[158:161], v[94:97]
	v_mfma_f32_16x16x32_bf16 v[90:93], v[138:141], v[158:161], v[90:93]
	v_mfma_f32_16x16x32_bf16 v[86:89], v[142:145], v[158:161], v[86:89]
	v_mfma_f32_16x16x32_bf16 v[82:85], v[146:149], v[158:161], v[82:85]
	v_mfma_f32_16x16x32_bf16 v[78:81], v[132:135], v[162:165], v[78:81]
	v_mfma_f32_16x16x32_bf16 v[74:77], v[138:141], v[162:165], v[74:77]
	v_mfma_f32_16x16x32_bf16 v[70:73], v[142:145], v[162:165], v[70:73]
	v_mfma_f32_16x16x32_bf16 v[66:69], v[146:149], v[162:165], v[66:69]
	ds_read_b128 v[106:109], v167 offset:28672
	ds_read_b128 v[154:157], v167 offset:29696
	ds_read_b128 v[158:161], v167 offset:30720
	ds_read_b128 v[162:165], v167 offset:31744
	s_waitcnt lgkmcnt(0)
	v_mfma_f32_16x16x32_bf16 v[62:65], v[132:135], v[106:109], v[62:65]
	v_mfma_f32_16x16x32_bf16 v[58:61], v[138:141], v[106:109], v[58:61]
	v_mfma_f32_16x16x32_bf16 v[54:57], v[142:145], v[106:109], v[54:57]
	v_mfma_f32_16x16x32_bf16 v[50:53], v[146:149], v[106:109], v[50:53]
	v_mfma_f32_16x16x32_bf16 v[46:49], v[132:135], v[154:157], v[46:49]
	v_mfma_f32_16x16x32_bf16 v[42:45], v[138:141], v[154:157], v[42:45]
	v_mfma_f32_16x16x32_bf16 v[38:41], v[142:145], v[154:157], v[38:41]
	v_mfma_f32_16x16x32_bf16 v[34:37], v[146:149], v[154:157], v[34:37]
	v_mfma_f32_16x16x32_bf16 v[30:33], v[132:135], v[158:161], v[30:33]
	v_mfma_f32_16x16x32_bf16 v[26:29], v[138:141], v[158:161], v[26:29]
	v_mfma_f32_16x16x32_bf16 v[22:25], v[142:145], v[158:161], v[22:25]
	v_mfma_f32_16x16x32_bf16 v[18:21], v[146:149], v[158:161], v[18:21]
	v_mfma_f32_16x16x32_bf16 v[14:17], v[132:135], v[162:165], v[14:17]
	v_mfma_f32_16x16x32_bf16 v[10:13], v[138:141], v[162:165], v[10:13]
	v_mfma_f32_16x16x32_bf16 v[6:9], v[142:145], v[162:165], v[6:9]
	v_mfma_f32_16x16x32_bf16 v[2:5], v[146:149], v[162:165], v[2:5]
	v_lshl_add_u64 v[106:107], s[46:47], 0, v[130:131]
	v_lshl_add_u64 v[108:109], v[106:107], 2, s[8:9]
	s_waitcnt vmcnt(0)
	s_barrier
	flat_load_dword v138, v[108:109]
	v_max_f32_e32 v109, v126, v126
	v_max_f32_e32 v126, v127, v127
	v_max_f32_e32 v127, v128, v128
	v_max_f32_e32 v128, v129, v129
	v_max_f32_e32 v122, v122, v122
	v_max_f32_e32 v124, v124, v124
	v_max_f32_e32 v129, v118, v118
	v_max_f32_e32 v139, v115, v115
	v_max_f32_e32 v133, v120, v120
	v_max_f32_e32 v120, 0, v122
	v_max_f32_e32 v122, 0, v124
	v_max_f32_e32 v124, 0, v129
	v_max_f32_e32 v129, 0, v139
	v_max_f32_e32 v123, v123, v123
	v_max_f32_e32 v125, v125, v125
	v_max_f32_e32 v132, v119, v119
	v_max_f32_e32 v140, v116, v116
	v_max_f32_e32 v134, v121, v121
	v_max_f32_e32 v121, 0, v123
	v_max_f32_e32 v123, 0, v125
	v_max_f32_e32 v125, 0, v132
	v_max_f32_e32 v132, 0, v140
	v_max_f32_e32 v141, v117, v117
	v_max_f32_e32 v117, 0, v126
	v_max_f32_e32 v126, 0, v133
	v_max_f32_e32 v133, 0, v141
	v_lshl_or_b32 v108, s44, 7, v136
	v_max_f32_e32 v135, v114, v114
	v_max_f32_e32 v116, 0, v109
	v_max_f32_e32 v118, 0, v127
	v_max_f32_e32 v119, 0, v128
	v_lshlrev_b64 v[114:115], 13, v[106:107]
	v_ashrrev_i32_e32 v109, 31, v108
	v_max_f32_e32 v127, 0, v134
	v_max_f32_e32 v128, 0, v135
	v_lshl_add_u64 v[114:115], s[6:7], 0, v[114:115]
	v_lshlrev_b64 v[108:109], 1, v[108:109]
	v_or_b32_e32 v134, 16, v106
	v_mov_b32_e32 v135, v107
	v_lshl_add_u64 v[114:115], v[114:115], 0, v[108:109]
	v_max_f32_e32 v110, v110, v110
	v_max_f32_e32 v111, v111, v111
	v_max_f32_e32 v112, v112, v112
	v_max_f32_e32 v113, v113, v113
	v_max_f32_e32 v94, v94, v94
	v_max_f32_e32 v95, v95, v95
	v_max_f32_e32 v96, v96, v96
	v_max_f32_e32 v97, v97, v97
	v_max_f32_e32 v90, v90, v90
	v_max_f32_e32 v91, v91, v91
	v_max_f32_e32 v92, v92, v92
	v_max_f32_e32 v93, v93, v93
	v_max_f32_e32 v78, v78, v78
	v_max_f32_e32 v79, v79, v79
	v_max_f32_e32 v80, v80, v80
	v_max_f32_e32 v81, v81, v81
	v_max_f32_e32 v74, v74, v74
	v_max_f32_e32 v75, v75, v75
	v_max_f32_e32 v76, v76, v76
	v_max_f32_e32 v77, v77, v77
	v_max_f32_e32 v62, v62, v62
	v_max_f32_e32 v63, v63, v63
	v_max_f32_e32 v64, v64, v64
	v_max_f32_e32 v65, v65, v65
	v_max_f32_e32 v58, v58, v58
	v_max_f32_e32 v59, v59, v59
	v_max_f32_e32 v60, v60, v60
	v_max_f32_e32 v61, v61, v61
	v_max_f32_e32 v46, v46, v46
	v_max_f32_e32 v47, v47, v47
	v_max_f32_e32 v48, v48, v48
	v_max_f32_e32 v49, v49, v49
	v_max_f32_e32 v42, v42, v42
	v_max_f32_e32 v43, v43, v43
	v_max_f32_e32 v44, v44, v44
	v_max_f32_e32 v45, v45, v45
	v_max_f32_e32 v28, v28, v28
	v_max_f32_e32 v29, v29, v29
	v_max_f32_e32 v30, v30, v30
	s_waitcnt vmcnt(0) lgkmcnt(0)
	v_fmamk_f32 v138, v138, 0x3a800000, v137
	v_mul_f32_e32 v139, 0x4b800000, v138
	v_cmp_gt_f32_e32 vcc, s43, v138
	v_max_f32_e32 v31, v31, v31
	v_max_f32_e32 v32, v32, v32
	v_cndmask_b32_e32 v138, v138, v139, vcc
	v_rsq_f32_e32 v140, v138
	v_lshl_add_u64 v[138:139], v[134:135], 2, s[8:9]
	v_max_f32_e32 v33, v33, v33
	v_max_f32_e32 v26, v26, v26
	v_mul_f32_e32 v141, 0x45800000, v140
	v_cndmask_b32_e32 v140, v140, v141, vcc
	v_pk_mul_f32 v[116:117], v[116:117], v[140:141] op_sel_hi:[1,0]
	v_pk_mul_f32 v[118:119], v[118:119], v[140:141] op_sel_hi:[1,0]
	v_pk_mul_f32 v[120:121], v[120:121], v[140:141] op_sel_hi:[1,0]
	v_pk_mul_f32 v[122:123], v[122:123], v[140:141] op_sel_hi:[1,0]
	v_pk_mul_f32 v[124:125], v[124:125], v[140:141] op_sel_hi:[1,0]
	v_pk_mul_f32 v[126:127], v[126:127], v[140:141] op_sel_hi:[1,0]
	v_pk_mul_f32 v[128:129], v[128:129], v[140:141] op_sel_hi:[1,0]
	v_pk_mul_f32 v[132:133], v[132:133], v[140:141] op_sel_hi:[1,0]
	v_pk_mul_f32 v[116:117], v[116:117], v[116:117]
	v_pk_mul_f32 v[118:119], v[118:119], v[118:119]
	v_pk_mul_f32 v[120:121], v[120:121], v[120:121]
	v_pk_mul_f32 v[122:123], v[122:123], v[122:123]
	v_pk_mul_f32 v[124:125], v[124:125], v[124:125]
	v_pk_mul_f32 v[126:127], v[126:127], v[126:127]
	v_pk_mul_f32 v[128:129], v[128:129], v[128:129]
	v_pk_mul_f32 v[132:133], v[132:133], v[132:133]
	v_cvt_pk_bf16_f32 v116, v116, v117
	v_cvt_pk_bf16_f32 v117, v118, v119
	v_cvt_pk_bf16_f32 v118, v120, v121
	v_cvt_pk_bf16_f32 v119, v122, v123
	v_cvt_pk_bf16_f32 v120, v124, v125
	v_cvt_pk_bf16_f32 v121, v126, v127
	v_cvt_pk_bf16_f32 v122, v128, v129
	v_cvt_pk_bf16_f32 v123, v132, v133
	flat_store_dwordx2 v[114:115], v[116:117]
	flat_store_dwordx2 v[114:115], v[118:119] offset:32
	flat_store_dwordx2 v[114:115], v[120:121] offset:64
	flat_store_dwordx2 v[114:115], v[122:123] offset:96
	flat_load_dword v122, v[138:139]
	v_max_f32_e32 v114, v150, v150
	v_max_f32_e32 v123, v98, v98
	v_max_f32_e32 v118, v102, v102
	v_max_f32_e32 v102, 0, v114
	v_max_f32_e32 v114, 0, v123
	v_max_f32_e32 v115, v151, v151
	v_max_f32_e32 v124, v99, v99
	v_max_f32_e32 v119, v103, v103
	v_max_f32_e32 v103, 0, v115
	v_max_f32_e32 v115, 0, v124
	v_max_f32_e32 v116, v152, v152
	v_max_f32_e32 v125, v100, v100
	v_max_f32_e32 v120, v104, v104
	v_max_f32_e32 v104, 0, v116
	v_max_f32_e32 v116, 0, v125
	v_max_f32_e32 v117, v153, v153
	v_max_f32_e32 v121, v105, v105
	v_max_f32_e32 v126, v101, v101
	v_max_f32_e32 v98, 0, v110
	v_max_f32_e32 v99, 0, v111
	v_max_f32_e32 v100, 0, v112
	v_max_f32_e32 v101, 0, v113
	v_max_f32_e32 v105, 0, v117
	v_max_f32_e32 v110, 0, v118
	v_max_f32_e32 v111, 0, v119
	v_max_f32_e32 v112, 0, v120
	v_max_f32_e32 v113, 0, v121
	v_max_f32_e32 v117, 0, v126
	v_lshlrev_b64 v[120:121], 13, v[134:135]
	v_lshl_add_u64 v[120:121], s[6:7], 0, v[120:121]
	v_or_b32_e32 v118, 32, v106
	v_mov_b32_e32 v119, v107
	v_lshl_add_u64 v[120:121], v[120:121], 0, v[108:109]
	v_max_f32_e32 v27, v27, v27
	v_max_f32_e32 v10, v10, v10
	v_max_f32_e32 v11, v11, v11
	v_max_f32_e32 v12, v12, v12
	v_max_f32_e32 v14, v14, v14
	v_max_f32_e32 v15, v15, v15
	v_max_f32_e32 v16, v16, v16
	v_max_f32_e32 v17, v17, v17
	v_max_f32_e32 v13, v13, v13
	s_add_i32 s50, s50, s40
	s_cmpk_gt_i32 s50, 0x1fff
	s_waitcnt vmcnt(0) lgkmcnt(0)
	v_fmamk_f32 v122, v122, 0x3a800000, v137
	v_mul_f32_e32 v123, 0x4b800000, v122
	v_cmp_gt_f32_e32 vcc, s43, v122
	s_nop 1
	v_cndmask_b32_e32 v122, v122, v123, vcc
	v_rsq_f32_e32 v124, v122
	v_lshl_add_u64 v[122:123], v[118:119], 2, s[8:9]
	v_mul_f32_e32 v125, 0x45800000, v124
	v_cndmask_b32_e32 v124, v124, v125, vcc
	v_pk_mul_f32 v[98:99], v[98:99], v[124:125] op_sel_hi:[1,0]
	v_pk_mul_f32 v[100:101], v[100:101], v[124:125] op_sel_hi:[1,0]
	v_pk_mul_f32 v[102:103], v[102:103], v[124:125] op_sel_hi:[1,0]
	v_pk_mul_f32 v[104:105], v[104:105], v[124:125] op_sel_hi:[1,0]
	v_pk_mul_f32 v[110:111], v[110:111], v[124:125] op_sel_hi:[1,0]
	v_pk_mul_f32 v[112:113], v[112:113], v[124:125] op_sel_hi:[1,0]
	v_pk_mul_f32 v[114:115], v[114:115], v[124:125] op_sel_hi:[1,0]
	v_pk_mul_f32 v[116:117], v[116:117], v[124:125] op_sel_hi:[1,0]
	v_pk_mul_f32 v[98:99], v[98:99], v[98:99]
	v_pk_mul_f32 v[100:101], v[100:101], v[100:101]
	v_pk_mul_f32 v[102:103], v[102:103], v[102:103]
	v_pk_mul_f32 v[104:105], v[104:105], v[104:105]
	v_pk_mul_f32 v[110:111], v[110:111], v[110:111]
	v_pk_mul_f32 v[112:113], v[112:113], v[112:113]
	v_pk_mul_f32 v[114:115], v[114:115], v[114:115]
	v_pk_mul_f32 v[116:117], v[116:117], v[116:117]
	v_cvt_pk_bf16_f32 v98, v98, v99
	v_cvt_pk_bf16_f32 v99, v100, v101
	v_cvt_pk_bf16_f32 v100, v102, v103
	v_cvt_pk_bf16_f32 v101, v104, v105
	v_cvt_pk_bf16_f32 v102, v110, v111
	v_cvt_pk_bf16_f32 v103, v112, v113
	v_cvt_pk_bf16_f32 v104, v114, v115
	v_cvt_pk_bf16_f32 v105, v116, v117
	flat_store_dwordx2 v[120:121], v[98:99]
	flat_store_dwordx2 v[120:121], v[100:101] offset:32
	flat_store_dwordx2 v[120:121], v[102:103] offset:64
	flat_store_dwordx2 v[120:121], v[104:105] offset:96
	flat_load_dword v102, v[122:123]
	v_max_f32_e32 v103, v82, v82
	v_max_f32_e32 v82, 0, v94
	v_max_f32_e32 v94, 0, v103
	v_max_f32_e32 v104, v83, v83
	v_max_f32_e32 v83, 0, v95
	v_max_f32_e32 v95, 0, v104
	v_max_f32_e32 v105, v84, v84
	v_max_f32_e32 v84, 0, v96
	v_max_f32_e32 v96, 0, v105
	v_max_f32_e32 v98, v86, v86
	v_max_f32_e32 v99, v87, v87
	v_max_f32_e32 v100, v88, v88
	v_max_f32_e32 v101, v89, v89
	v_max_f32_e32 v110, v85, v85
	v_max_f32_e32 v85, 0, v97
	v_max_f32_e32 v86, 0, v90
	v_max_f32_e32 v87, 0, v91
	v_max_f32_e32 v88, 0, v92
	v_max_f32_e32 v89, 0, v93
	v_max_f32_e32 v90, 0, v98
	v_max_f32_e32 v91, 0, v99
	v_max_f32_e32 v92, 0, v100
	v_max_f32_e32 v93, 0, v101
	v_max_f32_e32 v97, 0, v110
	v_lshlrev_b64 v[100:101], 13, v[118:119]
	v_lshl_add_u64 v[100:101], s[6:7], 0, v[100:101]
	v_or_b32_e32 v98, 48, v106
	v_mov_b32_e32 v99, v107
	v_lshl_add_u64 v[100:101], v[100:101], 0, v[108:109]
	s_waitcnt vmcnt(0) lgkmcnt(0)
	v_fmamk_f32 v102, v102, 0x3a800000, v137
	v_mul_f32_e32 v103, 0x4b800000, v102
	v_cmp_gt_f32_e32 vcc, s43, v102
	s_nop 1
	v_cndmask_b32_e32 v102, v102, v103, vcc
	v_rsq_f32_e32 v104, v102
	v_lshl_add_u64 v[102:103], v[98:99], 2, s[8:9]
	v_mul_f32_e32 v105, 0x45800000, v104
	v_cndmask_b32_e32 v104, v104, v105, vcc
	v_pk_mul_f32 v[82:83], v[82:83], v[104:105] op_sel_hi:[1,0]
	v_pk_mul_f32 v[84:85], v[84:85], v[104:105] op_sel_hi:[1,0]
	v_pk_mul_f32 v[86:87], v[86:87], v[104:105] op_sel_hi:[1,0]
	v_pk_mul_f32 v[88:89], v[88:89], v[104:105] op_sel_hi:[1,0]
	v_pk_mul_f32 v[90:91], v[90:91], v[104:105] op_sel_hi:[1,0]
	v_pk_mul_f32 v[92:93], v[92:93], v[104:105] op_sel_hi:[1,0]
	v_pk_mul_f32 v[94:95], v[94:95], v[104:105] op_sel_hi:[1,0]
	v_pk_mul_f32 v[96:97], v[96:97], v[104:105] op_sel_hi:[1,0]
	v_pk_mul_f32 v[82:83], v[82:83], v[82:83]
	v_pk_mul_f32 v[84:85], v[84:85], v[84:85]
	v_pk_mul_f32 v[86:87], v[86:87], v[86:87]
	v_pk_mul_f32 v[88:89], v[88:89], v[88:89]
	v_pk_mul_f32 v[90:91], v[90:91], v[90:91]
	v_pk_mul_f32 v[92:93], v[92:93], v[92:93]
	v_pk_mul_f32 v[94:95], v[94:95], v[94:95]
	v_pk_mul_f32 v[96:97], v[96:97], v[96:97]
	v_cvt_pk_bf16_f32 v82, v82, v83
	v_cvt_pk_bf16_f32 v83, v84, v85
	v_cvt_pk_bf16_f32 v84, v86, v87
	v_cvt_pk_bf16_f32 v85, v88, v89
	v_cvt_pk_bf16_f32 v86, v90, v91
	v_cvt_pk_bf16_f32 v87, v92, v93
	v_cvt_pk_bf16_f32 v88, v94, v95
	v_cvt_pk_bf16_f32 v89, v96, v97
	flat_store_dwordx2 v[100:101], v[82:83]
	flat_store_dwordx2 v[100:101], v[84:85] offset:32
	flat_store_dwordx2 v[100:101], v[86:87] offset:64
	flat_store_dwordx2 v[100:101], v[88:89] offset:96
	flat_load_dword v86, v[102:103]
	v_max_f32_e32 v87, v66, v66
	v_max_f32_e32 v66, 0, v78
	v_max_f32_e32 v78, 0, v87
	v_max_f32_e32 v88, v67, v67
	v_max_f32_e32 v67, 0, v79
	v_max_f32_e32 v79, 0, v88
	v_max_f32_e32 v89, v68, v68
	v_max_f32_e32 v68, 0, v80
	v_max_f32_e32 v80, 0, v89
	v_max_f32_e32 v82, v70, v70
	v_max_f32_e32 v83, v71, v71
	v_max_f32_e32 v84, v72, v72
	v_max_f32_e32 v85, v73, v73
	v_max_f32_e32 v90, v69, v69
	v_max_f32_e32 v69, 0, v81
	v_max_f32_e32 v70, 0, v74
	v_max_f32_e32 v71, 0, v75
	v_max_f32_e32 v72, 0, v76
	v_max_f32_e32 v73, 0, v77
	v_max_f32_e32 v74, 0, v82
	v_max_f32_e32 v75, 0, v83
	v_max_f32_e32 v76, 0, v84
	v_max_f32_e32 v77, 0, v85
	v_max_f32_e32 v81, 0, v90
	v_lshlrev_b64 v[84:85], 13, v[98:99]
	v_lshl_add_u64 v[84:85], s[6:7], 0, v[84:85]
	v_or_b32_e32 v82, 64, v106
	v_mov_b32_e32 v83, v107
	v_lshl_add_u64 v[84:85], v[84:85], 0, v[108:109]
	s_waitcnt vmcnt(0) lgkmcnt(0)
	v_fmamk_f32 v86, v86, 0x3a800000, v137
	v_mul_f32_e32 v87, 0x4b800000, v86
	v_cmp_gt_f32_e32 vcc, s43, v86
	s_nop 1
	v_cndmask_b32_e32 v86, v86, v87, vcc
	v_rsq_f32_e32 v88, v86
	v_lshl_add_u64 v[86:87], v[82:83], 2, s[8:9]
	v_mul_f32_e32 v89, 0x45800000, v88
	v_cndmask_b32_e32 v88, v88, v89, vcc
	v_pk_mul_f32 v[66:67], v[66:67], v[88:89] op_sel_hi:[1,0]
	v_pk_mul_f32 v[68:69], v[68:69], v[88:89] op_sel_hi:[1,0]
	v_pk_mul_f32 v[70:71], v[70:71], v[88:89] op_sel_hi:[1,0]
	v_pk_mul_f32 v[72:73], v[72:73], v[88:89] op_sel_hi:[1,0]
	v_pk_mul_f32 v[74:75], v[74:75], v[88:89] op_sel_hi:[1,0]
	v_pk_mul_f32 v[76:77], v[76:77], v[88:89] op_sel_hi:[1,0]
	v_pk_mul_f32 v[78:79], v[78:79], v[88:89] op_sel_hi:[1,0]
	v_pk_mul_f32 v[80:81], v[80:81], v[88:89] op_sel_hi:[1,0]
	v_pk_mul_f32 v[66:67], v[66:67], v[66:67]
	v_pk_mul_f32 v[68:69], v[68:69], v[68:69]
	v_pk_mul_f32 v[70:71], v[70:71], v[70:71]
	v_pk_mul_f32 v[72:73], v[72:73], v[72:73]
	v_pk_mul_f32 v[74:75], v[74:75], v[74:75]
	v_pk_mul_f32 v[76:77], v[76:77], v[76:77]
	v_pk_mul_f32 v[78:79], v[78:79], v[78:79]
	v_pk_mul_f32 v[80:81], v[80:81], v[80:81]
	v_cvt_pk_bf16_f32 v66, v66, v67
	v_cvt_pk_bf16_f32 v67, v68, v69
	v_cvt_pk_bf16_f32 v68, v70, v71
	v_cvt_pk_bf16_f32 v69, v72, v73
	v_cvt_pk_bf16_f32 v70, v74, v75
	v_cvt_pk_bf16_f32 v71, v76, v77
	v_cvt_pk_bf16_f32 v72, v78, v79
	v_cvt_pk_bf16_f32 v73, v80, v81
	flat_store_dwordx2 v[84:85], v[66:67]
	flat_store_dwordx2 v[84:85], v[68:69] offset:32
	flat_store_dwordx2 v[84:85], v[70:71] offset:64
	flat_store_dwordx2 v[84:85], v[72:73] offset:96
	flat_load_dword v70, v[86:87]
	v_max_f32_e32 v71, v50, v50
	v_max_f32_e32 v50, 0, v62
	v_max_f32_e32 v62, 0, v71
	v_max_f32_e32 v72, v51, v51
	v_max_f32_e32 v51, 0, v63
	v_max_f32_e32 v63, 0, v72
	v_max_f32_e32 v73, v52, v52
	v_max_f32_e32 v52, 0, v64
	v_max_f32_e32 v64, 0, v73
	v_max_f32_e32 v66, v54, v54
	v_max_f32_e32 v67, v55, v55
	v_max_f32_e32 v68, v56, v56
	v_max_f32_e32 v69, v57, v57
	v_max_f32_e32 v74, v53, v53
	v_max_f32_e32 v53, 0, v65
	v_max_f32_e32 v54, 0, v58
	v_max_f32_e32 v55, 0, v59
	v_max_f32_e32 v56, 0, v60
	v_max_f32_e32 v57, 0, v61
	v_max_f32_e32 v58, 0, v66
	v_max_f32_e32 v59, 0, v67
	v_max_f32_e32 v60, 0, v68
	v_max_f32_e32 v61, 0, v69
	v_max_f32_e32 v65, 0, v74
	v_lshlrev_b64 v[68:69], 13, v[82:83]
	v_lshl_add_u64 v[68:69], s[6:7], 0, v[68:69]
	v_or_b32_e32 v66, 0x50, v106
	v_mov_b32_e32 v67, v107
	v_lshl_add_u64 v[68:69], v[68:69], 0, v[108:109]
	s_waitcnt vmcnt(0) lgkmcnt(0)
	v_fmamk_f32 v70, v70, 0x3a800000, v137
	v_mul_f32_e32 v71, 0x4b800000, v70
	v_cmp_gt_f32_e32 vcc, s43, v70
	s_nop 1
	v_cndmask_b32_e32 v70, v70, v71, vcc
	v_rsq_f32_e32 v72, v70
	v_lshl_add_u64 v[70:71], v[66:67], 2, s[8:9]
	v_mul_f32_e32 v73, 0x45800000, v72
	v_cndmask_b32_e32 v72, v72, v73, vcc
	v_pk_mul_f32 v[50:51], v[50:51], v[72:73] op_sel_hi:[1,0]
	v_pk_mul_f32 v[52:53], v[52:53], v[72:73] op_sel_hi:[1,0]
	v_pk_mul_f32 v[54:55], v[54:55], v[72:73] op_sel_hi:[1,0]
	v_pk_mul_f32 v[56:57], v[56:57], v[72:73] op_sel_hi:[1,0]
	v_pk_mul_f32 v[58:59], v[58:59], v[72:73] op_sel_hi:[1,0]
	v_pk_mul_f32 v[60:61], v[60:61], v[72:73] op_sel_hi:[1,0]
	v_pk_mul_f32 v[62:63], v[62:63], v[72:73] op_sel_hi:[1,0]
	v_pk_mul_f32 v[64:65], v[64:65], v[72:73] op_sel_hi:[1,0]
	v_pk_mul_f32 v[50:51], v[50:51], v[50:51]
	v_pk_mul_f32 v[52:53], v[52:53], v[52:53]
	v_pk_mul_f32 v[54:55], v[54:55], v[54:55]
	v_pk_mul_f32 v[56:57], v[56:57], v[56:57]
	v_pk_mul_f32 v[58:59], v[58:59], v[58:59]
	v_pk_mul_f32 v[60:61], v[60:61], v[60:61]
	v_pk_mul_f32 v[62:63], v[62:63], v[62:63]
	v_pk_mul_f32 v[64:65], v[64:65], v[64:65]
	v_cvt_pk_bf16_f32 v50, v50, v51
	v_cvt_pk_bf16_f32 v51, v52, v53
	v_cvt_pk_bf16_f32 v52, v54, v55
	v_cvt_pk_bf16_f32 v53, v56, v57
	v_cvt_pk_bf16_f32 v54, v58, v59
	v_cvt_pk_bf16_f32 v55, v60, v61
	v_cvt_pk_bf16_f32 v56, v62, v63
	v_cvt_pk_bf16_f32 v57, v64, v65
	flat_store_dwordx2 v[68:69], v[50:51]
	flat_store_dwordx2 v[68:69], v[52:53] offset:32
	flat_store_dwordx2 v[68:69], v[54:55] offset:64
	flat_store_dwordx2 v[68:69], v[56:57] offset:96
	flat_load_dword v54, v[70:71]
	v_max_f32_e32 v55, v34, v34
	v_max_f32_e32 v34, 0, v46
	v_max_f32_e32 v46, 0, v55
	v_max_f32_e32 v56, v35, v35
	v_max_f32_e32 v35, 0, v47
	v_max_f32_e32 v47, 0, v56
	v_max_f32_e32 v57, v36, v36
	v_max_f32_e32 v36, 0, v48
	v_max_f32_e32 v48, 0, v57
	v_max_f32_e32 v50, v38, v38
	v_max_f32_e32 v51, v39, v39
	v_max_f32_e32 v52, v40, v40
	v_max_f32_e32 v53, v41, v41
	v_max_f32_e32 v58, v37, v37
	v_max_f32_e32 v37, 0, v49
	v_max_f32_e32 v38, 0, v42
	v_max_f32_e32 v39, 0, v43
	v_max_f32_e32 v40, 0, v44
	v_max_f32_e32 v41, 0, v45
	v_max_f32_e32 v42, 0, v50
	v_max_f32_e32 v43, 0, v51
	v_max_f32_e32 v44, 0, v52
	v_max_f32_e32 v45, 0, v53
	v_max_f32_e32 v49, 0, v58
	v_lshlrev_b64 v[52:53], 13, v[66:67]
	v_lshl_add_u64 v[52:53], s[6:7], 0, v[52:53]
	v_or_b32_e32 v50, 0x60, v106
	v_mov_b32_e32 v51, v107
	v_lshl_add_u64 v[52:53], v[52:53], 0, v[108:109]
	v_or_b32_e32 v106, 0x70, v106
	s_waitcnt vmcnt(0) lgkmcnt(0)
	v_fmamk_f32 v54, v54, 0x3a800000, v137
	v_mul_f32_e32 v55, 0x4b800000, v54
	v_cmp_gt_f32_e32 vcc, s43, v54
	s_nop 1
	v_cndmask_b32_e32 v54, v54, v55, vcc
	v_rsq_f32_e32 v56, v54
	v_lshl_add_u64 v[54:55], v[50:51], 2, s[8:9]
	v_mul_f32_e32 v57, 0x45800000, v56
	v_cndmask_b32_e32 v56, v56, v57, vcc
	v_pk_mul_f32 v[34:35], v[34:35], v[56:57] op_sel_hi:[1,0]
	v_pk_mul_f32 v[36:37], v[36:37], v[56:57] op_sel_hi:[1,0]
	v_pk_mul_f32 v[38:39], v[38:39], v[56:57] op_sel_hi:[1,0]
	v_pk_mul_f32 v[40:41], v[40:41], v[56:57] op_sel_hi:[1,0]
	v_pk_mul_f32 v[42:43], v[42:43], v[56:57] op_sel_hi:[1,0]
	v_pk_mul_f32 v[44:45], v[44:45], v[56:57] op_sel_hi:[1,0]
	v_pk_mul_f32 v[46:47], v[46:47], v[56:57] op_sel_hi:[1,0]
	v_pk_mul_f32 v[48:49], v[48:49], v[56:57] op_sel_hi:[1,0]
	v_pk_mul_f32 v[34:35], v[34:35], v[34:35]
	v_pk_mul_f32 v[36:37], v[36:37], v[36:37]
	v_pk_mul_f32 v[38:39], v[38:39], v[38:39]
	v_pk_mul_f32 v[40:41], v[40:41], v[40:41]
	v_pk_mul_f32 v[42:43], v[42:43], v[42:43]
	v_pk_mul_f32 v[44:45], v[44:45], v[44:45]
	v_pk_mul_f32 v[46:47], v[46:47], v[46:47]
	v_pk_mul_f32 v[48:49], v[48:49], v[48:49]
	v_cvt_pk_bf16_f32 v34, v34, v35
	v_cvt_pk_bf16_f32 v35, v36, v37
	v_cvt_pk_bf16_f32 v36, v38, v39
	v_cvt_pk_bf16_f32 v37, v40, v41
	v_cvt_pk_bf16_f32 v38, v42, v43
	v_cvt_pk_bf16_f32 v39, v44, v45
	v_cvt_pk_bf16_f32 v40, v46, v47
	v_cvt_pk_bf16_f32 v41, v48, v49
	flat_store_dwordx2 v[52:53], v[34:35]
	flat_store_dwordx2 v[52:53], v[36:37] offset:32
	flat_store_dwordx2 v[52:53], v[38:39] offset:64
	flat_store_dwordx2 v[52:53], v[40:41] offset:96
	flat_load_dword v36, v[54:55]
	v_max_f32_e32 v37, v24, v24
	v_max_f32_e32 v24, 0, v28
	v_max_f32_e32 v28, 0, v37
	v_max_f32_e32 v38, v25, v25
	v_max_f32_e32 v25, 0, v29
	v_max_f32_e32 v29, 0, v38
	v_max_f32_e32 v39, v18, v18
	v_max_f32_e32 v18, 0, v30
	v_max_f32_e32 v30, 0, v39
	v_max_f32_e32 v34, v22, v22
	v_max_f32_e32 v35, v23, v23
	v_max_f32_e32 v40, v19, v19
	v_max_f32_e32 v41, v20, v20
	v_max_f32_e32 v42, v21, v21
	v_max_f32_e32 v19, 0, v31
	v_max_f32_e32 v20, 0, v32
	v_max_f32_e32 v21, 0, v33
	v_max_f32_e32 v22, 0, v26
	v_max_f32_e32 v23, 0, v27
	v_max_f32_e32 v26, 0, v34
	v_max_f32_e32 v27, 0, v35
	v_max_f32_e32 v31, 0, v40
	v_max_f32_e32 v32, 0, v41
	v_max_f32_e32 v33, 0, v42
	v_lshlrev_b64 v[34:35], 13, v[50:51]
	v_lshl_add_u64 v[34:35], s[6:7], 0, v[34:35]
	v_lshl_add_u64 v[34:35], v[34:35], 0, v[108:109]
	s_waitcnt vmcnt(0) lgkmcnt(0)
	v_fmamk_f32 v36, v36, 0x3a800000, v137
	v_mul_f32_e32 v37, 0x4b800000, v36
	v_cmp_gt_f32_e32 vcc, s43, v36
	s_nop 1
	v_cndmask_b32_e32 v36, v36, v37, vcc
	v_rsq_f32_e32 v38, v36
	v_lshl_add_u64 v[36:37], v[106:107], 2, s[8:9]
	v_mul_f32_e32 v39, 0x45800000, v38
	v_cndmask_b32_e32 v38, v38, v39, vcc
	v_pk_mul_f32 v[18:19], v[18:19], v[38:39] op_sel_hi:[1,0]
	v_pk_mul_f32 v[20:21], v[20:21], v[38:39] op_sel_hi:[1,0]
	v_pk_mul_f32 v[22:23], v[22:23], v[38:39] op_sel_hi:[1,0]
	v_pk_mul_f32 v[24:25], v[24:25], v[38:39] op_sel_hi:[1,0]
	v_pk_mul_f32 v[26:27], v[26:27], v[38:39] op_sel_hi:[1,0]
	v_pk_mul_f32 v[28:29], v[28:29], v[38:39] op_sel_hi:[1,0]
	v_pk_mul_f32 v[30:31], v[30:31], v[38:39] op_sel_hi:[1,0]
	v_pk_mul_f32 v[32:33], v[32:33], v[38:39] op_sel_hi:[1,0]
	v_pk_mul_f32 v[18:19], v[18:19], v[18:19]
	v_pk_mul_f32 v[20:21], v[20:21], v[20:21]
	v_pk_mul_f32 v[22:23], v[22:23], v[22:23]
	v_pk_mul_f32 v[24:25], v[24:25], v[24:25]
	v_pk_mul_f32 v[26:27], v[26:27], v[26:27]
	v_pk_mul_f32 v[28:29], v[28:29], v[28:29]
	v_pk_mul_f32 v[30:31], v[30:31], v[30:31]
	v_pk_mul_f32 v[32:33], v[32:33], v[32:33]
	v_cvt_pk_bf16_f32 v18, v18, v19
	v_cvt_pk_bf16_f32 v19, v20, v21
	v_cvt_pk_bf16_f32 v20, v22, v23
	v_cvt_pk_bf16_f32 v21, v24, v25
	v_cvt_pk_bf16_f32 v22, v26, v27
	v_cvt_pk_bf16_f32 v23, v28, v29
	v_cvt_pk_bf16_f32 v24, v30, v31
	v_cvt_pk_bf16_f32 v25, v32, v33
	flat_store_dwordx2 v[34:35], v[18:19]
	flat_store_dwordx2 v[34:35], v[20:21] offset:32
	flat_store_dwordx2 v[34:35], v[22:23] offset:64
	flat_store_dwordx2 v[34:35], v[24:25] offset:96
	flat_load_dword v18, v[36:37]
	v_max_f32_e32 v19, v6, v6
	v_max_f32_e32 v6, 0, v10
	v_max_f32_e32 v10, 0, v19
	v_max_f32_e32 v20, v7, v7
	v_max_f32_e32 v7, 0, v11
	v_max_f32_e32 v11, 0, v20
	v_max_f32_e32 v21, v8, v8
	v_max_f32_e32 v8, 0, v12
	v_max_f32_e32 v12, 0, v21
	v_max_f32_e32 v22, v9, v9
	v_max_f32_e32 v23, v2, v2
	v_max_f32_e32 v24, v3, v3
	v_max_f32_e32 v25, v4, v4
	v_max_f32_e32 v26, v5, v5
	v_max_f32_e32 v2, 0, v14
	v_max_f32_e32 v3, 0, v15
	v_max_f32_e32 v4, 0, v16
	v_max_f32_e32 v5, 0, v17
	v_max_f32_e32 v9, 0, v13
	v_max_f32_e32 v13, 0, v22
	v_max_f32_e32 v14, 0, v23
	v_max_f32_e32 v15, 0, v24
	v_max_f32_e32 v16, 0, v25
	v_max_f32_e32 v17, 0, v26
	s_waitcnt vmcnt(0) lgkmcnt(0)
	v_fmamk_f32 v18, v18, 0x3a800000, v137
	v_mul_f32_e32 v19, 0x4b800000, v18
	v_cmp_gt_f32_e32 vcc, s43, v18
	s_nop 1
	v_cndmask_b32_e32 v18, v18, v19, vcc
	v_rsq_f32_e32 v20, v18
	v_lshlrev_b64 v[18:19], 13, v[106:107]
	v_lshl_add_u64 v[18:19], s[6:7], 0, v[18:19]
	v_lshl_add_u64 v[18:19], v[18:19], 0, v[108:109]
	v_mul_f32_e32 v21, 0x45800000, v20
	v_cndmask_b32_e32 v20, v20, v21, vcc
	v_pk_mul_f32 v[2:3], v[2:3], v[20:21] op_sel_hi:[1,0]
	v_pk_mul_f32 v[4:5], v[4:5], v[20:21] op_sel_hi:[1,0]
	v_pk_mul_f32 v[6:7], v[6:7], v[20:21] op_sel_hi:[1,0]
	v_pk_mul_f32 v[8:9], v[8:9], v[20:21] op_sel_hi:[1,0]
	v_pk_mul_f32 v[10:11], v[10:11], v[20:21] op_sel_hi:[1,0]
	v_pk_mul_f32 v[12:13], v[12:13], v[20:21] op_sel_hi:[1,0]
	v_pk_mul_f32 v[14:15], v[14:15], v[20:21] op_sel_hi:[1,0]
	v_pk_mul_f32 v[16:17], v[16:17], v[20:21] op_sel_hi:[1,0]
	v_pk_mul_f32 v[2:3], v[2:3], v[2:3]
	v_pk_mul_f32 v[4:5], v[4:5], v[4:5]
	v_pk_mul_f32 v[6:7], v[6:7], v[6:7]
	v_pk_mul_f32 v[8:9], v[8:9], v[8:9]
	v_pk_mul_f32 v[10:11], v[10:11], v[10:11]
	v_pk_mul_f32 v[12:13], v[12:13], v[12:13]
	v_pk_mul_f32 v[14:15], v[14:15], v[14:15]
	v_pk_mul_f32 v[16:17], v[16:17], v[16:17]
	v_cvt_pk_bf16_f32 v2, v2, v3
	v_cvt_pk_bf16_f32 v3, v4, v5
	v_cvt_pk_bf16_f32 v4, v6, v7
	v_cvt_pk_bf16_f32 v5, v8, v9
	v_cvt_pk_bf16_f32 v6, v10, v11
	v_cvt_pk_bf16_f32 v7, v12, v13
	v_cvt_pk_bf16_f32 v8, v14, v15
	v_cvt_pk_bf16_f32 v9, v16, v17
	flat_store_dwordx2 v[18:19], v[2:3]
	flat_store_dwordx2 v[18:19], v[4:5] offset:32
	flat_store_dwordx2 v[18:19], v[6:7] offset:64
	flat_store_dwordx2 v[18:19], v[8:9] offset:96
	s_cbranch_scc0 .LBB0_563

.LBB0_568:
	v_mov_b32_e32 v4, v1
	s_movk_i32 s84, 0x1320
	v_lshrrev_b32_e32 v6, 2, v4
	v_and_b32_e32 v6, 12, v6
	v_lshrrev_b32_e64 v6, v6, s84
	s_ashr_i32 s80, s2, 3
	v_xor_b32_e32 v6, v6, v4
	v_lshlrev_b32_e32 v11, 6, v4
	s_ashr_i32 s81, s80, 31
	v_and_b32_e32 v7, 0xffffff00, v11
	v_lshlrev_b32_e32 v6, 3, v6
	s_and_b32 s41, s2, 7
	s_lshl_b64 s[42:43], s[80:81], 17
	v_and_or_b32 v6, v6, 24, v7
	s_add_u32 s42, s36, s42
	v_lshl_add_u32 v14, v4, 4, 0
	v_ashrrev_i32_e32 v7, 31, v6
	s_addc_u32 s43, s37, s43
	v_lshlrev_b64 v[8:9], 1, v[6:7]
	v_readfirstlane_b32 s88, v14
	v_add_u32_e32 v15, 0x1000, v14
	v_lshl_add_u64 v[6:7], s[42:43], 0, v[8:9]
	s_mov_b32 m0, s88
	v_readfirstlane_b32 s86, v15
	v_add_u32_e32 v15, 0x2000, v14
	global_load_lds_dwordx4 v[6:7], off
	v_lshl_add_u64 v[12:13], v[6:7], 0, s[4:5]
	s_mov_b32 m0, s86
	v_readfirstlane_b32 s87, v15
	v_add_u32_e32 v15, 0x3000, v14
	global_load_lds_dwordx4 v[12:13], off
	v_lshl_add_u64 v[12:13], v[6:7], 0, s[6:7]
	s_mov_b32 m0, s87
	v_readfirstlane_b32 s89, v15
	s_lshl_b32 s82, s41, 16
	global_load_lds_dwordx4 v[12:13], off
	v_lshl_add_u64 v[12:13], v[6:7], 0, s[8:9]
	s_mov_b32 m0, s89
	s_add_u32 s82, s3, s82
	global_load_lds_dwordx4 v[12:13], off
	v_add_u32_e32 v12, 0x4000, v14
	s_addc_u32 s83, s33, 0
	v_readfirstlane_b32 s90, v12
	v_add_u32_e32 v15, 0x5000, v14
	v_lshl_add_u64 v[8:9], s[82:83], 0, v[8:9]
	s_mov_b32 m0, s90
	v_readfirstlane_b32 s91, v15
	v_add_u32_e32 v15, 0x6000, v14
	global_load_lds_dwordx4 v[8:9], off
	v_lshl_add_u64 v[12:13], v[8:9], 0, s[4:5]
	s_mov_b32 m0, s91
	v_readfirstlane_b32 s43, v15
	v_add_u32_e32 v15, 0x7000, v14
	global_load_lds_dwordx4 v[12:13], off
	v_lshl_add_u64 v[12:13], v[6:7], 0, 64
	s_mov_b32 m0, s43
	v_readfirstlane_b32 s42, v15
	global_load_lds_dwordx4 v[12:13], off
	v_lshl_add_u64 v[12:13], v[6:7], 0, s[10:11]
	s_mov_b32 m0, s42
	s_mov_b64 s[82:83], 0x10040
	v_add_u32_e32 v15, 0x8000, v14
	global_load_lds_dwordx4 v[12:13], off
	v_lshl_add_u64 v[12:13], v[6:7], 0, s[82:83]
	v_readfirstlane_b32 s82, v15
	v_add_u32_e32 v15, 0x9000, v14
	s_mov_b32 m0, s82
	v_readfirstlane_b32 s83, v15
	v_add_u32_e32 v15, 0xa000, v14
	global_load_lds_dwordx4 v[12:13], off
	v_lshl_add_u64 v[12:13], v[6:7], 0, s[12:13]
	s_mov_b32 m0, s83
	v_readfirstlane_b32 s84, v15
	v_add_u32_e32 v15, 0xb000, v14
	global_load_lds_dwordx4 v[12:13], off
	v_lshl_add_u64 v[12:13], v[8:9], 0, 64
	s_mov_b32 m0, s84
	v_readfirstlane_b32 s85, v15
	v_add_u32_e32 v15, 0xc000, v14
	global_load_lds_dwordx4 v[12:13], off
	v_lshl_add_u64 v[12:13], v[8:9], 0, s[10:11]
	s_mov_b32 m0, s85
	v_readfirstlane_b32 s94, v15
	v_add_u32_e32 v15, 0xd000, v14
	global_load_lds_dwordx4 v[12:13], off
	v_lshl_add_u64 v[12:13], v[6:7], 0, s[14:15]
	s_mov_b32 m0, s94
	v_readfirstlane_b32 s92, v15
	v_add_u32_e32 v15, 0xe000, v14
	s_waitcnt vmcnt(6)
	s_barrier
	global_load_lds_dwordx4 v[12:13], off
	v_lshl_add_u64 v[12:13], v[6:7], 0, s[16:17]
	s_mov_b32 m0, s92
	v_readfirstlane_b32 s93, v15
	v_add_u32_e32 v15, 0xf000, v14
	global_load_lds_dwordx4 v[12:13], off
	v_lshl_add_u64 v[12:13], v[6:7], 0, s[18:19]
	s_mov_b32 m0, s93
	v_readfirstlane_b32 s95, v15
	v_add_u32_e32 v15, 0x10000, v14
	global_load_lds_dwordx4 v[12:13], off
	v_lshl_add_u64 v[12:13], v[6:7], 0, s[20:21]
	s_mov_b32 m0, s95
	v_readfirstlane_b32 s96, v15
	v_add_u32_e32 v14, 0x11000, v14
	global_load_lds_dwordx4 v[12:13], off
	v_lshl_add_u64 v[12:13], v[8:9], 0, s[14:15]
	s_mov_b32 m0, s96
	v_readfirstlane_b32 s97, v14
	global_load_lds_dwordx4 v[12:13], off
	v_lshl_add_u64 v[12:13], v[8:9], 0, s[16:17]
	s_mov_b32 m0, s97
	s_nop 0
	global_load_lds_dwordx4 v[12:13], off
	v_and_b32_e32 v12, 12, v4
	v_lshrrev_b32_e64 v12, v12, vcc_lo
	v_and_b32_e32 v13, 0x13c0, v11
	v_and_b32_e32 v11, 0xffffe3c0, v11
	v_bitop3_b32 v4, v12, 48, v4 bitop3:0x48
	v_add3_u32 v172, 0, v13, v4
	v_add3_u32 v4, 0, v11, v4
	ds_read_b128 v[12:15], v172 offset:16384
	ds_read_b128 v[16:19], v172 offset:17408
	ds_read_b128 v[20:23], v172 offset:18432
	ds_read_b128 v[24:27], v172 offset:19456
	ds_read_b128 v[28:31], v4
	ds_read_b128 v[32:35], v4 offset:1024
	ds_read_b128 v[36:39], v4 offset:2048
	ds_read_b128 v[40:43], v4 offset:3072
	s_waitcnt lgkmcnt(0)
	v_mfma_f32_16x16x32_bf16 v[44:47], v[12:15], v[28:31], 0
	v_mfma_f32_16x16x32_bf16 v[48:51], v[16:19], v[28:31], 0
	v_mfma_f32_16x16x32_bf16 v[52:55], v[20:23], v[28:31], 0
	v_mfma_f32_16x16x32_bf16 v[28:31], v[24:27], v[28:31], 0
	v_mfma_f32_16x16x32_bf16 v[56:59], v[12:15], v[32:35], 0
	v_mfma_f32_16x16x32_bf16 v[60:63], v[16:19], v[32:35], 0
	v_mfma_f32_16x16x32_bf16 v[64:67], v[20:23], v[32:35], 0
	v_mfma_f32_16x16x32_bf16 v[32:35], v[24:27], v[32:35], 0
	v_mfma_f32_16x16x32_bf16 v[68:71], v[12:15], v[36:39], 0
	v_mfma_f32_16x16x32_bf16 v[72:75], v[16:19], v[36:39], 0
	v_mfma_f32_16x16x32_bf16 v[76:79], v[20:23], v[36:39], 0
	v_mfma_f32_16x16x32_bf16 v[36:39], v[24:27], v[36:39], 0
	v_mfma_f32_16x16x32_bf16 v[80:83], v[12:15], v[40:43], 0
	v_mfma_f32_16x16x32_bf16 v[84:87], v[16:19], v[40:43], 0
	v_mfma_f32_16x16x32_bf16 v[88:91], v[20:23], v[40:43], 0
	v_mfma_f32_16x16x32_bf16 v[40:43], v[24:27], v[40:43], 0
	ds_read_b128 v[92:95], v4 offset:4096
	ds_read_b128 v[96:99], v4 offset:5120
	ds_read_b128 v[100:103], v4 offset:6144
	ds_read_b128 v[104:107], v4 offset:7168
	s_waitcnt lgkmcnt(0)
	v_mfma_f32_16x16x32_bf16 v[108:111], v[12:15], v[92:95], 0
	v_mfma_f32_16x16x32_bf16 v[112:115], v[16:19], v[92:95], 0
	v_mfma_f32_16x16x32_bf16 v[116:119], v[20:23], v[92:95], 0
	v_mfma_f32_16x16x32_bf16 v[92:95], v[24:27], v[92:95], 0
	v_mfma_f32_16x16x32_bf16 v[120:123], v[12:15], v[96:99], 0
	v_mfma_f32_16x16x32_bf16 v[124:127], v[16:19], v[96:99], 0
	v_mfma_f32_16x16x32_bf16 v[128:131], v[20:23], v[96:99], 0
	v_mfma_f32_16x16x32_bf16 v[96:99], v[24:27], v[96:99], 0
	v_mfma_f32_16x16x32_bf16 v[132:135], v[12:15], v[100:103], 0
	v_mfma_f32_16x16x32_bf16 v[136:139], v[16:19], v[100:103], 0
	v_mfma_f32_16x16x32_bf16 v[140:143], v[20:23], v[100:103], 0
	v_mfma_f32_16x16x32_bf16 v[100:103], v[24:27], v[100:103], 0
	v_mfma_f32_16x16x32_bf16 v[12:15], v[12:15], v[104:107], 0
	v_mfma_f32_16x16x32_bf16 v[16:19], v[16:19], v[104:107], 0
	v_mfma_f32_16x16x32_bf16 v[20:23], v[20:23], v[104:107], 0
	v_mfma_f32_16x16x32_bf16 v[24:27], v[24:27], v[104:107], 0
	s_mov_b32 m0, s88
	v_lshl_add_u64 v[104:105], v[6:7], 0, s[22:23]
	s_waitcnt vmcnt(6)
	s_barrier
	global_load_lds_dwordx4 v[104:105], off
	v_lshl_add_u64 v[104:105], v[6:7], 0, s[24:25]
	s_mov_b32 m0, s86
	s_nop 0
	global_load_lds_dwordx4 v[104:105], off
	v_lshl_add_u64 v[104:105], v[6:7], 0, s[26:27]
	s_mov_b32 m0, s87
	s_nop 0
	global_load_lds_dwordx4 v[104:105], off
	v_lshl_add_u64 v[104:105], v[6:7], 0, s[28:29]
	s_mov_b32 m0, s89
	s_nop 0
	global_load_lds_dwordx4 v[104:105], off
	v_lshl_add_u64 v[104:105], v[8:9], 0, s[22:23]
	s_mov_b32 m0, s90
	s_nop 0
	global_load_lds_dwordx4 v[104:105], off
	v_lshl_add_u64 v[104:105], v[8:9], 0, s[24:25]
	s_mov_b32 m0, s91
	s_nop 0
	global_load_lds_dwordx4 v[104:105], off
	ds_read_b128 v[104:107], v172 offset:40960
	ds_read_b128 v[144:147], v172 offset:41984
	ds_read_b128 v[148:151], v172 offset:43008
	ds_read_b128 v[152:155], v172 offset:44032
	ds_read_b128 v[156:159], v4 offset:24576
	ds_read_b128 v[160:163], v4 offset:25600
	ds_read_b128 v[164:167], v4 offset:26624
	ds_read_b128 v[168:171], v4 offset:27648
	s_waitcnt lgkmcnt(0)
	v_mfma_f32_16x16x32_bf16 v[44:47], v[104:107], v[156:159], v[44:47]
	v_mfma_f32_16x16x32_bf16 v[48:51], v[144:147], v[156:159], v[48:51]
	v_mfma_f32_16x16x32_bf16 v[52:55], v[148:151], v[156:159], v[52:55]
	v_mfma_f32_16x16x32_bf16 v[28:31], v[152:155], v[156:159], v[28:31]
	v_mfma_f32_16x16x32_bf16 v[56:59], v[104:107], v[160:163], v[56:59]
	v_mfma_f32_16x16x32_bf16 v[60:63], v[144:147], v[160:163], v[60:63]
	v_mfma_f32_16x16x32_bf16 v[64:67], v[148:151], v[160:163], v[64:67]
	v_mfma_f32_16x16x32_bf16 v[32:35], v[152:155], v[160:163], v[32:35]
	v_mfma_f32_16x16x32_bf16 v[68:71], v[104:107], v[164:167], v[68:71]
	v_mfma_f32_16x16x32_bf16 v[72:75], v[144:147], v[164:167], v[72:75]
	v_mfma_f32_16x16x32_bf16 v[76:79], v[148:151], v[164:167], v[76:79]
	v_mfma_f32_16x16x32_bf16 v[36:39], v[152:155], v[164:167], v[36:39]
	v_mfma_f32_16x16x32_bf16 v[80:83], v[104:107], v[168:171], v[80:83]
	v_mfma_f32_16x16x32_bf16 v[84:87], v[144:147], v[168:171], v[84:87]
	v_mfma_f32_16x16x32_bf16 v[88:91], v[148:151], v[168:171], v[88:91]
	v_mfma_f32_16x16x32_bf16 v[40:43], v[152:155], v[168:171], v[40:43]
	ds_read_b128 v[156:159], v4 offset:28672
	ds_read_b128 v[160:163], v4 offset:29696
	ds_read_b128 v[164:167], v4 offset:30720
	ds_read_b128 v[168:171], v4 offset:31744
	s_waitcnt lgkmcnt(0)
	v_mfma_f32_16x16x32_bf16 v[108:111], v[104:107], v[156:159], v[108:111]
	v_mfma_f32_16x16x32_bf16 v[112:115], v[144:147], v[156:159], v[112:115]
	v_mfma_f32_16x16x32_bf16 v[116:119], v[148:151], v[156:159], v[116:119]
	v_mfma_f32_16x16x32_bf16 v[92:95], v[152:155], v[156:159], v[92:95]
	v_mfma_f32_16x16x32_bf16 v[120:123], v[104:107], v[160:163], v[120:123]
	v_mfma_f32_16x16x32_bf16 v[124:127], v[144:147], v[160:163], v[124:127]
	v_mfma_f32_16x16x32_bf16 v[128:131], v[148:151], v[160:163], v[128:131]
	v_mfma_f32_16x16x32_bf16 v[96:99], v[152:155], v[160:163], v[96:99]
	v_mfma_f32_16x16x32_bf16 v[132:135], v[104:107], v[164:167], v[132:135]
	v_mfma_f32_16x16x32_bf16 v[136:139], v[144:147], v[164:167], v[136:139]
	v_mfma_f32_16x16x32_bf16 v[140:143], v[148:151], v[164:167], v[140:143]
	v_mfma_f32_16x16x32_bf16 v[100:103], v[152:155], v[164:167], v[100:103]
	v_mfma_f32_16x16x32_bf16 v[12:15], v[104:107], v[168:171], v[12:15]
	v_mfma_f32_16x16x32_bf16 v[16:19], v[144:147], v[168:171], v[16:19]
	v_mfma_f32_16x16x32_bf16 v[20:23], v[148:151], v[168:171], v[20:23]
	v_mfma_f32_16x16x32_bf16 v[24:27], v[152:155], v[168:171], v[24:27]
	s_mov_b32 m0, s43
	v_lshl_add_u64 v[104:105], v[6:7], 0, s[30:31]
	s_waitcnt vmcnt(6)
	s_barrier
	global_load_lds_dwordx4 v[104:105], off
	v_lshl_add_u64 v[104:105], v[6:7], 0, s[34:35]
	s_mov_b32 m0, s42
	v_add_u32_e32 v11, 0xc000, v172
	global_load_lds_dwordx4 v[104:105], off
	v_lshl_add_u64 v[104:105], v[6:7], 0, s[44:45]
	s_mov_b32 m0, s82
	s_nop 0
	global_load_lds_dwordx4 v[104:105], off
	v_lshl_add_u64 v[104:105], v[6:7], 0, s[46:47]
	s_mov_b32 m0, s83
	s_nop 0
	global_load_lds_dwordx4 v[104:105], off
	v_lshl_add_u64 v[104:105], v[8:9], 0, s[30:31]
	s_mov_b32 m0, s84
	s_nop 0
	global_load_lds_dwordx4 v[104:105], off
	v_lshl_add_u64 v[104:105], v[8:9], 0, s[34:35]
	s_mov_b32 m0, s85
	s_nop 0
	global_load_lds_dwordx4 v[104:105], off
	ds_read_b128 v[104:107], v11 offset:16384
	ds_read_b128 v[144:147], v11 offset:17408
	ds_read_b128 v[148:151], v11 offset:18432
	ds_read_b128 v[152:155], v11 offset:19456
	ds_read_b128 v[156:159], v4 offset:49152
	ds_read_b128 v[160:163], v4 offset:50176
	ds_read_b128 v[164:167], v4 offset:51200
	ds_read_b128 v[168:171], v4 offset:52224
	s_waitcnt lgkmcnt(0)
	v_mfma_f32_16x16x32_bf16 v[44:47], v[104:107], v[156:159], v[44:47]
	v_mfma_f32_16x16x32_bf16 v[48:51], v[144:147], v[156:159], v[48:51]
	v_mfma_f32_16x16x32_bf16 v[52:55], v[148:151], v[156:159], v[52:55]
	v_mfma_f32_16x16x32_bf16 v[28:31], v[152:155], v[156:159], v[28:31]
	v_mfma_f32_16x16x32_bf16 v[56:59], v[104:107], v[160:163], v[56:59]
	v_mfma_f32_16x16x32_bf16 v[60:63], v[144:147], v[160:163], v[60:63]
	v_mfma_f32_16x16x32_bf16 v[64:67], v[148:151], v[160:163], v[64:67]
	v_mfma_f32_16x16x32_bf16 v[32:35], v[152:155], v[160:163], v[32:35]
	v_mfma_f32_16x16x32_bf16 v[68:71], v[104:107], v[164:167], v[68:71]
	v_mfma_f32_16x16x32_bf16 v[72:75], v[144:147], v[164:167], v[72:75]
	v_mfma_f32_16x16x32_bf16 v[76:79], v[148:151], v[164:167], v[76:79]
	v_mfma_f32_16x16x32_bf16 v[36:39], v[152:155], v[164:167], v[36:39]
	v_mfma_f32_16x16x32_bf16 v[80:83], v[104:107], v[168:171], v[80:83]
	v_mfma_f32_16x16x32_bf16 v[84:87], v[144:147], v[168:171], v[84:87]
	v_mfma_f32_16x16x32_bf16 v[88:91], v[148:151], v[168:171], v[88:91]
	v_mfma_f32_16x16x32_bf16 v[40:43], v[152:155], v[168:171], v[40:43]
	ds_read_b128 v[156:159], v4 offset:53248
	ds_read_b128 v[160:163], v4 offset:54272
	ds_read_b128 v[164:167], v4 offset:55296
	ds_read_b128 v[168:171], v4 offset:56320
	s_waitcnt lgkmcnt(0)
	v_mfma_f32_16x16x32_bf16 v[108:111], v[104:107], v[156:159], v[108:111]
	v_mfma_f32_16x16x32_bf16 v[112:115], v[144:147], v[156:159], v[112:115]
	v_mfma_f32_16x16x32_bf16 v[116:119], v[148:151], v[156:159], v[116:119]
	v_mfma_f32_16x16x32_bf16 v[92:95], v[152:155], v[156:159], v[92:95]
	v_mfma_f32_16x16x32_bf16 v[120:123], v[104:107], v[160:163], v[120:123]
	v_mfma_f32_16x16x32_bf16 v[124:127], v[144:147], v[160:163], v[124:127]
	v_mfma_f32_16x16x32_bf16 v[128:131], v[148:151], v[160:163], v[128:131]
	v_mfma_f32_16x16x32_bf16 v[96:99], v[152:155], v[160:163], v[96:99]
	v_mfma_f32_16x16x32_bf16 v[132:135], v[104:107], v[164:167], v[132:135]
	v_mfma_f32_16x16x32_bf16 v[136:139], v[144:147], v[164:167], v[136:139]
	v_mfma_f32_16x16x32_bf16 v[140:143], v[148:151], v[164:167], v[140:143]
	v_mfma_f32_16x16x32_bf16 v[100:103], v[152:155], v[164:167], v[100:103]
	v_mfma_f32_16x16x32_bf16 v[12:15], v[104:107], v[168:171], v[12:15]
	v_mfma_f32_16x16x32_bf16 v[16:19], v[144:147], v[168:171], v[16:19]
	v_mfma_f32_16x16x32_bf16 v[20:23], v[148:151], v[168:171], v[20:23]
	v_mfma_f32_16x16x32_bf16 v[24:27], v[152:155], v[168:171], v[24:27]
	s_mov_b32 m0, s94
	v_lshl_add_u64 v[104:105], v[6:7], 0, s[48:49]
	s_waitcnt vmcnt(6)
	s_barrier
	global_load_lds_dwordx4 v[104:105], off
	v_lshl_add_u64 v[104:105], v[6:7], 0, s[50:51]
	s_mov_b32 m0, s92
	s_nop 0
	global_load_lds_dwordx4 v[104:105], off
	v_lshl_add_u64 v[104:105], v[6:7], 0, s[52:53]
	s_mov_b32 m0, s93
	s_nop 0
	global_load_lds_dwordx4 v[104:105], off
	v_lshl_add_u64 v[104:105], v[6:7], 0, s[54:55]
	s_mov_b32 m0, s95
	s_nop 0
	global_load_lds_dwordx4 v[104:105], off
	v_lshl_add_u64 v[104:105], v[8:9], 0, s[48:49]
	s_mov_b32 m0, s96
	s_nop 0
	global_load_lds_dwordx4 v[104:105], off
	v_lshl_add_u64 v[104:105], v[8:9], 0, s[50:51]
	s_mov_b32 m0, s97
	s_nop 0
	global_load_lds_dwordx4 v[104:105], off
	ds_read_b128 v[104:107], v172 offset:16384
	ds_read_b128 v[144:147], v172 offset:17408
	ds_read_b128 v[148:151], v172 offset:18432
	ds_read_b128 v[152:155], v172 offset:19456
	ds_read_b128 v[156:159], v4
	ds_read_b128 v[160:163], v4 offset:1024
	ds_read_b128 v[164:167], v4 offset:2048
	ds_read_b128 v[168:171], v4 offset:3072
	s_waitcnt lgkmcnt(0)
	v_mfma_f32_16x16x32_bf16 v[44:47], v[104:107], v[156:159], v[44:47]
	v_mfma_f32_16x16x32_bf16 v[48:51], v[144:147], v[156:159], v[48:51]
	v_mfma_f32_16x16x32_bf16 v[52:55], v[148:151], v[156:159], v[52:55]
	v_mfma_f32_16x16x32_bf16 v[28:31], v[152:155], v[156:159], v[28:31]
	v_mfma_f32_16x16x32_bf16 v[56:59], v[104:107], v[160:163], v[56:59]
	v_mfma_f32_16x16x32_bf16 v[60:63], v[144:147], v[160:163], v[60:63]
	v_mfma_f32_16x16x32_bf16 v[64:67], v[148:151], v[160:163], v[64:67]
	v_mfma_f32_16x16x32_bf16 v[32:35], v[152:155], v[160:163], v[32:35]
	v_mfma_f32_16x16x32_bf16 v[68:71], v[104:107], v[164:167], v[68:71]
	v_mfma_f32_16x16x32_bf16 v[72:75], v[144:147], v[164:167], v[72:75]
	v_mfma_f32_16x16x32_bf16 v[76:79], v[148:151], v[164:167], v[76:79]
	v_mfma_f32_16x16x32_bf16 v[36:39], v[152:155], v[164:167], v[36:39]
	v_mfma_f32_16x16x32_bf16 v[80:83], v[104:107], v[168:171], v[80:83]
	v_mfma_f32_16x16x32_bf16 v[84:87], v[144:147], v[168:171], v[84:87]
	v_mfma_f32_16x16x32_bf16 v[88:91], v[148:151], v[168:171], v[88:91]
	v_mfma_f32_16x16x32_bf16 v[40:43], v[152:155], v[168:171], v[40:43]
	ds_read_b128 v[156:159], v4 offset:4096
	ds_read_b128 v[160:163], v4 offset:5120
	ds_read_b128 v[164:167], v4 offset:6144
	ds_read_b128 v[168:171], v4 offset:7168
	s_waitcnt lgkmcnt(0)
	v_mfma_f32_16x16x32_bf16 v[108:111], v[104:107], v[156:159], v[108:111]
	v_mfma_f32_16x16x32_bf16 v[112:115], v[144:147], v[156:159], v[112:115]
	v_mfma_f32_16x16x32_bf16 v[116:119], v[148:151], v[156:159], v[116:119]
	v_mfma_f32_16x16x32_bf16 v[92:95], v[152:155], v[156:159], v[92:95]
	v_mfma_f32_16x16x32_bf16 v[120:123], v[104:107], v[160:163], v[120:123]
	v_mfma_f32_16x16x32_bf16 v[124:127], v[144:147], v[160:163], v[124:127]
	v_mfma_f32_16x16x32_bf16 v[128:131], v[148:151], v[160:163], v[128:131]
	v_mfma_f32_16x16x32_bf16 v[96:99], v[152:155], v[160:163], v[96:99]
	v_mfma_f32_16x16x32_bf16 v[132:135], v[104:107], v[164:167], v[132:135]
	v_mfma_f32_16x16x32_bf16 v[136:139], v[144:147], v[164:167], v[136:139]
	v_mfma_f32_16x16x32_bf16 v[140:143], v[148:151], v[164:167], v[140:143]
	v_mfma_f32_16x16x32_bf16 v[100:103], v[152:155], v[164:167], v[100:103]
	v_mfma_f32_16x16x32_bf16 v[12:15], v[104:107], v[168:171], v[12:15]
	v_mfma_f32_16x16x32_bf16 v[16:19], v[144:147], v[168:171], v[16:19]
	v_mfma_f32_16x16x32_bf16 v[20:23], v[148:151], v[168:171], v[20:23]
	v_mfma_f32_16x16x32_bf16 v[24:27], v[152:155], v[168:171], v[24:27]
	s_mov_b32 m0, s88
	v_lshl_add_u64 v[104:105], v[6:7], 0, s[56:57]
	s_waitcnt vmcnt(6)
	s_barrier
	global_load_lds_dwordx4 v[104:105], off
	v_lshl_add_u64 v[104:105], v[6:7], 0, s[58:59]
	s_mov_b32 m0, s86
	s_nop 0
	global_load_lds_dwordx4 v[104:105], off
	v_lshl_add_u64 v[104:105], v[6:7], 0, s[60:61]
	s_mov_b32 m0, s87
	s_nop 0
	global_load_lds_dwordx4 v[104:105], off
	v_lshl_add_u64 v[104:105], v[6:7], 0, s[62:63]
	s_mov_b32 m0, s89
	s_nop 0
	global_load_lds_dwordx4 v[104:105], off
	v_lshl_add_u64 v[104:105], v[8:9], 0, s[56:57]
	s_mov_b32 m0, s90
	s_nop 0
	global_load_lds_dwordx4 v[104:105], off
	v_lshl_add_u64 v[104:105], v[8:9], 0, s[58:59]
	s_mov_b32 m0, s91
	s_nop 0
	global_load_lds_dwordx4 v[104:105], off
	ds_read_b128 v[104:107], v172 offset:40960
	ds_read_b128 v[144:147], v172 offset:41984
	ds_read_b128 v[148:151], v172 offset:43008
	ds_read_b128 v[152:155], v172 offset:44032
	ds_read_b128 v[156:159], v4 offset:24576
	ds_read_b128 v[160:163], v4 offset:25600
	ds_read_b128 v[164:167], v4 offset:26624
	ds_read_b128 v[168:171], v4 offset:27648
	s_waitcnt lgkmcnt(0)
	v_mfma_f32_16x16x32_bf16 v[44:47], v[104:107], v[156:159], v[44:47]
	v_mfma_f32_16x16x32_bf16 v[48:51], v[144:147], v[156:159], v[48:51]
	v_mfma_f32_16x16x32_bf16 v[52:55], v[148:151], v[156:159], v[52:55]
	v_mfma_f32_16x16x32_bf16 v[28:31], v[152:155], v[156:159], v[28:31]
	v_mfma_f32_16x16x32_bf16 v[56:59], v[104:107], v[160:163], v[56:59]
	v_mfma_f32_16x16x32_bf16 v[60:63], v[144:147], v[160:163], v[60:63]
	v_mfma_f32_16x16x32_bf16 v[64:67], v[148:151], v[160:163], v[64:67]
	v_mfma_f32_16x16x32_bf16 v[32:35], v[152:155], v[160:163], v[32:35]
	v_mfma_f32_16x16x32_bf16 v[68:71], v[104:107], v[164:167], v[68:71]
	v_mfma_f32_16x16x32_bf16 v[72:75], v[144:147], v[164:167], v[72:75]
	v_mfma_f32_16x16x32_bf16 v[76:79], v[148:151], v[164:167], v[76:79]
	v_mfma_f32_16x16x32_bf16 v[36:39], v[152:155], v[164:167], v[36:39]
	v_mfma_f32_16x16x32_bf16 v[80:83], v[104:107], v[168:171], v[80:83]
	v_mfma_f32_16x16x32_bf16 v[84:87], v[144:147], v[168:171], v[84:87]
	v_mfma_f32_16x16x32_bf16 v[88:91], v[148:151], v[168:171], v[88:91]
	v_mfma_f32_16x16x32_bf16 v[40:43], v[152:155], v[168:171], v[40:43]
	ds_read_b128 v[156:159], v4 offset:28672
	ds_read_b128 v[160:163], v4 offset:29696
	ds_read_b128 v[164:167], v4 offset:30720
	ds_read_b128 v[168:171], v4 offset:31744
	s_waitcnt lgkmcnt(0)
	v_mfma_f32_16x16x32_bf16 v[108:111], v[104:107], v[156:159], v[108:111]
	v_mfma_f32_16x16x32_bf16 v[112:115], v[144:147], v[156:159], v[112:115]
	v_mfma_f32_16x16x32_bf16 v[116:119], v[148:151], v[156:159], v[116:119]
	v_mfma_f32_16x16x32_bf16 v[92:95], v[152:155], v[156:159], v[92:95]
	v_mfma_f32_16x16x32_bf16 v[120:123], v[104:107], v[160:163], v[120:123]
	v_mfma_f32_16x16x32_bf16 v[124:127], v[144:147], v[160:163], v[124:127]
	v_mfma_f32_16x16x32_bf16 v[128:131], v[148:151], v[160:163], v[128:131]
	v_mfma_f32_16x16x32_bf16 v[96:99], v[152:155], v[160:163], v[96:99]
	v_mfma_f32_16x16x32_bf16 v[132:135], v[104:107], v[164:167], v[132:135]
	v_mfma_f32_16x16x32_bf16 v[136:139], v[144:147], v[164:167], v[136:139]
	v_mfma_f32_16x16x32_bf16 v[140:143], v[148:151], v[164:167], v[140:143]
	v_mfma_f32_16x16x32_bf16 v[100:103], v[152:155], v[164:167], v[100:103]
	v_mfma_f32_16x16x32_bf16 v[12:15], v[104:107], v[168:171], v[12:15]
	v_mfma_f32_16x16x32_bf16 v[16:19], v[144:147], v[168:171], v[16:19]
	v_mfma_f32_16x16x32_bf16 v[20:23], v[148:151], v[168:171], v[20:23]
	v_mfma_f32_16x16x32_bf16 v[24:27], v[152:155], v[168:171], v[24:27]
	s_mov_b32 m0, s43
	v_lshl_add_u64 v[104:105], v[6:7], 0, s[64:65]
	s_waitcnt vmcnt(6)
	s_barrier
	global_load_lds_dwordx4 v[104:105], off
	v_lshl_add_u64 v[104:105], v[6:7], 0, s[66:67]
	s_mov_b32 m0, s42
	s_nop 0
	global_load_lds_dwordx4 v[104:105], off
	v_lshl_add_u64 v[104:105], v[6:7], 0, s[68:69]
	s_mov_b32 m0, s82
	v_lshl_add_u64 v[6:7], v[6:7], 0, s[70:71]
	global_load_lds_dwordx4 v[104:105], off
	s_mov_b32 m0, s83
	s_nop 0
	global_load_lds_dwordx4 v[6:7], off
	v_lshl_add_u64 v[6:7], v[8:9], 0, s[64:65]
	s_mov_b32 m0, s84
	s_nop 0
	global_load_lds_dwordx4 v[6:7], off
	v_lshl_add_u64 v[6:7], v[8:9], 0, s[66:67]
	s_mov_b32 m0, s85
	s_nop 0
	global_load_lds_dwordx4 v[6:7], off
	ds_read_b128 v[6:9], v11 offset:16384
	ds_read_b128 v[104:107], v11 offset:17408
	ds_read_b128 v[144:147], v11 offset:18432
	ds_read_b128 v[148:151], v11 offset:19456
	ds_read_b128 v[152:155], v4 offset:49152
	ds_read_b128 v[156:159], v4 offset:50176
	ds_read_b128 v[160:163], v4 offset:51200
	ds_read_b128 v[164:167], v4 offset:52224
	s_waitcnt lgkmcnt(0)
	v_mfma_f32_16x16x32_bf16 v[44:47], v[6:9], v[152:155], v[44:47]
	v_mfma_f32_16x16x32_bf16 v[48:51], v[104:107], v[152:155], v[48:51]
	v_mfma_f32_16x16x32_bf16 v[52:55], v[144:147], v[152:155], v[52:55]
	v_mfma_f32_16x16x32_bf16 v[28:31], v[148:151], v[152:155], v[28:31]
	v_mfma_f32_16x16x32_bf16 v[56:59], v[6:9], v[156:159], v[56:59]
	v_mfma_f32_16x16x32_bf16 v[60:63], v[104:107], v[156:159], v[60:63]
	v_mfma_f32_16x16x32_bf16 v[64:67], v[144:147], v[156:159], v[64:67]
	v_mfma_f32_16x16x32_bf16 v[32:35], v[148:151], v[156:159], v[32:35]
	v_mfma_f32_16x16x32_bf16 v[68:71], v[6:9], v[160:163], v[68:71]
	v_mfma_f32_16x16x32_bf16 v[72:75], v[104:107], v[160:163], v[72:75]
	v_mfma_f32_16x16x32_bf16 v[76:79], v[144:147], v[160:163], v[76:79]
	v_mfma_f32_16x16x32_bf16 v[36:39], v[148:151], v[160:163], v[36:39]
	v_mfma_f32_16x16x32_bf16 v[80:83], v[6:9], v[164:167], v[80:83]
	v_mfma_f32_16x16x32_bf16 v[84:87], v[104:107], v[164:167], v[84:87]
	v_mfma_f32_16x16x32_bf16 v[88:91], v[144:147], v[164:167], v[88:91]
	v_mfma_f32_16x16x32_bf16 v[40:43], v[148:151], v[164:167], v[40:43]
	ds_read_b128 v[152:155], v4 offset:53248
	ds_read_b128 v[156:159], v4 offset:54272
	ds_read_b128 v[160:163], v4 offset:55296
	ds_read_b128 v[164:167], v4 offset:56320
	s_waitcnt lgkmcnt(0)
	v_mfma_f32_16x16x32_bf16 v[108:111], v[6:9], v[152:155], v[108:111]
	v_mfma_f32_16x16x32_bf16 v[112:115], v[104:107], v[152:155], v[112:115]
	v_mfma_f32_16x16x32_bf16 v[116:119], v[144:147], v[152:155], v[116:119]
	v_mfma_f32_16x16x32_bf16 v[92:95], v[148:151], v[152:155], v[92:95]
	v_mfma_f32_16x16x32_bf16 v[120:123], v[6:9], v[156:159], v[120:123]
	v_mfma_f32_16x16x32_bf16 v[124:127], v[104:107], v[156:159], v[124:127]
	v_mfma_f32_16x16x32_bf16 v[128:131], v[144:147], v[156:159], v[128:131]
	v_mfma_f32_16x16x32_bf16 v[96:99], v[148:151], v[156:159], v[96:99]
	v_mfma_f32_16x16x32_bf16 v[132:135], v[6:9], v[160:163], v[132:135]
	v_mfma_f32_16x16x32_bf16 v[136:139], v[104:107], v[160:163], v[136:139]
	v_mfma_f32_16x16x32_bf16 v[140:143], v[144:147], v[160:163], v[140:143]
	v_mfma_f32_16x16x32_bf16 v[100:103], v[148:151], v[160:163], v[100:103]
	v_mfma_f32_16x16x32_bf16 v[6:9], v[6:9], v[164:167], v[12:15]
	v_mfma_f32_16x16x32_bf16 v[12:15], v[104:107], v[164:167], v[16:19]
	v_mfma_f32_16x16x32_bf16 v[16:19], v[144:147], v[164:167], v[20:23]
	v_mfma_f32_16x16x32_bf16 v[20:23], v[148:151], v[164:167], v[24:27]
	s_waitcnt vmcnt(6)
	s_barrier
	s_nop 0
	ds_read_b128 v[24:27], v4 offset:3072
	ds_read_b128 v[104:107], v4 offset:2048
	ds_read_b128 v[144:147], v4 offset:1024
	ds_read_b128 v[148:151], v4
	ds_read_b128 v[152:155], v172 offset:19456
	ds_read_b128 v[156:159], v172 offset:18432
	ds_read_b128 v[160:163], v172 offset:17408
	ds_read_b128 v[164:167], v172 offset:16384
	s_waitcnt lgkmcnt(0)
	v_mfma_f32_16x16x32_bf16 v[44:47], v[164:167], v[148:151], v[44:47]
	v_mfma_f32_16x16x32_bf16 v[48:51], v[160:163], v[148:151], v[48:51]
	v_mfma_f32_16x16x32_bf16 v[52:55], v[156:159], v[148:151], v[52:55]
	v_mfma_f32_16x16x32_bf16 v[28:31], v[152:155], v[148:151], v[28:31]
	v_mfma_f32_16x16x32_bf16 v[56:59], v[164:167], v[144:147], v[56:59]
	v_mfma_f32_16x16x32_bf16 v[60:63], v[160:163], v[144:147], v[60:63]
	v_mfma_f32_16x16x32_bf16 v[64:67], v[156:159], v[144:147], v[64:67]
	v_mfma_f32_16x16x32_bf16 v[32:35], v[152:155], v[144:147], v[32:35]
	v_mfma_f32_16x16x32_bf16 v[68:71], v[164:167], v[104:107], v[68:71]
	v_mfma_f32_16x16x32_bf16 v[72:75], v[160:163], v[104:107], v[72:75]
	v_mfma_f32_16x16x32_bf16 v[76:79], v[156:159], v[104:107], v[76:79]
	v_mfma_f32_16x16x32_bf16 v[36:39], v[152:155], v[104:107], v[36:39]
	v_mfma_f32_16x16x32_bf16 v[80:83], v[164:167], v[24:27], v[80:83]
	v_mfma_f32_16x16x32_bf16 v[84:87], v[160:163], v[24:27], v[84:87]
	v_mfma_f32_16x16x32_bf16 v[88:91], v[156:159], v[24:27], v[88:91]
	v_mfma_f32_16x16x32_bf16 v[24:27], v[152:155], v[24:27], v[40:43]
	s_nop 1
	ds_read_b128 v[40:43], v4 offset:4096
	ds_read_b128 v[104:107], v4 offset:5120
	ds_read_b128 v[144:147], v4 offset:6144
	ds_read_b128 v[148:151], v4 offset:7168
	s_waitcnt lgkmcnt(0)
	v_mfma_f32_16x16x32_bf16 v[108:111], v[164:167], v[40:43], v[108:111]
	v_mfma_f32_16x16x32_bf16 v[112:115], v[160:163], v[40:43], v[112:115]
	v_mfma_f32_16x16x32_bf16 v[116:119], v[156:159], v[40:43], v[116:119]
	v_mfma_f32_16x16x32_bf16 v[40:43], v[152:155], v[40:43], v[92:95]
	v_mfma_f32_16x16x32_bf16 v[92:95], v[164:167], v[104:107], v[120:123]
	v_mfma_f32_16x16x32_bf16 v[120:123], v[160:163], v[104:107], v[124:127]
	v_mfma_f32_16x16x32_bf16 v[124:127], v[156:159], v[104:107], v[128:131]
	v_mfma_f32_16x16x32_bf16 v[96:99], v[152:155], v[104:107], v[96:99]
	v_mfma_f32_16x16x32_bf16 v[104:107], v[164:167], v[144:147], v[132:135]
	v_mfma_f32_16x16x32_bf16 v[128:131], v[160:163], v[144:147], v[136:139]
	v_mfma_f32_16x16x32_bf16 v[132:135], v[156:159], v[144:147], v[140:143]
	v_mfma_f32_16x16x32_bf16 v[100:103], v[152:155], v[144:147], v[100:103]
	v_mfma_f32_16x16x32_bf16 v[6:9], v[164:167], v[148:151], v[6:9]
	v_mfma_f32_16x16x32_bf16 v[12:15], v[160:163], v[148:151], v[12:15]
	v_mfma_f32_16x16x32_bf16 v[16:19], v[156:159], v[148:151], v[16:19]
	v_mfma_f32_16x16x32_bf16 v[20:23], v[152:155], v[148:151], v[20:23]
	s_waitcnt vmcnt(0)
	s_barrier
	ds_read_b128 v[136:139], v172 offset:40960
	ds_read_b128 v[140:143], v172 offset:41984
	ds_read_b128 v[144:147], v172 offset:43008
	ds_read_b128 v[148:151], v172 offset:44032
	ds_read_b128 v[152:155], v4 offset:24576
	ds_read_b128 v[156:159], v4 offset:25600
	ds_read_b128 v[160:163], v4 offset:26624
	ds_read_b128 v[164:167], v4 offset:27648
	s_waitcnt lgkmcnt(0)
	v_mfma_f32_16x16x32_bf16 v[44:47], v[136:139], v[152:155], v[44:47]
	v_mfma_f32_16x16x32_bf16 v[48:51], v[140:143], v[152:155], v[48:51]
	v_mfma_f32_16x16x32_bf16 v[52:55], v[144:147], v[152:155], v[52:55]
	v_mfma_f32_16x16x32_bf16 v[28:31], v[148:151], v[152:155], v[28:31]
	v_mfma_f32_16x16x32_bf16 v[56:59], v[136:139], v[156:159], v[56:59]
	v_mfma_f32_16x16x32_bf16 v[60:63], v[140:143], v[156:159], v[60:63]
	v_mfma_f32_16x16x32_bf16 v[64:67], v[144:147], v[156:159], v[64:67]
	v_mfma_f32_16x16x32_bf16 v[32:35], v[148:151], v[156:159], v[32:35]
	v_mfma_f32_16x16x32_bf16 v[68:71], v[136:139], v[160:163], v[68:71]
	v_mfma_f32_16x16x32_bf16 v[72:75], v[140:143], v[160:163], v[72:75]
	v_mfma_f32_16x16x32_bf16 v[76:79], v[144:147], v[160:163], v[76:79]
	v_mfma_f32_16x16x32_bf16 v[36:39], v[148:151], v[160:163], v[36:39]
	v_mfma_f32_16x16x32_bf16 v[80:83], v[136:139], v[164:167], v[80:83]
	v_mfma_f32_16x16x32_bf16 v[84:87], v[140:143], v[164:167], v[84:87]
	v_mfma_f32_16x16x32_bf16 v[88:91], v[144:147], v[164:167], v[88:91]
	v_mfma_f32_16x16x32_bf16 v[24:27], v[148:151], v[164:167], v[24:27]
	ds_read_b128 v[152:155], v4 offset:28672
	ds_read_b128 v[156:159], v4 offset:29696
	ds_read_b128 v[160:163], v4 offset:30720
	ds_read_b128 v[164:167], v4 offset:31744
	s_waitcnt lgkmcnt(0)
	v_mfma_f32_16x16x32_bf16 v[108:111], v[136:139], v[152:155], v[108:111]
	v_mfma_f32_16x16x32_bf16 v[112:115], v[140:143], v[152:155], v[112:115]
	v_mfma_f32_16x16x32_bf16 v[116:119], v[144:147], v[152:155], v[116:119]
	v_mfma_f32_16x16x32_bf16 v[40:43], v[148:151], v[152:155], v[40:43]
	v_mfma_f32_16x16x32_bf16 v[92:95], v[136:139], v[156:159], v[92:95]
	v_mfma_f32_16x16x32_bf16 v[120:123], v[140:143], v[156:159], v[120:123]
	v_mfma_f32_16x16x32_bf16 v[124:127], v[144:147], v[156:159], v[124:127]
	v_mfma_f32_16x16x32_bf16 v[96:99], v[148:151], v[156:159], v[96:99]
	v_mfma_f32_16x16x32_bf16 v[104:107], v[136:139], v[160:163], v[104:107]
	v_mfma_f32_16x16x32_bf16 v[128:131], v[140:143], v[160:163], v[128:131]
	v_mfma_f32_16x16x32_bf16 v[132:135], v[144:147], v[160:163], v[132:135]
	v_mfma_f32_16x16x32_bf16 v[100:103], v[148:151], v[160:163], v[100:103]
	v_mfma_f32_16x16x32_bf16 v[6:9], v[136:139], v[164:167], v[6:9]
	v_mfma_f32_16x16x32_bf16 v[12:15], v[140:143], v[164:167], v[12:15]
	v_mfma_f32_16x16x32_bf16 v[16:19], v[144:147], v[164:167], v[16:19]
	v_mfma_f32_16x16x32_bf16 v[20:23], v[148:151], v[164:167], v[20:23]
	s_lshl_b64 s[42:43], s[80:81], 19
	v_lshl_add_u64 v[136:137], v[2:3], 0, s[42:43]
	v_lshl_or_b32 v4, s41, 8, v10
	v_cvt_pk_bf16_f32 v44, v44, v45
	v_cvt_pk_bf16_f32 v45, v46, v47
	v_lshl_add_u64 v[46:47], v[136:137], 0, v[4:5]
	s_waitcnt vmcnt(0)
	s_barrier
	flat_store_dwordx2 v[46:47], v[44:45]
	v_cvt_pk_bf16_f32 v44, v48, v49
	v_cvt_pk_bf16_f32 v45, v50, v51
	v_cvt_pk_bf16_f32 v28, v28, v29
	v_cvt_pk_bf16_f32 v29, v30, v31
	flat_store_dwordx2 v[46:47], v[44:45] offset:32
	v_cvt_pk_bf16_f32 v44, v52, v53
	v_cvt_pk_bf16_f32 v45, v54, v55
	flat_store_dwordx2 v[46:47], v[28:29] offset:96
	v_lshl_add_u64 v[28:29], v[136:137], 0, s[4:5]
	flat_store_dwordx2 v[46:47], v[44:45] offset:64
	v_cvt_pk_bf16_f32 v30, v56, v57
	v_cvt_pk_bf16_f32 v31, v58, v59
	v_lshl_add_u64 v[44:45], v[28:29], 0, v[4:5]
	flat_store_dwordx2 v[44:45], v[30:31]
	v_or_b32_e32 v44, 32, v4
	v_mov_b32_e32 v45, v5
	v_cvt_pk_bf16_f32 v30, v60, v61
	v_cvt_pk_bf16_f32 v31, v62, v63
	v_lshl_add_u64 v[46:47], v[28:29], 0, v[44:45]
	flat_store_dwordx2 v[46:47], v[30:31]
	v_or_b32_e32 v46, 64, v4
	v_mov_b32_e32 v47, v5
	v_cvt_pk_bf16_f32 v30, v64, v65
	v_cvt_pk_bf16_f32 v31, v66, v67
	v_lshl_add_u64 v[48:49], v[28:29], 0, v[46:47]
	flat_store_dwordx2 v[48:49], v[30:31]
	v_cvt_pk_bf16_f32 v30, v32, v33
	v_or_b32_e32 v32, 0x60, v4
	v_mov_b32_e32 v33, v5
	v_cvt_pk_bf16_f32 v31, v34, v35
	v_lshl_add_u64 v[28:29], v[28:29], 0, v[32:33]
	flat_store_dwordx2 v[28:29], v[30:31]
	v_lshl_add_u64 v[28:29], v[136:137], 0, s[6:7]
	v_cvt_pk_bf16_f32 v30, v68, v69
	v_cvt_pk_bf16_f32 v31, v70, v71
	v_lshl_add_u64 v[34:35], v[28:29], 0, v[4:5]
	flat_store_dwordx2 v[34:35], v[30:31]
	v_cvt_pk_bf16_f32 v30, v72, v73
	v_cvt_pk_bf16_f32 v31, v74, v75
	v_lshl_add_u64 v[34:35], v[28:29], 0, v[44:45]
	flat_store_dwordx2 v[34:35], v[30:31]
	v_cvt_pk_bf16_f32 v30, v76, v77
	v_cvt_pk_bf16_f32 v31, v78, v79
	v_lshl_add_u64 v[34:35], v[28:29], 0, v[46:47]
	flat_store_dwordx2 v[34:35], v[30:31]
	v_cvt_pk_bf16_f32 v30, v36, v37
	v_cvt_pk_bf16_f32 v31, v38, v39
	v_lshl_add_u64 v[28:29], v[28:29], 0, v[32:33]
	flat_store_dwordx2 v[28:29], v[30:31]
	v_lshl_add_u64 v[28:29], v[136:137], 0, s[8:9]
	v_cvt_pk_bf16_f32 v30, v80, v81
	v_cvt_pk_bf16_f32 v31, v82, v83
	v_lshl_add_u64 v[34:35], v[28:29], 0, v[4:5]
	v_cvt_pk_bf16_f32 v24, v24, v25
	v_cvt_pk_bf16_f32 v25, v26, v27
	v_lshl_add_u64 v[26:27], v[28:29], 0, v[32:33]
	flat_store_dwordx2 v[34:35], v[30:31]
	v_cvt_pk_bf16_f32 v30, v84, v85
	v_cvt_pk_bf16_f32 v31, v86, v87
	v_lshl_add_u64 v[34:35], v[28:29], 0, v[44:45]
	flat_store_dwordx2 v[26:27], v[24:25]
	v_lshl_add_u64 v[24:25], v[136:137], 0, s[72:73]
	flat_store_dwordx2 v[34:35], v[30:31]
	v_lshl_add_u64 v[34:35], v[28:29], 0, v[46:47]
	v_cvt_pk_bf16_f32 v26, v108, v109
	v_cvt_pk_bf16_f32 v27, v110, v111
	v_lshl_add_u64 v[28:29], v[24:25], 0, v[4:5]
	flat_store_dwordx2 v[28:29], v[26:27]
	v_cvt_pk_bf16_f32 v26, v112, v113
	v_cvt_pk_bf16_f32 v27, v114, v115
	v_lshl_add_u64 v[28:29], v[24:25], 0, v[44:45]
	flat_store_dwordx2 v[28:29], v[26:27]
	v_cvt_pk_bf16_f32 v26, v116, v117
	v_cvt_pk_bf16_f32 v27, v118, v119
	v_lshl_add_u64 v[28:29], v[24:25], 0, v[46:47]
	flat_store_dwordx2 v[28:29], v[26:27]
	v_cvt_pk_bf16_f32 v26, v40, v41
	v_cvt_pk_bf16_f32 v27, v42, v43
	v_lshl_add_u64 v[24:25], v[24:25], 0, v[32:33]
	flat_store_dwordx2 v[24:25], v[26:27]
	v_lshl_add_u64 v[24:25], v[136:137], 0, s[74:75]
	v_cvt_pk_bf16_f32 v26, v92, v93
	v_cvt_pk_bf16_f32 v27, v94, v95
	v_lshl_add_u64 v[28:29], v[24:25], 0, v[4:5]
	flat_store_dwordx2 v[28:29], v[26:27]
	v_cvt_pk_bf16_f32 v26, v120, v121
	v_cvt_pk_bf16_f32 v27, v122, v123
	v_lshl_add_u64 v[28:29], v[24:25], 0, v[44:45]
	flat_store_dwordx2 v[28:29], v[26:27]
	v_cvt_pk_bf16_f32 v26, v124, v125
	v_cvt_pk_bf16_f32 v27, v126, v127
	v_lshl_add_u64 v[28:29], v[24:25], 0, v[46:47]
	flat_store_dwordx2 v[28:29], v[26:27]
	v_cvt_pk_bf16_f32 v26, v96, v97
	v_cvt_pk_bf16_f32 v27, v98, v99
	v_lshl_add_u64 v[24:25], v[24:25], 0, v[32:33]
	flat_store_dwordx2 v[24:25], v[26:27]
	v_lshl_add_u64 v[24:25], v[136:137], 0, s[76:77]
	v_cvt_pk_bf16_f32 v26, v104, v105
	v_cvt_pk_bf16_f32 v27, v106, v107
	v_lshl_add_u64 v[28:29], v[24:25], 0, v[4:5]
	flat_store_dwordx2 v[28:29], v[26:27]
	v_cvt_pk_bf16_f32 v26, v128, v129
	v_cvt_pk_bf16_f32 v27, v130, v131
	v_lshl_add_u64 v[28:29], v[24:25], 0, v[44:45]
	flat_store_dwordx2 v[28:29], v[26:27]
	v_cvt_pk_bf16_f32 v26, v132, v133
	v_cvt_pk_bf16_f32 v27, v134, v135
	v_lshl_add_u64 v[28:29], v[24:25], 0, v[46:47]
	flat_store_dwordx2 v[28:29], v[26:27]
	v_cvt_pk_bf16_f32 v26, v100, v101
	v_cvt_pk_bf16_f32 v27, v102, v103
	v_lshl_add_u64 v[24:25], v[24:25], 0, v[32:33]
	flat_store_dwordx2 v[24:25], v[26:27]
	v_lshl_add_u64 v[24:25], v[136:137], 0, s[78:79]
	v_cvt_pk_bf16_f32 v6, v6, v7
	v_cvt_pk_bf16_f32 v7, v8, v9
	v_lshl_add_u64 v[8:9], v[24:25], 0, v[4:5]
	flat_store_dwordx2 v[8:9], v[6:7]
	v_cvt_pk_bf16_f32 v6, v12, v13
	v_cvt_pk_bf16_f32 v7, v14, v15
	v_lshl_add_u64 v[8:9], v[24:25], 0, v[44:45]
	flat_store_dwordx2 v[8:9], v[6:7]
	v_cvt_pk_bf16_f32 v6, v16, v17
	v_cvt_pk_bf16_f32 v7, v18, v19
	v_lshl_add_u64 v[8:9], v[24:25], 0, v[46:47]
	s_add_i32 s2, s2, s40
	v_cvt_pk_bf16_f32 v30, v88, v89
	v_cvt_pk_bf16_f32 v31, v90, v91
	flat_store_dwordx2 v[8:9], v[6:7]
	v_cvt_pk_bf16_f32 v6, v20, v21
	v_cvt_pk_bf16_f32 v7, v22, v23
	v_lshl_add_u64 v[8:9], v[24:25], 0, v[32:33]
	s_cmpk_lt_i32 s2, 0x800
	flat_store_dwordx2 v[34:35], v[30:31]
	flat_store_dwordx2 v[8:9], v[6:7]
	s_cbranch_scc1 .LBB0_568
	v_readlane_b32 s80, v247, 2
	s_mov_b32 s82, s38
	v_readlane_b32 s38, v247, 4
	v_readlane_b32 s84, v247, 6
	v_readlane_b32 s81, v247, 3
	v_readlane_b32 s39, v247, 5
	v_readlane_b32 s85, v247, 7

.LBB0_587:
	s_mul_i32 s43, s1, 0x6000
	s_add_i32 s50, s43, 0xffffa000
	s_cmp_lg_u32 s1, 0
	s_cselect_b32 s50, s50, 0xc000
	v_add_u32_e32 v148, s50, v143
	v_lshl_add_u64 v[144:145], v[136:137], 0, s[48:49]
	v_readfirstlane_b32 s50, v148
	v_add_u32_e32 v149, 0x1000, v148
	v_lshl_add_u64 v[146:147], v[144:145], 0, s[24:25]
	s_mov_b32 m0, s50
	v_readfirstlane_b32 s50, v149
	v_add_u32_e32 v149, 0x2000, v148
	s_waitcnt vmcnt(6)
	s_barrier
	global_load_lds_dwordx4 v[146:147], off
	v_lshl_add_u64 v[146:147], v[144:145], 0, s[26:27]
	s_mov_b32 m0, s50
	v_readfirstlane_b32 s50, v149
	global_load_lds_dwordx4 v[146:147], off
	v_lshl_add_u64 v[146:147], v[144:145], 0, s[28:29]
	s_mov_b32 m0, s50
	v_lshl_add_u64 v[144:145], v[144:145], 0, s[30:31]
	global_load_lds_dwordx4 v[146:147], off
	v_add_u32_e32 v146, 0x3000, v148
	v_add_u32_e32 v149, 0x4000, v148
	v_readfirstlane_b32 s50, v146
	s_mov_b32 m0, s50
	v_readfirstlane_b32 s50, v149
	global_load_lds_dwordx4 v[144:145], off
	v_lshl_add_u64 v[144:145], v[134:135], 0, s[48:49]
	v_lshl_add_u64 v[146:147], v[144:145], 0, s[34:35]
	s_mov_b32 m0, s50
	v_lshl_add_u64 v[144:145], v[144:145], 0, s[44:45]
	global_load_lds_dwordx4 v[146:147], off
	v_add_u32_e32 v146, 0x5000, v148
	s_add_i32 s43, s43, 0
	v_readfirstlane_b32 s50, v146
	s_mov_b32 m0, s50
	v_add3_u32 v156, s43, v140, v142
	global_load_lds_dwordx4 v[144:145], off
	v_add3_u32 v176, s43, v141, v142
	ds_read_b128 v[144:147], v156 offset:16384
	ds_read_b128 v[148:151], v156 offset:17408
	ds_read_b128 v[152:155], v156 offset:18432
	ds_read_b128 v[156:159], v156 offset:19456
	ds_read_b128 v[160:163], v176
	ds_read_b128 v[164:167], v176 offset:1024
	ds_read_b128 v[168:171], v176 offset:2048
	ds_read_b128 v[172:175], v176 offset:3072
	s_waitcnt lgkmcnt(0)
	v_mfma_f32_16x16x32_bf16 v[126:129], v[144:147], v[160:163], v[126:129]
	v_mfma_f32_16x16x32_bf16 v[122:125], v[148:151], v[160:163], v[122:125]
	v_mfma_f32_16x16x32_bf16 v[118:121], v[152:155], v[160:163], v[118:121]
	v_mfma_f32_16x16x32_bf16 v[114:117], v[156:159], v[160:163], v[114:117]
	v_mfma_f32_16x16x32_bf16 v[110:113], v[144:147], v[164:167], v[110:113]
	v_mfma_f32_16x16x32_bf16 v[106:109], v[148:151], v[164:167], v[106:109]
	v_mfma_f32_16x16x32_bf16 v[102:105], v[152:155], v[164:167], v[102:105]
	v_mfma_f32_16x16x32_bf16 v[98:101], v[156:159], v[164:167], v[98:101]
	v_mfma_f32_16x16x32_bf16 v[94:97], v[144:147], v[168:171], v[94:97]
	v_mfma_f32_16x16x32_bf16 v[90:93], v[148:151], v[168:171], v[90:93]
	v_mfma_f32_16x16x32_bf16 v[86:89], v[152:155], v[168:171], v[86:89]
	v_mfma_f32_16x16x32_bf16 v[82:85], v[156:159], v[168:171], v[82:85]
	v_mfma_f32_16x16x32_bf16 v[78:81], v[144:147], v[172:175], v[78:81]
	v_mfma_f32_16x16x32_bf16 v[74:77], v[148:151], v[172:175], v[74:77]
	v_mfma_f32_16x16x32_bf16 v[70:73], v[152:155], v[172:175], v[70:73]
	v_mfma_f32_16x16x32_bf16 v[66:69], v[156:159], v[172:175], v[66:69]
	ds_read_b128 v[160:163], v176 offset:4096
	ds_read_b128 v[164:167], v176 offset:5120
	ds_read_b128 v[168:171], v176 offset:6144
	ds_read_b128 v[172:175], v176 offset:7168
	s_waitcnt lgkmcnt(0)
	v_mfma_f32_16x16x32_bf16 v[62:65], v[144:147], v[160:163], v[62:65]
	v_mfma_f32_16x16x32_bf16 v[58:61], v[148:151], v[160:163], v[58:61]
	v_mfma_f32_16x16x32_bf16 v[54:57], v[152:155], v[160:163], v[54:57]
	v_mfma_f32_16x16x32_bf16 v[50:53], v[156:159], v[160:163], v[50:53]
	v_mfma_f32_16x16x32_bf16 v[46:49], v[144:147], v[164:167], v[46:49]
	v_mfma_f32_16x16x32_bf16 v[42:45], v[148:151], v[164:167], v[42:45]
	v_mfma_f32_16x16x32_bf16 v[38:41], v[152:155], v[164:167], v[38:41]
	v_mfma_f32_16x16x32_bf16 v[34:37], v[156:159], v[164:167], v[34:37]
	v_mfma_f32_16x16x32_bf16 v[30:33], v[144:147], v[168:171], v[30:33]
	v_mfma_f32_16x16x32_bf16 v[26:29], v[148:151], v[168:171], v[26:29]
	v_mfma_f32_16x16x32_bf16 v[22:25], v[152:155], v[168:171], v[22:25]
	v_mfma_f32_16x16x32_bf16 v[18:21], v[156:159], v[168:171], v[18:21]
	v_mfma_f32_16x16x32_bf16 v[14:17], v[144:147], v[172:175], v[14:17]
	v_mfma_f32_16x16x32_bf16 v[10:13], v[148:151], v[172:175], v[10:13]
	v_mfma_f32_16x16x32_bf16 v[6:9], v[152:155], v[172:175], v[6:9]
	v_mfma_f32_16x16x32_bf16 v[2:5], v[156:159], v[172:175], v[2:5]
	s_add_i32 s43, s1, 1
	s_cmp_lg_u32 s1, 2
	s_cselect_b32 s1, s43, 0
	s_add_u32 s48, s48, 64
	s_addc_u32 s49, s49, 0
	s_cmpk_eq_i32 s48, 0x1f80
	s_cbranch_scc0 .LBB0_587
	s_mul_i32 s43, s1, 0x6000
	s_add_i32 s48, s43, 0
	v_add3_u32 v143, s48, v140, v142
	s_waitcnt vmcnt(6)
	s_barrier
	ds_read_b128 v[134:137], v143 offset:16384
	ds_read_b128 v[144:147], v143 offset:17408
	ds_read_b128 v[148:151], v143 offset:18432
	ds_read_b128 v[152:155], v143 offset:19456
	v_add3_u32 v143, s48, v141, v142
	ds_read_b128 v[156:159], v143
	ds_read_b128 v[160:163], v143 offset:1024
	ds_read_b128 v[164:167], v143 offset:2048
	ds_read_b128 v[168:171], v143 offset:3072
	s_lshl_b64 s[46:47], s[46:47], 8
	s_waitcnt lgkmcnt(0)
	v_mfma_f32_16x16x32_bf16 v[118:121], v[148:151], v[156:159], v[118:121]
	v_mfma_f32_16x16x32_bf16 v[114:117], v[152:155], v[156:159], v[114:117]
	v_mfma_f32_16x16x32_bf16 v[110:113], v[134:137], v[160:163], v[110:113]
	v_mfma_f32_16x16x32_bf16 v[106:109], v[144:147], v[160:163], v[106:109]
	v_mfma_f32_16x16x32_bf16 v[102:105], v[148:151], v[160:163], v[102:105]
	v_mfma_f32_16x16x32_bf16 v[98:101], v[152:155], v[160:163], v[98:101]
	v_mfma_f32_16x16x32_bf16 v[94:97], v[134:137], v[164:167], v[94:97]
	v_mfma_f32_16x16x32_bf16 v[90:93], v[144:147], v[164:167], v[90:93]
	v_mfma_f32_16x16x32_bf16 v[86:89], v[148:151], v[164:167], v[86:89]
	v_mfma_f32_16x16x32_bf16 v[82:85], v[152:155], v[164:167], v[82:85]
	v_mfma_f32_16x16x32_bf16 v[78:81], v[134:137], v[168:171], v[78:81]
	v_mfma_f32_16x16x32_bf16 v[74:77], v[144:147], v[168:171], v[74:77]
	v_mfma_f32_16x16x32_bf16 v[70:73], v[148:151], v[168:171], v[70:73]
	v_mfma_f32_16x16x32_bf16 v[66:69], v[152:155], v[168:171], v[66:69]
	v_mfma_f32_16x16x32_bf16 v[126:129], v[134:137], v[156:159], v[126:129]
	v_mfma_f32_16x16x32_bf16 v[122:125], v[144:147], v[156:159], v[122:125]
	ds_read_b128 v[156:159], v143 offset:4096
	ds_read_b128 v[160:163], v143 offset:5120
	ds_read_b128 v[164:167], v143 offset:6144
	ds_read_b128 v[168:171], v143 offset:7168
	s_waitcnt lgkmcnt(0)
	v_mfma_f32_16x16x32_bf16 v[62:65], v[134:137], v[156:159], v[62:65]
	v_mfma_f32_16x16x32_bf16 v[58:61], v[144:147], v[156:159], v[58:61]
	v_mfma_f32_16x16x32_bf16 v[54:57], v[148:151], v[156:159], v[54:57]
	v_mfma_f32_16x16x32_bf16 v[50:53], v[152:155], v[156:159], v[50:53]
	v_mfma_f32_16x16x32_bf16 v[46:49], v[134:137], v[160:163], v[46:49]
	v_mfma_f32_16x16x32_bf16 v[42:45], v[144:147], v[160:163], v[42:45]
	v_mfma_f32_16x16x32_bf16 v[38:41], v[148:151], v[160:163], v[38:41]
	v_mfma_f32_16x16x32_bf16 v[34:37], v[152:155], v[160:163], v[34:37]
	v_mfma_f32_16x16x32_bf16 v[30:33], v[134:137], v[164:167], v[30:33]
	v_mfma_f32_16x16x32_bf16 v[26:29], v[144:147], v[164:167], v[26:29]
	v_mfma_f32_16x16x32_bf16 v[22:25], v[148:151], v[164:167], v[22:25]
	v_mfma_f32_16x16x32_bf16 v[18:21], v[152:155], v[164:167], v[18:21]
	v_mfma_f32_16x16x32_bf16 v[14:17], v[134:137], v[168:171], v[14:17]
	v_mfma_f32_16x16x32_bf16 v[10:13], v[144:147], v[168:171], v[10:13]
	v_mfma_f32_16x16x32_bf16 v[6:9], v[148:151], v[168:171], v[6:9]
	v_mfma_f32_16x16x32_bf16 v[2:5], v[152:155], v[168:171], v[2:5]
	s_addk_i32 s43, 0x6000
	s_cmp_lg_u32 s1, 2
	s_cselect_b32 s1, s43, 0
	s_add_i32 s1, s1, 0
	v_add3_u32 v140, s1, v140, v142
	v_add3_u32 v168, s1, v141, v142
	s_waitcnt vmcnt(0)
	s_barrier
	ds_read_b128 v[134:137], v140 offset:16384
	ds_read_b128 v[144:147], v140 offset:17408
	ds_read_b128 v[148:151], v140 offset:18432
	ds_read_b128 v[152:155], v140 offset:19456
	ds_read_b128 v[140:143], v168
	ds_read_b128 v[156:159], v168 offset:1024
	ds_read_b128 v[160:163], v168 offset:2048
	ds_read_b128 v[164:167], v168 offset:3072
	s_waitcnt lgkmcnt(0)
	v_mfma_f32_16x16x32_bf16 v[118:121], v[148:151], v[140:143], v[118:121]
	v_mfma_f32_16x16x32_bf16 v[110:113], v[134:137], v[156:159], v[110:113]
	v_mfma_f32_16x16x32_bf16 v[106:109], v[144:147], v[156:159], v[106:109]
	v_mfma_f32_16x16x32_bf16 v[102:105], v[148:151], v[156:159], v[102:105]
	v_mfma_f32_16x16x32_bf16 v[98:101], v[152:155], v[156:159], v[98:101]
	v_mfma_f32_16x16x32_bf16 v[94:97], v[134:137], v[160:163], v[94:97]
	v_mfma_f32_16x16x32_bf16 v[90:93], v[144:147], v[160:163], v[90:93]
	v_mfma_f32_16x16x32_bf16 v[86:89], v[148:151], v[160:163], v[86:89]
	v_mfma_f32_16x16x32_bf16 v[82:85], v[152:155], v[160:163], v[82:85]
	v_mfma_f32_16x16x32_bf16 v[78:81], v[134:137], v[164:167], v[78:81]
	v_mfma_f32_16x16x32_bf16 v[74:77], v[144:147], v[164:167], v[74:77]
	v_mfma_f32_16x16x32_bf16 v[70:73], v[148:151], v[164:167], v[70:73]
	v_mfma_f32_16x16x32_bf16 v[66:69], v[152:155], v[164:167], v[66:69]
	v_mfma_f32_16x16x32_bf16 v[126:129], v[134:137], v[140:143], v[126:129]
	v_mfma_f32_16x16x32_bf16 v[122:125], v[144:147], v[140:143], v[122:125]
	v_mfma_f32_16x16x32_bf16 v[140:143], v[152:155], v[140:143], v[114:117]
	s_nop 1
	ds_read_b128 v[114:117], v168 offset:4096
	ds_read_b128 v[156:159], v168 offset:5120
	ds_read_b128 v[160:163], v168 offset:6144
	ds_read_b128 v[164:167], v168 offset:7168
	s_waitcnt lgkmcnt(0)
	v_mfma_f32_16x16x32_bf16 v[62:65], v[134:137], v[114:117], v[62:65]
	v_mfma_f32_16x16x32_bf16 v[58:61], v[144:147], v[114:117], v[58:61]
	v_mfma_f32_16x16x32_bf16 v[54:57], v[148:151], v[114:117], v[54:57]
	v_mfma_f32_16x16x32_bf16 v[50:53], v[152:155], v[114:117], v[50:53]
	v_mfma_f32_16x16x32_bf16 v[46:49], v[134:137], v[156:159], v[46:49]
	v_mfma_f32_16x16x32_bf16 v[42:45], v[144:147], v[156:159], v[42:45]
	v_mfma_f32_16x16x32_bf16 v[38:41], v[148:151], v[156:159], v[38:41]
	v_mfma_f32_16x16x32_bf16 v[34:37], v[152:155], v[156:159], v[34:37]
	v_mfma_f32_16x16x32_bf16 v[30:33], v[134:137], v[160:163], v[30:33]
	v_mfma_f32_16x16x32_bf16 v[26:29], v[144:147], v[160:163], v[26:29]
	v_mfma_f32_16x16x32_bf16 v[22:25], v[148:151], v[160:163], v[22:25]
	v_mfma_f32_16x16x32_bf16 v[18:21], v[152:155], v[160:163], v[18:21]
	v_mfma_f32_16x16x32_bf16 v[14:17], v[134:137], v[164:167], v[14:17]
	v_mfma_f32_16x16x32_bf16 v[10:13], v[144:147], v[164:167], v[10:13]
	v_mfma_f32_16x16x32_bf16 v[6:9], v[148:151], v[164:167], v[6:9]
	v_mfma_f32_16x16x32_bf16 v[2:5], v[152:155], v[164:167], v[2:5]
	v_lshl_add_u64 v[114:115], s[46:47], 0, v[132:133]
	v_lshl_or_b32 v116, s0, 7, v138
	v_lshlrev_b64 v[134:135], 12, v[114:115]
	s_waitcnt vmcnt(0)
	v_lshl_add_u64 v[134:135], v[130:131], 0, v[134:135]
	v_ashrrev_i32_e32 v117, 31, v116
	v_lshl_add_u64 v[148:149], v[116:117], 2, v[134:135]
	s_barrier
	flat_load_dwordx4 v[134:137], v[148:149]
	v_lshlrev_b64 v[144:145], 11, v[114:115]
	v_lshl_add_u64 v[144:145], s[8:9], 0, v[144:145]
	v_lshl_add_u64 v[150:151], v[116:117], 1, v[144:145]
	s_waitcnt vmcnt(0) lgkmcnt(0)
	v_pk_add_f32 v[126:127], v[126:127], v[134:135]
	v_pk_add_f32 v[128:129], v[128:129], v[136:137]
	v_cvt_pk_bf16_f32 v134, v126, v127
	v_cvt_pk_bf16_f32 v135, v128, v129
	flat_store_dwordx4 v[148:149], v[126:129]
	flat_store_dwordx2 v[150:151], v[134:135]
	flat_load_dwordx4 v[134:137], v[148:149] offset:64
	s_waitcnt vmcnt(0) lgkmcnt(0)
	v_pk_add_f32 v[122:123], v[122:123], v[134:135]
	v_pk_add_f32 v[124:125], v[124:125], v[136:137]
	v_cvt_pk_bf16_f32 v134, v122, v123
	v_cvt_pk_bf16_f32 v135, v124, v125
	flat_store_dwordx4 v[148:149], v[122:125] offset:64
	flat_store_dwordx2 v[150:151], v[134:135] offset:32
	flat_load_dwordx4 v[134:137], v[148:149] offset:128
	s_waitcnt vmcnt(0) lgkmcnt(0)
	v_pk_add_f32 v[134:135], v[118:119], v[134:135]
	v_pk_add_f32 v[136:137], v[120:121], v[136:137]
	v_cvt_pk_bf16_f32 v118, v134, v135
	v_cvt_pk_bf16_f32 v119, v136, v137
	flat_store_dwordx4 v[148:149], v[134:137] offset:128
	flat_store_dwordx2 v[150:151], v[118:119] offset:64
	flat_load_dwordx4 v[144:147], v[148:149] offset:192
	v_and_b32_e32 v119, 64, v139
	v_xor_b32_e32 v118, 16, v139
	v_add_u32_e32 v121, 64, v119
	v_cmp_lt_i32_e64 s[0:1], v118, v121
	s_nop 1
	v_cndmask_b32_e64 v118, v139, v118, s[0:1]
	v_lshlrev_b32_e32 v120, 2, v118
	v_pk_mul_f32 v[118:119], v[126:127], v[126:127]
	v_pk_mul_f32 v[126:127], v[128:129], v[128:129]
	v_add_f32_e32 v118, v118, v119
	v_add_f32_e32 v118, v118, v126
	v_add_f32_e32 v126, v118, v127
	v_pk_mul_f32 v[118:119], v[122:123], v[122:123]
	v_pk_mul_f32 v[122:123], v[124:125], v[124:125]
	v_add_f32_e32 v118, v118, v119
	v_add_f32_e32 v118, v118, v122
	v_add_f32_e32 v118, v118, v123
	v_add_f32_e32 v128, v126, v118
	v_pk_mul_f32 v[118:119], v[134:135], v[134:135]
	v_pk_mul_f32 v[122:123], v[136:137], v[136:137]
	v_add_f32_e32 v118, v118, v119
	v_add_f32_e32 v118, v118, v122
	v_add_f32_e32 v129, v118, v123
	v_add_f32_e32 v128, v128, v129
	s_waitcnt vmcnt(0) lgkmcnt(0)
	v_pk_add_f32 v[122:123], v[140:141], v[144:145]
	v_pk_add_f32 v[124:125], v[142:143], v[146:147]
	v_pk_mul_f32 v[118:119], v[122:123], v[122:123]
	v_pk_mul_f32 v[126:127], v[124:125], v[124:125]
	v_add_f32_e32 v118, v118, v119
	v_add_f32_e32 v118, v118, v126
	v_add_f32_e32 v118, v118, v127
	v_add_f32_e32 v118, v128, v118
	ds_bpermute_b32 v119, v120, v118
	v_xor_b32_e32 v126, 32, v139
	v_cmp_lt_i32_e64 s[0:1], v126, v121
	flat_store_dwordx4 v[148:149], v[122:125] offset:192
	s_waitcnt lgkmcnt(0)
	v_add_f32_e32 v118, v118, v119
	v_cndmask_b32_e64 v121, v139, v126, s[0:1]
	v_lshlrev_b32_e32 v121, 2, v121
	ds_bpermute_b32 v119, v121, v118
	v_cvt_pk_bf16_f32 v122, v122, v123
	v_cvt_pk_bf16_f32 v123, v124, v125
	flat_store_dwordx2 v[150:151], v[122:123] offset:96
	s_and_saveexec_b64 s[0:1], vcc
	s_cbranch_execz .LBB0_590
	s_waitcnt lgkmcnt(0)
	v_add_f32_e32 v122, v118, v119
	v_lshl_add_u64 v[118:119], v[114:115], 2, s[10:11]
	flat_atomic_add_f32 v[118:119], v122

.LBB0_621:
	s_mul_i32 s57, s9, 0x6000
	s_add_i32 s58, s57, 0xffffa000
	s_cmp_lg_u32 s9, 0
	s_cselect_b32 s58, s58, 0xc000
	v_add_u32_e32 v143, s58, v138
	v_lshl_add_u64 v[144:145], v[132:133], 0, s[6:7]
	v_readfirstlane_b32 s58, v143
	v_add_u32_e32 v148, 0x1000, v143
	v_lshl_add_u64 v[146:147], v[144:145], 0, s[44:45]
	s_mov_b32 m0, s58
	v_readfirstlane_b32 s58, v148
	v_add_u32_e32 v148, 0x2000, v143
	s_waitcnt vmcnt(6)
	s_barrier
	global_load_lds_dwordx4 v[146:147], off
	v_lshl_add_u64 v[146:147], v[144:145], 0, s[46:47]
	s_mov_b32 m0, s58
	v_readfirstlane_b32 s58, v148
	global_load_lds_dwordx4 v[146:147], off
	v_lshl_add_u64 v[146:147], v[144:145], 0, s[48:49]
	s_mov_b32 m0, s58
	v_lshl_add_u64 v[144:145], v[144:145], 0, s[50:51]
	global_load_lds_dwordx4 v[146:147], off
	v_add_u32_e32 v146, 0x3000, v143
	v_add_u32_e32 v148, 0x4000, v143
	v_readfirstlane_b32 s58, v146
	s_mov_b32 m0, s58
	v_readfirstlane_b32 s58, v148
	global_load_lds_dwordx4 v[144:145], off
	v_lshl_add_u64 v[144:145], v[130:131], 0, s[6:7]
	v_add_u32_e32 v143, 0x5000, v143
	v_lshl_add_u64 v[146:147], v[144:145], 0, s[52:53]
	s_mov_b32 m0, s58
	v_readfirstlane_b32 s58, v143
	global_load_lds_dwordx4 v[146:147], off
	v_lshl_add_u64 v[144:145], v[144:145], 0, s[54:55]
	s_mov_b32 m0, s58
	s_add_i32 s57, s57, 0
	global_load_lds_dwordx4 v[144:145], off
	v_add3_u32 v143, s57, v140, v142
	ds_read_b128 v[144:147], v143 offset:16384
	ds_read_b128 v[148:151], v143 offset:17408
	ds_read_b128 v[156:159], v143 offset:18432
	ds_read_b128 v[160:163], v143 offset:19456
	v_add3_u32 v143, s57, v141, v142
	ds_read_b128 v[164:167], v143
	ds_read_b128 v[168:171], v143 offset:1024
	ds_read_b128 v[172:175], v143 offset:2048
	ds_read_b128 v[176:179], v143 offset:3072
	s_waitcnt lgkmcnt(0)
	v_mfma_f32_16x16x32_bf16 v[126:129], v[144:147], v[164:167], v[126:129]
	v_mfma_f32_16x16x32_bf16 v[122:125], v[148:151], v[164:167], v[122:125]
	v_mfma_f32_16x16x32_bf16 v[118:121], v[156:159], v[164:167], v[118:121]
	v_mfma_f32_16x16x32_bf16 v[114:117], v[160:163], v[164:167], v[114:117]
	v_mfma_f32_16x16x32_bf16 v[110:113], v[144:147], v[168:171], v[110:113]
	v_mfma_f32_16x16x32_bf16 v[106:109], v[148:151], v[168:171], v[106:109]
	v_mfma_f32_16x16x32_bf16 v[102:105], v[156:159], v[168:171], v[102:105]
	v_mfma_f32_16x16x32_bf16 v[98:101], v[160:163], v[168:171], v[98:101]
	v_mfma_f32_16x16x32_bf16 v[94:97], v[144:147], v[172:175], v[94:97]
	v_mfma_f32_16x16x32_bf16 v[90:93], v[148:151], v[172:175], v[90:93]
	v_mfma_f32_16x16x32_bf16 v[86:89], v[156:159], v[172:175], v[86:89]
	v_mfma_f32_16x16x32_bf16 v[82:85], v[160:163], v[172:175], v[82:85]
	v_mfma_f32_16x16x32_bf16 v[78:81], v[144:147], v[176:179], v[78:81]
	v_mfma_f32_16x16x32_bf16 v[74:77], v[148:151], v[176:179], v[74:77]
	v_mfma_f32_16x16x32_bf16 v[70:73], v[156:159], v[176:179], v[70:73]
	v_mfma_f32_16x16x32_bf16 v[66:69], v[160:163], v[176:179], v[66:69]
	ds_read_b128 v[164:167], v143 offset:4096
	ds_read_b128 v[168:171], v143 offset:5120
	ds_read_b128 v[172:175], v143 offset:6144
	ds_read_b128 v[176:179], v143 offset:7168
	s_waitcnt lgkmcnt(0)
	v_mfma_f32_16x16x32_bf16 v[62:65], v[144:147], v[164:167], v[62:65]
	v_mfma_f32_16x16x32_bf16 v[58:61], v[148:151], v[164:167], v[58:61]
	v_mfma_f32_16x16x32_bf16 v[54:57], v[156:159], v[164:167], v[54:57]
	v_mfma_f32_16x16x32_bf16 v[50:53], v[160:163], v[164:167], v[50:53]
	v_mfma_f32_16x16x32_bf16 v[46:49], v[144:147], v[168:171], v[46:49]
	v_mfma_f32_16x16x32_bf16 v[42:45], v[148:151], v[168:171], v[42:45]
	v_mfma_f32_16x16x32_bf16 v[38:41], v[156:159], v[168:171], v[38:41]
	v_mfma_f32_16x16x32_bf16 v[34:37], v[160:163], v[168:171], v[34:37]
	v_mfma_f32_16x16x32_bf16 v[30:33], v[144:147], v[172:175], v[30:33]
	v_mfma_f32_16x16x32_bf16 v[26:29], v[148:151], v[172:175], v[26:29]
	v_mfma_f32_16x16x32_bf16 v[22:25], v[156:159], v[172:175], v[22:25]
	v_mfma_f32_16x16x32_bf16 v[18:21], v[160:163], v[172:175], v[18:21]
	v_mfma_f32_16x16x32_bf16 v[14:17], v[144:147], v[176:179], v[14:17]
	v_mfma_f32_16x16x32_bf16 v[10:13], v[148:151], v[176:179], v[10:13]
	v_mfma_f32_16x16x32_bf16 v[6:9], v[156:159], v[176:179], v[6:9]
	v_mfma_f32_16x16x32_bf16 v[2:5], v[160:163], v[176:179], v[2:5]
	s_add_i32 s57, s9, 1
	s_cmp_lg_u32 s9, 2
	s_cselect_b32 s9, s57, 0
	s_add_u32 s6, s6, 64
	s_addc_u32 s7, s7, 0
	s_cmpk_eq_i32 s6, 0x780
	s_cbranch_scc0 .LBB0_621
	v_add3_u32 v138, 0, v140, v142
	v_add3_u32 v155, 0, v141, v142
	s_waitcnt vmcnt(6)
	s_barrier
	ds_read_b128 v[130:133], v138 offset:16384
	ds_read_b128 v[144:147], v138 offset:17408
	ds_read_b128 v[148:151], v138 offset:18432
	ds_read_b128 v[156:159], v138 offset:19456
	ds_read_b128 v[140:143], v155
	ds_read_b128 v[160:163], v155 offset:1024
	ds_read_b128 v[164:167], v155 offset:2048
	ds_read_b128 v[168:171], v155 offset:3072
	s_waitcnt lgkmcnt(0)
	v_mfma_f32_16x16x32_bf16 v[126:129], v[130:133], v[140:143], v[126:129]
	v_mfma_f32_16x16x32_bf16 v[114:117], v[156:159], v[140:143], v[114:117]
	v_mfma_f32_16x16x32_bf16 v[110:113], v[130:133], v[160:163], v[110:113]
	v_mfma_f32_16x16x32_bf16 v[106:109], v[144:147], v[160:163], v[106:109]
	v_mfma_f32_16x16x32_bf16 v[102:105], v[148:151], v[160:163], v[102:105]
	v_mfma_f32_16x16x32_bf16 v[98:101], v[156:159], v[160:163], v[98:101]
	v_mfma_f32_16x16x32_bf16 v[94:97], v[130:133], v[164:167], v[94:97]
	v_mfma_f32_16x16x32_bf16 v[90:93], v[144:147], v[164:167], v[90:93]
	v_mfma_f32_16x16x32_bf16 v[86:89], v[148:151], v[164:167], v[86:89]
	v_mfma_f32_16x16x32_bf16 v[82:85], v[156:159], v[164:167], v[82:85]
	v_mfma_f32_16x16x32_bf16 v[78:81], v[130:133], v[168:171], v[78:81]
	v_mfma_f32_16x16x32_bf16 v[74:77], v[144:147], v[168:171], v[74:77]
	v_mfma_f32_16x16x32_bf16 v[70:73], v[148:151], v[168:171], v[70:73]
	v_mfma_f32_16x16x32_bf16 v[66:69], v[156:159], v[168:171], v[66:69]
	v_mfma_f32_16x16x32_bf16 v[122:125], v[144:147], v[140:143], v[122:125]
	v_mfma_f32_16x16x32_bf16 v[118:121], v[148:151], v[140:143], v[118:121]
	ds_read_b128 v[140:143], v155 offset:4096
	ds_read_b128 v[160:163], v155 offset:5120
	ds_read_b128 v[164:167], v155 offset:6144
	ds_read_b128 v[168:171], v155 offset:7168
	s_waitcnt lgkmcnt(0)
	v_mfma_f32_16x16x32_bf16 v[62:65], v[130:133], v[140:143], v[62:65]
	v_mfma_f32_16x16x32_bf16 v[58:61], v[144:147], v[140:143], v[58:61]
	v_mfma_f32_16x16x32_bf16 v[54:57], v[148:151], v[140:143], v[54:57]
	v_mfma_f32_16x16x32_bf16 v[50:53], v[156:159], v[140:143], v[50:53]
	v_mfma_f32_16x16x32_bf16 v[46:49], v[130:133], v[160:163], v[46:49]
	v_mfma_f32_16x16x32_bf16 v[42:45], v[144:147], v[160:163], v[42:45]
	v_mfma_f32_16x16x32_bf16 v[38:41], v[148:151], v[160:163], v[38:41]
	v_mfma_f32_16x16x32_bf16 v[34:37], v[156:159], v[160:163], v[34:37]
	v_mfma_f32_16x16x32_bf16 v[30:33], v[130:133], v[164:167], v[30:33]
	v_mfma_f32_16x16x32_bf16 v[26:29], v[144:147], v[164:167], v[26:29]
	v_mfma_f32_16x16x32_bf16 v[22:25], v[148:151], v[164:167], v[22:25]
	v_mfma_f32_16x16x32_bf16 v[18:21], v[156:159], v[164:167], v[18:21]
	v_mfma_f32_16x16x32_bf16 v[14:17], v[130:133], v[168:171], v[14:17]
	v_mfma_f32_16x16x32_bf16 v[10:13], v[144:147], v[168:171], v[10:13]
	v_mfma_f32_16x16x32_bf16 v[6:9], v[148:151], v[168:171], v[6:9]
	v_mfma_f32_16x16x32_bf16 v[2:5], v[156:159], v[168:171], v[2:5]
	s_waitcnt vmcnt(0)
	s_barrier
	ds_read_b128 v[130:133], v138 offset:40960
	ds_read_b128 v[140:143], v138 offset:41984
	ds_read_b128 v[144:147], v138 offset:43008
	ds_read_b128 v[148:151], v138 offset:44032
	ds_read_b128 v[156:159], v155 offset:24576
	ds_read_b128 v[160:163], v155 offset:25600
	ds_read_b128 v[164:167], v155 offset:26624
	ds_read_b128 v[168:171], v155 offset:27648
	s_lshl_b64 s[4:5], s[4:5], 8
	s_waitcnt lgkmcnt(0)
	v_mfma_f32_16x16x32_bf16 v[172:175], v[130:133], v[156:159], v[126:129]
	v_mfma_f32_16x16x32_bf16 v[126:129], v[140:143], v[156:159], v[122:125]
	v_mfma_f32_16x16x32_bf16 v[114:117], v[148:151], v[156:159], v[114:117]
	v_mfma_f32_16x16x32_bf16 v[110:113], v[130:133], v[160:163], v[110:113]
	v_mfma_f32_16x16x32_bf16 v[106:109], v[140:143], v[160:163], v[106:109]
	v_mfma_f32_16x16x32_bf16 v[102:105], v[144:147], v[160:163], v[102:105]
	v_mfma_f32_16x16x32_bf16 v[98:101], v[148:151], v[160:163], v[98:101]
	v_mfma_f32_16x16x32_bf16 v[94:97], v[130:133], v[164:167], v[94:97]
	v_mfma_f32_16x16x32_bf16 v[90:93], v[140:143], v[164:167], v[90:93]
	v_mfma_f32_16x16x32_bf16 v[86:89], v[144:147], v[164:167], v[86:89]
	v_mfma_f32_16x16x32_bf16 v[82:85], v[148:151], v[164:167], v[82:85]
	v_mfma_f32_16x16x32_bf16 v[78:81], v[130:133], v[168:171], v[78:81]
	v_mfma_f32_16x16x32_bf16 v[74:77], v[140:143], v[168:171], v[74:77]
	v_mfma_f32_16x16x32_bf16 v[70:73], v[144:147], v[168:171], v[70:73]
	v_mfma_f32_16x16x32_bf16 v[66:69], v[148:151], v[168:171], v[66:69]
	v_mfma_f32_16x16x32_bf16 v[122:125], v[144:147], v[156:159], v[118:121]
	s_nop 1
	ds_read_b128 v[118:121], v155 offset:28672
	ds_read_b128 v[156:159], v155 offset:29696
	ds_read_b128 v[160:163], v155 offset:30720
	ds_read_b128 v[164:167], v155 offset:31744
	s_waitcnt lgkmcnt(0)
	v_mfma_f32_16x16x32_bf16 v[62:65], v[130:133], v[118:121], v[62:65]
	v_mfma_f32_16x16x32_bf16 v[58:61], v[140:143], v[118:121], v[58:61]
	v_mfma_f32_16x16x32_bf16 v[54:57], v[144:147], v[118:121], v[54:57]
	v_mfma_f32_16x16x32_bf16 v[50:53], v[148:151], v[118:121], v[50:53]
	v_mfma_f32_16x16x32_bf16 v[46:49], v[130:133], v[156:159], v[46:49]
	v_mfma_f32_16x16x32_bf16 v[42:45], v[140:143], v[156:159], v[42:45]
	v_mfma_f32_16x16x32_bf16 v[38:41], v[144:147], v[156:159], v[38:41]
	v_mfma_f32_16x16x32_bf16 v[34:37], v[148:151], v[156:159], v[34:37]
	v_mfma_f32_16x16x32_bf16 v[30:33], v[130:133], v[160:163], v[30:33]
	v_mfma_f32_16x16x32_bf16 v[26:29], v[140:143], v[160:163], v[26:29]
	v_mfma_f32_16x16x32_bf16 v[22:25], v[144:147], v[160:163], v[22:25]
	v_mfma_f32_16x16x32_bf16 v[18:21], v[148:151], v[160:163], v[18:21]
	v_mfma_f32_16x16x32_bf16 v[14:17], v[130:133], v[164:167], v[14:17]
	v_mfma_f32_16x16x32_bf16 v[10:13], v[140:143], v[164:167], v[10:13]
	v_mfma_f32_16x16x32_bf16 v[6:9], v[144:147], v[164:167], v[6:9]
	v_mfma_f32_16x16x32_bf16 v[2:5], v[148:151], v[164:167], v[2:5]
	v_lshl_add_u64 v[140:141], s[4:5], 0, v[136:137]
	v_lshl_add_u64 v[118:119], v[140:141], 2, s[18:19]
	s_waitcnt vmcnt(0)
	s_barrier
	flat_load_dword v150, v[118:119]
	v_lshl_or_b32 v132, s8, 7, v152
	v_lshlrev_b64 v[118:119], 11, v[140:141]
	v_lshl_add_u64 v[120:121], s[14:15], 0, v[118:119]
	v_lshlrev_b32_e32 v142, 1, v132
	v_mov_b32_e32 v143, v139
	v_lshl_add_u64 v[148:149], v[120:121], 0, v[142:143]
	v_lshlrev_b64 v[120:121], 12, v[140:141]
	v_lshlrev_b32_e32 v138, 2, v132
	v_lshl_add_u64 v[120:121], v[134:135], 0, v[120:121]
	flat_load_dwordx2 v[130:131], v[148:149]
	v_lshl_add_u64 v[144:145], v[120:121], 0, v[138:139]
	v_lshl_add_u64 v[132:133], s[16:17], 0, v[118:119]
	flat_load_dwordx4 v[118:121], v[144:145]
	v_lshl_add_u64 v[146:147], v[132:133], 0, v[142:143]
	s_waitcnt vmcnt(0) lgkmcnt(0)
	v_fmamk_f32 v132, v150, 0x3a800000, v153
	v_mul_f32_e32 v133, 0x4b800000, v132
	v_cmp_gt_f32_e32 vcc, s56, v132
	s_nop 1
	v_cndmask_b32_e32 v132, v132, v133, vcc
	v_rsq_f32_e32 v150, v132
	v_lshlrev_b32_e32 v132, 16, v130
	v_mul_f32_e32 v151, 0x45800000, v150
	v_cndmask_b32_e32 v155, v150, v151, vcc
	v_mul_f32_e32 v150, v172, v155
	v_mul_f32_e32 v151, v173, v155
	v_mul_f32_e32 v150, 0xbfb8aa3b, v150
	v_mul_f32_e32 v151, 0xbfb8aa3b, v151
	v_mul_f32_e32 v156, v174, v155
	v_mul_f32_e32 v157, v175, v155
	v_exp_f32_e32 v150, v150
	v_exp_f32_e32 v151, v151
	v_mul_f32_e32 v156, 0xbfb8aa3b, v156
	v_mul_f32_e32 v157, 0xbfb8aa3b, v157
	v_exp_f32_e32 v156, v156
	v_exp_f32_e32 v157, v157
	v_pk_add_f32 v[150:151], v[150:151], 1.0 op_sel_hi:[1,0]
	v_and_b32_e32 v133, 0xffff0000, v130
	v_div_scale_f32 v158, s[4:5], v151, v151, 1.0
	v_pk_add_f32 v[156:157], v[156:157], 1.0 op_sel_hi:[1,0]
	v_div_scale_f32 v160, s[4:5], v150, v150, 1.0
	v_rcp_f32_e32 v166, v158
	v_div_scale_f32 v162, s[6:7], v157, v157, 1.0
	v_rcp_f32_e32 v167, v160
	v_div_scale_f32 v164, s[8:9], v156, v156, 1.0
	v_rcp_f32_e32 v168, v162
	v_rcp_f32_e32 v169, v164
	v_fma_f32 v170, -v158, v166, 1.0
	v_div_scale_f32 v159, vcc, 1.0, v151, 1.0
	v_fma_f32 v171, -v160, v167, 1.0
	v_fmac_f32_e32 v166, v170, v166
	v_div_scale_f32 v161, s[4:5], 1.0, v150, 1.0
	v_fma_f32 v172, -v162, v168, 1.0
	v_fmac_f32_e32 v167, v171, v167
	v_mul_f32_e32 v170, v159, v166
	v_div_scale_f32 v163, s[6:7], 1.0, v157, 1.0
	v_fma_f32 v173, -v164, v169, 1.0
	v_fmac_f32_e32 v168, v172, v168
	v_mul_f32_e32 v171, v161, v167
	v_fma_f32 v174, -v158, v170, v159
	v_div_scale_f32 v165, s[8:9], 1.0, v156, 1.0
	v_fmac_f32_e32 v169, v173, v169
	v_mul_f32_e32 v172, v163, v168
	v_fma_f32 v175, -v160, v171, v161
	v_fmac_f32_e32 v170, v174, v166
	v_mul_f32_e32 v173, v165, v169
	v_fma_f32 v176, -v162, v172, v163
	v_fmac_f32_e32 v171, v175, v167
	v_fma_f32 v158, -v158, v170, v159
	v_fma_f32 v177, -v164, v173, v165
	v_fmac_f32_e32 v172, v176, v168
	v_fma_f32 v159, -v160, v171, v161
	v_div_fmas_f32 v158, v158, v166, v170
	s_mov_b64 vcc, s[4:5]
	v_fmac_f32_e32 v173, v177, v169
	v_fma_f32 v160, -v162, v172, v163
	v_div_fixup_f32 v151, v158, v151, 1.0
	v_div_fmas_f32 v158, v159, v167, v171
	s_mov_b64 vcc, s[6:7]
	v_fma_f32 v161, -v164, v173, v165
	v_div_fixup_f32 v150, v158, v150, 1.0
	v_div_fmas_f32 v158, v160, v168, v172
	s_mov_b64 vcc, s[8:9]
	v_pk_fma_f32 v[118:119], v[150:151], v[132:133], v[118:119]
	v_div_fmas_f32 v132, v161, v169, v173
	v_lshlrev_b32_e32 v130, 16, v131
	v_and_b32_e32 v131, 0xffff0000, v131
	v_div_fixup_f32 v133, v158, v157, 1.0
	v_div_fixup_f32 v132, v132, v156, 1.0
	v_pk_fma_f32 v[120:121], v[132:133], v[130:131], v[120:121]
	flat_store_dwordx4 v[144:145], v[118:121]
	v_cvt_pk_bf16_f32 v130, v118, v119
	v_cvt_pk_bf16_f32 v131, v120, v121
	flat_load_dwordx2 v[150:151], v[148:149] offset:32
	v_mul_f32_e32 v126, v126, v155
	flat_store_dwordx2 v[146:147], v[130:131]
	flat_load_dwordx4 v[130:133], v[144:145] offset:64
	v_mul_f32_e32 v127, v127, v155
	v_mul_f32_e32 v128, v128, v155
	v_mul_f32_e32 v129, v129, v155
	v_mul_f32_e32 v156, v122, v155
	v_mul_f32_e32 v157, v123, v155
	v_mul_f32_e32 v122, 0xbfb8aa3b, v126
	v_mul_f32_e32 v123, 0xbfb8aa3b, v127
	v_mul_f32_e32 v158, v124, v155
	v_mul_f32_e32 v159, v125, v155
	v_mul_f32_e32 v124, 0xbfb8aa3b, v128
	v_mul_f32_e32 v125, 0xbfb8aa3b, v129
	v_exp_f32_e32 v122, v122
	v_exp_f32_e32 v123, v123
	v_exp_f32_e32 v124, v124
	v_exp_f32_e32 v125, v125
	v_mul_f32_e32 v160, v114, v155
	v_mul_f32_e32 v161, v115, v155
	v_pk_add_f32 v[114:115], v[122:123], 1.0 op_sel_hi:[1,0]
	v_pk_add_f32 v[122:123], v[124:125], 1.0 op_sel_hi:[1,0]
	v_div_scale_f32 v124, s[4:5], v115, v115, 1.0
	v_div_scale_f32 v126, s[4:5], v114, v114, 1.0
	v_rcp_f32_e32 v164, v124
	v_div_scale_f32 v128, s[6:7], v123, v123, 1.0
	v_rcp_f32_e32 v165, v126
	v_div_scale_f32 v162, s[8:9], v122, v122, 1.0
	v_rcp_f32_e32 v166, v128
	v_rcp_f32_e32 v167, v162
	v_fma_f32 v168, -v124, v164, 1.0
	v_div_scale_f32 v125, vcc, 1.0, v115, 1.0
	v_fma_f32 v169, -v126, v165, 1.0
	v_fmac_f32_e32 v164, v168, v164
	v_div_scale_f32 v127, s[4:5], 1.0, v114, 1.0
	v_fma_f32 v170, -v128, v166, 1.0
	v_fmac_f32_e32 v165, v169, v165
	v_mul_f32_e32 v168, v125, v164
	v_div_scale_f32 v129, s[6:7], 1.0, v123, 1.0
	v_fma_f32 v171, -v162, v167, 1.0
	v_fmac_f32_e32 v166, v170, v166
	v_mul_f32_e32 v169, v127, v165
	v_fma_f32 v172, -v124, v168, v125
	v_div_scale_f32 v163, s[8:9], 1.0, v122, 1.0
	v_fmac_f32_e32 v167, v171, v167
	v_mul_f32_e32 v170, v129, v166
	v_fma_f32 v173, -v126, v169, v127
	v_fmac_f32_e32 v168, v172, v164
	v_mul_f32_e32 v171, v163, v167
	v_fma_f32 v174, -v128, v170, v129
	v_fmac_f32_e32 v169, v173, v165
	v_fma_f32 v124, -v124, v168, v125
	v_fma_f32 v175, -v162, v171, v163
	v_fmac_f32_e32 v170, v174, v166
	v_fma_f32 v125, -v126, v169, v127
	v_div_fmas_f32 v124, v124, v164, v168
	s_mov_b64 vcc, s[4:5]
	v_fmac_f32_e32 v171, v175, v167
	v_fma_f32 v126, -v128, v170, v129
	v_div_fixup_f32 v115, v124, v115, 1.0
	v_div_fmas_f32 v124, v125, v165, v169
	s_mov_b64 vcc, s[6:7]
	v_fma_f32 v127, -v162, v171, v163
	v_div_fixup_f32 v114, v124, v114, 1.0
	v_div_fmas_f32 v124, v126, v166, v170
	s_mov_b64 vcc, s[8:9]
	v_div_fixup_f32 v125, v124, v123, 1.0
	v_div_fmas_f32 v123, v127, v167, v171
	v_div_fixup_f32 v124, v123, v122, 1.0
	v_mul_f32_e32 v116, v116, v155
	v_mul_f32_e32 v117, v117, v155
	s_waitcnt vmcnt(0) lgkmcnt(0)
	v_lshlrev_b32_e32 v122, 16, v150
	v_and_b32_e32 v123, 0xffff0000, v150
	v_lshlrev_b32_e32 v126, 16, v151
	v_and_b32_e32 v127, 0xffff0000, v151
	v_pk_fma_f32 v[122:123], v[114:115], v[122:123], v[130:131]
	v_pk_fma_f32 v[124:125], v[124:125], v[126:127], v[132:133]
	flat_store_dwordx4 v[144:145], v[122:125] offset:64
	v_cvt_pk_bf16_f32 v126, v122, v123
	v_cvt_pk_bf16_f32 v127, v124, v125
	flat_load_dwordx2 v[114:115], v[148:149] offset:64
	v_mul_f32_e32 v130, 0xbfb8aa3b, v156
	flat_store_dwordx2 v[146:147], v[126:127] offset:32
	flat_load_dwordx4 v[126:129], v[144:145] offset:128
	v_mul_f32_e32 v131, 0xbfb8aa3b, v157
	v_mul_f32_e32 v150, 0xbfb8aa3b, v160
	v_mul_f32_e32 v155, 0xbfb8aa3b, v116
	v_mul_f32_e32 v160, 0xbfb8aa3b, v117
	v_exp_f32_e32 v116, v130
	v_exp_f32_e32 v117, v131
	v_mul_f32_e32 v132, 0xbfb8aa3b, v158
	v_mul_f32_e32 v133, 0xbfb8aa3b, v159
	v_exp_f32_e32 v130, v132
	v_exp_f32_e32 v131, v133
	v_mul_f32_e32 v151, 0xbfb8aa3b, v161
	v_pk_add_f32 v[116:117], v[116:117], 1.0 op_sel_hi:[1,0]
	v_exp_f32_e32 v133, v151
	v_div_scale_f32 v151, s[4:5], v117, v117, 1.0
	v_pk_add_f32 v[130:131], v[130:131], 1.0 op_sel_hi:[1,0]
	v_div_scale_f32 v156, s[4:5], v116, v116, 1.0
	v_rcp_f32_e32 v163, v151
	v_div_scale_f32 v158, s[6:7], v131, v131, 1.0
	v_rcp_f32_e32 v164, v156
	v_div_scale_f32 v161, s[8:9], v130, v130, 1.0
	v_rcp_f32_e32 v165, v158
	v_rcp_f32_e32 v166, v161
	v_fma_f32 v167, -v151, v163, 1.0
	v_exp_f32_e32 v132, v150
	v_exp_f32_e32 v150, v155
	v_div_scale_f32 v155, vcc, 1.0, v117, 1.0
	v_fma_f32 v168, -v156, v164, 1.0
	v_fmac_f32_e32 v163, v167, v163
	v_div_scale_f32 v157, s[4:5], 1.0, v116, 1.0
	v_fma_f32 v169, -v158, v165, 1.0
	v_fmac_f32_e32 v164, v168, v164
	v_mul_f32_e32 v167, v155, v163
	v_div_scale_f32 v159, s[6:7], 1.0, v131, 1.0
	v_fma_f32 v170, -v161, v166, 1.0
	v_fmac_f32_e32 v165, v169, v165
	v_mul_f32_e32 v168, v157, v164
	v_fma_f32 v171, -v151, v167, v155
	v_div_scale_f32 v162, s[8:9], 1.0, v130, 1.0
	v_fmac_f32_e32 v166, v170, v166
	v_mul_f32_e32 v169, v159, v165
	v_fma_f32 v172, -v156, v168, v157
	v_fmac_f32_e32 v167, v171, v163
	v_mul_f32_e32 v170, v162, v166
	v_fma_f32 v173, -v158, v169, v159
	v_fmac_f32_e32 v168, v172, v164
	v_fma_f32 v151, -v151, v167, v155
	v_fma_f32 v174, -v161, v170, v162
	v_fmac_f32_e32 v169, v173, v165
	v_fma_f32 v155, -v156, v168, v157
	v_div_fmas_f32 v151, v151, v163, v167
	s_mov_b64 vcc, s[4:5]
	v_fmac_f32_e32 v170, v174, v166
	v_fma_f32 v156, -v158, v169, v159
	v_div_fixup_f32 v117, v151, v117, 1.0
	v_div_fmas_f32 v151, v155, v164, v168
	s_mov_b64 vcc, s[6:7]
	v_fma_f32 v157, -v161, v170, v162
	v_div_fixup_f32 v116, v151, v116, 1.0
	v_div_fmas_f32 v151, v156, v165, v169
	s_mov_b64 vcc, s[8:9]
	v_div_fixup_f32 v131, v151, v131, 1.0
	v_div_fmas_f32 v151, v157, v166, v170
	v_div_fixup_f32 v130, v151, v130, 1.0
	v_exp_f32_e32 v151, v160
	v_pk_add_f32 v[132:133], v[132:133], 1.0 op_sel_hi:[1,0]
	v_pk_mul_f32 v[118:119], v[118:119], v[118:119]
	v_div_scale_f32 v155, s[4:5], v132, v132, 1.0
	s_waitcnt vmcnt(0) lgkmcnt(0)
	v_lshlrev_b32_e32 v156, 16, v114
	v_and_b32_e32 v157, 0xffff0000, v114
	v_lshlrev_b32_e32 v158, 16, v115
	v_and_b32_e32 v159, 0xffff0000, v115
	v_pk_fma_f32 v[114:115], v[116:117], v[156:157], v[126:127]
	v_pk_fma_f32 v[116:117], v[130:131], v[158:159], v[128:129]
	flat_store_dwordx4 v[144:145], v[114:117] offset:128
	v_cvt_pk_bf16_f32 v126, v114, v115
	v_cvt_pk_bf16_f32 v127, v116, v117
	flat_load_dwordx2 v[130:131], v[148:149] offset:96
	v_pk_add_f32 v[148:149], v[150:151], 1.0 op_sel_hi:[1,0]
	flat_store_dwordx2 v[146:147], v[126:127] offset:64
	flat_load_dwordx4 v[126:129], v[144:145] offset:192
	v_div_scale_f32 v150, s[4:5], v133, v133, 1.0
	v_div_scale_f32 v157, s[6:7], v149, v149, 1.0
	v_rcp_f32_e32 v161, v150
	v_rcp_f32_e32 v162, v155
	v_rcp_f32_e32 v163, v157
	v_div_scale_f32 v159, s[8:9], v148, v148, 1.0
	v_rcp_f32_e32 v164, v159
	v_fma_f32 v165, -v150, v161, 1.0
	v_fma_f32 v166, -v155, v162, 1.0
	v_fma_f32 v167, -v157, v163, 1.0
	v_div_scale_f32 v151, vcc, 1.0, v133, 1.0
	v_div_scale_f32 v156, s[4:5], 1.0, v132, 1.0
	v_div_scale_f32 v158, s[6:7], 1.0, v149, 1.0
	v_fmac_f32_e32 v161, v165, v161
	v_fmac_f32_e32 v162, v166, v162
	v_fmac_f32_e32 v163, v167, v163
	v_mul_f32_e32 v165, v151, v161
	v_mul_f32_e32 v166, v156, v162
	v_mul_f32_e32 v167, v158, v163
	v_fma_f32 v169, -v150, v165, v151
	v_fma_f32 v170, -v155, v166, v156
	v_fma_f32 v171, -v157, v167, v158
	v_fma_f32 v168, -v159, v164, 1.0
	v_fmac_f32_e32 v165, v169, v161
	v_fmac_f32_e32 v166, v170, v162
	v_fmac_f32_e32 v167, v171, v163
	v_div_scale_f32 v160, s[8:9], 1.0, v148, 1.0
	v_fmac_f32_e32 v164, v168, v164
	v_fma_f32 v150, -v150, v165, v151
	v_fma_f32 v151, -v155, v166, v156
	v_fma_f32 v155, -v157, v167, v158
	v_add_f32_e32 v157, v118, v119
	v_pk_mul_f32 v[118:119], v[120:121], v[120:121]
	v_mul_f32_e32 v168, v160, v164
	v_add_f32_e32 v118, v118, v157
	v_fma_f32 v172, -v159, v168, v160
	v_add_f32_e32 v157, v119, v118
	v_div_fmas_f32 v118, v150, v161, v165
	s_mov_b64 vcc, s[4:5]
	v_pk_mul_f32 v[122:123], v[122:123], v[122:123]
	v_fmac_f32_e32 v168, v172, v164
	v_div_fixup_f32 v119, v118, v133, 1.0
	v_div_fmas_f32 v118, v151, v162, v166
	s_mov_b64 vcc, s[6:7]
	v_pk_mul_f32 v[124:125], v[124:125], v[124:125]
	v_add_f32_e32 v122, v122, v123
	v_fma_f32 v156, -v159, v168, v160
	v_div_fmas_f32 v120, v155, v163, v167
	s_mov_b64 vcc, s[8:9]
	v_add_f32_e32 v122, v124, v122
	v_pk_mul_f32 v[114:115], v[114:115], v[114:115]
	v_div_fixup_f32 v118, v118, v132, 1.0
	v_div_fixup_f32 v121, v120, v149, 1.0
	v_div_fmas_f32 v120, v156, v164, v168
	v_add_f32_e32 v122, v125, v122
	v_add_f32_e32 v133, v114, v115
	v_div_fixup_f32 v120, v120, v148, 1.0
	v_add_f32_e32 v132, v157, v122
	v_pk_mul_f32 v[122:123], v[116:117], v[116:117]
	s_waitcnt vmcnt(0) lgkmcnt(0)
	v_lshlrev_b32_e32 v114, 16, v130
	v_and_b32_e32 v115, 0xffff0000, v130
	v_lshlrev_b32_e32 v124, 16, v131
	v_and_b32_e32 v125, 0xffff0000, v131
	v_pk_fma_f32 v[116:117], v[118:119], v[114:115], v[126:127]
	v_pk_fma_f32 v[118:119], v[120:121], v[124:125], v[128:129]
	v_pk_mul_f32 v[114:115], v[116:117], v[116:117]
	v_pk_mul_f32 v[120:121], v[118:119], v[118:119]
	v_add_f32_e32 v114, v114, v115
	v_add_f32_e32 v114, v120, v114
	v_and_b32_e32 v120, 64, v154
	v_add_f32_e32 v122, v122, v133
	v_xor_b32_e32 v115, 16, v154
	v_add_u32_e32 v120, 64, v120
	v_add_f32_e32 v122, v123, v122
	v_cmp_lt_i32_e32 vcc, v115, v120
	v_add_f32_e32 v122, v132, v122
	v_add_f32_e32 v114, v121, v114
	v_cndmask_b32_e32 v115, v154, v115, vcc
	v_add_f32_e32 v114, v122, v114
	v_lshlrev_b32_e32 v126, 2, v115
	ds_bpermute_b32 v115, v126, v114
	flat_store_dwordx4 v[144:145], v[116:119] offset:192
	s_waitcnt lgkmcnt(0)
	v_add_f32_e32 v114, v114, v115
	v_xor_b32_e32 v115, 32, v154
	v_cmp_lt_i32_e32 vcc, v115, v120
	v_cvt_pk_bf16_f32 v116, v116, v117
	v_cvt_pk_bf16_f32 v117, v118, v119
	v_cndmask_b32_e32 v115, v154, v115, vcc
	v_lshlrev_b32_e32 v127, 2, v115
	ds_bpermute_b32 v115, v127, v114
	flat_store_dwordx2 v[146:147], v[116:117] offset:96
	s_and_saveexec_b64 s[4:5], s[0:1]
	s_cbranch_execz .LBB0_624
	s_waitcnt lgkmcnt(0)
	v_add_f32_e32 v116, v114, v115
	v_lshl_add_u64 v[114:115], v[140:141], 2, s[20:21]
	flat_atomic_add_f32 v[114:115], v116

.LBB0_672:
	s_mul_i32 s66, s7, 0x6000
	s_add_i32 s67, s66, 0xffffa000
	s_cmp_lg_u32 s7, 0
	s_cselect_b32 s67, s67, 0xc000
	v_add_u32_e32 v163, s67, v132
	v_lshl_add_u64 v[164:165], v[158:159], 0, s[62:63]
	v_readfirstlane_b32 s67, v163
	v_add_u32_e32 v168, 0x1000, v163
	v_lshl_add_u64 v[166:167], v[164:165], 0, s[30:31]
	s_mov_b32 m0, s67
	v_readfirstlane_b32 s67, v168
	v_add_u32_e32 v168, 0x2000, v163
	s_waitcnt vmcnt(6)
	s_barrier
	global_load_lds_dwordx4 v[166:167], off
	v_lshl_add_u64 v[166:167], v[164:165], 0, s[34:35]
	s_mov_b32 m0, s67
	v_readfirstlane_b32 s67, v168
	global_load_lds_dwordx4 v[166:167], off
	v_lshl_add_u64 v[166:167], v[164:165], 0, s[44:45]
	s_mov_b32 m0, s67
	v_lshl_add_u64 v[164:165], v[164:165], 0, s[46:47]
	global_load_lds_dwordx4 v[166:167], off
	v_add_u32_e32 v166, 0x3000, v163
	v_add_u32_e32 v168, 0x4000, v163
	v_readfirstlane_b32 s67, v166
	s_mov_b32 m0, s67
	v_readfirstlane_b32 s67, v168
	global_load_lds_dwordx4 v[164:165], off
	v_lshl_add_u64 v[164:165], v[156:157], 0, s[62:63]
	v_add_u32_e32 v163, 0x5000, v163
	v_lshl_add_u64 v[166:167], v[164:165], 0, s[48:49]
	s_mov_b32 m0, s67
	v_readfirstlane_b32 s67, v163
	global_load_lds_dwordx4 v[166:167], off
	v_lshl_add_u64 v[164:165], v[164:165], 0, s[50:51]
	s_mov_b32 m0, s67
	s_add_i32 s66, s66, 0
	global_load_lds_dwordx4 v[164:165], off
	v_add3_u32 v163, s66, v160, v162
	ds_read_b128 v[164:167], v163 offset:16384
	ds_read_b128 v[168:171], v163 offset:17408
	ds_read_b128 v[178:181], v163 offset:18432
	ds_read_b128 v[182:185], v163 offset:19456
	v_add3_u32 v163, s66, v161, v162
	ds_read_b128 v[186:189], v163
	ds_read_b128 v[190:193], v163 offset:1024
	ds_read_b128 v[194:197], v163 offset:2048
	ds_read_b128 v[198:201], v163 offset:3072
	s_waitcnt lgkmcnt(0)
	v_mfma_f32_16x16x32_bf16 v[126:129], v[164:167], v[186:189], v[126:129]
	v_mfma_f32_16x16x32_bf16 v[122:125], v[168:171], v[186:189], v[122:125]
	v_mfma_f32_16x16x32_bf16 v[118:121], v[178:181], v[186:189], v[118:121]
	v_mfma_f32_16x16x32_bf16 v[114:117], v[182:185], v[186:189], v[114:117]
	v_mfma_f32_16x16x32_bf16 v[110:113], v[164:167], v[190:193], v[110:113]
	v_mfma_f32_16x16x32_bf16 v[106:109], v[168:171], v[190:193], v[106:109]
	v_mfma_f32_16x16x32_bf16 v[102:105], v[178:181], v[190:193], v[102:105]
	v_mfma_f32_16x16x32_bf16 v[98:101], v[182:185], v[190:193], v[98:101]
	v_mfma_f32_16x16x32_bf16 v[94:97], v[164:167], v[194:197], v[94:97]
	v_mfma_f32_16x16x32_bf16 v[90:93], v[168:171], v[194:197], v[90:93]
	v_mfma_f32_16x16x32_bf16 v[86:89], v[178:181], v[194:197], v[86:89]
	v_mfma_f32_16x16x32_bf16 v[82:85], v[182:185], v[194:197], v[82:85]
	v_mfma_f32_16x16x32_bf16 v[78:81], v[164:167], v[198:201], v[78:81]
	v_mfma_f32_16x16x32_bf16 v[74:77], v[168:171], v[198:201], v[74:77]
	v_mfma_f32_16x16x32_bf16 v[70:73], v[178:181], v[198:201], v[70:73]
	v_mfma_f32_16x16x32_bf16 v[66:69], v[182:185], v[198:201], v[66:69]
	ds_read_b128 v[186:189], v163 offset:4096
	ds_read_b128 v[190:193], v163 offset:5120
	ds_read_b128 v[194:197], v163 offset:6144
	ds_read_b128 v[198:201], v163 offset:7168
	s_waitcnt lgkmcnt(0)
	v_mfma_f32_16x16x32_bf16 v[62:65], v[164:167], v[186:189], v[62:65]
	v_mfma_f32_16x16x32_bf16 v[58:61], v[168:171], v[186:189], v[58:61]
	v_mfma_f32_16x16x32_bf16 v[54:57], v[178:181], v[186:189], v[54:57]
	v_mfma_f32_16x16x32_bf16 v[50:53], v[182:185], v[186:189], v[50:53]
	v_mfma_f32_16x16x32_bf16 v[46:49], v[164:167], v[190:193], v[46:49]
	v_mfma_f32_16x16x32_bf16 v[42:45], v[168:171], v[190:193], v[42:45]
	v_mfma_f32_16x16x32_bf16 v[38:41], v[178:181], v[190:193], v[38:41]
	v_mfma_f32_16x16x32_bf16 v[34:37], v[182:185], v[190:193], v[34:37]
	v_mfma_f32_16x16x32_bf16 v[30:33], v[164:167], v[194:197], v[30:33]
	v_mfma_f32_16x16x32_bf16 v[26:29], v[168:171], v[194:197], v[26:29]
	v_mfma_f32_16x16x32_bf16 v[22:25], v[178:181], v[194:197], v[22:25]
	v_mfma_f32_16x16x32_bf16 v[18:21], v[182:185], v[194:197], v[18:21]
	v_mfma_f32_16x16x32_bf16 v[14:17], v[164:167], v[198:201], v[14:17]
	v_mfma_f32_16x16x32_bf16 v[10:13], v[168:171], v[198:201], v[10:13]
	v_mfma_f32_16x16x32_bf16 v[6:9], v[178:181], v[198:201], v[6:9]
	v_mfma_f32_16x16x32_bf16 v[2:5], v[182:185], v[198:201], v[2:5]
	s_add_i32 s66, s7, 1
	s_cmp_lg_u32 s7, 2
	s_cselect_b32 s7, s66, 0
	s_add_u32 s62, s62, 64
	s_addc_u32 s63, s63, 0
	s_cmpk_eq_i32 s62, 0x780
	s_cbranch_scc0 .LBB0_672
	v_add3_u32 v132, 0, v160, v162
	v_add3_u32 v177, 0, v161, v162
	s_waitcnt vmcnt(6)
	s_barrier
	ds_read_b128 v[156:159], v132 offset:16384
	ds_read_b128 v[164:167], v132 offset:17408
	ds_read_b128 v[168:171], v132 offset:18432
	ds_read_b128 v[178:181], v132 offset:19456
	ds_read_b128 v[160:163], v177
	ds_read_b128 v[182:185], v177 offset:1024
	ds_read_b128 v[186:189], v177 offset:2048
	ds_read_b128 v[190:193], v177 offset:3072
	s_waitcnt lgkmcnt(0)
	v_mfma_f32_16x16x32_bf16 v[126:129], v[156:159], v[160:163], v[126:129]
	v_mfma_f32_16x16x32_bf16 v[122:125], v[164:167], v[160:163], v[122:125]
	v_mfma_f32_16x16x32_bf16 v[118:121], v[168:171], v[160:163], v[118:121]
	v_mfma_f32_16x16x32_bf16 v[114:117], v[178:181], v[160:163], v[114:117]
	v_mfma_f32_16x16x32_bf16 v[110:113], v[156:159], v[182:185], v[110:113]
	v_mfma_f32_16x16x32_bf16 v[106:109], v[164:167], v[182:185], v[106:109]
	v_mfma_f32_16x16x32_bf16 v[102:105], v[168:171], v[182:185], v[102:105]
	v_mfma_f32_16x16x32_bf16 v[98:101], v[178:181], v[182:185], v[98:101]
	v_mfma_f32_16x16x32_bf16 v[94:97], v[156:159], v[186:189], v[94:97]
	v_mfma_f32_16x16x32_bf16 v[90:93], v[164:167], v[186:189], v[90:93]
	v_mfma_f32_16x16x32_bf16 v[86:89], v[168:171], v[186:189], v[86:89]
	v_mfma_f32_16x16x32_bf16 v[82:85], v[178:181], v[186:189], v[82:85]
	v_mfma_f32_16x16x32_bf16 v[78:81], v[156:159], v[190:193], v[78:81]
	v_mfma_f32_16x16x32_bf16 v[74:77], v[164:167], v[190:193], v[74:77]
	v_mfma_f32_16x16x32_bf16 v[70:73], v[168:171], v[190:193], v[70:73]
	v_mfma_f32_16x16x32_bf16 v[66:69], v[178:181], v[190:193], v[66:69]
	ds_read_b128 v[160:163], v177 offset:4096
	ds_read_b128 v[182:185], v177 offset:5120
	ds_read_b128 v[186:189], v177 offset:6144
	ds_read_b128 v[190:193], v177 offset:7168
	s_waitcnt lgkmcnt(0)
	v_mfma_f32_16x16x32_bf16 v[62:65], v[156:159], v[160:163], v[62:65]
	v_mfma_f32_16x16x32_bf16 v[58:61], v[164:167], v[160:163], v[58:61]
	v_mfma_f32_16x16x32_bf16 v[54:57], v[168:171], v[160:163], v[54:57]
	v_mfma_f32_16x16x32_bf16 v[50:53], v[178:181], v[160:163], v[50:53]
	v_mfma_f32_16x16x32_bf16 v[46:49], v[156:159], v[182:185], v[46:49]
	v_mfma_f32_16x16x32_bf16 v[42:45], v[164:167], v[182:185], v[42:45]
	v_mfma_f32_16x16x32_bf16 v[38:41], v[168:171], v[182:185], v[38:41]
	v_mfma_f32_16x16x32_bf16 v[34:37], v[178:181], v[182:185], v[34:37]
	v_mfma_f32_16x16x32_bf16 v[30:33], v[156:159], v[186:189], v[30:33]
	v_mfma_f32_16x16x32_bf16 v[26:29], v[164:167], v[186:189], v[26:29]
	v_mfma_f32_16x16x32_bf16 v[22:25], v[168:171], v[186:189], v[22:25]
	v_mfma_f32_16x16x32_bf16 v[18:21], v[178:181], v[186:189], v[18:21]
	v_mfma_f32_16x16x32_bf16 v[14:17], v[156:159], v[190:193], v[14:17]
	v_mfma_f32_16x16x32_bf16 v[10:13], v[164:167], v[190:193], v[10:13]
	v_mfma_f32_16x16x32_bf16 v[6:9], v[168:171], v[190:193], v[6:9]
	v_mfma_f32_16x16x32_bf16 v[2:5], v[178:181], v[190:193], v[2:5]
	s_waitcnt vmcnt(0)
	s_barrier
	ds_read_b128 v[156:159], v132 offset:40960
	ds_read_b128 v[160:163], v132 offset:41984
	ds_read_b128 v[164:167], v132 offset:43008
	ds_read_b128 v[168:171], v132 offset:44032
	ds_read_b128 v[178:181], v177 offset:24576
	ds_read_b128 v[182:185], v177 offset:25600
	ds_read_b128 v[186:189], v177 offset:26624
	ds_read_b128 v[190:193], v177 offset:27648
	s_lshl_b64 s[62:63], s[60:61], 8
	s_waitcnt lgkmcnt(0)
	v_mfma_f32_16x16x32_bf16 v[126:129], v[156:159], v[178:181], v[126:129]
	v_mfma_f32_16x16x32_bf16 v[122:125], v[160:163], v[178:181], v[122:125]
	v_mfma_f32_16x16x32_bf16 v[118:121], v[164:167], v[178:181], v[118:121]
	v_mfma_f32_16x16x32_bf16 v[114:117], v[168:171], v[178:181], v[114:117]
	v_mfma_f32_16x16x32_bf16 v[110:113], v[156:159], v[182:185], v[110:113]
	v_mfma_f32_16x16x32_bf16 v[106:109], v[160:163], v[182:185], v[106:109]
	v_mfma_f32_16x16x32_bf16 v[102:105], v[164:167], v[182:185], v[102:105]
	v_mfma_f32_16x16x32_bf16 v[98:101], v[168:171], v[182:185], v[98:101]
	v_mfma_f32_16x16x32_bf16 v[94:97], v[156:159], v[186:189], v[94:97]
	v_mfma_f32_16x16x32_bf16 v[90:93], v[160:163], v[186:189], v[90:93]
	v_mfma_f32_16x16x32_bf16 v[86:89], v[164:167], v[186:189], v[86:89]
	v_mfma_f32_16x16x32_bf16 v[82:85], v[168:171], v[186:189], v[82:85]
	v_mfma_f32_16x16x32_bf16 v[78:81], v[156:159], v[190:193], v[78:81]
	v_mfma_f32_16x16x32_bf16 v[74:77], v[160:163], v[190:193], v[74:77]
	v_mfma_f32_16x16x32_bf16 v[70:73], v[164:167], v[190:193], v[70:73]
	v_mfma_f32_16x16x32_bf16 v[66:69], v[168:171], v[190:193], v[66:69]
	ds_read_b128 v[178:181], v177 offset:28672
	ds_read_b128 v[182:185], v177 offset:29696
	ds_read_b128 v[186:189], v177 offset:30720
	ds_read_b128 v[190:193], v177 offset:31744
	s_waitcnt lgkmcnt(0)
	v_mfma_f32_16x16x32_bf16 v[62:65], v[156:159], v[178:181], v[62:65]
	v_mfma_f32_16x16x32_bf16 v[58:61], v[160:163], v[178:181], v[58:61]
	v_mfma_f32_16x16x32_bf16 v[54:57], v[164:167], v[178:181], v[54:57]
	v_mfma_f32_16x16x32_bf16 v[50:53], v[168:171], v[178:181], v[50:53]
	v_mfma_f32_16x16x32_bf16 v[46:49], v[156:159], v[182:185], v[46:49]
	v_mfma_f32_16x16x32_bf16 v[42:45], v[160:163], v[182:185], v[42:45]
	v_mfma_f32_16x16x32_bf16 v[38:41], v[164:167], v[182:185], v[38:41]
	v_mfma_f32_16x16x32_bf16 v[34:37], v[168:171], v[182:185], v[34:37]
	v_mfma_f32_16x16x32_bf16 v[30:33], v[156:159], v[186:189], v[30:33]
	v_mfma_f32_16x16x32_bf16 v[26:29], v[160:163], v[186:189], v[26:29]
	v_mfma_f32_16x16x32_bf16 v[22:25], v[164:167], v[186:189], v[22:25]
	v_mfma_f32_16x16x32_bf16 v[18:21], v[168:171], v[186:189], v[18:21]
	v_mfma_f32_16x16x32_bf16 v[14:17], v[156:159], v[190:193], v[14:17]
	v_mfma_f32_16x16x32_bf16 v[10:13], v[160:163], v[190:193], v[10:13]
	v_mfma_f32_16x16x32_bf16 v[6:9], v[164:167], v[190:193], v[6:9]
	v_mfma_f32_16x16x32_bf16 v[2:5], v[168:171], v[190:193], v[2:5]
	s_andn2_b64 vcc, exec, s[4:5]
	s_mov_b64 s[4:5], -1
	s_waitcnt vmcnt(0)
	s_barrier
	s_cbranch_vccnz .LBB0_683
	v_lshl_add_u64 v[158:159], s[62:63], 0, v[134:135]
	v_lshl_add_u64 v[156:157], v[158:159], 2, s[52:53]
	flat_load_dword v132, v[156:157]
	s_and_b64 s[4:5], exec, s[64:65]
	v_mbcnt_hi_u32_b32 v177, -1, v176
	s_waitcnt vmcnt(0) lgkmcnt(0)
	v_fmamk_f32 v132, v132, 0x3a800000, v139
	v_mul_f32_e32 v156, 0x4b800000, v132
	v_cmp_gt_f32_e32 vcc, s68, v132
	s_nop 1
	v_cndmask_b32_e32 v132, v132, v156, vcc
	v_rsq_f32_e32 v132, v132
	s_nop 0
	v_mul_f32_e32 v156, 0x45800000, v132
	v_cndmask_b32_e32 v162, v132, v156, vcc
	v_pk_mul_f32 v[164:165], v[128:129], v[162:163] op_sel_hi:[1,0]
	v_pk_mul_f32 v[166:167], v[126:127], v[162:163] op_sel_hi:[1,0]
	s_mov_b64 vcc, s[4:5]
	s_cbranch_vccz .LBB0_676
	v_lshlrev_b64 v[156:157], 6, v[158:159]
	v_lshl_add_u64 v[156:157], v[152:153], 0, v[156:157]
	flat_load_dwordx4 v[168:171], v[156:157] offset:32
	flat_load_dwordx4 v[178:181], v[156:157]
	v_and_b32_e32 v156, 64, v177
	v_xor_b32_e32 v132, 32, v177
	v_add_u32_e32 v156, 64, v156
	v_cmp_lt_i32_e32 vcc, v132, v156
	s_nop 1
	v_cndmask_b32_e32 v132, v177, v132, vcc
	v_lshlrev_b32_e32 v132, 2, v132
	ds_bpermute_b32 v156, v132, v166
	ds_bpermute_b32 v157, v132, v167
	ds_bpermute_b32 v160, v132, v164
	ds_bpermute_b32 v161, v132, v165
	s_waitcnt vmcnt(0) lgkmcnt(0)
	v_pk_mul_f32 v[156:157], v[168:169], v[156:157]
	v_pk_mul_f32 v[160:161], v[170:171], v[160:161]
	v_cndmask_b32_e64 v157, v157, -v157, s[0:1]
	v_cndmask_b32_e64 v156, v156, -v156, s[0:1]
	v_cndmask_b32_e64 v161, v161, -v161, s[0:1]
	v_cndmask_b32_e64 v160, v160, -v160, s[0:1]
	v_pk_fma_f32 v[164:165], v[164:165], v[180:181], v[160:161]
	v_pk_fma_f32 v[166:167], v[166:167], v[178:179], v[156:157]

.LBB0_1356:
	s_mul_i32 s43, s1, 0x6000
	s_add_i32 s50, s43, 0xffffa000
	s_cmp_lg_u32 s1, 0
	s_cselect_b32 s50, s50, 0xc000
	v_add_u32_e32 v148, s50, v141
	v_lshl_add_u64 v[144:145], v[136:137], 0, s[48:49]
	v_readfirstlane_b32 s50, v148
	v_add_u32_e32 v149, 0x1000, v148
	v_lshl_add_u64 v[146:147], v[144:145], 0, s[24:25]
	s_mov_b32 m0, s50
	v_readfirstlane_b32 s50, v149
	v_add_u32_e32 v149, 0x2000, v148
	s_waitcnt vmcnt(6)
	s_barrier
	global_load_lds_dwordx4 v[146:147], off
	v_lshl_add_u64 v[146:147], v[144:145], 0, s[26:27]
	s_mov_b32 m0, s50
	v_readfirstlane_b32 s50, v149
	global_load_lds_dwordx4 v[146:147], off
	v_lshl_add_u64 v[146:147], v[144:145], 0, s[28:29]
	s_mov_b32 m0, s50
	v_lshl_add_u64 v[144:145], v[144:145], 0, s[30:31]
	global_load_lds_dwordx4 v[146:147], off
	v_add_u32_e32 v146, 0x3000, v148
	v_add_u32_e32 v149, 0x4000, v148
	v_readfirstlane_b32 s50, v146
	s_mov_b32 m0, s50
	v_readfirstlane_b32 s50, v149
	global_load_lds_dwordx4 v[144:145], off
	v_lshl_add_u64 v[144:145], v[134:135], 0, s[48:49]
	v_lshl_add_u64 v[146:147], v[144:145], 0, s[34:35]
	s_mov_b32 m0, s50
	v_lshl_add_u64 v[144:145], v[144:145], 0, s[44:45]
	global_load_lds_dwordx4 v[146:147], off
	v_add_u32_e32 v146, 0x5000, v148
	s_add_i32 s43, s43, 0
	v_readfirstlane_b32 s50, v146
	s_mov_b32 m0, s50
	v_add3_u32 v156, s43, v140, v143
	global_load_lds_dwordx4 v[144:145], off
	v_add3_u32 v176, s43, v142, v143
	ds_read_b128 v[144:147], v156 offset:16384
	ds_read_b128 v[148:151], v156 offset:17408
	ds_read_b128 v[152:155], v156 offset:18432
	ds_read_b128 v[156:159], v156 offset:19456
	ds_read_b128 v[160:163], v176
	ds_read_b128 v[164:167], v176 offset:1024
	ds_read_b128 v[168:171], v176 offset:2048
	ds_read_b128 v[172:175], v176 offset:3072
	s_waitcnt lgkmcnt(0)
	v_mfma_f32_16x16x32_bf16 v[126:129], v[144:147], v[160:163], v[126:129]
	v_mfma_f32_16x16x32_bf16 v[122:125], v[148:151], v[160:163], v[122:125]
	v_mfma_f32_16x16x32_bf16 v[118:121], v[152:155], v[160:163], v[118:121]
	v_mfma_f32_16x16x32_bf16 v[114:117], v[156:159], v[160:163], v[114:117]
	v_mfma_f32_16x16x32_bf16 v[110:113], v[144:147], v[164:167], v[110:113]
	v_mfma_f32_16x16x32_bf16 v[106:109], v[148:151], v[164:167], v[106:109]
	v_mfma_f32_16x16x32_bf16 v[102:105], v[152:155], v[164:167], v[102:105]
	v_mfma_f32_16x16x32_bf16 v[98:101], v[156:159], v[164:167], v[98:101]
	v_mfma_f32_16x16x32_bf16 v[94:97], v[144:147], v[168:171], v[94:97]
	v_mfma_f32_16x16x32_bf16 v[90:93], v[148:151], v[168:171], v[90:93]
	v_mfma_f32_16x16x32_bf16 v[86:89], v[152:155], v[168:171], v[86:89]
	v_mfma_f32_16x16x32_bf16 v[82:85], v[156:159], v[168:171], v[82:85]
	v_mfma_f32_16x16x32_bf16 v[78:81], v[144:147], v[172:175], v[78:81]
	v_mfma_f32_16x16x32_bf16 v[74:77], v[148:151], v[172:175], v[74:77]
	v_mfma_f32_16x16x32_bf16 v[70:73], v[152:155], v[172:175], v[70:73]
	v_mfma_f32_16x16x32_bf16 v[66:69], v[156:159], v[172:175], v[66:69]
	ds_read_b128 v[160:163], v176 offset:4096
	ds_read_b128 v[164:167], v176 offset:5120
	ds_read_b128 v[168:171], v176 offset:6144
	ds_read_b128 v[172:175], v176 offset:7168
	s_waitcnt lgkmcnt(0)
	v_mfma_f32_16x16x32_bf16 v[62:65], v[144:147], v[160:163], v[62:65]
	v_mfma_f32_16x16x32_bf16 v[58:61], v[148:151], v[160:163], v[58:61]
	v_mfma_f32_16x16x32_bf16 v[54:57], v[152:155], v[160:163], v[54:57]
	v_mfma_f32_16x16x32_bf16 v[50:53], v[156:159], v[160:163], v[50:53]
	v_mfma_f32_16x16x32_bf16 v[46:49], v[144:147], v[164:167], v[46:49]
	v_mfma_f32_16x16x32_bf16 v[42:45], v[148:151], v[164:167], v[42:45]
	v_mfma_f32_16x16x32_bf16 v[38:41], v[152:155], v[164:167], v[38:41]
	v_mfma_f32_16x16x32_bf16 v[34:37], v[156:159], v[164:167], v[34:37]
	v_mfma_f32_16x16x32_bf16 v[30:33], v[144:147], v[168:171], v[30:33]
	v_mfma_f32_16x16x32_bf16 v[26:29], v[148:151], v[168:171], v[26:29]
	v_mfma_f32_16x16x32_bf16 v[22:25], v[152:155], v[168:171], v[22:25]
	v_mfma_f32_16x16x32_bf16 v[18:21], v[156:159], v[168:171], v[18:21]
	v_mfma_f32_16x16x32_bf16 v[14:17], v[144:147], v[172:175], v[14:17]
	v_mfma_f32_16x16x32_bf16 v[10:13], v[148:151], v[172:175], v[10:13]
	v_mfma_f32_16x16x32_bf16 v[6:9], v[152:155], v[172:175], v[6:9]
	v_mfma_f32_16x16x32_bf16 v[2:5], v[156:159], v[172:175], v[2:5]
	s_add_i32 s43, s1, 1
	s_cmp_lg_u32 s1, 2
	s_cselect_b32 s1, s43, 0
	s_add_u32 s48, s48, 64
	s_addc_u32 s49, s49, 0
	s_cmpk_eq_i32 s48, 0x780
	s_cbranch_scc0 .LBB0_1356
	v_add3_u32 v168, 0, v140, v143
	v_add3_u32 v169, 0, v142, v143
	s_waitcnt vmcnt(6)
	s_barrier
	ds_read_b128 v[134:137], v168 offset:16384
	ds_read_b128 v[144:147], v168 offset:17408
	ds_read_b128 v[148:151], v168 offset:18432
	ds_read_b128 v[152:155], v168 offset:19456
	ds_read_b128 v[140:143], v169
	ds_read_b128 v[156:159], v169 offset:1024
	ds_read_b128 v[160:163], v169 offset:2048
	ds_read_b128 v[164:167], v169 offset:3072
	s_lshl_b64 s[46:47], s[46:47], 8
	s_waitcnt lgkmcnt(0)
	v_mfma_f32_16x16x32_bf16 v[118:121], v[148:151], v[140:143], v[118:121]
	v_mfma_f32_16x16x32_bf16 v[114:117], v[152:155], v[140:143], v[114:117]
	v_mfma_f32_16x16x32_bf16 v[110:113], v[134:137], v[156:159], v[110:113]
	v_mfma_f32_16x16x32_bf16 v[106:109], v[144:147], v[156:159], v[106:109]
	v_mfma_f32_16x16x32_bf16 v[102:105], v[148:151], v[156:159], v[102:105]
	v_mfma_f32_16x16x32_bf16 v[98:101], v[152:155], v[156:159], v[98:101]
	v_mfma_f32_16x16x32_bf16 v[94:97], v[134:137], v[160:163], v[94:97]
	v_mfma_f32_16x16x32_bf16 v[90:93], v[144:147], v[160:163], v[90:93]
	v_mfma_f32_16x16x32_bf16 v[86:89], v[148:151], v[160:163], v[86:89]
	v_mfma_f32_16x16x32_bf16 v[82:85], v[152:155], v[160:163], v[82:85]
	v_mfma_f32_16x16x32_bf16 v[78:81], v[134:137], v[164:167], v[78:81]
	v_mfma_f32_16x16x32_bf16 v[74:77], v[144:147], v[164:167], v[74:77]
	v_mfma_f32_16x16x32_bf16 v[70:73], v[148:151], v[164:167], v[70:73]
	v_mfma_f32_16x16x32_bf16 v[66:69], v[152:155], v[164:167], v[66:69]
	v_mfma_f32_16x16x32_bf16 v[126:129], v[134:137], v[140:143], v[126:129]
	v_mfma_f32_16x16x32_bf16 v[122:125], v[144:147], v[140:143], v[122:125]
	ds_read_b128 v[140:143], v169 offset:4096
	ds_read_b128 v[156:159], v169 offset:5120
	ds_read_b128 v[160:163], v169 offset:6144
	ds_read_b128 v[164:167], v169 offset:7168
	s_waitcnt lgkmcnt(0)
	v_mfma_f32_16x16x32_bf16 v[62:65], v[134:137], v[140:143], v[62:65]
	v_mfma_f32_16x16x32_bf16 v[58:61], v[144:147], v[140:143], v[58:61]
	v_mfma_f32_16x16x32_bf16 v[54:57], v[148:151], v[140:143], v[54:57]
	v_mfma_f32_16x16x32_bf16 v[50:53], v[152:155], v[140:143], v[50:53]
	v_mfma_f32_16x16x32_bf16 v[46:49], v[134:137], v[156:159], v[46:49]
	v_mfma_f32_16x16x32_bf16 v[42:45], v[144:147], v[156:159], v[42:45]
	v_mfma_f32_16x16x32_bf16 v[38:41], v[148:151], v[156:159], v[38:41]
	v_mfma_f32_16x16x32_bf16 v[34:37], v[152:155], v[156:159], v[34:37]
	v_mfma_f32_16x16x32_bf16 v[30:33], v[134:137], v[160:163], v[30:33]
	v_mfma_f32_16x16x32_bf16 v[26:29], v[144:147], v[160:163], v[26:29]
	v_mfma_f32_16x16x32_bf16 v[22:25], v[148:151], v[160:163], v[22:25]
	v_mfma_f32_16x16x32_bf16 v[18:21], v[152:155], v[160:163], v[18:21]
	v_mfma_f32_16x16x32_bf16 v[14:17], v[134:137], v[164:167], v[14:17]
	v_mfma_f32_16x16x32_bf16 v[10:13], v[144:147], v[164:167], v[10:13]
	v_mfma_f32_16x16x32_bf16 v[6:9], v[148:151], v[164:167], v[6:9]
	v_mfma_f32_16x16x32_bf16 v[2:5], v[152:155], v[164:167], v[2:5]
	s_waitcnt vmcnt(0)
	s_barrier
	ds_read_b128 v[134:137], v168 offset:40960
	ds_read_b128 v[140:143], v168 offset:41984
	ds_read_b128 v[144:147], v168 offset:43008
	ds_read_b128 v[148:151], v168 offset:44032
	ds_read_b128 v[152:155], v169 offset:24576
	ds_read_b128 v[156:159], v169 offset:25600
	ds_read_b128 v[160:163], v169 offset:26624
	ds_read_b128 v[164:167], v169 offset:27648
	s_waitcnt lgkmcnt(0)
	v_mfma_f32_16x16x32_bf16 v[118:121], v[144:147], v[152:155], v[118:121]
	v_mfma_f32_16x16x32_bf16 v[110:113], v[134:137], v[156:159], v[110:113]
	v_mfma_f32_16x16x32_bf16 v[106:109], v[140:143], v[156:159], v[106:109]
	v_mfma_f32_16x16x32_bf16 v[102:105], v[144:147], v[156:159], v[102:105]
	v_mfma_f32_16x16x32_bf16 v[98:101], v[148:151], v[156:159], v[98:101]
	v_mfma_f32_16x16x32_bf16 v[94:97], v[134:137], v[160:163], v[94:97]
	v_mfma_f32_16x16x32_bf16 v[90:93], v[140:143], v[160:163], v[90:93]
	v_mfma_f32_16x16x32_bf16 v[86:89], v[144:147], v[160:163], v[86:89]
	v_mfma_f32_16x16x32_bf16 v[82:85], v[148:151], v[160:163], v[82:85]
	v_mfma_f32_16x16x32_bf16 v[78:81], v[134:137], v[164:167], v[78:81]
	v_mfma_f32_16x16x32_bf16 v[74:77], v[140:143], v[164:167], v[74:77]
	v_mfma_f32_16x16x32_bf16 v[70:73], v[144:147], v[164:167], v[70:73]
	v_mfma_f32_16x16x32_bf16 v[66:69], v[148:151], v[164:167], v[66:69]
	v_mfma_f32_16x16x32_bf16 v[126:129], v[134:137], v[152:155], v[126:129]
	v_mfma_f32_16x16x32_bf16 v[122:125], v[140:143], v[152:155], v[122:125]
	v_mfma_f32_16x16x32_bf16 v[152:155], v[148:151], v[152:155], v[114:117]
	s_nop 1
	ds_read_b128 v[114:117], v169 offset:28672
	ds_read_b128 v[156:159], v169 offset:29696
	ds_read_b128 v[160:163], v169 offset:30720
	ds_read_b128 v[164:167], v169 offset:31744
	s_waitcnt lgkmcnt(0)
	v_mfma_f32_16x16x32_bf16 v[62:65], v[134:137], v[114:117], v[62:65]
	v_mfma_f32_16x16x32_bf16 v[58:61], v[140:143], v[114:117], v[58:61]
	v_mfma_f32_16x16x32_bf16 v[54:57], v[144:147], v[114:117], v[54:57]
	v_mfma_f32_16x16x32_bf16 v[50:53], v[148:151], v[114:117], v[50:53]
	v_mfma_f32_16x16x32_bf16 v[46:49], v[134:137], v[156:159], v[46:49]
	v_mfma_f32_16x16x32_bf16 v[42:45], v[140:143], v[156:159], v[42:45]
	v_mfma_f32_16x16x32_bf16 v[38:41], v[144:147], v[156:159], v[38:41]
	v_mfma_f32_16x16x32_bf16 v[34:37], v[148:151], v[156:159], v[34:37]
	v_mfma_f32_16x16x32_bf16 v[30:33], v[134:137], v[160:163], v[30:33]
	v_mfma_f32_16x16x32_bf16 v[26:29], v[140:143], v[160:163], v[26:29]
	v_mfma_f32_16x16x32_bf16 v[22:25], v[144:147], v[160:163], v[22:25]
	v_mfma_f32_16x16x32_bf16 v[18:21], v[148:151], v[160:163], v[18:21]
	v_mfma_f32_16x16x32_bf16 v[14:17], v[134:137], v[164:167], v[14:17]
	v_mfma_f32_16x16x32_bf16 v[10:13], v[140:143], v[164:167], v[10:13]
	v_mfma_f32_16x16x32_bf16 v[6:9], v[144:147], v[164:167], v[6:9]
	v_mfma_f32_16x16x32_bf16 v[2:5], v[148:151], v[164:167], v[2:5]
	v_lshl_add_u64 v[114:115], s[46:47], 0, v[132:133]
	v_lshl_or_b32 v116, s0, 7, v138
	v_lshlrev_b64 v[134:135], 12, v[114:115]
	s_waitcnt vmcnt(0)
	v_lshl_add_u64 v[134:135], v[130:131], 0, v[134:135]
	v_ashrrev_i32_e32 v117, 31, v116
	v_lshl_add_u64 v[144:145], v[116:117], 2, v[134:135]
	s_barrier
	flat_load_dwordx4 v[134:137], v[144:145]
	v_lshlrev_b64 v[140:141], 11, v[114:115]
	v_lshl_add_u64 v[140:141], s[8:9], 0, v[140:141]
	v_lshl_add_u64 v[146:147], v[116:117], 1, v[140:141]
	s_waitcnt vmcnt(0) lgkmcnt(0)
	v_pk_add_f32 v[126:127], v[126:127], v[134:135]
	v_pk_add_f32 v[128:129], v[128:129], v[136:137]
	v_cvt_pk_bf16_f32 v134, v126, v127
	v_cvt_pk_bf16_f32 v135, v128, v129
	flat_store_dwordx4 v[144:145], v[126:129]
	flat_store_dwordx2 v[146:147], v[134:135]
	flat_load_dwordx4 v[134:137], v[144:145] offset:64
	s_waitcnt vmcnt(0) lgkmcnt(0)
	v_pk_add_f32 v[122:123], v[122:123], v[134:135]
	v_pk_add_f32 v[124:125], v[124:125], v[136:137]
	v_cvt_pk_bf16_f32 v134, v122, v123
	v_cvt_pk_bf16_f32 v135, v124, v125
	flat_store_dwordx4 v[144:145], v[122:125] offset:64
	flat_store_dwordx2 v[146:147], v[134:135] offset:32
	flat_load_dwordx4 v[134:137], v[144:145] offset:128
	s_waitcnt vmcnt(0) lgkmcnt(0)
	v_pk_add_f32 v[134:135], v[118:119], v[134:135]
	v_pk_add_f32 v[136:137], v[120:121], v[136:137]
	v_cvt_pk_bf16_f32 v118, v134, v135
	v_cvt_pk_bf16_f32 v119, v136, v137
	flat_store_dwordx4 v[144:145], v[134:137] offset:128
	flat_store_dwordx2 v[146:147], v[118:119] offset:64
	flat_load_dwordx4 v[140:143], v[144:145] offset:192
	v_and_b32_e32 v119, 64, v139
	v_xor_b32_e32 v118, 16, v139
	v_add_u32_e32 v121, 64, v119
	v_cmp_lt_i32_e64 s[0:1], v118, v121
	s_nop 1
	v_cndmask_b32_e64 v118, v139, v118, s[0:1]
	v_lshlrev_b32_e32 v120, 2, v118
	v_pk_mul_f32 v[118:119], v[126:127], v[126:127]
	v_pk_mul_f32 v[126:127], v[128:129], v[128:129]
	v_add_f32_e32 v118, v118, v119
	v_add_f32_e32 v118, v118, v126
	v_add_f32_e32 v126, v118, v127
	v_pk_mul_f32 v[118:119], v[122:123], v[122:123]
	v_pk_mul_f32 v[122:123], v[124:125], v[124:125]
	v_add_f32_e32 v118, v118, v119
	v_add_f32_e32 v118, v118, v122
	v_add_f32_e32 v118, v118, v123
	v_add_f32_e32 v128, v126, v118
	v_pk_mul_f32 v[118:119], v[134:135], v[134:135]
	v_pk_mul_f32 v[122:123], v[136:137], v[136:137]
	v_add_f32_e32 v118, v118, v119
	v_add_f32_e32 v118, v118, v122
	v_add_f32_e32 v129, v118, v123
	v_add_f32_e32 v128, v128, v129
	s_waitcnt vmcnt(0) lgkmcnt(0)
	v_pk_add_f32 v[122:123], v[152:153], v[140:141]
	v_pk_add_f32 v[124:125], v[154:155], v[142:143]
	v_pk_mul_f32 v[118:119], v[122:123], v[122:123]
	v_pk_mul_f32 v[126:127], v[124:125], v[124:125]
	v_add_f32_e32 v118, v118, v119
	v_add_f32_e32 v118, v118, v126
	v_add_f32_e32 v118, v118, v127
	v_add_f32_e32 v118, v128, v118
	ds_bpermute_b32 v119, v120, v118
	v_xor_b32_e32 v126, 32, v139
	v_cmp_lt_i32_e64 s[0:1], v126, v121
	flat_store_dwordx4 v[144:145], v[122:125] offset:192
	s_waitcnt lgkmcnt(0)
	v_add_f32_e32 v118, v118, v119
	v_cndmask_b32_e64 v121, v139, v126, s[0:1]
	v_lshlrev_b32_e32 v121, 2, v121
	ds_bpermute_b32 v119, v121, v118
	v_cvt_pk_bf16_f32 v122, v122, v123
	v_cvt_pk_bf16_f32 v123, v124, v125
	flat_store_dwordx2 v[146:147], v[122:123] offset:96
	s_and_saveexec_b64 s[0:1], vcc
	s_cbranch_execz .LBB0_1359
	s_waitcnt lgkmcnt(0)
	v_add_f32_e32 v122, v118, v119
	v_lshl_add_u64 v[118:119], v[114:115], 2, s[10:11]
	flat_atomic_add_f32 v[118:119], v122

.LBB0_1445:
	s_mul_i32 s51, s7, 0x6000
	s_add_i32 s52, s51, 0xffffa000
	s_cmp_lg_u32 s7, 0
	s_cselect_b32 s52, s52, 0xc000
	v_add_u32_e32 v145, s52, v134
	v_lshl_add_u64 v[146:147], v[138:139], 0, s[4:5]
	v_readfirstlane_b32 s52, v145
	v_add_u32_e32 v150, 0x1000, v145
	v_lshl_add_u64 v[148:149], v[146:147], 0, s[28:29]
	s_mov_b32 m0, s52
	v_readfirstlane_b32 s52, v150
	v_add_u32_e32 v150, 0x2000, v145
	s_waitcnt vmcnt(6)
	s_barrier
	global_load_lds_dwordx4 v[148:149], off
	v_lshl_add_u64 v[148:149], v[146:147], 0, s[30:31]
	s_mov_b32 m0, s52
	v_readfirstlane_b32 s52, v150
	global_load_lds_dwordx4 v[148:149], off
	v_lshl_add_u64 v[148:149], v[146:147], 0, s[34:35]
	s_mov_b32 m0, s52
	v_lshl_add_u64 v[146:147], v[146:147], 0, s[44:45]
	global_load_lds_dwordx4 v[148:149], off
	v_add_u32_e32 v148, 0x3000, v145
	v_add_u32_e32 v150, 0x4000, v145
	v_readfirstlane_b32 s52, v148
	s_mov_b32 m0, s52
	v_readfirstlane_b32 s52, v150
	global_load_lds_dwordx4 v[146:147], off
	v_lshl_add_u64 v[146:147], v[136:137], 0, s[4:5]
	v_add_u32_e32 v145, 0x5000, v145
	v_lshl_add_u64 v[148:149], v[146:147], 0, s[46:47]
	s_mov_b32 m0, s52
	v_readfirstlane_b32 s52, v145
	global_load_lds_dwordx4 v[148:149], off
	v_lshl_add_u64 v[146:147], v[146:147], 0, s[48:49]
	s_mov_b32 m0, s52
	s_add_i32 s51, s51, 0
	global_load_lds_dwordx4 v[146:147], off
	v_add3_u32 v145, s51, v142, v144
	ds_read_b128 v[146:149], v145 offset:16384
	ds_read_b128 v[150:153], v145 offset:17408
	ds_read_b128 v[154:157], v145 offset:18432
	ds_read_b128 v[158:161], v145 offset:19456
	v_add3_u32 v145, s51, v143, v144
	ds_read_b128 v[162:165], v145
	ds_read_b128 v[166:169], v145 offset:1024
	ds_read_b128 v[170:173], v145 offset:2048
	ds_read_b128 v[174:177], v145 offset:3072
	s_waitcnt lgkmcnt(0)
	v_mfma_f32_16x16x32_bf16 v[126:129], v[146:149], v[162:165], v[126:129]
	v_mfma_f32_16x16x32_bf16 v[122:125], v[150:153], v[162:165], v[122:125]
	v_mfma_f32_16x16x32_bf16 v[118:121], v[154:157], v[162:165], v[118:121]
	v_mfma_f32_16x16x32_bf16 v[114:117], v[158:161], v[162:165], v[114:117]
	v_mfma_f32_16x16x32_bf16 v[110:113], v[146:149], v[166:169], v[110:113]
	v_mfma_f32_16x16x32_bf16 v[106:109], v[150:153], v[166:169], v[106:109]
	v_mfma_f32_16x16x32_bf16 v[102:105], v[154:157], v[166:169], v[102:105]
	v_mfma_f32_16x16x32_bf16 v[98:101], v[158:161], v[166:169], v[98:101]
	v_mfma_f32_16x16x32_bf16 v[94:97], v[146:149], v[170:173], v[94:97]
	v_mfma_f32_16x16x32_bf16 v[90:93], v[150:153], v[170:173], v[90:93]
	v_mfma_f32_16x16x32_bf16 v[86:89], v[154:157], v[170:173], v[86:89]
	v_mfma_f32_16x16x32_bf16 v[82:85], v[158:161], v[170:173], v[82:85]
	v_mfma_f32_16x16x32_bf16 v[78:81], v[146:149], v[174:177], v[78:81]
	v_mfma_f32_16x16x32_bf16 v[74:77], v[150:153], v[174:177], v[74:77]
	v_mfma_f32_16x16x32_bf16 v[70:73], v[154:157], v[174:177], v[70:73]
	v_mfma_f32_16x16x32_bf16 v[66:69], v[158:161], v[174:177], v[66:69]
	ds_read_b128 v[162:165], v145 offset:4096
	ds_read_b128 v[166:169], v145 offset:5120
	ds_read_b128 v[170:173], v145 offset:6144
	ds_read_b128 v[174:177], v145 offset:7168
	s_waitcnt lgkmcnt(0)
	v_mfma_f32_16x16x32_bf16 v[62:65], v[146:149], v[162:165], v[62:65]
	v_mfma_f32_16x16x32_bf16 v[58:61], v[150:153], v[162:165], v[58:61]
	v_mfma_f32_16x16x32_bf16 v[54:57], v[154:157], v[162:165], v[54:57]
	v_mfma_f32_16x16x32_bf16 v[50:53], v[158:161], v[162:165], v[50:53]
	v_mfma_f32_16x16x32_bf16 v[46:49], v[146:149], v[166:169], v[46:49]
	v_mfma_f32_16x16x32_bf16 v[42:45], v[150:153], v[166:169], v[42:45]
	v_mfma_f32_16x16x32_bf16 v[38:41], v[154:157], v[166:169], v[38:41]
	v_mfma_f32_16x16x32_bf16 v[34:37], v[158:161], v[166:169], v[34:37]
	v_mfma_f32_16x16x32_bf16 v[30:33], v[146:149], v[170:173], v[30:33]
	v_mfma_f32_16x16x32_bf16 v[26:29], v[150:153], v[170:173], v[26:29]
	v_mfma_f32_16x16x32_bf16 v[22:25], v[154:157], v[170:173], v[22:25]
	v_mfma_f32_16x16x32_bf16 v[18:21], v[158:161], v[170:173], v[18:21]
	v_mfma_f32_16x16x32_bf16 v[14:17], v[146:149], v[174:177], v[14:17]
	v_mfma_f32_16x16x32_bf16 v[10:13], v[150:153], v[174:177], v[10:13]
	v_mfma_f32_16x16x32_bf16 v[6:9], v[154:157], v[174:177], v[6:9]
	v_mfma_f32_16x16x32_bf16 v[2:5], v[158:161], v[174:177], v[2:5]
	s_add_i32 s51, s7, 1
	s_cmp_lg_u32 s7, 2
	s_cselect_b32 s7, s51, 0
	s_add_u32 s4, s4, 64
	s_addc_u32 s5, s5, 0
	s_cmpk_eq_i32 s4, 0x780
	s_cbranch_scc0 .LBB0_1445
	v_add3_u32 v134, 0, v142, v144
	v_add3_u32 v174, 0, v143, v144
	s_waitcnt vmcnt(6)
	s_barrier
	ds_read_b128 v[136:139], v134 offset:16384
	ds_read_b128 v[146:149], v134 offset:17408
	ds_read_b128 v[150:153], v134 offset:18432
	ds_read_b128 v[154:157], v134 offset:19456
	ds_read_b128 v[142:145], v174
	ds_read_b128 v[158:161], v174 offset:1024
	ds_read_b128 v[162:165], v174 offset:2048
	ds_read_b128 v[166:169], v174 offset:3072
	s_waitcnt lgkmcnt(0)
	v_mfma_f32_16x16x32_bf16 v[126:129], v[136:139], v[142:145], v[126:129]
	v_mfma_f32_16x16x32_bf16 v[122:125], v[146:149], v[142:145], v[122:125]
	v_mfma_f32_16x16x32_bf16 v[118:121], v[150:153], v[142:145], v[118:121]
	v_mfma_f32_16x16x32_bf16 v[114:117], v[154:157], v[142:145], v[114:117]
	v_mfma_f32_16x16x32_bf16 v[110:113], v[136:139], v[158:161], v[110:113]
	v_mfma_f32_16x16x32_bf16 v[106:109], v[146:149], v[158:161], v[106:109]
	v_mfma_f32_16x16x32_bf16 v[102:105], v[150:153], v[158:161], v[102:105]
	v_mfma_f32_16x16x32_bf16 v[98:101], v[154:157], v[158:161], v[98:101]
	v_mfma_f32_16x16x32_bf16 v[94:97], v[136:139], v[162:165], v[94:97]
	v_mfma_f32_16x16x32_bf16 v[90:93], v[146:149], v[162:165], v[90:93]
	v_mfma_f32_16x16x32_bf16 v[86:89], v[150:153], v[162:165], v[86:89]
	v_mfma_f32_16x16x32_bf16 v[82:85], v[154:157], v[162:165], v[82:85]
	v_mfma_f32_16x16x32_bf16 v[78:81], v[136:139], v[166:169], v[78:81]
	v_mfma_f32_16x16x32_bf16 v[74:77], v[146:149], v[166:169], v[74:77]
	v_mfma_f32_16x16x32_bf16 v[70:73], v[150:153], v[166:169], v[70:73]
	v_mfma_f32_16x16x32_bf16 v[66:69], v[154:157], v[166:169], v[66:69]
	ds_read_b128 v[142:145], v174 offset:4096
	ds_read_b128 v[158:161], v174 offset:5120
	ds_read_b128 v[162:165], v174 offset:6144
	ds_read_b128 v[166:169], v174 offset:7168
	s_waitcnt lgkmcnt(0)
	v_mfma_f32_16x16x32_bf16 v[62:65], v[136:139], v[142:145], v[62:65]
	v_mfma_f32_16x16x32_bf16 v[58:61], v[146:149], v[142:145], v[58:61]
	v_mfma_f32_16x16x32_bf16 v[54:57], v[150:153], v[142:145], v[54:57]
	v_mfma_f32_16x16x32_bf16 v[50:53], v[154:157], v[142:145], v[50:53]
	v_mfma_f32_16x16x32_bf16 v[46:49], v[136:139], v[158:161], v[46:49]
	v_mfma_f32_16x16x32_bf16 v[42:45], v[146:149], v[158:161], v[42:45]
	v_mfma_f32_16x16x32_bf16 v[38:41], v[150:153], v[158:161], v[38:41]
	v_mfma_f32_16x16x32_bf16 v[34:37], v[154:157], v[158:161], v[34:37]
	v_mfma_f32_16x16x32_bf16 v[30:33], v[136:139], v[162:165], v[30:33]
	v_mfma_f32_16x16x32_bf16 v[26:29], v[146:149], v[162:165], v[26:29]
	v_mfma_f32_16x16x32_bf16 v[22:25], v[150:153], v[162:165], v[22:25]
	v_mfma_f32_16x16x32_bf16 v[18:21], v[154:157], v[162:165], v[18:21]
	v_mfma_f32_16x16x32_bf16 v[14:17], v[136:139], v[166:169], v[14:17]
	v_mfma_f32_16x16x32_bf16 v[10:13], v[146:149], v[166:169], v[10:13]
	v_mfma_f32_16x16x32_bf16 v[6:9], v[150:153], v[166:169], v[6:9]
	v_mfma_f32_16x16x32_bf16 v[2:5], v[154:157], v[166:169], v[2:5]
	s_waitcnt vmcnt(0)
	s_barrier
	ds_read_b128 v[136:139], v134 offset:40960
	ds_read_b128 v[142:145], v134 offset:41984
	ds_read_b128 v[146:149], v134 offset:43008
	ds_read_b128 v[150:153], v134 offset:44032
	ds_read_b128 v[154:157], v174 offset:24576
	ds_read_b128 v[158:161], v174 offset:25600
	ds_read_b128 v[162:165], v174 offset:26624
	ds_read_b128 v[166:169], v174 offset:27648
	s_lshl_b64 s[0:1], s[0:1], 8
	s_waitcnt lgkmcnt(0)
	v_mfma_f32_16x16x32_bf16 v[170:173], v[136:139], v[154:157], v[126:129]
	v_mfma_f32_16x16x32_bf16 v[122:125], v[142:145], v[154:157], v[122:125]
	v_mfma_f32_16x16x32_bf16 v[118:121], v[146:149], v[154:157], v[118:121]
	v_mfma_f32_16x16x32_bf16 v[114:117], v[150:153], v[154:157], v[114:117]
	v_mfma_f32_16x16x32_bf16 v[110:113], v[136:139], v[158:161], v[110:113]
	v_mfma_f32_16x16x32_bf16 v[106:109], v[142:145], v[158:161], v[106:109]
	v_mfma_f32_16x16x32_bf16 v[102:105], v[146:149], v[158:161], v[102:105]
	v_mfma_f32_16x16x32_bf16 v[98:101], v[150:153], v[158:161], v[98:101]
	v_mfma_f32_16x16x32_bf16 v[94:97], v[136:139], v[162:165], v[94:97]
	v_mfma_f32_16x16x32_bf16 v[90:93], v[142:145], v[162:165], v[90:93]
	v_mfma_f32_16x16x32_bf16 v[86:89], v[146:149], v[162:165], v[86:89]
	v_mfma_f32_16x16x32_bf16 v[82:85], v[150:153], v[162:165], v[82:85]
	v_mfma_f32_16x16x32_bf16 v[78:81], v[136:139], v[166:169], v[78:81]
	v_mfma_f32_16x16x32_bf16 v[74:77], v[142:145], v[166:169], v[74:77]
	v_mfma_f32_16x16x32_bf16 v[70:73], v[146:149], v[166:169], v[70:73]
	v_mfma_f32_16x16x32_bf16 v[66:69], v[150:153], v[166:169], v[66:69]
	ds_read_b128 v[126:129], v174 offset:28672
	ds_read_b128 v[154:157], v174 offset:29696
	ds_read_b128 v[158:161], v174 offset:30720
	ds_read_b128 v[162:165], v174 offset:31744
	s_waitcnt lgkmcnt(0)
	v_mfma_f32_16x16x32_bf16 v[62:65], v[136:139], v[126:129], v[62:65]
	v_mfma_f32_16x16x32_bf16 v[58:61], v[142:145], v[126:129], v[58:61]
	v_mfma_f32_16x16x32_bf16 v[54:57], v[146:149], v[126:129], v[54:57]
	v_mfma_f32_16x16x32_bf16 v[50:53], v[150:153], v[126:129], v[50:53]
	v_mfma_f32_16x16x32_bf16 v[46:49], v[136:139], v[154:157], v[46:49]
	v_mfma_f32_16x16x32_bf16 v[42:45], v[142:145], v[154:157], v[42:45]
	v_mfma_f32_16x16x32_bf16 v[38:41], v[146:149], v[154:157], v[38:41]
	v_mfma_f32_16x16x32_bf16 v[34:37], v[150:153], v[154:157], v[34:37]
	v_mfma_f32_16x16x32_bf16 v[30:33], v[136:139], v[158:161], v[30:33]
	v_mfma_f32_16x16x32_bf16 v[26:29], v[142:145], v[158:161], v[26:29]
	v_mfma_f32_16x16x32_bf16 v[22:25], v[146:149], v[158:161], v[22:25]
	v_mfma_f32_16x16x32_bf16 v[18:21], v[150:153], v[158:161], v[18:21]
	v_mfma_f32_16x16x32_bf16 v[14:17], v[136:139], v[162:165], v[14:17]
	v_mfma_f32_16x16x32_bf16 v[10:13], v[142:145], v[162:165], v[10:13]
	v_mfma_f32_16x16x32_bf16 v[6:9], v[146:149], v[162:165], v[6:9]
	v_mfma_f32_16x16x32_bf16 v[2:5], v[150:153], v[162:165], v[2:5]
	v_lshl_add_u64 v[126:127], s[0:1], 0, v[132:133]
	v_lshl_add_u64 v[128:129], v[126:127], 2, s[14:15]
	s_waitcnt vmcnt(0)
	s_barrier
	flat_load_dword v146, v[128:129]
	v_lshl_or_b32 v134, s6, 7, v140
	v_lshlrev_b64 v[128:129], 11, v[126:127]
	v_lshl_add_u64 v[136:137], s[12:13], 0, v[128:129]
	v_lshlrev_b32_e32 v128, 1, v134
	v_mov_b32_e32 v129, v135
	v_lshl_add_u64 v[138:139], v[136:137], 0, v[128:129]
	flat_load_dwordx2 v[150:151], v[138:139]
	v_lshlrev_b64 v[136:137], 12, v[126:127]
	v_lshlrev_b32_e32 v134, 2, v134
	v_lshl_add_u64 v[136:137], v[130:131], 0, v[136:137]
	v_lshl_add_u64 v[136:137], v[136:137], 0, v[134:135]
	flat_load_dwordx4 v[142:145], v[136:137]
	s_waitcnt vmcnt(0) lgkmcnt(0)
	v_fmamk_f32 v146, v146, 0x3a800000, v141
	v_mul_f32_e32 v147, 0x4b800000, v146
	v_cmp_gt_f32_e32 vcc, s50, v146
	v_lshlrev_b32_e32 v152, 16, v150
	s_nop 0
	v_cndmask_b32_e32 v146, v146, v147, vcc
	v_rsq_f32_e32 v154, v146
	v_and_b32_e32 v153, 0xffff0000, v150
	flat_load_dwordx4 v[146:149], v[136:137] offset:64
	v_mul_f32_e32 v150, 0x45800000, v154
	v_cndmask_b32_e32 v158, v154, v150, vcc
	v_mul_f32_e32 v150, v170, v158
	v_mul_f32_e32 v154, v171, v158
	v_mul_f32_e32 v155, v172, v158
	v_mul_f32_e32 v150, 0xbfb8aa3b, v150
	v_mul_f32_e32 v157, 0xbfb8aa3b, v154
	v_mul_f32_e32 v156, v173, v158
	v_mul_f32_e32 v159, 0xbfb8aa3b, v155
	v_exp_f32_e32 v154, v150
	v_exp_f32_e32 v155, v157
	v_mul_f32_e32 v160, 0xbfb8aa3b, v156
	v_exp_f32_e32 v156, v159
	v_exp_f32_e32 v157, v160
	v_pk_add_f32 v[154:155], v[154:155], 1.0 op_sel_hi:[1,0]
	v_lshlrev_b32_e32 v150, 16, v151
	v_div_scale_f32 v159, s[0:1], v155, v155, 1.0
	v_pk_add_f32 v[156:157], v[156:157], 1.0 op_sel_hi:[1,0]
	v_div_scale_f32 v161, s[0:1], v154, v154, 1.0
	v_rcp_f32_e32 v167, v159
	v_div_scale_f32 v163, s[4:5], v157, v157, 1.0
	v_rcp_f32_e32 v168, v161
	v_div_scale_f32 v165, s[6:7], v156, v156, 1.0
	v_rcp_f32_e32 v169, v163
	v_rcp_f32_e32 v170, v165
	v_fma_f32 v171, -v159, v167, 1.0
	v_div_scale_f32 v160, vcc, 1.0, v155, 1.0
	v_fma_f32 v172, -v161, v168, 1.0
	v_fmac_f32_e32 v167, v171, v167
	v_div_scale_f32 v162, s[0:1], 1.0, v154, 1.0
	v_fma_f32 v173, -v163, v169, 1.0
	v_fmac_f32_e32 v168, v172, v168
	v_mul_f32_e32 v171, v160, v167
	v_div_scale_f32 v164, s[4:5], 1.0, v157, 1.0
	v_fma_f32 v174, -v165, v170, 1.0
	v_fmac_f32_e32 v169, v173, v169
	v_mul_f32_e32 v172, v162, v168
	v_fma_f32 v175, -v159, v171, v160
	v_div_scale_f32 v166, s[6:7], 1.0, v156, 1.0
	v_fmac_f32_e32 v170, v174, v170
	v_mul_f32_e32 v173, v164, v169
	v_fma_f32 v176, -v161, v172, v162
	v_fmac_f32_e32 v171, v175, v167
	v_mul_f32_e32 v174, v166, v170
	v_fma_f32 v177, -v163, v173, v164
	v_fmac_f32_e32 v172, v176, v168
	v_fma_f32 v159, -v159, v171, v160
	v_fma_f32 v178, -v165, v174, v166
	v_fmac_f32_e32 v173, v177, v169
	v_fma_f32 v160, -v161, v172, v162
	v_div_fmas_f32 v159, v159, v167, v171
	s_mov_b64 vcc, s[0:1]
	v_fmac_f32_e32 v174, v178, v170
	v_fma_f32 v161, -v163, v173, v164
	v_div_fixup_f32 v155, v159, v155, 1.0
	v_div_fmas_f32 v159, v160, v168, v172
	s_mov_b64 vcc, s[4:5]
	v_fma_f32 v162, -v165, v174, v166
	v_div_fixup_f32 v154, v159, v154, 1.0
	v_div_fmas_f32 v159, v161, v169, v173
	s_mov_b64 vcc, s[6:7]
	v_pk_fma_f32 v[142:143], v[154:155], v[152:153], v[142:143]
	v_div_fmas_f32 v152, v162, v170, v174
	v_and_b32_e32 v151, 0xffff0000, v151
	v_div_fixup_f32 v153, v159, v157, 1.0
	v_div_fixup_f32 v152, v152, v156, 1.0
	v_pk_fma_f32 v[144:145], v[152:153], v[150:151], v[144:145]
	flat_store_dwordx4 v[136:137], v[142:145]
	flat_load_dwordx2 v[142:143], v[138:139] offset:32
	v_mul_f32_e32 v122, v122, v158
	v_mul_f32_e32 v123, v123, v158
	v_mul_f32_e32 v122, 0xbfb8aa3b, v122
	v_mul_f32_e32 v123, 0xbfb8aa3b, v123
	v_mul_f32_e32 v124, v124, v158
	v_mul_f32_e32 v125, v125, v158
	v_exp_f32_e32 v122, v122
	v_exp_f32_e32 v123, v123
	v_mul_f32_e32 v124, 0xbfb8aa3b, v124
	v_mul_f32_e32 v125, 0xbfb8aa3b, v125
	v_exp_f32_e32 v124, v124
	v_exp_f32_e32 v125, v125
	v_pk_add_f32 v[122:123], v[122:123], 1.0 op_sel_hi:[1,0]
	v_mul_f32_e32 v118, v118, v158
	v_div_scale_f32 v144, s[0:1], v123, v123, 1.0
	v_pk_add_f32 v[124:125], v[124:125], 1.0 op_sel_hi:[1,0]
	v_div_scale_f32 v150, s[0:1], v122, v122, 1.0
	v_rcp_f32_e32 v156, v144
	v_div_scale_f32 v152, s[4:5], v125, v125, 1.0
	v_rcp_f32_e32 v157, v150
	v_div_scale_f32 v154, s[6:7], v124, v124, 1.0
	v_rcp_f32_e32 v159, v152
	v_rcp_f32_e32 v160, v154
	v_fma_f32 v161, -v144, v156, 1.0
	v_div_scale_f32 v145, vcc, 1.0, v123, 1.0
	v_fma_f32 v162, -v150, v157, 1.0
	v_fmac_f32_e32 v156, v161, v156
	v_div_scale_f32 v151, s[0:1], 1.0, v122, 1.0
	v_fma_f32 v163, -v152, v159, 1.0
	v_fmac_f32_e32 v157, v162, v157
	v_mul_f32_e32 v161, v145, v156
	v_div_scale_f32 v153, s[4:5], 1.0, v125, 1.0
	v_fma_f32 v164, -v154, v160, 1.0
	v_fmac_f32_e32 v159, v163, v159
	v_mul_f32_e32 v162, v151, v157
	v_fma_f32 v165, -v144, v161, v145
	v_div_scale_f32 v155, s[6:7], 1.0, v124, 1.0
	v_fmac_f32_e32 v160, v164, v160
	v_mul_f32_e32 v163, v153, v159
	v_fma_f32 v166, -v150, v162, v151
	v_fmac_f32_e32 v161, v165, v156
	v_mul_f32_e32 v164, v155, v160
	v_fma_f32 v167, -v152, v163, v153
	v_fmac_f32_e32 v162, v166, v157
	v_fma_f32 v144, -v144, v161, v145
	v_fma_f32 v168, -v154, v164, v155
	v_fmac_f32_e32 v163, v167, v159
	v_fma_f32 v145, -v150, v162, v151
	v_div_fmas_f32 v144, v144, v156, v161
	s_mov_b64 vcc, s[0:1]
	v_fmac_f32_e32 v164, v168, v160
	v_fma_f32 v150, -v152, v163, v153
	v_div_fixup_f32 v123, v144, v123, 1.0
	v_div_fmas_f32 v144, v145, v157, v162
	s_mov_b64 vcc, s[4:5]
	v_fma_f32 v151, -v154, v164, v155
	v_div_fixup_f32 v122, v144, v122, 1.0
	v_div_fmas_f32 v144, v150, v159, v163
	s_mov_b64 vcc, s[6:7]
	v_div_fixup_f32 v125, v144, v125, 1.0
	v_div_fmas_f32 v144, v151, v160, v164
	v_div_fixup_f32 v124, v144, v124, 1.0
	v_mul_f32_e32 v119, v119, v158
	v_mul_f32_e32 v118, 0xbfb8aa3b, v118
	v_mul_f32_e32 v119, 0xbfb8aa3b, v119
	v_mul_f32_e32 v120, v120, v158
	v_mul_f32_e32 v121, v121, v158
	v_mul_f32_e32 v120, 0xbfb8aa3b, v120
	v_mul_f32_e32 v121, 0xbfb8aa3b, v121
	v_mul_f32_e32 v114, v114, v158
	v_mul_f32_e32 v115, v115, v158
	s_waitcnt vmcnt(0) lgkmcnt(0)
	v_lshlrev_b32_e32 v144, 16, v142
	v_and_b32_e32 v145, 0xffff0000, v142
	v_lshlrev_b32_e32 v142, 16, v143
	v_and_b32_e32 v143, 0xffff0000, v143
	v_pk_fma_f32 v[122:123], v[122:123], v[144:145], v[146:147]
	v_pk_fma_f32 v[124:125], v[124:125], v[142:143], v[148:149]
	flat_store_dwordx4 v[136:137], v[122:125] offset:64
	flat_load_dwordx2 v[142:143], v[138:139] offset:64
	s_nop 0
	flat_load_dwordx4 v[122:125], v[136:137] offset:128
	v_exp_f32_e32 v144, v118
	v_exp_f32_e32 v145, v119
	v_exp_f32_e32 v146, v120
	v_exp_f32_e32 v147, v121
	flat_load_dwordx4 v[118:121], v[136:137] offset:192
	v_pk_add_f32 v[144:145], v[144:145], 1.0 op_sel_hi:[1,0]
	v_mul_f32_e32 v114, 0xbfb8aa3b, v114
	v_div_scale_f32 v148, s[0:1], v145, v145, 1.0
	v_pk_add_f32 v[146:147], v[146:147], 1.0 op_sel_hi:[1,0]
	v_div_scale_f32 v150, s[0:1], v144, v144, 1.0
	v_rcp_f32_e32 v156, v148
	v_div_scale_f32 v152, s[4:5], v147, v147, 1.0
	v_rcp_f32_e32 v157, v150
	v_div_scale_f32 v154, s[6:7], v146, v146, 1.0
	v_rcp_f32_e32 v159, v152
	v_rcp_f32_e32 v160, v154
	v_fma_f32 v161, -v148, v156, 1.0
	v_div_scale_f32 v149, vcc, 1.0, v145, 1.0
	v_fma_f32 v162, -v150, v157, 1.0
	v_fmac_f32_e32 v156, v161, v156
	v_div_scale_f32 v151, s[0:1], 1.0, v144, 1.0
	v_fma_f32 v163, -v152, v159, 1.0
	v_fmac_f32_e32 v157, v162, v157
	v_mul_f32_e32 v161, v149, v156
	v_div_scale_f32 v153, s[4:5], 1.0, v147, 1.0
	v_fma_f32 v164, -v154, v160, 1.0
	v_fmac_f32_e32 v159, v163, v159
	v_mul_f32_e32 v162, v151, v157
	v_fma_f32 v165, -v148, v161, v149
	v_div_scale_f32 v155, s[6:7], 1.0, v146, 1.0
	v_fmac_f32_e32 v160, v164, v160
	v_mul_f32_e32 v163, v153, v159
	v_fma_f32 v166, -v150, v162, v151
	v_fmac_f32_e32 v161, v165, v156
	v_mul_f32_e32 v164, v155, v160
	v_fma_f32 v167, -v152, v163, v153
	v_fmac_f32_e32 v162, v166, v157
	v_fma_f32 v148, -v148, v161, v149
	v_fma_f32 v168, -v154, v164, v155
	v_fmac_f32_e32 v163, v167, v159
	v_fma_f32 v149, -v150, v162, v151
	v_div_fmas_f32 v148, v148, v156, v161
	s_mov_b64 vcc, s[0:1]
	v_fmac_f32_e32 v164, v168, v160
	v_fma_f32 v150, -v152, v163, v153
	v_div_fixup_f32 v145, v148, v145, 1.0
	v_div_fmas_f32 v148, v149, v157, v162
	s_mov_b64 vcc, s[4:5]
	v_fma_f32 v151, -v154, v164, v155
	v_div_fixup_f32 v144, v148, v144, 1.0
	v_div_fmas_f32 v148, v150, v159, v163
	s_mov_b64 vcc, s[6:7]
	v_div_fixup_f32 v147, v148, v147, 1.0
	v_div_fmas_f32 v148, v151, v160, v164
	v_div_fixup_f32 v146, v148, v146, 1.0
	v_mul_f32_e32 v115, 0xbfb8aa3b, v115
	v_mul_f32_e32 v116, v116, v158
	v_mul_f32_e32 v117, v117, v158
	v_exp_f32_e32 v114, v114
	v_exp_f32_e32 v115, v115
	v_mul_f32_e32 v116, 0xbfb8aa3b, v116
	v_mul_f32_e32 v117, 0xbfb8aa3b, v117
	v_exp_f32_e32 v116, v116
	v_exp_f32_e32 v117, v117
	v_pk_add_f32 v[114:115], v[114:115], 1.0 op_sel_hi:[1,0]
	v_pk_add_f32 v[116:117], v[116:117], 1.0 op_sel_hi:[1,0]
	s_waitcnt vmcnt(0) lgkmcnt(0)
	v_lshlrev_b32_e32 v148, 16, v142
	v_and_b32_e32 v149, 0xffff0000, v142
	v_lshlrev_b32_e32 v142, 16, v143
	v_and_b32_e32 v143, 0xffff0000, v143
	v_pk_fma_f32 v[122:123], v[144:145], v[148:149], v[122:123]
	v_pk_fma_f32 v[124:125], v[146:147], v[142:143], v[124:125]
	flat_store_dwordx4 v[136:137], v[122:125] offset:128
	flat_load_dwordx2 v[122:123], v[138:139] offset:96
	v_div_scale_f32 v138, s[0:1], v114, v114, 1.0
	v_div_scale_f32 v124, s[0:1], v115, v115, 1.0
	v_rcp_f32_e32 v146, v124
	v_div_scale_f32 v142, s[4:5], v117, v117, 1.0
	v_rcp_f32_e32 v147, v138
	v_div_scale_f32 v144, s[6:7], v116, v116, 1.0
	v_rcp_f32_e32 v148, v142
	v_rcp_f32_e32 v149, v144
	v_fma_f32 v150, -v124, v146, 1.0
	v_div_scale_f32 v125, vcc, 1.0, v115, 1.0
	v_fma_f32 v151, -v138, v147, 1.0
	v_fmac_f32_e32 v146, v150, v146
	v_div_scale_f32 v139, s[0:1], 1.0, v114, 1.0
	v_fma_f32 v152, -v142, v148, 1.0
	v_fmac_f32_e32 v147, v151, v147
	v_mul_f32_e32 v150, v125, v146
	v_div_scale_f32 v143, s[4:5], 1.0, v117, 1.0
	v_fma_f32 v153, -v144, v149, 1.0
	v_fmac_f32_e32 v148, v152, v148
	v_mul_f32_e32 v151, v139, v147
	v_fma_f32 v154, -v124, v150, v125
	v_div_scale_f32 v145, s[6:7], 1.0, v116, 1.0
	v_fmac_f32_e32 v149, v153, v149
	v_mul_f32_e32 v152, v143, v148
	v_fma_f32 v155, -v138, v151, v139
	v_fmac_f32_e32 v150, v154, v146
	v_mul_f32_e32 v153, v145, v149
	v_fma_f32 v156, -v142, v152, v143
	v_fmac_f32_e32 v151, v155, v147
	v_fma_f32 v124, -v124, v150, v125
	v_fma_f32 v157, -v144, v153, v145
	v_fmac_f32_e32 v152, v156, v148
	v_fma_f32 v125, -v138, v151, v139
	v_div_fmas_f32 v124, v124, v146, v150
	s_mov_b64 vcc, s[0:1]
	v_fmac_f32_e32 v153, v157, v149
	v_fma_f32 v138, -v142, v152, v143
	v_div_fixup_f32 v115, v124, v115, 1.0
	v_div_fmas_f32 v124, v125, v147, v151
	s_mov_b64 vcc, s[4:5]
	v_fma_f32 v139, -v144, v153, v145
	v_div_fixup_f32 v114, v124, v114, 1.0
	v_div_fmas_f32 v124, v138, v148, v152
	s_mov_b64 vcc, s[6:7]
	v_div_fixup_f32 v117, v124, v117, 1.0
	v_div_fmas_f32 v124, v139, v149, v153
	v_div_fixup_f32 v116, v124, v116, 1.0
	s_waitcnt vmcnt(0) lgkmcnt(0)
	v_lshlrev_b32_e32 v124, 16, v122
	v_and_b32_e32 v125, 0xffff0000, v122
	v_lshlrev_b32_e32 v122, 16, v123
	v_and_b32_e32 v123, 0xffff0000, v123
	v_pk_fma_f32 v[114:115], v[114:115], v[124:125], v[118:119]
	v_pk_fma_f32 v[116:117], v[116:117], v[122:123], v[120:121]
	flat_store_dwordx4 v[136:137], v[114:117] offset:192
	s_nop 1
	v_or_b32_e32 v114, 16, v126
	v_mov_b32_e32 v115, v127
	v_lshl_add_u64 v[116:117], v[114:115], 2, s[14:15]
	flat_load_dword v122, v[116:117]
	v_lshlrev_b64 v[116:117], 11, v[114:115]
	v_lshl_add_u64 v[116:117], s[12:13], 0, v[116:117]
	v_lshl_add_u64 v[116:117], v[116:117], 0, v[128:129]
	flat_load_dwordx2 v[136:137], v[116:117]
	v_lshlrev_b64 v[114:115], 12, v[114:115]
	v_lshl_add_u64 v[114:115], v[130:131], 0, v[114:115]
	v_lshl_add_u64 v[114:115], v[114:115], 0, v[134:135]
	flat_load_dwordx4 v[118:121], v[114:115]
	s_waitcnt vmcnt(0) lgkmcnt(0)
	v_fmamk_f32 v122, v122, 0x3a800000, v141
	v_mul_f32_e32 v123, 0x4b800000, v122
	v_cmp_gt_f32_e32 vcc, s50, v122
	v_lshlrev_b32_e32 v138, 16, v136
	s_nop 0
	v_cndmask_b32_e32 v122, v122, v123, vcc
	v_rsq_f32_e32 v142, v122
	v_and_b32_e32 v139, 0xffff0000, v136
	flat_load_dwordx4 v[122:125], v[114:115] offset:64
	v_mul_f32_e32 v136, 0x45800000, v142
	v_cndmask_b32_e32 v142, v142, v136, vcc
	v_mul_f32_e32 v110, v110, v142
	v_mul_f32_e32 v111, v111, v142
	v_mul_f32_e32 v110, 0xbfb8aa3b, v110
	v_mul_f32_e32 v111, 0xbfb8aa3b, v111
	v_mul_f32_e32 v112, v112, v142
	v_mul_f32_e32 v113, v113, v142
	v_exp_f32_e32 v110, v110
	v_exp_f32_e32 v111, v111
	v_mul_f32_e32 v112, 0xbfb8aa3b, v112
	v_mul_f32_e32 v113, 0xbfb8aa3b, v113
	v_exp_f32_e32 v112, v112
	v_exp_f32_e32 v113, v113
	v_pk_add_f32 v[110:111], v[110:111], 1.0 op_sel_hi:[1,0]
	v_lshlrev_b32_e32 v136, 16, v137
	v_div_scale_f32 v143, s[0:1], v111, v111, 1.0
	v_pk_add_f32 v[112:113], v[112:113], 1.0 op_sel_hi:[1,0]
	v_div_scale_f32 v145, s[0:1], v110, v110, 1.0
	v_rcp_f32_e32 v151, v143
	v_div_scale_f32 v147, s[4:5], v113, v113, 1.0
	v_rcp_f32_e32 v152, v145
	v_div_scale_f32 v149, s[6:7], v112, v112, 1.0
	v_rcp_f32_e32 v153, v147
	v_rcp_f32_e32 v154, v149
	v_fma_f32 v155, -v143, v151, 1.0
	v_div_scale_f32 v144, vcc, 1.0, v111, 1.0
	v_fma_f32 v156, -v145, v152, 1.0
	v_fmac_f32_e32 v151, v155, v151
	v_div_scale_f32 v146, s[0:1], 1.0, v110, 1.0
	v_fma_f32 v157, -v147, v153, 1.0
	v_fmac_f32_e32 v152, v156, v152
	v_mul_f32_e32 v155, v144, v151
	v_div_scale_f32 v148, s[4:5], 1.0, v113, 1.0
	v_fma_f32 v158, -v149, v154, 1.0
	v_fmac_f32_e32 v153, v157, v153
	v_mul_f32_e32 v156, v146, v152
	v_fma_f32 v159, -v143, v155, v144
	v_div_scale_f32 v150, s[6:7], 1.0, v112, 1.0
	v_fmac_f32_e32 v154, v158, v154
	v_mul_f32_e32 v157, v148, v153
	v_fma_f32 v160, -v145, v156, v146
	v_fmac_f32_e32 v155, v159, v151
	v_mul_f32_e32 v158, v150, v154
	v_fma_f32 v161, -v147, v157, v148
	v_fmac_f32_e32 v156, v160, v152
	v_fma_f32 v143, -v143, v155, v144
	v_fma_f32 v162, -v149, v158, v150
	v_fmac_f32_e32 v157, v161, v153
	v_fma_f32 v144, -v145, v156, v146
	v_div_fmas_f32 v143, v143, v151, v155
	s_mov_b64 vcc, s[0:1]
	v_fmac_f32_e32 v158, v162, v154
	v_fma_f32 v145, -v147, v157, v148
	v_div_fixup_f32 v111, v143, v111, 1.0
	v_div_fmas_f32 v143, v144, v152, v156
	s_mov_b64 vcc, s[4:5]
	v_fma_f32 v146, -v149, v158, v150
	v_div_fixup_f32 v110, v143, v110, 1.0
	v_div_fmas_f32 v143, v145, v153, v157
	s_mov_b64 vcc, s[6:7]
	v_pk_fma_f32 v[110:111], v[110:111], v[138:139], v[118:119]
	v_div_fmas_f32 v118, v146, v154, v158
	v_and_b32_e32 v137, 0xffff0000, v137
	v_div_fixup_f32 v113, v143, v113, 1.0
	v_div_fixup_f32 v112, v118, v112, 1.0
	v_pk_fma_f32 v[112:113], v[112:113], v[136:137], v[120:121]
	flat_store_dwordx4 v[114:115], v[110:113]
	flat_load_dwordx2 v[110:111], v[116:117] offset:32
	v_mul_f32_e32 v106, v106, v142
	v_mul_f32_e32 v107, v107, v142
	v_mul_f32_e32 v106, 0xbfb8aa3b, v106
	v_mul_f32_e32 v107, 0xbfb8aa3b, v107
	v_mul_f32_e32 v108, v108, v142
	v_mul_f32_e32 v109, v109, v142
	v_exp_f32_e32 v106, v106
	v_exp_f32_e32 v107, v107
	v_mul_f32_e32 v108, 0xbfb8aa3b, v108
	v_mul_f32_e32 v109, 0xbfb8aa3b, v109
	v_exp_f32_e32 v108, v108
	v_exp_f32_e32 v109, v109
	v_pk_add_f32 v[106:107], v[106:107], 1.0 op_sel_hi:[1,0]
	v_mul_f32_e32 v102, v102, v142
	v_div_scale_f32 v112, s[0:1], v107, v107, 1.0
	v_pk_add_f32 v[108:109], v[108:109], 1.0 op_sel_hi:[1,0]
	v_div_scale_f32 v118, s[0:1], v106, v106, 1.0
	v_rcp_f32_e32 v138, v112
	v_div_scale_f32 v120, s[4:5], v109, v109, 1.0
	v_rcp_f32_e32 v139, v118
	v_div_scale_f32 v136, s[6:7], v108, v108, 1.0
	v_rcp_f32_e32 v143, v120
	v_rcp_f32_e32 v144, v136
	v_fma_f32 v145, -v112, v138, 1.0
	v_div_scale_f32 v113, vcc, 1.0, v107, 1.0
	v_fma_f32 v146, -v118, v139, 1.0
	v_fmac_f32_e32 v138, v145, v138
	v_div_scale_f32 v119, s[0:1], 1.0, v106, 1.0
	v_fma_f32 v147, -v120, v143, 1.0
	v_fmac_f32_e32 v139, v146, v139
	v_mul_f32_e32 v145, v113, v138
	v_div_scale_f32 v121, s[4:5], 1.0, v109, 1.0
	v_fma_f32 v148, -v136, v144, 1.0
	v_fmac_f32_e32 v143, v147, v143
	v_mul_f32_e32 v146, v119, v139
	v_fma_f32 v149, -v112, v145, v113
	v_div_scale_f32 v137, s[6:7], 1.0, v108, 1.0
	v_fmac_f32_e32 v144, v148, v144
	v_mul_f32_e32 v147, v121, v143
	v_fma_f32 v150, -v118, v146, v119
	v_fmac_f32_e32 v145, v149, v138
	v_mul_f32_e32 v148, v137, v144
	v_fma_f32 v151, -v120, v147, v121
	v_fmac_f32_e32 v146, v150, v139
	v_fma_f32 v112, -v112, v145, v113
	v_fma_f32 v152, -v136, v148, v137
	v_fmac_f32_e32 v147, v151, v143
	v_fma_f32 v113, -v118, v146, v119
	v_div_fmas_f32 v112, v112, v138, v145
	s_mov_b64 vcc, s[0:1]
	v_fmac_f32_e32 v148, v152, v144
	v_fma_f32 v118, -v120, v147, v121
	v_div_fixup_f32 v107, v112, v107, 1.0
	v_div_fmas_f32 v112, v113, v139, v146
	s_mov_b64 vcc, s[4:5]
	v_fma_f32 v119, -v136, v148, v137
	v_div_fixup_f32 v106, v112, v106, 1.0
	v_div_fmas_f32 v112, v118, v143, v147
	s_mov_b64 vcc, s[6:7]
	v_div_fixup_f32 v109, v112, v109, 1.0
	v_div_fmas_f32 v112, v119, v144, v148
	v_div_fixup_f32 v108, v112, v108, 1.0
	v_mul_f32_e32 v103, v103, v142
	v_mul_f32_e32 v102, 0xbfb8aa3b, v102
	v_mul_f32_e32 v103, 0xbfb8aa3b, v103
	v_mul_f32_e32 v104, v104, v142
	v_mul_f32_e32 v105, v105, v142
	v_mul_f32_e32 v104, 0xbfb8aa3b, v104
	v_mul_f32_e32 v105, 0xbfb8aa3b, v105
	v_exp_f32_e32 v118, v104
	v_exp_f32_e32 v119, v105
	s_waitcnt vmcnt(0) lgkmcnt(0)
	v_lshlrev_b32_e32 v112, 16, v110
	v_and_b32_e32 v113, 0xffff0000, v110
	v_lshlrev_b32_e32 v110, 16, v111
	v_and_b32_e32 v111, 0xffff0000, v111
	v_pk_fma_f32 v[106:107], v[106:107], v[112:113], v[122:123]
	v_pk_fma_f32 v[108:109], v[108:109], v[110:111], v[124:125]
	flat_store_dwordx4 v[114:115], v[106:109] offset:64
	flat_load_dwordx2 v[110:111], v[116:117] offset:64
	s_nop 0
	flat_load_dwordx4 v[106:109], v[114:115] offset:128
	v_exp_f32_e32 v112, v102
	v_exp_f32_e32 v113, v103
	v_pk_add_f32 v[118:119], v[118:119], 1.0 op_sel_hi:[1,0]
	flat_load_dwordx4 v[102:105], v[114:115] offset:192
	v_div_scale_f32 v124, s[4:5], v119, v119, 1.0
	v_pk_add_f32 v[112:113], v[112:113], 1.0 op_sel_hi:[1,0]
	v_div_scale_f32 v136, s[6:7], v118, v118, 1.0
	v_div_scale_f32 v120, s[0:1], v113, v113, 1.0
	v_div_scale_f32 v122, s[0:1], v112, v112, 1.0
	v_rcp_f32_e32 v138, v120
	v_rcp_f32_e32 v139, v122
	v_rcp_f32_e32 v143, v124
	v_rcp_f32_e32 v144, v136
	v_fma_f32 v145, -v120, v138, 1.0
	v_div_scale_f32 v121, vcc, 1.0, v113, 1.0
	v_fma_f32 v146, -v122, v139, 1.0
	v_fmac_f32_e32 v138, v145, v138
	v_div_scale_f32 v123, s[0:1], 1.0, v112, 1.0
	v_fma_f32 v147, -v124, v143, 1.0
	v_fmac_f32_e32 v139, v146, v139
	v_mul_f32_e32 v145, v121, v138
	v_div_scale_f32 v125, s[4:5], 1.0, v119, 1.0
	v_fma_f32 v148, -v136, v144, 1.0
	v_fmac_f32_e32 v143, v147, v143
	v_mul_f32_e32 v146, v123, v139
	v_fma_f32 v149, -v120, v145, v121
	v_div_scale_f32 v137, s[6:7], 1.0, v118, 1.0
	v_fmac_f32_e32 v144, v148, v144
	v_mul_f32_e32 v147, v125, v143
	v_fma_f32 v150, -v122, v146, v123
	v_fmac_f32_e32 v145, v149, v138
	v_mul_f32_e32 v148, v137, v144
	v_fma_f32 v151, -v124, v147, v125
	v_fmac_f32_e32 v146, v150, v139
	v_fma_f32 v120, -v120, v145, v121
	v_fma_f32 v152, -v136, v148, v137
	v_fmac_f32_e32 v147, v151, v143
	v_fma_f32 v121, -v122, v146, v123
	v_div_fmas_f32 v120, v120, v138, v145
	s_mov_b64 vcc, s[0:1]
	v_fmac_f32_e32 v148, v152, v144
	v_fma_f32 v122, -v124, v147, v125
	v_div_fixup_f32 v113, v120, v113, 1.0
	v_div_fmas_f32 v120, v121, v139, v146
	s_mov_b64 vcc, s[4:5]
	v_fma_f32 v123, -v136, v148, v137
	v_div_fixup_f32 v112, v120, v112, 1.0
	v_div_fmas_f32 v120, v122, v143, v147
	s_mov_b64 vcc, s[6:7]
	v_div_fixup_f32 v119, v120, v119, 1.0
	v_div_fmas_f32 v120, v123, v144, v148
	v_div_fixup_f32 v118, v120, v118, 1.0
	v_mul_f32_e32 v98, v98, v142
	v_mul_f32_e32 v99, v99, v142
	v_mul_f32_e32 v98, 0xbfb8aa3b, v98
	v_mul_f32_e32 v99, 0xbfb8aa3b, v99
	v_mul_f32_e32 v100, v100, v142
	v_mul_f32_e32 v101, v101, v142
	v_exp_f32_e32 v98, v98
	v_exp_f32_e32 v99, v99
	v_mul_f32_e32 v100, 0xbfb8aa3b, v100
	v_mul_f32_e32 v101, 0xbfb8aa3b, v101
	v_exp_f32_e32 v100, v100
	v_exp_f32_e32 v101, v101
	v_pk_add_f32 v[98:99], v[98:99], 1.0 op_sel_hi:[1,0]
	v_pk_add_f32 v[100:101], v[100:101], 1.0 op_sel_hi:[1,0]
	s_waitcnt vmcnt(0) lgkmcnt(0)
	v_lshlrev_b32_e32 v120, 16, v110
	v_and_b32_e32 v121, 0xffff0000, v110
	v_lshlrev_b32_e32 v110, 16, v111
	v_and_b32_e32 v111, 0xffff0000, v111
	v_pk_fma_f32 v[106:107], v[112:113], v[120:121], v[106:107]
	v_pk_fma_f32 v[108:109], v[118:119], v[110:111], v[108:109]
	flat_store_dwordx4 v[114:115], v[106:109] offset:128
	flat_load_dwordx2 v[106:107], v[116:117] offset:96
	v_div_scale_f32 v110, s[0:1], v98, v98, 1.0
	v_div_scale_f32 v108, s[0:1], v99, v99, 1.0
	v_rcp_f32_e32 v118, v108
	v_div_scale_f32 v112, s[4:5], v101, v101, 1.0
	v_rcp_f32_e32 v119, v110
	v_div_scale_f32 v116, s[6:7], v100, v100, 1.0
	v_rcp_f32_e32 v120, v112
	v_rcp_f32_e32 v121, v116
	v_fma_f32 v122, -v108, v118, 1.0
	v_div_scale_f32 v109, vcc, 1.0, v99, 1.0
	v_fma_f32 v123, -v110, v119, 1.0
	v_fmac_f32_e32 v118, v122, v118
	v_div_scale_f32 v111, s[0:1], 1.0, v98, 1.0
	v_fma_f32 v124, -v112, v120, 1.0
	v_fmac_f32_e32 v119, v123, v119
	v_mul_f32_e32 v122, v109, v118
	v_div_scale_f32 v113, s[4:5], 1.0, v101, 1.0
	v_fma_f32 v125, -v116, v121, 1.0
	v_fmac_f32_e32 v120, v124, v120
	v_mul_f32_e32 v123, v111, v119
	v_fma_f32 v136, -v108, v122, v109
	v_div_scale_f32 v117, s[6:7], 1.0, v100, 1.0
	v_fmac_f32_e32 v121, v125, v121
	v_mul_f32_e32 v124, v113, v120
	v_fma_f32 v137, -v110, v123, v111
	v_fmac_f32_e32 v122, v136, v118
	v_mul_f32_e32 v125, v117, v121
	v_fma_f32 v138, -v112, v124, v113
	v_fmac_f32_e32 v123, v137, v119
	v_fma_f32 v108, -v108, v122, v109
	v_fma_f32 v139, -v116, v125, v117
	v_fmac_f32_e32 v124, v138, v120
	v_fma_f32 v109, -v110, v123, v111
	v_div_fmas_f32 v108, v108, v118, v122
	s_mov_b64 vcc, s[0:1]
	v_fmac_f32_e32 v125, v139, v121
	v_fma_f32 v110, -v112, v124, v113
	v_div_fixup_f32 v99, v108, v99, 1.0
	v_div_fmas_f32 v108, v109, v119, v123
	s_mov_b64 vcc, s[4:5]
	v_fma_f32 v111, -v116, v125, v117
	v_div_fixup_f32 v98, v108, v98, 1.0
	v_div_fmas_f32 v108, v110, v120, v124
	s_mov_b64 vcc, s[6:7]
	v_div_fixup_f32 v101, v108, v101, 1.0
	v_div_fmas_f32 v108, v111, v121, v125
	v_div_fixup_f32 v100, v108, v100, 1.0
	s_waitcnt vmcnt(0) lgkmcnt(0)
	v_lshlrev_b32_e32 v108, 16, v106
	v_and_b32_e32 v109, 0xffff0000, v106
	v_lshlrev_b32_e32 v106, 16, v107
	v_and_b32_e32 v107, 0xffff0000, v107
	v_pk_fma_f32 v[98:99], v[98:99], v[108:109], v[102:103]
	v_pk_fma_f32 v[100:101], v[100:101], v[106:107], v[104:105]
	flat_store_dwordx4 v[114:115], v[98:101] offset:192
	s_nop 1
	v_or_b32_e32 v98, 32, v126
	v_mov_b32_e32 v99, v127
	v_lshl_add_u64 v[100:101], v[98:99], 2, s[14:15]
	flat_load_dword v106, v[100:101]
	v_lshlrev_b64 v[100:101], 11, v[98:99]
	v_lshl_add_u64 v[100:101], s[12:13], 0, v[100:101]
	v_lshl_add_u64 v[100:101], v[100:101], 0, v[128:129]
	flat_load_dwordx2 v[110:111], v[100:101]
	v_lshlrev_b64 v[98:99], 12, v[98:99]
	v_lshl_add_u64 v[98:99], v[130:131], 0, v[98:99]
	v_lshl_add_u64 v[98:99], v[98:99], 0, v[134:135]
	flat_load_dwordx4 v[102:105], v[98:99]
	s_waitcnt vmcnt(0) lgkmcnt(0)
	v_fmamk_f32 v106, v106, 0x3a800000, v141
	v_mul_f32_e32 v107, 0x4b800000, v106
	v_cmp_gt_f32_e32 vcc, s50, v106
	v_lshlrev_b32_e32 v112, 16, v110
	s_nop 0
	v_cndmask_b32_e32 v106, v106, v107, vcc
	v_rsq_f32_e32 v114, v106
	v_and_b32_e32 v113, 0xffff0000, v110
	flat_load_dwordx4 v[106:109], v[98:99] offset:64
	v_mul_f32_e32 v110, 0x45800000, v114
	v_cndmask_b32_e32 v114, v114, v110, vcc
	v_mul_f32_e32 v94, v94, v114
	v_mul_f32_e32 v95, v95, v114
	v_mul_f32_e32 v94, 0xbfb8aa3b, v94
	v_mul_f32_e32 v95, 0xbfb8aa3b, v95
	v_mul_f32_e32 v96, v96, v114
	v_mul_f32_e32 v97, v97, v114
	v_exp_f32_e32 v94, v94
	v_exp_f32_e32 v95, v95
	v_mul_f32_e32 v96, 0xbfb8aa3b, v96
	v_mul_f32_e32 v97, 0xbfb8aa3b, v97
	v_exp_f32_e32 v96, v96
	v_exp_f32_e32 v97, v97
	v_pk_add_f32 v[94:95], v[94:95], 1.0 op_sel_hi:[1,0]
	v_lshlrev_b32_e32 v110, 16, v111
	v_div_scale_f32 v115, s[0:1], v95, v95, 1.0
	v_pk_add_f32 v[96:97], v[96:97], 1.0 op_sel_hi:[1,0]
	v_div_scale_f32 v117, s[0:1], v94, v94, 1.0
	v_rcp_f32_e32 v123, v115
	v_div_scale_f32 v119, s[4:5], v97, v97, 1.0
	v_rcp_f32_e32 v124, v117
	v_div_scale_f32 v121, s[6:7], v96, v96, 1.0
	v_rcp_f32_e32 v125, v119
	v_rcp_f32_e32 v136, v121
	v_fma_f32 v137, -v115, v123, 1.0
	v_div_scale_f32 v116, vcc, 1.0, v95, 1.0
	v_fma_f32 v138, -v117, v124, 1.0
	v_fmac_f32_e32 v123, v137, v123
	v_div_scale_f32 v118, s[0:1], 1.0, v94, 1.0
	v_fma_f32 v139, -v119, v125, 1.0
	v_fmac_f32_e32 v124, v138, v124
	v_mul_f32_e32 v137, v116, v123
	v_div_scale_f32 v120, s[4:5], 1.0, v97, 1.0
	v_fma_f32 v142, -v121, v136, 1.0
	v_fmac_f32_e32 v125, v139, v125
	v_mul_f32_e32 v138, v118, v124
	v_fma_f32 v143, -v115, v137, v116
	v_div_scale_f32 v122, s[6:7], 1.0, v96, 1.0
	v_fmac_f32_e32 v136, v142, v136
	v_mul_f32_e32 v139, v120, v125
	v_fma_f32 v144, -v117, v138, v118
	v_fmac_f32_e32 v137, v143, v123
	v_mul_f32_e32 v142, v122, v136
	v_fma_f32 v145, -v119, v139, v120
	v_fmac_f32_e32 v138, v144, v124
	v_fma_f32 v115, -v115, v137, v116
	v_fma_f32 v146, -v121, v142, v122
	v_fmac_f32_e32 v139, v145, v125
	v_fma_f32 v116, -v117, v138, v118
	v_div_fmas_f32 v115, v115, v123, v137
	s_mov_b64 vcc, s[0:1]
	v_fmac_f32_e32 v142, v146, v136
	v_fma_f32 v117, -v119, v139, v120
	v_div_fixup_f32 v95, v115, v95, 1.0
	v_div_fmas_f32 v115, v116, v124, v138
	s_mov_b64 vcc, s[4:5]
	v_fma_f32 v118, -v121, v142, v122
	v_div_fixup_f32 v94, v115, v94, 1.0
	v_div_fmas_f32 v115, v117, v125, v139
	s_mov_b64 vcc, s[6:7]
	v_pk_fma_f32 v[94:95], v[94:95], v[112:113], v[102:103]
	v_div_fmas_f32 v102, v118, v136, v142
	v_and_b32_e32 v111, 0xffff0000, v111
	v_div_fixup_f32 v97, v115, v97, 1.0
	v_div_fixup_f32 v96, v102, v96, 1.0
	v_pk_fma_f32 v[96:97], v[96:97], v[110:111], v[104:105]
	flat_store_dwordx4 v[98:99], v[94:97]
	flat_load_dwordx2 v[94:95], v[100:101] offset:32
	v_mul_f32_e32 v90, v90, v114
	v_mul_f32_e32 v91, v91, v114
	v_mul_f32_e32 v90, 0xbfb8aa3b, v90
	v_mul_f32_e32 v91, 0xbfb8aa3b, v91
	v_mul_f32_e32 v92, v92, v114
	v_mul_f32_e32 v93, v93, v114
	v_exp_f32_e32 v90, v90
	v_exp_f32_e32 v91, v91
	v_mul_f32_e32 v92, 0xbfb8aa3b, v92
	v_mul_f32_e32 v93, 0xbfb8aa3b, v93
	v_exp_f32_e32 v92, v92
	v_exp_f32_e32 v93, v93
	v_pk_add_f32 v[90:91], v[90:91], 1.0 op_sel_hi:[1,0]
	v_mul_f32_e32 v86, v86, v114
	v_div_scale_f32 v96, s[0:1], v91, v91, 1.0
	v_pk_add_f32 v[92:93], v[92:93], 1.0 op_sel_hi:[1,0]
	v_div_scale_f32 v102, s[0:1], v90, v90, 1.0
	v_rcp_f32_e32 v112, v96
	v_div_scale_f32 v104, s[4:5], v93, v93, 1.0
	v_rcp_f32_e32 v113, v102
	v_div_scale_f32 v110, s[6:7], v92, v92, 1.0
	v_rcp_f32_e32 v115, v104
	v_rcp_f32_e32 v116, v110
	v_fma_f32 v117, -v96, v112, 1.0
	v_div_scale_f32 v97, vcc, 1.0, v91, 1.0
	v_fma_f32 v118, -v102, v113, 1.0
	v_fmac_f32_e32 v112, v117, v112
	v_div_scale_f32 v103, s[0:1], 1.0, v90, 1.0
	v_fma_f32 v119, -v104, v115, 1.0
	v_fmac_f32_e32 v113, v118, v113
	v_mul_f32_e32 v117, v97, v112
	v_div_scale_f32 v105, s[4:5], 1.0, v93, 1.0
	v_fma_f32 v120, -v110, v116, 1.0
	v_fmac_f32_e32 v115, v119, v115
	v_mul_f32_e32 v118, v103, v113
	v_fma_f32 v121, -v96, v117, v97
	v_div_scale_f32 v111, s[6:7], 1.0, v92, 1.0
	v_fmac_f32_e32 v116, v120, v116
	v_mul_f32_e32 v119, v105, v115
	v_fma_f32 v122, -v102, v118, v103
	v_fmac_f32_e32 v117, v121, v112
	v_mul_f32_e32 v120, v111, v116
	v_fma_f32 v123, -v104, v119, v105
	v_fmac_f32_e32 v118, v122, v113
	v_fma_f32 v96, -v96, v117, v97
	v_fma_f32 v124, -v110, v120, v111
	v_fmac_f32_e32 v119, v123, v115
	v_fma_f32 v97, -v102, v118, v103
	v_div_fmas_f32 v96, v96, v112, v117
	s_mov_b64 vcc, s[0:1]
	v_fmac_f32_e32 v120, v124, v116
	v_fma_f32 v102, -v104, v119, v105
	v_div_fixup_f32 v91, v96, v91, 1.0
	v_div_fmas_f32 v96, v97, v113, v118
	s_mov_b64 vcc, s[4:5]
	v_fma_f32 v103, -v110, v120, v111
	v_div_fixup_f32 v90, v96, v90, 1.0
	v_div_fmas_f32 v96, v102, v115, v119
	s_mov_b64 vcc, s[6:7]
	v_div_fixup_f32 v93, v96, v93, 1.0
	v_div_fmas_f32 v96, v103, v116, v120
	v_div_fixup_f32 v92, v96, v92, 1.0
	v_mul_f32_e32 v87, v87, v114
	v_mul_f32_e32 v86, 0xbfb8aa3b, v86
	v_mul_f32_e32 v87, 0xbfb8aa3b, v87
	v_mul_f32_e32 v88, v88, v114
	v_mul_f32_e32 v89, v89, v114
	v_mul_f32_e32 v88, 0xbfb8aa3b, v88
	v_mul_f32_e32 v89, 0xbfb8aa3b, v89
	v_exp_f32_e32 v102, v88
	v_exp_f32_e32 v103, v89
	s_waitcnt vmcnt(0) lgkmcnt(0)
	v_lshlrev_b32_e32 v96, 16, v94
	v_and_b32_e32 v97, 0xffff0000, v94
	v_lshlrev_b32_e32 v94, 16, v95
	v_and_b32_e32 v95, 0xffff0000, v95
	v_pk_fma_f32 v[90:91], v[90:91], v[96:97], v[106:107]
	v_pk_fma_f32 v[92:93], v[92:93], v[94:95], v[108:109]
	flat_store_dwordx4 v[98:99], v[90:93] offset:64
	flat_load_dwordx2 v[94:95], v[100:101] offset:64
	s_nop 0
	flat_load_dwordx4 v[90:93], v[98:99] offset:128
	v_exp_f32_e32 v96, v86
	v_exp_f32_e32 v97, v87
	v_pk_add_f32 v[102:103], v[102:103], 1.0 op_sel_hi:[1,0]
	flat_load_dwordx4 v[86:89], v[98:99] offset:192
	v_div_scale_f32 v108, s[4:5], v103, v103, 1.0
	v_pk_add_f32 v[96:97], v[96:97], 1.0 op_sel_hi:[1,0]
	v_div_scale_f32 v110, s[6:7], v102, v102, 1.0
	v_div_scale_f32 v104, s[0:1], v97, v97, 1.0
	v_div_scale_f32 v106, s[0:1], v96, v96, 1.0
	v_rcp_f32_e32 v112, v104
	v_rcp_f32_e32 v113, v106
	v_rcp_f32_e32 v115, v108
	v_rcp_f32_e32 v116, v110
	v_fma_f32 v117, -v104, v112, 1.0
	v_div_scale_f32 v105, vcc, 1.0, v97, 1.0
	v_fma_f32 v118, -v106, v113, 1.0
	v_fmac_f32_e32 v112, v117, v112
	v_div_scale_f32 v107, s[0:1], 1.0, v96, 1.0
	v_fma_f32 v119, -v108, v115, 1.0
	v_fmac_f32_e32 v113, v118, v113
	v_mul_f32_e32 v117, v105, v112
	v_div_scale_f32 v109, s[4:5], 1.0, v103, 1.0
	v_fma_f32 v120, -v110, v116, 1.0
	v_fmac_f32_e32 v115, v119, v115
	v_mul_f32_e32 v118, v107, v113
	v_fma_f32 v121, -v104, v117, v105
	v_div_scale_f32 v111, s[6:7], 1.0, v102, 1.0
	v_fmac_f32_e32 v116, v120, v116
	v_mul_f32_e32 v119, v109, v115
	v_fma_f32 v122, -v106, v118, v107
	v_fmac_f32_e32 v117, v121, v112
	v_mul_f32_e32 v120, v111, v116
	v_fma_f32 v123, -v108, v119, v109
	v_fmac_f32_e32 v118, v122, v113
	v_fma_f32 v104, -v104, v117, v105
	v_fma_f32 v124, -v110, v120, v111
	v_fmac_f32_e32 v119, v123, v115
	v_fma_f32 v105, -v106, v118, v107
	v_div_fmas_f32 v104, v104, v112, v117
	s_mov_b64 vcc, s[0:1]
	v_fmac_f32_e32 v120, v124, v116
	v_fma_f32 v106, -v108, v119, v109
	v_div_fixup_f32 v97, v104, v97, 1.0
	v_div_fmas_f32 v104, v105, v113, v118
	s_mov_b64 vcc, s[4:5]
	v_fma_f32 v107, -v110, v120, v111
	v_div_fixup_f32 v96, v104, v96, 1.0
	v_div_fmas_f32 v104, v106, v115, v119
	s_mov_b64 vcc, s[6:7]
	v_div_fixup_f32 v103, v104, v103, 1.0
	v_div_fmas_f32 v104, v107, v116, v120
	v_div_fixup_f32 v102, v104, v102, 1.0
	v_mul_f32_e32 v82, v82, v114
	v_mul_f32_e32 v83, v83, v114
	v_mul_f32_e32 v82, 0xbfb8aa3b, v82
	v_mul_f32_e32 v83, 0xbfb8aa3b, v83
	v_mul_f32_e32 v84, v84, v114
	v_mul_f32_e32 v85, v85, v114
	v_exp_f32_e32 v82, v82
	v_exp_f32_e32 v83, v83
	v_mul_f32_e32 v84, 0xbfb8aa3b, v84
	v_mul_f32_e32 v85, 0xbfb8aa3b, v85
	v_exp_f32_e32 v84, v84
	v_exp_f32_e32 v85, v85
	v_pk_add_f32 v[82:83], v[82:83], 1.0 op_sel_hi:[1,0]
	v_pk_add_f32 v[84:85], v[84:85], 1.0 op_sel_hi:[1,0]
	s_waitcnt vmcnt(0) lgkmcnt(0)
	v_lshlrev_b32_e32 v104, 16, v94
	v_and_b32_e32 v105, 0xffff0000, v94
	v_lshlrev_b32_e32 v94, 16, v95
	v_and_b32_e32 v95, 0xffff0000, v95
	v_pk_fma_f32 v[90:91], v[96:97], v[104:105], v[90:91]
	v_pk_fma_f32 v[92:93], v[102:103], v[94:95], v[92:93]
	flat_store_dwordx4 v[98:99], v[90:93] offset:128
	flat_load_dwordx2 v[90:91], v[100:101] offset:96
	v_div_scale_f32 v94, s[0:1], v82, v82, 1.0
	v_div_scale_f32 v92, s[0:1], v83, v83, 1.0
	v_rcp_f32_e32 v102, v92
	v_div_scale_f32 v96, s[4:5], v85, v85, 1.0
	v_rcp_f32_e32 v103, v94
	v_div_scale_f32 v100, s[6:7], v84, v84, 1.0
	v_rcp_f32_e32 v104, v96
	v_rcp_f32_e32 v105, v100
	v_fma_f32 v106, -v92, v102, 1.0
	v_div_scale_f32 v93, vcc, 1.0, v83, 1.0
	v_fma_f32 v107, -v94, v103, 1.0
	v_fmac_f32_e32 v102, v106, v102
	v_div_scale_f32 v95, s[0:1], 1.0, v82, 1.0
	v_fma_f32 v108, -v96, v104, 1.0
	v_fmac_f32_e32 v103, v107, v103
	v_mul_f32_e32 v106, v93, v102
	v_div_scale_f32 v97, s[4:5], 1.0, v85, 1.0
	v_fma_f32 v109, -v100, v105, 1.0
	v_fmac_f32_e32 v104, v108, v104
	v_mul_f32_e32 v107, v95, v103
	v_fma_f32 v110, -v92, v106, v93
	v_div_scale_f32 v101, s[6:7], 1.0, v84, 1.0
	v_fmac_f32_e32 v105, v109, v105
	v_mul_f32_e32 v108, v97, v104
	v_fma_f32 v111, -v94, v107, v95
	v_fmac_f32_e32 v106, v110, v102
	v_mul_f32_e32 v109, v101, v105
	v_fma_f32 v112, -v96, v108, v97
	v_fmac_f32_e32 v107, v111, v103
	v_fma_f32 v92, -v92, v106, v93
	v_fma_f32 v113, -v100, v109, v101
	v_fmac_f32_e32 v108, v112, v104
	v_fma_f32 v93, -v94, v107, v95
	v_div_fmas_f32 v92, v92, v102, v106
	s_mov_b64 vcc, s[0:1]
	v_fmac_f32_e32 v109, v113, v105
	v_fma_f32 v94, -v96, v108, v97
	v_div_fixup_f32 v83, v92, v83, 1.0
	v_div_fmas_f32 v92, v93, v103, v107
	s_mov_b64 vcc, s[4:5]
	v_fma_f32 v95, -v100, v109, v101
	v_div_fixup_f32 v82, v92, v82, 1.0
	v_div_fmas_f32 v92, v94, v104, v108
	s_mov_b64 vcc, s[6:7]
	v_div_fixup_f32 v85, v92, v85, 1.0
	v_div_fmas_f32 v92, v95, v105, v109
	v_div_fixup_f32 v84, v92, v84, 1.0
	s_waitcnt vmcnt(0) lgkmcnt(0)
	v_lshlrev_b32_e32 v92, 16, v90
	v_and_b32_e32 v93, 0xffff0000, v90
	v_lshlrev_b32_e32 v90, 16, v91
	v_and_b32_e32 v91, 0xffff0000, v91
	v_pk_fma_f32 v[82:83], v[82:83], v[92:93], v[86:87]
	v_pk_fma_f32 v[84:85], v[84:85], v[90:91], v[88:89]
	flat_store_dwordx4 v[98:99], v[82:85] offset:192
	s_nop 1
	v_or_b32_e32 v82, 48, v126
	v_mov_b32_e32 v83, v127
	v_lshl_add_u64 v[84:85], v[82:83], 2, s[14:15]
	flat_load_dword v90, v[84:85]
	v_lshlrev_b64 v[84:85], 11, v[82:83]
	v_lshl_add_u64 v[84:85], s[12:13], 0, v[84:85]
	v_lshl_add_u64 v[84:85], v[84:85], 0, v[128:129]
	flat_load_dwordx2 v[94:95], v[84:85]
	v_lshlrev_b64 v[82:83], 12, v[82:83]
	v_lshl_add_u64 v[82:83], v[130:131], 0, v[82:83]
	v_lshl_add_u64 v[82:83], v[82:83], 0, v[134:135]
	flat_load_dwordx4 v[86:89], v[82:83]
	s_waitcnt vmcnt(0) lgkmcnt(0)
	v_fmamk_f32 v90, v90, 0x3a800000, v141
	v_mul_f32_e32 v91, 0x4b800000, v90
	v_cmp_gt_f32_e32 vcc, s50, v90
	v_lshlrev_b32_e32 v96, 16, v94
	s_nop 0
	v_cndmask_b32_e32 v90, v90, v91, vcc
	v_rsq_f32_e32 v98, v90
	v_and_b32_e32 v97, 0xffff0000, v94
	flat_load_dwordx4 v[90:93], v[82:83] offset:64
	v_mul_f32_e32 v94, 0x45800000, v98
	v_cndmask_b32_e32 v98, v98, v94, vcc
	v_mul_f32_e32 v78, v78, v98
	v_mul_f32_e32 v79, v79, v98
	v_mul_f32_e32 v78, 0xbfb8aa3b, v78
	v_mul_f32_e32 v79, 0xbfb8aa3b, v79
	v_mul_f32_e32 v80, v80, v98
	v_mul_f32_e32 v81, v81, v98
	v_exp_f32_e32 v78, v78
	v_exp_f32_e32 v79, v79
	v_mul_f32_e32 v80, 0xbfb8aa3b, v80
	v_mul_f32_e32 v81, 0xbfb8aa3b, v81
	v_exp_f32_e32 v80, v80
	v_exp_f32_e32 v81, v81
	v_pk_add_f32 v[78:79], v[78:79], 1.0 op_sel_hi:[1,0]
	v_lshlrev_b32_e32 v94, 16, v95
	v_div_scale_f32 v99, s[0:1], v79, v79, 1.0
	v_pk_add_f32 v[80:81], v[80:81], 1.0 op_sel_hi:[1,0]
	v_div_scale_f32 v101, s[0:1], v78, v78, 1.0
	v_rcp_f32_e32 v107, v99
	v_div_scale_f32 v103, s[4:5], v81, v81, 1.0
	v_rcp_f32_e32 v108, v101
	v_div_scale_f32 v105, s[6:7], v80, v80, 1.0
	v_rcp_f32_e32 v109, v103
	v_rcp_f32_e32 v110, v105
	v_fma_f32 v111, -v99, v107, 1.0
	v_div_scale_f32 v100, vcc, 1.0, v79, 1.0
	v_fma_f32 v112, -v101, v108, 1.0
	v_fmac_f32_e32 v107, v111, v107
	v_div_scale_f32 v102, s[0:1], 1.0, v78, 1.0
	v_fma_f32 v113, -v103, v109, 1.0
	v_fmac_f32_e32 v108, v112, v108
	v_mul_f32_e32 v111, v100, v107
	v_div_scale_f32 v104, s[4:5], 1.0, v81, 1.0
	v_fma_f32 v114, -v105, v110, 1.0
	v_fmac_f32_e32 v109, v113, v109
	v_mul_f32_e32 v112, v102, v108
	v_fma_f32 v115, -v99, v111, v100
	v_div_scale_f32 v106, s[6:7], 1.0, v80, 1.0
	v_fmac_f32_e32 v110, v114, v110
	v_mul_f32_e32 v113, v104, v109
	v_fma_f32 v116, -v101, v112, v102
	v_fmac_f32_e32 v111, v115, v107
	v_mul_f32_e32 v114, v106, v110
	v_fma_f32 v117, -v103, v113, v104
	v_fmac_f32_e32 v112, v116, v108
	v_fma_f32 v99, -v99, v111, v100
	v_fma_f32 v118, -v105, v114, v106
	v_fmac_f32_e32 v113, v117, v109
	v_fma_f32 v100, -v101, v112, v102
	v_div_fmas_f32 v99, v99, v107, v111
	s_mov_b64 vcc, s[0:1]
	v_fmac_f32_e32 v114, v118, v110
	v_fma_f32 v101, -v103, v113, v104
	v_div_fixup_f32 v79, v99, v79, 1.0
	v_div_fmas_f32 v99, v100, v108, v112
	s_mov_b64 vcc, s[4:5]
	v_fma_f32 v102, -v105, v114, v106
	v_div_fixup_f32 v78, v99, v78, 1.0
	v_div_fmas_f32 v99, v101, v109, v113
	s_mov_b64 vcc, s[6:7]
	v_pk_fma_f32 v[78:79], v[78:79], v[96:97], v[86:87]
	v_div_fmas_f32 v86, v102, v110, v114
	v_and_b32_e32 v95, 0xffff0000, v95
	v_div_fixup_f32 v81, v99, v81, 1.0
	v_div_fixup_f32 v80, v86, v80, 1.0
	v_pk_fma_f32 v[80:81], v[80:81], v[94:95], v[88:89]
	flat_store_dwordx4 v[82:83], v[78:81]
	flat_load_dwordx2 v[78:79], v[84:85] offset:32
	v_mul_f32_e32 v74, v74, v98
	v_mul_f32_e32 v75, v75, v98
	v_mul_f32_e32 v74, 0xbfb8aa3b, v74
	v_mul_f32_e32 v75, 0xbfb8aa3b, v75
	v_mul_f32_e32 v76, v76, v98
	v_mul_f32_e32 v77, v77, v98
	v_exp_f32_e32 v74, v74
	v_exp_f32_e32 v75, v75
	v_mul_f32_e32 v76, 0xbfb8aa3b, v76
	v_mul_f32_e32 v77, 0xbfb8aa3b, v77
	v_exp_f32_e32 v76, v76
	v_exp_f32_e32 v77, v77
	v_pk_add_f32 v[74:75], v[74:75], 1.0 op_sel_hi:[1,0]
	v_mul_f32_e32 v70, v70, v98
	v_div_scale_f32 v80, s[0:1], v75, v75, 1.0
	v_pk_add_f32 v[76:77], v[76:77], 1.0 op_sel_hi:[1,0]
	v_div_scale_f32 v86, s[0:1], v74, v74, 1.0
	v_rcp_f32_e32 v96, v80
	v_div_scale_f32 v88, s[4:5], v77, v77, 1.0
	v_rcp_f32_e32 v97, v86
	v_div_scale_f32 v94, s[6:7], v76, v76, 1.0
	v_rcp_f32_e32 v99, v88
	v_rcp_f32_e32 v100, v94
	v_fma_f32 v101, -v80, v96, 1.0
	v_div_scale_f32 v81, vcc, 1.0, v75, 1.0
	v_fma_f32 v102, -v86, v97, 1.0
	v_fmac_f32_e32 v96, v101, v96
	v_div_scale_f32 v87, s[0:1], 1.0, v74, 1.0
	v_fma_f32 v103, -v88, v99, 1.0
	v_fmac_f32_e32 v97, v102, v97
	v_mul_f32_e32 v101, v81, v96
	v_div_scale_f32 v89, s[4:5], 1.0, v77, 1.0
	v_fma_f32 v104, -v94, v100, 1.0
	v_fmac_f32_e32 v99, v103, v99
	v_mul_f32_e32 v102, v87, v97
	v_fma_f32 v105, -v80, v101, v81
	v_div_scale_f32 v95, s[6:7], 1.0, v76, 1.0
	v_fmac_f32_e32 v100, v104, v100
	v_mul_f32_e32 v103, v89, v99
	v_fma_f32 v106, -v86, v102, v87
	v_fmac_f32_e32 v101, v105, v96
	v_mul_f32_e32 v104, v95, v100
	v_fma_f32 v107, -v88, v103, v89
	v_fmac_f32_e32 v102, v106, v97
	v_fma_f32 v80, -v80, v101, v81
	v_fma_f32 v108, -v94, v104, v95
	v_fmac_f32_e32 v103, v107, v99
	v_fma_f32 v81, -v86, v102, v87
	v_div_fmas_f32 v80, v80, v96, v101
	s_mov_b64 vcc, s[0:1]
	v_fmac_f32_e32 v104, v108, v100
	v_fma_f32 v86, -v88, v103, v89
	v_div_fixup_f32 v75, v80, v75, 1.0
	v_div_fmas_f32 v80, v81, v97, v102
	s_mov_b64 vcc, s[4:5]
	v_fma_f32 v87, -v94, v104, v95
	v_div_fixup_f32 v74, v80, v74, 1.0
	v_div_fmas_f32 v80, v86, v99, v103
	s_mov_b64 vcc, s[6:7]
	v_div_fixup_f32 v77, v80, v77, 1.0
	v_div_fmas_f32 v80, v87, v100, v104
	v_div_fixup_f32 v76, v80, v76, 1.0
	v_mul_f32_e32 v71, v71, v98
	v_mul_f32_e32 v70, 0xbfb8aa3b, v70
	v_mul_f32_e32 v71, 0xbfb8aa3b, v71
	v_mul_f32_e32 v72, v72, v98
	v_mul_f32_e32 v73, v73, v98
	v_mul_f32_e32 v72, 0xbfb8aa3b, v72
	v_mul_f32_e32 v73, 0xbfb8aa3b, v73
	v_exp_f32_e32 v86, v72
	v_exp_f32_e32 v87, v73
	s_waitcnt vmcnt(0) lgkmcnt(0)
	v_lshlrev_b32_e32 v80, 16, v78
	v_and_b32_e32 v81, 0xffff0000, v78
	v_lshlrev_b32_e32 v78, 16, v79
	v_and_b32_e32 v79, 0xffff0000, v79
	v_pk_fma_f32 v[74:75], v[74:75], v[80:81], v[90:91]
	v_pk_fma_f32 v[76:77], v[76:77], v[78:79], v[92:93]
	flat_store_dwordx4 v[82:83], v[74:77] offset:64
	flat_load_dwordx2 v[78:79], v[84:85] offset:64
	s_nop 0
	flat_load_dwordx4 v[74:77], v[82:83] offset:128
	v_exp_f32_e32 v80, v70
	v_exp_f32_e32 v81, v71
	v_pk_add_f32 v[86:87], v[86:87], 1.0 op_sel_hi:[1,0]
	flat_load_dwordx4 v[70:73], v[82:83] offset:192
	v_div_scale_f32 v92, s[4:5], v87, v87, 1.0
	v_pk_add_f32 v[80:81], v[80:81], 1.0 op_sel_hi:[1,0]
	v_div_scale_f32 v94, s[6:7], v86, v86, 1.0
	v_div_scale_f32 v88, s[0:1], v81, v81, 1.0
	v_div_scale_f32 v90, s[0:1], v80, v80, 1.0
	v_rcp_f32_e32 v96, v88
	v_rcp_f32_e32 v97, v90
	v_rcp_f32_e32 v99, v92
	v_rcp_f32_e32 v100, v94
	v_fma_f32 v101, -v88, v96, 1.0
	v_div_scale_f32 v89, vcc, 1.0, v81, 1.0
	v_fma_f32 v102, -v90, v97, 1.0
	v_fmac_f32_e32 v96, v101, v96
	v_div_scale_f32 v91, s[0:1], 1.0, v80, 1.0
	v_fma_f32 v103, -v92, v99, 1.0
	v_fmac_f32_e32 v97, v102, v97
	v_mul_f32_e32 v101, v89, v96
	v_div_scale_f32 v93, s[4:5], 1.0, v87, 1.0
	v_fma_f32 v104, -v94, v100, 1.0
	v_fmac_f32_e32 v99, v103, v99
	v_mul_f32_e32 v102, v91, v97
	v_fma_f32 v105, -v88, v101, v89
	v_div_scale_f32 v95, s[6:7], 1.0, v86, 1.0
	v_fmac_f32_e32 v100, v104, v100
	v_mul_f32_e32 v103, v93, v99
	v_fma_f32 v106, -v90, v102, v91
	v_fmac_f32_e32 v101, v105, v96
	v_mul_f32_e32 v104, v95, v100
	v_fma_f32 v107, -v92, v103, v93
	v_fmac_f32_e32 v102, v106, v97
	v_fma_f32 v88, -v88, v101, v89
	v_fma_f32 v108, -v94, v104, v95
	v_fmac_f32_e32 v103, v107, v99
	v_fma_f32 v89, -v90, v102, v91
	v_div_fmas_f32 v88, v88, v96, v101
	s_mov_b64 vcc, s[0:1]
	v_fmac_f32_e32 v104, v108, v100
	v_fma_f32 v90, -v92, v103, v93
	v_div_fixup_f32 v81, v88, v81, 1.0
	v_div_fmas_f32 v88, v89, v97, v102
	s_mov_b64 vcc, s[4:5]
	v_fma_f32 v91, -v94, v104, v95
	v_div_fixup_f32 v80, v88, v80, 1.0
	v_div_fmas_f32 v88, v90, v99, v103
	s_mov_b64 vcc, s[6:7]
	v_div_fixup_f32 v87, v88, v87, 1.0
	v_div_fmas_f32 v88, v91, v100, v104
	v_div_fixup_f32 v86, v88, v86, 1.0
	v_mul_f32_e32 v66, v66, v98
	v_mul_f32_e32 v67, v67, v98
	v_mul_f32_e32 v66, 0xbfb8aa3b, v66
	v_mul_f32_e32 v67, 0xbfb8aa3b, v67
	v_mul_f32_e32 v68, v68, v98
	v_mul_f32_e32 v69, v69, v98
	v_exp_f32_e32 v66, v66
	v_exp_f32_e32 v67, v67
	v_mul_f32_e32 v68, 0xbfb8aa3b, v68
	v_mul_f32_e32 v69, 0xbfb8aa3b, v69
	v_exp_f32_e32 v68, v68
	v_exp_f32_e32 v69, v69
	v_pk_add_f32 v[66:67], v[66:67], 1.0 op_sel_hi:[1,0]
	v_pk_add_f32 v[68:69], v[68:69], 1.0 op_sel_hi:[1,0]
	s_waitcnt vmcnt(0) lgkmcnt(0)
	v_lshlrev_b32_e32 v88, 16, v78
	v_and_b32_e32 v89, 0xffff0000, v78
	v_lshlrev_b32_e32 v78, 16, v79
	v_and_b32_e32 v79, 0xffff0000, v79
	v_pk_fma_f32 v[74:75], v[80:81], v[88:89], v[74:75]
	v_pk_fma_f32 v[76:77], v[86:87], v[78:79], v[76:77]
	flat_store_dwordx4 v[82:83], v[74:77] offset:128
	flat_load_dwordx2 v[74:75], v[84:85] offset:96
	v_div_scale_f32 v78, s[0:1], v66, v66, 1.0
	v_div_scale_f32 v76, s[0:1], v67, v67, 1.0
	v_rcp_f32_e32 v86, v76
	v_div_scale_f32 v80, s[4:5], v69, v69, 1.0
	v_rcp_f32_e32 v87, v78
	v_div_scale_f32 v84, s[6:7], v68, v68, 1.0
	v_rcp_f32_e32 v88, v80
	v_rcp_f32_e32 v89, v84
	v_fma_f32 v90, -v76, v86, 1.0
	v_div_scale_f32 v77, vcc, 1.0, v67, 1.0
	v_fma_f32 v91, -v78, v87, 1.0
	v_fmac_f32_e32 v86, v90, v86
	v_div_scale_f32 v79, s[0:1], 1.0, v66, 1.0
	v_fma_f32 v92, -v80, v88, 1.0
	v_fmac_f32_e32 v87, v91, v87
	v_mul_f32_e32 v90, v77, v86
	v_div_scale_f32 v81, s[4:5], 1.0, v69, 1.0
	v_fma_f32 v93, -v84, v89, 1.0
	v_fmac_f32_e32 v88, v92, v88
	v_mul_f32_e32 v91, v79, v87
	v_fma_f32 v94, -v76, v90, v77
	v_div_scale_f32 v85, s[6:7], 1.0, v68, 1.0
	v_fmac_f32_e32 v89, v93, v89
	v_mul_f32_e32 v92, v81, v88
	v_fma_f32 v95, -v78, v91, v79
	v_fmac_f32_e32 v90, v94, v86
	v_mul_f32_e32 v93, v85, v89
	v_fma_f32 v96, -v80, v92, v81
	v_fmac_f32_e32 v91, v95, v87
	v_fma_f32 v76, -v76, v90, v77
	v_fma_f32 v97, -v84, v93, v85
	v_fmac_f32_e32 v92, v96, v88
	v_fma_f32 v77, -v78, v91, v79
	v_div_fmas_f32 v76, v76, v86, v90
	s_mov_b64 vcc, s[0:1]
	v_fmac_f32_e32 v93, v97, v89
	v_fma_f32 v78, -v80, v92, v81
	v_div_fixup_f32 v67, v76, v67, 1.0
	v_div_fmas_f32 v76, v77, v87, v91
	s_mov_b64 vcc, s[4:5]
	v_fma_f32 v79, -v84, v93, v85
	v_div_fixup_f32 v66, v76, v66, 1.0
	v_div_fmas_f32 v76, v78, v88, v92
	s_mov_b64 vcc, s[6:7]
	v_div_fixup_f32 v69, v76, v69, 1.0
	v_div_fmas_f32 v76, v79, v89, v93
	v_div_fixup_f32 v68, v76, v68, 1.0
	s_waitcnt vmcnt(0) lgkmcnt(0)
	v_lshlrev_b32_e32 v76, 16, v74
	v_and_b32_e32 v77, 0xffff0000, v74
	v_lshlrev_b32_e32 v74, 16, v75
	v_and_b32_e32 v75, 0xffff0000, v75
	v_pk_fma_f32 v[66:67], v[66:67], v[76:77], v[70:71]
	v_pk_fma_f32 v[68:69], v[68:69], v[74:75], v[72:73]
	flat_store_dwordx4 v[82:83], v[66:69] offset:192
	s_nop 1
	v_or_b32_e32 v66, 64, v126
	v_mov_b32_e32 v67, v127
	v_lshl_add_u64 v[68:69], v[66:67], 2, s[14:15]
	flat_load_dword v74, v[68:69]
	v_lshlrev_b64 v[68:69], 11, v[66:67]
	v_lshl_add_u64 v[68:69], s[12:13], 0, v[68:69]
	v_lshl_add_u64 v[68:69], v[68:69], 0, v[128:129]
	flat_load_dwordx2 v[78:79], v[68:69]
	v_lshlrev_b64 v[66:67], 12, v[66:67]
	v_lshl_add_u64 v[66:67], v[130:131], 0, v[66:67]
	v_lshl_add_u64 v[66:67], v[66:67], 0, v[134:135]
	flat_load_dwordx4 v[70:73], v[66:67]
	s_waitcnt vmcnt(0) lgkmcnt(0)
	v_fmamk_f32 v74, v74, 0x3a800000, v141
	v_mul_f32_e32 v75, 0x4b800000, v74
	v_cmp_gt_f32_e32 vcc, s50, v74
	v_lshlrev_b32_e32 v80, 16, v78
	s_nop 0
	v_cndmask_b32_e32 v74, v74, v75, vcc
	v_rsq_f32_e32 v82, v74
	v_and_b32_e32 v81, 0xffff0000, v78
	flat_load_dwordx4 v[74:77], v[66:67] offset:64
	v_mul_f32_e32 v78, 0x45800000, v82
	v_cndmask_b32_e32 v82, v82, v78, vcc
	v_mul_f32_e32 v62, v62, v82
	v_mul_f32_e32 v63, v63, v82
	v_mul_f32_e32 v62, 0xbfb8aa3b, v62
	v_mul_f32_e32 v63, 0xbfb8aa3b, v63
	v_mul_f32_e32 v64, v64, v82
	v_mul_f32_e32 v65, v65, v82
	v_exp_f32_e32 v62, v62
	v_exp_f32_e32 v63, v63
	v_mul_f32_e32 v64, 0xbfb8aa3b, v64
	v_mul_f32_e32 v65, 0xbfb8aa3b, v65
	v_exp_f32_e32 v64, v64
	v_exp_f32_e32 v65, v65
	v_pk_add_f32 v[62:63], v[62:63], 1.0 op_sel_hi:[1,0]
	v_lshlrev_b32_e32 v78, 16, v79
	v_div_scale_f32 v83, s[0:1], v63, v63, 1.0
	v_pk_add_f32 v[64:65], v[64:65], 1.0 op_sel_hi:[1,0]
	v_div_scale_f32 v85, s[0:1], v62, v62, 1.0
	v_rcp_f32_e32 v91, v83
	v_div_scale_f32 v87, s[4:5], v65, v65, 1.0
	v_rcp_f32_e32 v92, v85
	v_div_scale_f32 v89, s[6:7], v64, v64, 1.0
	v_rcp_f32_e32 v93, v87
	v_rcp_f32_e32 v94, v89
	v_fma_f32 v95, -v83, v91, 1.0
	v_div_scale_f32 v84, vcc, 1.0, v63, 1.0
	v_fma_f32 v96, -v85, v92, 1.0
	v_fmac_f32_e32 v91, v95, v91
	v_div_scale_f32 v86, s[0:1], 1.0, v62, 1.0
	v_fma_f32 v97, -v87, v93, 1.0
	v_fmac_f32_e32 v92, v96, v92
	v_mul_f32_e32 v95, v84, v91
	v_div_scale_f32 v88, s[4:5], 1.0, v65, 1.0
	v_fma_f32 v98, -v89, v94, 1.0
	v_fmac_f32_e32 v93, v97, v93
	v_mul_f32_e32 v96, v86, v92
	v_fma_f32 v99, -v83, v95, v84
	v_div_scale_f32 v90, s[6:7], 1.0, v64, 1.0
	v_fmac_f32_e32 v94, v98, v94
	v_mul_f32_e32 v97, v88, v93
	v_fma_f32 v100, -v85, v96, v86
	v_fmac_f32_e32 v95, v99, v91
	v_mul_f32_e32 v98, v90, v94
	v_fma_f32 v101, -v87, v97, v88
	v_fmac_f32_e32 v96, v100, v92
	v_fma_f32 v83, -v83, v95, v84
	v_fma_f32 v102, -v89, v98, v90
	v_fmac_f32_e32 v97, v101, v93
	v_fma_f32 v84, -v85, v96, v86
	v_div_fmas_f32 v83, v83, v91, v95
	s_mov_b64 vcc, s[0:1]
	v_fmac_f32_e32 v98, v102, v94
	v_fma_f32 v85, -v87, v97, v88
	v_div_fixup_f32 v63, v83, v63, 1.0
	v_div_fmas_f32 v83, v84, v92, v96
	s_mov_b64 vcc, s[4:5]
	v_fma_f32 v86, -v89, v98, v90
	v_div_fixup_f32 v62, v83, v62, 1.0
	v_div_fmas_f32 v83, v85, v93, v97
	s_mov_b64 vcc, s[6:7]
	v_pk_fma_f32 v[62:63], v[62:63], v[80:81], v[70:71]
	v_div_fmas_f32 v70, v86, v94, v98
	v_and_b32_e32 v79, 0xffff0000, v79
	v_div_fixup_f32 v65, v83, v65, 1.0
	v_div_fixup_f32 v64, v70, v64, 1.0
	v_pk_fma_f32 v[64:65], v[64:65], v[78:79], v[72:73]
	flat_store_dwordx4 v[66:67], v[62:65]
	flat_load_dwordx2 v[62:63], v[68:69] offset:32
	v_mul_f32_e32 v58, v58, v82
	v_mul_f32_e32 v59, v59, v82
	v_mul_f32_e32 v58, 0xbfb8aa3b, v58
	v_mul_f32_e32 v59, 0xbfb8aa3b, v59
	v_mul_f32_e32 v60, v60, v82
	v_mul_f32_e32 v61, v61, v82
	v_exp_f32_e32 v58, v58
	v_exp_f32_e32 v59, v59
	v_mul_f32_e32 v60, 0xbfb8aa3b, v60
	v_mul_f32_e32 v61, 0xbfb8aa3b, v61
	v_exp_f32_e32 v60, v60
	v_exp_f32_e32 v61, v61
	v_pk_add_f32 v[58:59], v[58:59], 1.0 op_sel_hi:[1,0]
	v_mul_f32_e32 v54, v54, v82
	v_div_scale_f32 v64, s[0:1], v59, v59, 1.0
	v_pk_add_f32 v[60:61], v[60:61], 1.0 op_sel_hi:[1,0]
	v_div_scale_f32 v70, s[0:1], v58, v58, 1.0
	v_rcp_f32_e32 v80, v64
	v_div_scale_f32 v72, s[4:5], v61, v61, 1.0
	v_rcp_f32_e32 v81, v70
	v_div_scale_f32 v78, s[6:7], v60, v60, 1.0
	v_rcp_f32_e32 v83, v72
	v_rcp_f32_e32 v84, v78
	v_fma_f32 v85, -v64, v80, 1.0
	v_div_scale_f32 v65, vcc, 1.0, v59, 1.0
	v_fma_f32 v86, -v70, v81, 1.0
	v_fmac_f32_e32 v80, v85, v80
	v_div_scale_f32 v71, s[0:1], 1.0, v58, 1.0
	v_fma_f32 v87, -v72, v83, 1.0
	v_fmac_f32_e32 v81, v86, v81
	v_mul_f32_e32 v85, v65, v80
	v_div_scale_f32 v73, s[4:5], 1.0, v61, 1.0
	v_fma_f32 v88, -v78, v84, 1.0
	v_fmac_f32_e32 v83, v87, v83
	v_mul_f32_e32 v86, v71, v81
	v_fma_f32 v89, -v64, v85, v65
	v_div_scale_f32 v79, s[6:7], 1.0, v60, 1.0
	v_fmac_f32_e32 v84, v88, v84
	v_mul_f32_e32 v87, v73, v83
	v_fma_f32 v90, -v70, v86, v71
	v_fmac_f32_e32 v85, v89, v80
	v_mul_f32_e32 v88, v79, v84
	v_fma_f32 v91, -v72, v87, v73
	v_fmac_f32_e32 v86, v90, v81
	v_fma_f32 v64, -v64, v85, v65
	v_fma_f32 v92, -v78, v88, v79
	v_fmac_f32_e32 v87, v91, v83
	v_fma_f32 v65, -v70, v86, v71
	v_div_fmas_f32 v64, v64, v80, v85
	s_mov_b64 vcc, s[0:1]
	v_fmac_f32_e32 v88, v92, v84
	v_fma_f32 v70, -v72, v87, v73
	v_div_fixup_f32 v59, v64, v59, 1.0
	v_div_fmas_f32 v64, v65, v81, v86
	s_mov_b64 vcc, s[4:5]
	v_fma_f32 v71, -v78, v88, v79
	v_div_fixup_f32 v58, v64, v58, 1.0
	v_div_fmas_f32 v64, v70, v83, v87
	s_mov_b64 vcc, s[6:7]
	v_div_fixup_f32 v61, v64, v61, 1.0
	v_div_fmas_f32 v64, v71, v84, v88
	v_div_fixup_f32 v60, v64, v60, 1.0
	v_mul_f32_e32 v55, v55, v82
	v_mul_f32_e32 v54, 0xbfb8aa3b, v54
	v_mul_f32_e32 v55, 0xbfb8aa3b, v55
	v_mul_f32_e32 v56, v56, v82
	v_mul_f32_e32 v57, v57, v82
	v_mul_f32_e32 v56, 0xbfb8aa3b, v56
	v_mul_f32_e32 v57, 0xbfb8aa3b, v57
	v_exp_f32_e32 v70, v56
	v_exp_f32_e32 v71, v57
	s_waitcnt vmcnt(0) lgkmcnt(0)
	v_lshlrev_b32_e32 v64, 16, v62
	v_and_b32_e32 v65, 0xffff0000, v62
	v_lshlrev_b32_e32 v62, 16, v63
	v_and_b32_e32 v63, 0xffff0000, v63
	v_pk_fma_f32 v[58:59], v[58:59], v[64:65], v[74:75]
	v_pk_fma_f32 v[60:61], v[60:61], v[62:63], v[76:77]
	flat_store_dwordx4 v[66:67], v[58:61] offset:64
	flat_load_dwordx2 v[62:63], v[68:69] offset:64
	s_nop 0
	flat_load_dwordx4 v[58:61], v[66:67] offset:128
	v_exp_f32_e32 v64, v54
	v_exp_f32_e32 v65, v55
	v_pk_add_f32 v[70:71], v[70:71], 1.0 op_sel_hi:[1,0]
	flat_load_dwordx4 v[54:57], v[66:67] offset:192
	v_div_scale_f32 v76, s[4:5], v71, v71, 1.0
	v_pk_add_f32 v[64:65], v[64:65], 1.0 op_sel_hi:[1,0]
	v_div_scale_f32 v78, s[6:7], v70, v70, 1.0
	v_div_scale_f32 v72, s[0:1], v65, v65, 1.0
	v_div_scale_f32 v74, s[0:1], v64, v64, 1.0
	v_rcp_f32_e32 v80, v72
	v_rcp_f32_e32 v81, v74
	v_rcp_f32_e32 v83, v76
	v_rcp_f32_e32 v84, v78
	v_fma_f32 v85, -v72, v80, 1.0
	v_div_scale_f32 v73, vcc, 1.0, v65, 1.0
	v_fma_f32 v86, -v74, v81, 1.0
	v_fmac_f32_e32 v80, v85, v80
	v_div_scale_f32 v75, s[0:1], 1.0, v64, 1.0
	v_fma_f32 v87, -v76, v83, 1.0
	v_fmac_f32_e32 v81, v86, v81
	v_mul_f32_e32 v85, v73, v80
	v_div_scale_f32 v77, s[4:5], 1.0, v71, 1.0
	v_fma_f32 v88, -v78, v84, 1.0
	v_fmac_f32_e32 v83, v87, v83
	v_mul_f32_e32 v86, v75, v81
	v_fma_f32 v89, -v72, v85, v73
	v_div_scale_f32 v79, s[6:7], 1.0, v70, 1.0
	v_fmac_f32_e32 v84, v88, v84
	v_mul_f32_e32 v87, v77, v83
	v_fma_f32 v90, -v74, v86, v75
	v_fmac_f32_e32 v85, v89, v80
	v_mul_f32_e32 v88, v79, v84
	v_fma_f32 v91, -v76, v87, v77
	v_fmac_f32_e32 v86, v90, v81
	v_fma_f32 v72, -v72, v85, v73
	v_fma_f32 v92, -v78, v88, v79
	v_fmac_f32_e32 v87, v91, v83
	v_fma_f32 v73, -v74, v86, v75
	v_div_fmas_f32 v72, v72, v80, v85
	s_mov_b64 vcc, s[0:1]
	v_fmac_f32_e32 v88, v92, v84
	v_fma_f32 v74, -v76, v87, v77
	v_div_fixup_f32 v65, v72, v65, 1.0
	v_div_fmas_f32 v72, v73, v81, v86
	s_mov_b64 vcc, s[4:5]
	v_fma_f32 v75, -v78, v88, v79
	v_div_fixup_f32 v64, v72, v64, 1.0
	v_div_fmas_f32 v72, v74, v83, v87
	s_mov_b64 vcc, s[6:7]
	v_div_fixup_f32 v71, v72, v71, 1.0
	v_div_fmas_f32 v72, v75, v84, v88
	v_div_fixup_f32 v70, v72, v70, 1.0
	v_mul_f32_e32 v50, v50, v82
	v_mul_f32_e32 v51, v51, v82
	v_mul_f32_e32 v50, 0xbfb8aa3b, v50
	v_mul_f32_e32 v51, 0xbfb8aa3b, v51
	v_mul_f32_e32 v52, v52, v82
	v_mul_f32_e32 v53, v53, v82
	v_exp_f32_e32 v50, v50
	v_exp_f32_e32 v51, v51
	v_mul_f32_e32 v52, 0xbfb8aa3b, v52
	v_mul_f32_e32 v53, 0xbfb8aa3b, v53
	v_exp_f32_e32 v52, v52
	v_exp_f32_e32 v53, v53
	v_pk_add_f32 v[50:51], v[50:51], 1.0 op_sel_hi:[1,0]
	v_pk_add_f32 v[52:53], v[52:53], 1.0 op_sel_hi:[1,0]
	s_waitcnt vmcnt(0) lgkmcnt(0)
	v_lshlrev_b32_e32 v72, 16, v62
	v_and_b32_e32 v73, 0xffff0000, v62
	v_lshlrev_b32_e32 v62, 16, v63
	v_and_b32_e32 v63, 0xffff0000, v63
	v_pk_fma_f32 v[58:59], v[64:65], v[72:73], v[58:59]
	v_pk_fma_f32 v[60:61], v[70:71], v[62:63], v[60:61]
	flat_store_dwordx4 v[66:67], v[58:61] offset:128
	flat_load_dwordx2 v[58:59], v[68:69] offset:96
	v_div_scale_f32 v62, s[0:1], v50, v50, 1.0
	v_div_scale_f32 v60, s[0:1], v51, v51, 1.0
	v_rcp_f32_e32 v70, v60
	v_div_scale_f32 v64, s[4:5], v53, v53, 1.0
	v_rcp_f32_e32 v71, v62
	v_div_scale_f32 v68, s[6:7], v52, v52, 1.0
	v_rcp_f32_e32 v72, v64
	v_rcp_f32_e32 v73, v68
	v_fma_f32 v74, -v60, v70, 1.0
	v_div_scale_f32 v61, vcc, 1.0, v51, 1.0
	v_fma_f32 v75, -v62, v71, 1.0
	v_fmac_f32_e32 v70, v74, v70
	v_div_scale_f32 v63, s[0:1], 1.0, v50, 1.0
	v_fma_f32 v76, -v64, v72, 1.0
	v_fmac_f32_e32 v71, v75, v71
	v_mul_f32_e32 v74, v61, v70
	v_div_scale_f32 v65, s[4:5], 1.0, v53, 1.0
	v_fma_f32 v77, -v68, v73, 1.0
	v_fmac_f32_e32 v72, v76, v72
	v_mul_f32_e32 v75, v63, v71
	v_fma_f32 v78, -v60, v74, v61
	v_div_scale_f32 v69, s[6:7], 1.0, v52, 1.0
	v_fmac_f32_e32 v73, v77, v73
	v_mul_f32_e32 v76, v65, v72
	v_fma_f32 v79, -v62, v75, v63
	v_fmac_f32_e32 v74, v78, v70
	v_mul_f32_e32 v77, v69, v73
	v_fma_f32 v80, -v64, v76, v65
	v_fmac_f32_e32 v75, v79, v71
	v_fma_f32 v60, -v60, v74, v61
	v_fma_f32 v81, -v68, v77, v69
	v_fmac_f32_e32 v76, v80, v72
	v_fma_f32 v61, -v62, v75, v63
	v_div_fmas_f32 v60, v60, v70, v74
	s_mov_b64 vcc, s[0:1]
	v_fmac_f32_e32 v77, v81, v73
	v_fma_f32 v62, -v64, v76, v65
	v_div_fixup_f32 v51, v60, v51, 1.0
	v_div_fmas_f32 v60, v61, v71, v75
	s_mov_b64 vcc, s[4:5]
	v_fma_f32 v63, -v68, v77, v69
	v_div_fixup_f32 v50, v60, v50, 1.0
	v_div_fmas_f32 v60, v62, v72, v76
	s_mov_b64 vcc, s[6:7]
	v_div_fixup_f32 v53, v60, v53, 1.0
	v_div_fmas_f32 v60, v63, v73, v77
	v_div_fixup_f32 v52, v60, v52, 1.0
	s_waitcnt vmcnt(0) lgkmcnt(0)
	v_lshlrev_b32_e32 v60, 16, v58
	v_and_b32_e32 v61, 0xffff0000, v58
	v_lshlrev_b32_e32 v58, 16, v59
	v_and_b32_e32 v59, 0xffff0000, v59
	v_pk_fma_f32 v[50:51], v[50:51], v[60:61], v[54:55]
	v_pk_fma_f32 v[52:53], v[52:53], v[58:59], v[56:57]
	flat_store_dwordx4 v[66:67], v[50:53] offset:192
	s_nop 1
	v_or_b32_e32 v50, 0x50, v126
	v_mov_b32_e32 v51, v127
	v_lshl_add_u64 v[52:53], v[50:51], 2, s[14:15]
	flat_load_dword v58, v[52:53]
	v_lshlrev_b64 v[52:53], 11, v[50:51]
	v_lshl_add_u64 v[52:53], s[12:13], 0, v[52:53]
	v_lshl_add_u64 v[52:53], v[52:53], 0, v[128:129]
	flat_load_dwordx2 v[62:63], v[52:53]
	v_lshlrev_b64 v[50:51], 12, v[50:51]
	v_lshl_add_u64 v[50:51], v[130:131], 0, v[50:51]
	v_lshl_add_u64 v[50:51], v[50:51], 0, v[134:135]
	flat_load_dwordx4 v[54:57], v[50:51]
	s_waitcnt vmcnt(0) lgkmcnt(0)
	v_fmamk_f32 v58, v58, 0x3a800000, v141
	v_mul_f32_e32 v59, 0x4b800000, v58
	v_cmp_gt_f32_e32 vcc, s50, v58
	v_lshlrev_b32_e32 v64, 16, v62
	s_nop 0
	v_cndmask_b32_e32 v58, v58, v59, vcc
	v_rsq_f32_e32 v66, v58
	v_and_b32_e32 v65, 0xffff0000, v62
	flat_load_dwordx4 v[58:61], v[50:51] offset:64
	v_mul_f32_e32 v62, 0x45800000, v66
	v_cndmask_b32_e32 v66, v66, v62, vcc
	v_mul_f32_e32 v46, v46, v66
	v_mul_f32_e32 v47, v47, v66
	v_mul_f32_e32 v46, 0xbfb8aa3b, v46
	v_mul_f32_e32 v47, 0xbfb8aa3b, v47
	v_mul_f32_e32 v48, v48, v66
	v_mul_f32_e32 v49, v49, v66
	v_exp_f32_e32 v46, v46
	v_exp_f32_e32 v47, v47
	v_mul_f32_e32 v48, 0xbfb8aa3b, v48
	v_mul_f32_e32 v49, 0xbfb8aa3b, v49
	v_exp_f32_e32 v48, v48
	v_exp_f32_e32 v49, v49
	v_pk_add_f32 v[46:47], v[46:47], 1.0 op_sel_hi:[1,0]
	v_lshlrev_b32_e32 v62, 16, v63
	v_div_scale_f32 v67, s[0:1], v47, v47, 1.0
	v_pk_add_f32 v[48:49], v[48:49], 1.0 op_sel_hi:[1,0]
	v_div_scale_f32 v69, s[0:1], v46, v46, 1.0
	v_rcp_f32_e32 v75, v67
	v_div_scale_f32 v71, s[4:5], v49, v49, 1.0
	v_rcp_f32_e32 v76, v69
	v_div_scale_f32 v73, s[6:7], v48, v48, 1.0
	v_rcp_f32_e32 v77, v71
	v_rcp_f32_e32 v78, v73
	v_fma_f32 v79, -v67, v75, 1.0
	v_div_scale_f32 v68, vcc, 1.0, v47, 1.0
	v_fma_f32 v80, -v69, v76, 1.0
	v_fmac_f32_e32 v75, v79, v75
	v_div_scale_f32 v70, s[0:1], 1.0, v46, 1.0
	v_fma_f32 v81, -v71, v77, 1.0
	v_fmac_f32_e32 v76, v80, v76
	v_mul_f32_e32 v79, v68, v75
	v_div_scale_f32 v72, s[4:5], 1.0, v49, 1.0
	v_fma_f32 v82, -v73, v78, 1.0
	v_fmac_f32_e32 v77, v81, v77
	v_mul_f32_e32 v80, v70, v76
	v_fma_f32 v83, -v67, v79, v68
	v_div_scale_f32 v74, s[6:7], 1.0, v48, 1.0
	v_fmac_f32_e32 v78, v82, v78
	v_mul_f32_e32 v81, v72, v77
	v_fma_f32 v84, -v69, v80, v70
	v_fmac_f32_e32 v79, v83, v75
	v_mul_f32_e32 v82, v74, v78
	v_fma_f32 v85, -v71, v81, v72
	v_fmac_f32_e32 v80, v84, v76
	v_fma_f32 v67, -v67, v79, v68
	v_fma_f32 v86, -v73, v82, v74
	v_fmac_f32_e32 v81, v85, v77
	v_fma_f32 v68, -v69, v80, v70
	v_div_fmas_f32 v67, v67, v75, v79
	s_mov_b64 vcc, s[0:1]
	v_fmac_f32_e32 v82, v86, v78
	v_fma_f32 v69, -v71, v81, v72
	v_div_fixup_f32 v47, v67, v47, 1.0
	v_div_fmas_f32 v67, v68, v76, v80
	s_mov_b64 vcc, s[4:5]
	v_fma_f32 v70, -v73, v82, v74
	v_div_fixup_f32 v46, v67, v46, 1.0
	v_div_fmas_f32 v67, v69, v77, v81
	s_mov_b64 vcc, s[6:7]
	v_pk_fma_f32 v[46:47], v[46:47], v[64:65], v[54:55]
	v_div_fmas_f32 v54, v70, v78, v82
	v_and_b32_e32 v63, 0xffff0000, v63
	v_div_fixup_f32 v49, v67, v49, 1.0
	v_div_fixup_f32 v48, v54, v48, 1.0
	v_pk_fma_f32 v[48:49], v[48:49], v[62:63], v[56:57]
	flat_store_dwordx4 v[50:51], v[46:49]
	flat_load_dwordx2 v[46:47], v[52:53] offset:32
	v_mul_f32_e32 v42, v42, v66
	v_mul_f32_e32 v43, v43, v66
	v_mul_f32_e32 v42, 0xbfb8aa3b, v42
	v_mul_f32_e32 v43, 0xbfb8aa3b, v43
	v_mul_f32_e32 v44, v44, v66
	v_mul_f32_e32 v45, v45, v66
	v_exp_f32_e32 v42, v42
	v_exp_f32_e32 v43, v43
	v_mul_f32_e32 v44, 0xbfb8aa3b, v44
	v_mul_f32_e32 v45, 0xbfb8aa3b, v45
	v_exp_f32_e32 v44, v44
	v_exp_f32_e32 v45, v45
	v_pk_add_f32 v[42:43], v[42:43], 1.0 op_sel_hi:[1,0]
	v_mul_f32_e32 v38, v38, v66
	v_div_scale_f32 v48, s[0:1], v43, v43, 1.0
	v_pk_add_f32 v[44:45], v[44:45], 1.0 op_sel_hi:[1,0]
	v_div_scale_f32 v54, s[0:1], v42, v42, 1.0
	v_rcp_f32_e32 v64, v48
	v_div_scale_f32 v56, s[4:5], v45, v45, 1.0
	v_rcp_f32_e32 v65, v54
	v_div_scale_f32 v62, s[6:7], v44, v44, 1.0
	v_rcp_f32_e32 v67, v56
	v_rcp_f32_e32 v68, v62
	v_fma_f32 v69, -v48, v64, 1.0
	v_div_scale_f32 v49, vcc, 1.0, v43, 1.0
	v_fma_f32 v70, -v54, v65, 1.0
	v_fmac_f32_e32 v64, v69, v64
	v_div_scale_f32 v55, s[0:1], 1.0, v42, 1.0
	v_fma_f32 v71, -v56, v67, 1.0
	v_fmac_f32_e32 v65, v70, v65
	v_mul_f32_e32 v69, v49, v64
	v_div_scale_f32 v57, s[4:5], 1.0, v45, 1.0
	v_fma_f32 v72, -v62, v68, 1.0
	v_fmac_f32_e32 v67, v71, v67
	v_mul_f32_e32 v70, v55, v65
	v_fma_f32 v73, -v48, v69, v49
	v_div_scale_f32 v63, s[6:7], 1.0, v44, 1.0
	v_fmac_f32_e32 v68, v72, v68
	v_mul_f32_e32 v71, v57, v67
	v_fma_f32 v74, -v54, v70, v55
	v_fmac_f32_e32 v69, v73, v64
	v_mul_f32_e32 v72, v63, v68
	v_fma_f32 v75, -v56, v71, v57
	v_fmac_f32_e32 v70, v74, v65
	v_fma_f32 v48, -v48, v69, v49
	v_fma_f32 v76, -v62, v72, v63
	v_fmac_f32_e32 v71, v75, v67
	v_fma_f32 v49, -v54, v70, v55
	v_div_fmas_f32 v48, v48, v64, v69
	s_mov_b64 vcc, s[0:1]
	v_fmac_f32_e32 v72, v76, v68
	v_fma_f32 v54, -v56, v71, v57
	v_div_fixup_f32 v43, v48, v43, 1.0
	v_div_fmas_f32 v48, v49, v65, v70
	s_mov_b64 vcc, s[4:5]
	v_fma_f32 v55, -v62, v72, v63
	v_div_fixup_f32 v42, v48, v42, 1.0
	v_div_fmas_f32 v48, v54, v67, v71
	s_mov_b64 vcc, s[6:7]
	v_div_fixup_f32 v45, v48, v45, 1.0
	v_div_fmas_f32 v48, v55, v68, v72
	v_div_fixup_f32 v44, v48, v44, 1.0
	v_mul_f32_e32 v39, v39, v66
	v_mul_f32_e32 v38, 0xbfb8aa3b, v38
	v_mul_f32_e32 v39, 0xbfb8aa3b, v39
	v_mul_f32_e32 v40, v40, v66
	v_mul_f32_e32 v41, v41, v66
	v_mul_f32_e32 v40, 0xbfb8aa3b, v40
	v_mul_f32_e32 v41, 0xbfb8aa3b, v41
	v_exp_f32_e32 v54, v40
	v_exp_f32_e32 v55, v41
	s_waitcnt vmcnt(0) lgkmcnt(0)
	v_lshlrev_b32_e32 v48, 16, v46
	v_and_b32_e32 v49, 0xffff0000, v46
	v_lshlrev_b32_e32 v46, 16, v47
	v_and_b32_e32 v47, 0xffff0000, v47
	v_pk_fma_f32 v[42:43], v[42:43], v[48:49], v[58:59]
	v_pk_fma_f32 v[44:45], v[44:45], v[46:47], v[60:61]
	flat_store_dwordx4 v[50:51], v[42:45] offset:64
	flat_load_dwordx2 v[46:47], v[52:53] offset:64
	s_nop 0
	flat_load_dwordx4 v[42:45], v[50:51] offset:128
	v_exp_f32_e32 v48, v38
	v_exp_f32_e32 v49, v39
	v_pk_add_f32 v[54:55], v[54:55], 1.0 op_sel_hi:[1,0]
	flat_load_dwordx4 v[38:41], v[50:51] offset:192
	v_div_scale_f32 v60, s[4:5], v55, v55, 1.0
	v_pk_add_f32 v[48:49], v[48:49], 1.0 op_sel_hi:[1,0]
	v_div_scale_f32 v62, s[6:7], v54, v54, 1.0
	v_div_scale_f32 v56, s[0:1], v49, v49, 1.0
	v_div_scale_f32 v58, s[0:1], v48, v48, 1.0
	v_rcp_f32_e32 v64, v56
	v_rcp_f32_e32 v65, v58
	v_rcp_f32_e32 v67, v60
	v_rcp_f32_e32 v68, v62
	v_fma_f32 v69, -v56, v64, 1.0
	v_div_scale_f32 v57, vcc, 1.0, v49, 1.0
	v_fma_f32 v70, -v58, v65, 1.0
	v_fmac_f32_e32 v64, v69, v64
	v_div_scale_f32 v59, s[0:1], 1.0, v48, 1.0
	v_fma_f32 v71, -v60, v67, 1.0
	v_fmac_f32_e32 v65, v70, v65
	v_mul_f32_e32 v69, v57, v64
	v_div_scale_f32 v61, s[4:5], 1.0, v55, 1.0
	v_fma_f32 v72, -v62, v68, 1.0
	v_fmac_f32_e32 v67, v71, v67
	v_mul_f32_e32 v70, v59, v65
	v_fma_f32 v73, -v56, v69, v57
	v_div_scale_f32 v63, s[6:7], 1.0, v54, 1.0
	v_fmac_f32_e32 v68, v72, v68
	v_mul_f32_e32 v71, v61, v67
	v_fma_f32 v74, -v58, v70, v59
	v_fmac_f32_e32 v69, v73, v64
	v_mul_f32_e32 v72, v63, v68
	v_fma_f32 v75, -v60, v71, v61
	v_fmac_f32_e32 v70, v74, v65
	v_fma_f32 v56, -v56, v69, v57
	v_fma_f32 v76, -v62, v72, v63
	v_fmac_f32_e32 v71, v75, v67
	v_fma_f32 v57, -v58, v70, v59
	v_div_fmas_f32 v56, v56, v64, v69
	s_mov_b64 vcc, s[0:1]
	v_fmac_f32_e32 v72, v76, v68
	v_fma_f32 v58, -v60, v71, v61
	v_div_fixup_f32 v49, v56, v49, 1.0
	v_div_fmas_f32 v56, v57, v65, v70
	s_mov_b64 vcc, s[4:5]
	v_fma_f32 v59, -v62, v72, v63
	v_div_fixup_f32 v48, v56, v48, 1.0
	v_div_fmas_f32 v56, v58, v67, v71
	s_mov_b64 vcc, s[6:7]
	v_div_fixup_f32 v55, v56, v55, 1.0
	v_div_fmas_f32 v56, v59, v68, v72
	v_div_fixup_f32 v54, v56, v54, 1.0
	v_mul_f32_e32 v34, v34, v66
	v_mul_f32_e32 v35, v35, v66
	v_mul_f32_e32 v34, 0xbfb8aa3b, v34
	v_mul_f32_e32 v35, 0xbfb8aa3b, v35
	v_mul_f32_e32 v36, v36, v66
	v_mul_f32_e32 v37, v37, v66
	v_exp_f32_e32 v34, v34
	v_exp_f32_e32 v35, v35
	v_mul_f32_e32 v36, 0xbfb8aa3b, v36
	v_mul_f32_e32 v37, 0xbfb8aa3b, v37
	v_exp_f32_e32 v36, v36
	v_exp_f32_e32 v37, v37
	v_pk_add_f32 v[34:35], v[34:35], 1.0 op_sel_hi:[1,0]
	v_pk_add_f32 v[36:37], v[36:37], 1.0 op_sel_hi:[1,0]
	s_waitcnt vmcnt(0) lgkmcnt(0)
	v_lshlrev_b32_e32 v56, 16, v46
	v_and_b32_e32 v57, 0xffff0000, v46
	v_lshlrev_b32_e32 v46, 16, v47
	v_and_b32_e32 v47, 0xffff0000, v47
	v_pk_fma_f32 v[42:43], v[48:49], v[56:57], v[42:43]
	v_pk_fma_f32 v[44:45], v[54:55], v[46:47], v[44:45]
	flat_store_dwordx4 v[50:51], v[42:45] offset:128
	flat_load_dwordx2 v[42:43], v[52:53] offset:96
	v_div_scale_f32 v46, s[0:1], v34, v34, 1.0
	v_div_scale_f32 v44, s[0:1], v35, v35, 1.0
	v_rcp_f32_e32 v54, v44
	v_div_scale_f32 v48, s[4:5], v37, v37, 1.0
	v_rcp_f32_e32 v55, v46
	v_div_scale_f32 v52, s[6:7], v36, v36, 1.0
	v_rcp_f32_e32 v56, v48
	v_rcp_f32_e32 v57, v52
	v_fma_f32 v58, -v44, v54, 1.0
	v_div_scale_f32 v45, vcc, 1.0, v35, 1.0
	v_fma_f32 v59, -v46, v55, 1.0
	v_fmac_f32_e32 v54, v58, v54
	v_div_scale_f32 v47, s[0:1], 1.0, v34, 1.0
	v_fma_f32 v60, -v48, v56, 1.0
	v_fmac_f32_e32 v55, v59, v55
	v_mul_f32_e32 v58, v45, v54
	v_div_scale_f32 v49, s[4:5], 1.0, v37, 1.0
	v_fma_f32 v61, -v52, v57, 1.0
	v_fmac_f32_e32 v56, v60, v56
	v_mul_f32_e32 v59, v47, v55
	v_fma_f32 v62, -v44, v58, v45
	v_div_scale_f32 v53, s[6:7], 1.0, v36, 1.0
	v_fmac_f32_e32 v57, v61, v57
	v_mul_f32_e32 v60, v49, v56
	v_fma_f32 v63, -v46, v59, v47
	v_fmac_f32_e32 v58, v62, v54
	v_mul_f32_e32 v61, v53, v57
	v_fma_f32 v64, -v48, v60, v49
	v_fmac_f32_e32 v59, v63, v55
	v_fma_f32 v44, -v44, v58, v45
	v_fma_f32 v65, -v52, v61, v53
	v_fmac_f32_e32 v60, v64, v56
	v_fma_f32 v45, -v46, v59, v47
	v_div_fmas_f32 v44, v44, v54, v58
	s_mov_b64 vcc, s[0:1]
	v_fmac_f32_e32 v61, v65, v57
	v_fma_f32 v46, -v48, v60, v49
	v_div_fixup_f32 v35, v44, v35, 1.0
	v_div_fmas_f32 v44, v45, v55, v59
	s_mov_b64 vcc, s[4:5]
	v_fma_f32 v47, -v52, v61, v53
	v_div_fixup_f32 v34, v44, v34, 1.0
	v_div_fmas_f32 v44, v46, v56, v60
	s_mov_b64 vcc, s[6:7]
	v_div_fixup_f32 v37, v44, v37, 1.0
	v_div_fmas_f32 v44, v47, v57, v61
	v_div_fixup_f32 v36, v44, v36, 1.0
	s_waitcnt vmcnt(0) lgkmcnt(0)
	v_lshlrev_b32_e32 v44, 16, v42
	v_and_b32_e32 v45, 0xffff0000, v42
	v_lshlrev_b32_e32 v42, 16, v43
	v_and_b32_e32 v43, 0xffff0000, v43
	v_pk_fma_f32 v[34:35], v[34:35], v[44:45], v[38:39]
	v_pk_fma_f32 v[36:37], v[36:37], v[42:43], v[40:41]
	flat_store_dwordx4 v[50:51], v[34:37] offset:192
	s_nop 1
	v_or_b32_e32 v34, 0x60, v126
	v_mov_b32_e32 v35, v127
	v_lshl_add_u64 v[36:37], v[34:35], 2, s[14:15]
	flat_load_dword v42, v[36:37]
	v_lshlrev_b64 v[36:37], 11, v[34:35]
	v_lshl_add_u64 v[36:37], s[12:13], 0, v[36:37]
	v_lshl_add_u64 v[36:37], v[36:37], 0, v[128:129]
	flat_load_dwordx2 v[46:47], v[36:37]
	v_lshlrev_b64 v[34:35], 12, v[34:35]
	v_lshl_add_u64 v[34:35], v[130:131], 0, v[34:35]
	v_lshl_add_u64 v[34:35], v[34:35], 0, v[134:135]
	flat_load_dwordx4 v[38:41], v[34:35]
	s_waitcnt vmcnt(0) lgkmcnt(0)
	v_fmamk_f32 v42, v42, 0x3a800000, v141
	v_mul_f32_e32 v43, 0x4b800000, v42
	v_cmp_gt_f32_e32 vcc, s50, v42
	v_lshlrev_b32_e32 v48, 16, v46
	s_nop 0
	v_cndmask_b32_e32 v42, v42, v43, vcc
	v_rsq_f32_e32 v50, v42
	v_and_b32_e32 v49, 0xffff0000, v46
	flat_load_dwordx4 v[42:45], v[34:35] offset:64
	v_mul_f32_e32 v46, 0x45800000, v50
	v_cndmask_b32_e32 v50, v50, v46, vcc
	v_mul_f32_e32 v30, v30, v50
	v_mul_f32_e32 v31, v31, v50
	v_mul_f32_e32 v30, 0xbfb8aa3b, v30
	v_mul_f32_e32 v31, 0xbfb8aa3b, v31
	v_mul_f32_e32 v32, v32, v50
	v_mul_f32_e32 v33, v33, v50
	v_exp_f32_e32 v30, v30
	v_exp_f32_e32 v31, v31
	v_mul_f32_e32 v32, 0xbfb8aa3b, v32
	v_mul_f32_e32 v33, 0xbfb8aa3b, v33
	v_exp_f32_e32 v32, v32
	v_exp_f32_e32 v33, v33
	v_pk_add_f32 v[30:31], v[30:31], 1.0 op_sel_hi:[1,0]
	v_lshlrev_b32_e32 v46, 16, v47
	v_div_scale_f32 v51, s[0:1], v31, v31, 1.0
	v_pk_add_f32 v[32:33], v[32:33], 1.0 op_sel_hi:[1,0]
	v_div_scale_f32 v53, s[0:1], v30, v30, 1.0
	v_rcp_f32_e32 v59, v51
	v_div_scale_f32 v55, s[4:5], v33, v33, 1.0
	v_rcp_f32_e32 v60, v53
	v_div_scale_f32 v57, s[6:7], v32, v32, 1.0
	v_rcp_f32_e32 v61, v55
	v_rcp_f32_e32 v62, v57
	v_fma_f32 v63, -v51, v59, 1.0
	v_div_scale_f32 v52, vcc, 1.0, v31, 1.0
	v_fma_f32 v64, -v53, v60, 1.0
	v_fmac_f32_e32 v59, v63, v59
	v_div_scale_f32 v54, s[0:1], 1.0, v30, 1.0
	v_fma_f32 v65, -v55, v61, 1.0
	v_fmac_f32_e32 v60, v64, v60
	v_mul_f32_e32 v63, v52, v59
	v_div_scale_f32 v56, s[4:5], 1.0, v33, 1.0
	v_fma_f32 v66, -v57, v62, 1.0
	v_fmac_f32_e32 v61, v65, v61
	v_mul_f32_e32 v64, v54, v60
	v_fma_f32 v67, -v51, v63, v52
	v_div_scale_f32 v58, s[6:7], 1.0, v32, 1.0
	v_fmac_f32_e32 v62, v66, v62
	v_mul_f32_e32 v65, v56, v61
	v_fma_f32 v68, -v53, v64, v54
	v_fmac_f32_e32 v63, v67, v59
	v_mul_f32_e32 v66, v58, v62
	v_fma_f32 v69, -v55, v65, v56
	v_fmac_f32_e32 v64, v68, v60
	v_fma_f32 v51, -v51, v63, v52
	v_fma_f32 v70, -v57, v66, v58
	v_fmac_f32_e32 v65, v69, v61
	v_fma_f32 v52, -v53, v64, v54
	v_div_fmas_f32 v51, v51, v59, v63
	s_mov_b64 vcc, s[0:1]
	v_fmac_f32_e32 v66, v70, v62
	v_fma_f32 v53, -v55, v65, v56
	v_div_fixup_f32 v31, v51, v31, 1.0
	v_div_fmas_f32 v51, v52, v60, v64
	s_mov_b64 vcc, s[4:5]
	v_fma_f32 v54, -v57, v66, v58
	v_div_fixup_f32 v30, v51, v30, 1.0
	v_div_fmas_f32 v51, v53, v61, v65
	s_mov_b64 vcc, s[6:7]
	v_pk_fma_f32 v[30:31], v[30:31], v[48:49], v[38:39]
	v_div_fmas_f32 v38, v54, v62, v66
	v_and_b32_e32 v47, 0xffff0000, v47
	v_div_fixup_f32 v33, v51, v33, 1.0
	v_div_fixup_f32 v32, v38, v32, 1.0
	v_pk_fma_f32 v[32:33], v[32:33], v[46:47], v[40:41]
	flat_store_dwordx4 v[34:35], v[30:33]
	flat_load_dwordx2 v[30:31], v[36:37] offset:32
	v_mul_f32_e32 v26, v26, v50
	v_mul_f32_e32 v27, v27, v50
	v_mul_f32_e32 v26, 0xbfb8aa3b, v26
	v_mul_f32_e32 v27, 0xbfb8aa3b, v27
	v_mul_f32_e32 v28, v28, v50
	v_mul_f32_e32 v29, v29, v50
	v_exp_f32_e32 v26, v26
	v_exp_f32_e32 v27, v27
	v_mul_f32_e32 v28, 0xbfb8aa3b, v28
	v_mul_f32_e32 v29, 0xbfb8aa3b, v29
	v_exp_f32_e32 v28, v28
	v_exp_f32_e32 v29, v29
	v_pk_add_f32 v[26:27], v[26:27], 1.0 op_sel_hi:[1,0]
	v_mul_f32_e32 v22, v22, v50
	v_div_scale_f32 v32, s[0:1], v27, v27, 1.0
	v_pk_add_f32 v[28:29], v[28:29], 1.0 op_sel_hi:[1,0]
	v_div_scale_f32 v38, s[0:1], v26, v26, 1.0
	v_rcp_f32_e32 v48, v32
	v_div_scale_f32 v40, s[4:5], v29, v29, 1.0
	v_rcp_f32_e32 v49, v38
	v_div_scale_f32 v46, s[6:7], v28, v28, 1.0
	v_rcp_f32_e32 v51, v40
	v_rcp_f32_e32 v52, v46
	v_fma_f32 v53, -v32, v48, 1.0
	v_div_scale_f32 v33, vcc, 1.0, v27, 1.0
	v_fma_f32 v54, -v38, v49, 1.0
	v_fmac_f32_e32 v48, v53, v48
	v_div_scale_f32 v39, s[0:1], 1.0, v26, 1.0
	v_fma_f32 v55, -v40, v51, 1.0
	v_fmac_f32_e32 v49, v54, v49
	v_mul_f32_e32 v53, v33, v48
	v_div_scale_f32 v41, s[4:5], 1.0, v29, 1.0
	v_fma_f32 v56, -v46, v52, 1.0
	v_fmac_f32_e32 v51, v55, v51
	v_mul_f32_e32 v54, v39, v49
	v_fma_f32 v57, -v32, v53, v33
	v_div_scale_f32 v47, s[6:7], 1.0, v28, 1.0
	v_fmac_f32_e32 v52, v56, v52
	v_mul_f32_e32 v55, v41, v51
	v_fma_f32 v58, -v38, v54, v39
	v_fmac_f32_e32 v53, v57, v48
	v_mul_f32_e32 v56, v47, v52
	v_fma_f32 v59, -v40, v55, v41
	v_fmac_f32_e32 v54, v58, v49
	v_fma_f32 v32, -v32, v53, v33
	v_fma_f32 v60, -v46, v56, v47
	v_fmac_f32_e32 v55, v59, v51
	v_fma_f32 v33, -v38, v54, v39
	v_div_fmas_f32 v32, v32, v48, v53
	s_mov_b64 vcc, s[0:1]
	v_fmac_f32_e32 v56, v60, v52
	v_fma_f32 v38, -v40, v55, v41
	v_div_fixup_f32 v27, v32, v27, 1.0
	v_div_fmas_f32 v32, v33, v49, v54
	s_mov_b64 vcc, s[4:5]
	v_fma_f32 v39, -v46, v56, v47
	v_div_fixup_f32 v26, v32, v26, 1.0
	v_div_fmas_f32 v32, v38, v51, v55
	s_mov_b64 vcc, s[6:7]
	v_div_fixup_f32 v29, v32, v29, 1.0
	v_div_fmas_f32 v32, v39, v52, v56
	v_div_fixup_f32 v28, v32, v28, 1.0
	v_mul_f32_e32 v23, v23, v50
	v_mul_f32_e32 v22, 0xbfb8aa3b, v22
	v_mul_f32_e32 v23, 0xbfb8aa3b, v23
	v_mul_f32_e32 v24, v24, v50
	v_mul_f32_e32 v25, v25, v50
	v_mul_f32_e32 v24, 0xbfb8aa3b, v24
	v_mul_f32_e32 v25, 0xbfb8aa3b, v25
	v_exp_f32_e32 v38, v24
	v_exp_f32_e32 v39, v25
	s_waitcnt vmcnt(0) lgkmcnt(0)
	v_lshlrev_b32_e32 v32, 16, v30
	v_and_b32_e32 v33, 0xffff0000, v30
	v_lshlrev_b32_e32 v30, 16, v31
	v_and_b32_e32 v31, 0xffff0000, v31
	v_pk_fma_f32 v[26:27], v[26:27], v[32:33], v[42:43]
	v_pk_fma_f32 v[28:29], v[28:29], v[30:31], v[44:45]
	flat_store_dwordx4 v[34:35], v[26:29] offset:64
	flat_load_dwordx2 v[30:31], v[36:37] offset:64
	s_nop 0
	flat_load_dwordx4 v[26:29], v[34:35] offset:128
	v_exp_f32_e32 v32, v22
	v_exp_f32_e32 v33, v23
	v_pk_add_f32 v[38:39], v[38:39], 1.0 op_sel_hi:[1,0]
	flat_load_dwordx4 v[22:25], v[34:35] offset:192
	v_div_scale_f32 v44, s[4:5], v39, v39, 1.0
	v_pk_add_f32 v[32:33], v[32:33], 1.0 op_sel_hi:[1,0]
	v_div_scale_f32 v46, s[6:7], v38, v38, 1.0
	v_div_scale_f32 v40, s[0:1], v33, v33, 1.0
	v_div_scale_f32 v42, s[0:1], v32, v32, 1.0
	v_rcp_f32_e32 v48, v40
	v_rcp_f32_e32 v49, v42
	v_rcp_f32_e32 v51, v44
	v_rcp_f32_e32 v52, v46
	v_fma_f32 v53, -v40, v48, 1.0
	v_div_scale_f32 v41, vcc, 1.0, v33, 1.0
	v_fma_f32 v54, -v42, v49, 1.0
	v_fmac_f32_e32 v48, v53, v48
	v_div_scale_f32 v43, s[0:1], 1.0, v32, 1.0
	v_fma_f32 v55, -v44, v51, 1.0
	v_fmac_f32_e32 v49, v54, v49
	v_mul_f32_e32 v53, v41, v48
	v_div_scale_f32 v45, s[4:5], 1.0, v39, 1.0
	v_fma_f32 v56, -v46, v52, 1.0
	v_fmac_f32_e32 v51, v55, v51
	v_mul_f32_e32 v54, v43, v49
	v_fma_f32 v57, -v40, v53, v41
	v_div_scale_f32 v47, s[6:7], 1.0, v38, 1.0
	v_fmac_f32_e32 v52, v56, v52
	v_mul_f32_e32 v55, v45, v51
	v_fma_f32 v58, -v42, v54, v43
	v_fmac_f32_e32 v53, v57, v48
	v_mul_f32_e32 v56, v47, v52
	v_fma_f32 v59, -v44, v55, v45
	v_fmac_f32_e32 v54, v58, v49
	v_fma_f32 v40, -v40, v53, v41
	v_fma_f32 v60, -v46, v56, v47
	v_fmac_f32_e32 v55, v59, v51
	v_fma_f32 v41, -v42, v54, v43
	v_div_fmas_f32 v40, v40, v48, v53
	s_mov_b64 vcc, s[0:1]
	v_fmac_f32_e32 v56, v60, v52
	v_fma_f32 v42, -v44, v55, v45
	v_div_fixup_f32 v33, v40, v33, 1.0
	v_div_fmas_f32 v40, v41, v49, v54
	s_mov_b64 vcc, s[4:5]
	v_fma_f32 v43, -v46, v56, v47
	v_div_fixup_f32 v32, v40, v32, 1.0
	v_div_fmas_f32 v40, v42, v51, v55
	s_mov_b64 vcc, s[6:7]
	v_div_fixup_f32 v39, v40, v39, 1.0
	v_div_fmas_f32 v40, v43, v52, v56
	v_div_fixup_f32 v38, v40, v38, 1.0
	v_mul_f32_e32 v18, v18, v50
	v_mul_f32_e32 v19, v19, v50
	v_mul_f32_e32 v18, 0xbfb8aa3b, v18
	v_mul_f32_e32 v19, 0xbfb8aa3b, v19
	v_mul_f32_e32 v20, v20, v50
	v_mul_f32_e32 v21, v21, v50
	v_exp_f32_e32 v18, v18
	v_exp_f32_e32 v19, v19
	v_mul_f32_e32 v20, 0xbfb8aa3b, v20
	v_mul_f32_e32 v21, 0xbfb8aa3b, v21
	v_exp_f32_e32 v20, v20
	v_exp_f32_e32 v21, v21
	v_pk_add_f32 v[18:19], v[18:19], 1.0 op_sel_hi:[1,0]
	v_pk_add_f32 v[20:21], v[20:21], 1.0 op_sel_hi:[1,0]
	s_waitcnt vmcnt(0) lgkmcnt(0)
	v_lshlrev_b32_e32 v40, 16, v30
	v_and_b32_e32 v41, 0xffff0000, v30
	v_lshlrev_b32_e32 v30, 16, v31
	v_and_b32_e32 v31, 0xffff0000, v31
	v_pk_fma_f32 v[26:27], v[32:33], v[40:41], v[26:27]
	v_pk_fma_f32 v[28:29], v[38:39], v[30:31], v[28:29]
	flat_store_dwordx4 v[34:35], v[26:29] offset:128
	flat_load_dwordx2 v[26:27], v[36:37] offset:96
	v_div_scale_f32 v30, s[0:1], v18, v18, 1.0
	v_div_scale_f32 v28, s[0:1], v19, v19, 1.0
	v_rcp_f32_e32 v38, v28
	v_div_scale_f32 v32, s[4:5], v21, v21, 1.0
	v_rcp_f32_e32 v39, v30
	v_div_scale_f32 v36, s[6:7], v20, v20, 1.0
	v_rcp_f32_e32 v40, v32
	v_rcp_f32_e32 v41, v36
	v_fma_f32 v42, -v28, v38, 1.0
	v_div_scale_f32 v29, vcc, 1.0, v19, 1.0
	v_fma_f32 v43, -v30, v39, 1.0
	v_fmac_f32_e32 v38, v42, v38
	v_div_scale_f32 v31, s[0:1], 1.0, v18, 1.0
	v_fma_f32 v44, -v32, v40, 1.0
	v_fmac_f32_e32 v39, v43, v39
	v_mul_f32_e32 v42, v29, v38
	v_div_scale_f32 v33, s[4:5], 1.0, v21, 1.0
	v_fma_f32 v45, -v36, v41, 1.0
	v_fmac_f32_e32 v40, v44, v40
	v_mul_f32_e32 v43, v31, v39
	v_fma_f32 v46, -v28, v42, v29
	v_div_scale_f32 v37, s[6:7], 1.0, v20, 1.0
	v_fmac_f32_e32 v41, v45, v41
	v_mul_f32_e32 v44, v33, v40
	v_fma_f32 v47, -v30, v43, v31
	v_fmac_f32_e32 v42, v46, v38
	v_mul_f32_e32 v45, v37, v41
	v_fma_f32 v48, -v32, v44, v33
	v_fmac_f32_e32 v43, v47, v39
	v_fma_f32 v28, -v28, v42, v29
	v_fma_f32 v49, -v36, v45, v37
	v_fmac_f32_e32 v44, v48, v40
	v_fma_f32 v29, -v30, v43, v31
	v_div_fmas_f32 v28, v28, v38, v42
	s_mov_b64 vcc, s[0:1]
	v_fmac_f32_e32 v45, v49, v41
	v_fma_f32 v30, -v32, v44, v33
	v_div_fixup_f32 v19, v28, v19, 1.0
	v_div_fmas_f32 v28, v29, v39, v43
	s_mov_b64 vcc, s[4:5]
	v_fma_f32 v31, -v36, v45, v37
	v_div_fixup_f32 v18, v28, v18, 1.0
	v_div_fmas_f32 v28, v30, v40, v44
	s_mov_b64 vcc, s[6:7]
	v_div_fixup_f32 v21, v28, v21, 1.0
	v_div_fmas_f32 v28, v31, v41, v45
	v_div_fixup_f32 v20, v28, v20, 1.0
	s_waitcnt vmcnt(0) lgkmcnt(0)
	v_lshlrev_b32_e32 v28, 16, v26
	v_and_b32_e32 v29, 0xffff0000, v26
	v_lshlrev_b32_e32 v26, 16, v27
	v_and_b32_e32 v27, 0xffff0000, v27
	v_pk_fma_f32 v[18:19], v[18:19], v[28:29], v[22:23]
	v_pk_fma_f32 v[20:21], v[20:21], v[26:27], v[24:25]
	flat_store_dwordx4 v[34:35], v[18:21] offset:192
	v_or_b32_e32 v126, 0x70, v126
	s_nop 0
	v_lshl_add_u64 v[18:19], v[126:127], 2, s[14:15]
	flat_load_dword v26, v[18:19]
	v_lshlrev_b64 v[18:19], 11, v[126:127]
	v_lshl_add_u64 v[18:19], s[12:13], 0, v[18:19]
	v_lshl_add_u64 v[20:21], v[18:19], 0, v[128:129]
	flat_load_dwordx2 v[30:31], v[20:21]
	v_lshlrev_b64 v[18:19], 12, v[126:127]
	v_lshl_add_u64 v[18:19], v[130:131], 0, v[18:19]
	v_lshl_add_u64 v[18:19], v[18:19], 0, v[134:135]
	flat_load_dwordx4 v[22:25], v[18:19]
	s_waitcnt vmcnt(0) lgkmcnt(0)
	v_fmamk_f32 v26, v26, 0x3a800000, v141
	v_mul_f32_e32 v27, 0x4b800000, v26
	v_cmp_gt_f32_e32 vcc, s50, v26
	v_lshlrev_b32_e32 v32, 16, v30
	s_nop 0
	v_cndmask_b32_e32 v26, v26, v27, vcc
	v_rsq_f32_e32 v34, v26
	v_and_b32_e32 v33, 0xffff0000, v30
	flat_load_dwordx4 v[26:29], v[18:19] offset:64
	v_mul_f32_e32 v30, 0x45800000, v34
	v_cndmask_b32_e32 v34, v34, v30, vcc
	v_mul_f32_e32 v14, v14, v34
	v_mul_f32_e32 v15, v15, v34
	v_mul_f32_e32 v14, 0xbfb8aa3b, v14
	v_mul_f32_e32 v15, 0xbfb8aa3b, v15
	v_mul_f32_e32 v16, v16, v34
	v_mul_f32_e32 v17, v17, v34
	v_exp_f32_e32 v14, v14
	v_exp_f32_e32 v15, v15
	v_mul_f32_e32 v16, 0xbfb8aa3b, v16
	v_mul_f32_e32 v17, 0xbfb8aa3b, v17
	v_exp_f32_e32 v16, v16
	v_exp_f32_e32 v17, v17
	v_pk_add_f32 v[14:15], v[14:15], 1.0 op_sel_hi:[1,0]
	v_lshlrev_b32_e32 v30, 16, v31
	v_div_scale_f32 v35, s[0:1], v15, v15, 1.0
	v_pk_add_f32 v[16:17], v[16:17], 1.0 op_sel_hi:[1,0]
	v_div_scale_f32 v37, s[0:1], v14, v14, 1.0
	v_rcp_f32_e32 v43, v35
	v_div_scale_f32 v39, s[4:5], v17, v17, 1.0
	v_rcp_f32_e32 v44, v37
	v_div_scale_f32 v41, s[6:7], v16, v16, 1.0
	v_rcp_f32_e32 v45, v39
	v_rcp_f32_e32 v46, v41
	v_fma_f32 v47, -v35, v43, 1.0
	v_div_scale_f32 v36, vcc, 1.0, v15, 1.0
	v_fma_f32 v48, -v37, v44, 1.0
	v_fmac_f32_e32 v43, v47, v43
	v_div_scale_f32 v38, s[0:1], 1.0, v14, 1.0
	v_fma_f32 v49, -v39, v45, 1.0
	v_fmac_f32_e32 v44, v48, v44
	v_mul_f32_e32 v47, v36, v43
	v_div_scale_f32 v40, s[4:5], 1.0, v17, 1.0
	v_fma_f32 v50, -v41, v46, 1.0
	v_fmac_f32_e32 v45, v49, v45
	v_mul_f32_e32 v48, v38, v44
	v_fma_f32 v51, -v35, v47, v36
	v_div_scale_f32 v42, s[6:7], 1.0, v16, 1.0
	v_fmac_f32_e32 v46, v50, v46
	v_mul_f32_e32 v49, v40, v45
	v_fma_f32 v52, -v37, v48, v38
	v_fmac_f32_e32 v47, v51, v43
	v_mul_f32_e32 v50, v42, v46
	v_fma_f32 v53, -v39, v49, v40
	v_fmac_f32_e32 v48, v52, v44
	v_fma_f32 v35, -v35, v47, v36
	v_fma_f32 v54, -v41, v50, v42
	v_fmac_f32_e32 v49, v53, v45
	v_fma_f32 v36, -v37, v48, v38
	v_div_fmas_f32 v35, v35, v43, v47
	s_mov_b64 vcc, s[0:1]
	v_fmac_f32_e32 v50, v54, v46
	v_fma_f32 v37, -v39, v49, v40
	v_div_fixup_f32 v15, v35, v15, 1.0
	v_div_fmas_f32 v35, v36, v44, v48
	s_mov_b64 vcc, s[4:5]
	v_fma_f32 v38, -v41, v50, v42
	v_div_fixup_f32 v14, v35, v14, 1.0
	v_div_fmas_f32 v35, v37, v45, v49
	s_mov_b64 vcc, s[6:7]
	v_pk_fma_f32 v[14:15], v[14:15], v[32:33], v[22:23]
	v_div_fmas_f32 v22, v38, v46, v50
	v_and_b32_e32 v31, 0xffff0000, v31
	v_div_fixup_f32 v17, v35, v17, 1.0
	v_div_fixup_f32 v16, v22, v16, 1.0
	v_pk_fma_f32 v[16:17], v[16:17], v[30:31], v[24:25]
	flat_store_dwordx4 v[18:19], v[14:17]
	flat_load_dwordx2 v[14:15], v[20:21] offset:32
	v_mul_f32_e32 v10, v10, v34
	v_mul_f32_e32 v11, v11, v34
	v_mul_f32_e32 v10, 0xbfb8aa3b, v10
	v_mul_f32_e32 v11, 0xbfb8aa3b, v11
	v_mul_f32_e32 v12, v12, v34
	v_mul_f32_e32 v13, v13, v34
	v_exp_f32_e32 v10, v10
	v_exp_f32_e32 v11, v11
	v_mul_f32_e32 v12, 0xbfb8aa3b, v12
	v_mul_f32_e32 v13, 0xbfb8aa3b, v13
	v_exp_f32_e32 v12, v12
	v_exp_f32_e32 v13, v13
	v_pk_add_f32 v[10:11], v[10:11], 1.0 op_sel_hi:[1,0]
	v_mul_f32_e32 v6, v6, v34
	v_div_scale_f32 v16, s[0:1], v11, v11, 1.0
	v_pk_add_f32 v[12:13], v[12:13], 1.0 op_sel_hi:[1,0]
	v_div_scale_f32 v22, s[0:1], v10, v10, 1.0
	v_rcp_f32_e32 v32, v16
	v_div_scale_f32 v24, s[4:5], v13, v13, 1.0
	v_rcp_f32_e32 v33, v22
	v_div_scale_f32 v30, s[6:7], v12, v12, 1.0
	v_rcp_f32_e32 v35, v24
	v_rcp_f32_e32 v36, v30
	v_fma_f32 v37, -v16, v32, 1.0
	v_div_scale_f32 v17, vcc, 1.0, v11, 1.0
	v_fma_f32 v38, -v22, v33, 1.0
	v_fmac_f32_e32 v32, v37, v32
	v_div_scale_f32 v23, s[0:1], 1.0, v10, 1.0
	v_fma_f32 v39, -v24, v35, 1.0
	v_fmac_f32_e32 v33, v38, v33
	v_mul_f32_e32 v37, v17, v32
	v_div_scale_f32 v25, s[4:5], 1.0, v13, 1.0
	v_fma_f32 v40, -v30, v36, 1.0
	v_fmac_f32_e32 v35, v39, v35
	v_mul_f32_e32 v38, v23, v33
	v_fma_f32 v41, -v16, v37, v17
	v_div_scale_f32 v31, s[6:7], 1.0, v12, 1.0
	v_fmac_f32_e32 v36, v40, v36
	v_mul_f32_e32 v39, v25, v35
	v_fma_f32 v42, -v22, v38, v23
	v_fmac_f32_e32 v37, v41, v32
	v_mul_f32_e32 v40, v31, v36
	v_fma_f32 v43, -v24, v39, v25
	v_fmac_f32_e32 v38, v42, v33
	v_fma_f32 v16, -v16, v37, v17
	v_fma_f32 v44, -v30, v40, v31
	v_fmac_f32_e32 v39, v43, v35
	v_fma_f32 v17, -v22, v38, v23
	v_div_fmas_f32 v16, v16, v32, v37
	s_mov_b64 vcc, s[0:1]
	v_fmac_f32_e32 v40, v44, v36
	v_fma_f32 v22, -v24, v39, v25
	v_div_fixup_f32 v11, v16, v11, 1.0
	v_div_fmas_f32 v16, v17, v33, v38
	s_mov_b64 vcc, s[4:5]
	v_fma_f32 v23, -v30, v40, v31
	v_div_fixup_f32 v10, v16, v10, 1.0
	v_div_fmas_f32 v16, v22, v35, v39
	s_mov_b64 vcc, s[6:7]
	v_div_fixup_f32 v13, v16, v13, 1.0
	v_div_fmas_f32 v16, v23, v36, v40
	v_div_fixup_f32 v12, v16, v12, 1.0
	v_mul_f32_e32 v7, v7, v34
	v_mul_f32_e32 v6, 0xbfb8aa3b, v6
	v_mul_f32_e32 v7, 0xbfb8aa3b, v7
	v_mul_f32_e32 v8, v8, v34
	v_mul_f32_e32 v9, v9, v34
	v_mul_f32_e32 v8, 0xbfb8aa3b, v8
	v_mul_f32_e32 v9, 0xbfb8aa3b, v9
	v_exp_f32_e32 v22, v8
	v_exp_f32_e32 v23, v9
	s_waitcnt vmcnt(0) lgkmcnt(0)
	v_lshlrev_b32_e32 v16, 16, v14
	v_and_b32_e32 v17, 0xffff0000, v14
	v_lshlrev_b32_e32 v14, 16, v15
	v_and_b32_e32 v15, 0xffff0000, v15
	v_pk_fma_f32 v[10:11], v[10:11], v[16:17], v[26:27]
	v_pk_fma_f32 v[12:13], v[12:13], v[14:15], v[28:29]
	flat_store_dwordx4 v[18:19], v[10:13] offset:64
	flat_load_dwordx2 v[14:15], v[20:21] offset:64
	s_nop 0
	flat_load_dwordx4 v[10:13], v[18:19] offset:128
	v_exp_f32_e32 v16, v6
	v_exp_f32_e32 v17, v7
	v_pk_add_f32 v[22:23], v[22:23], 1.0 op_sel_hi:[1,0]
	flat_load_dwordx4 v[6:9], v[18:19] offset:192
	v_div_scale_f32 v28, s[4:5], v23, v23, 1.0
	v_pk_add_f32 v[16:17], v[16:17], 1.0 op_sel_hi:[1,0]
	v_div_scale_f32 v30, s[6:7], v22, v22, 1.0
	v_div_scale_f32 v24, s[0:1], v17, v17, 1.0
	v_div_scale_f32 v26, s[0:1], v16, v16, 1.0
	v_rcp_f32_e32 v32, v24
	v_rcp_f32_e32 v33, v26
	v_rcp_f32_e32 v35, v28
	v_rcp_f32_e32 v36, v30
	v_fma_f32 v37, -v24, v32, 1.0
	v_div_scale_f32 v25, vcc, 1.0, v17, 1.0
	v_fma_f32 v38, -v26, v33, 1.0
	v_fmac_f32_e32 v32, v37, v32
	v_div_scale_f32 v27, s[0:1], 1.0, v16, 1.0
	v_fma_f32 v39, -v28, v35, 1.0
	v_fmac_f32_e32 v33, v38, v33
	v_mul_f32_e32 v37, v25, v32
	v_div_scale_f32 v29, s[4:5], 1.0, v23, 1.0
	v_fma_f32 v40, -v30, v36, 1.0
	v_fmac_f32_e32 v35, v39, v35
	v_mul_f32_e32 v38, v27, v33
	v_fma_f32 v41, -v24, v37, v25
	v_div_scale_f32 v31, s[6:7], 1.0, v22, 1.0
	v_fmac_f32_e32 v36, v40, v36
	v_mul_f32_e32 v39, v29, v35
	v_fma_f32 v42, -v26, v38, v27
	v_fmac_f32_e32 v37, v41, v32
	v_mul_f32_e32 v40, v31, v36
	v_fma_f32 v43, -v28, v39, v29
	v_fmac_f32_e32 v38, v42, v33
	v_fma_f32 v24, -v24, v37, v25
	v_fma_f32 v44, -v30, v40, v31
	v_fmac_f32_e32 v39, v43, v35
	v_fma_f32 v25, -v26, v38, v27
	v_div_fmas_f32 v24, v24, v32, v37
	s_mov_b64 vcc, s[0:1]
	v_fmac_f32_e32 v40, v44, v36
	v_fma_f32 v26, -v28, v39, v29
	v_div_fixup_f32 v17, v24, v17, 1.0
	v_div_fmas_f32 v24, v25, v33, v38
	s_mov_b64 vcc, s[4:5]
	v_fma_f32 v27, -v30, v40, v31
	v_div_fixup_f32 v16, v24, v16, 1.0
	v_div_fmas_f32 v24, v26, v35, v39
	s_mov_b64 vcc, s[6:7]
	v_div_fixup_f32 v23, v24, v23, 1.0
	v_div_fmas_f32 v24, v27, v36, v40
	v_div_fixup_f32 v22, v24, v22, 1.0
	v_mul_f32_e32 v2, v2, v34
	v_mul_f32_e32 v3, v3, v34
	v_mul_f32_e32 v2, 0xbfb8aa3b, v2
	v_mul_f32_e32 v3, 0xbfb8aa3b, v3
	v_mul_f32_e32 v4, v4, v34
	v_mul_f32_e32 v5, v5, v34
	v_exp_f32_e32 v2, v2
	v_exp_f32_e32 v3, v3
	v_mul_f32_e32 v4, 0xbfb8aa3b, v4
	v_mul_f32_e32 v5, 0xbfb8aa3b, v5
	v_exp_f32_e32 v4, v4
	v_exp_f32_e32 v5, v5
	v_pk_add_f32 v[2:3], v[2:3], 1.0 op_sel_hi:[1,0]
	v_pk_add_f32 v[4:5], v[4:5], 1.0 op_sel_hi:[1,0]
	s_waitcnt vmcnt(0) lgkmcnt(0)
	v_lshlrev_b32_e32 v24, 16, v14
	v_and_b32_e32 v25, 0xffff0000, v14
	v_lshlrev_b32_e32 v14, 16, v15
	v_and_b32_e32 v15, 0xffff0000, v15
	v_pk_fma_f32 v[10:11], v[16:17], v[24:25], v[10:11]
	v_pk_fma_f32 v[12:13], v[22:23], v[14:15], v[12:13]
	flat_store_dwordx4 v[18:19], v[10:13] offset:128
	flat_load_dwordx2 v[10:11], v[20:21] offset:96
	v_div_scale_f32 v14, s[0:1], v2, v2, 1.0
	v_div_scale_f32 v12, s[0:1], v3, v3, 1.0
	v_rcp_f32_e32 v22, v12
	v_div_scale_f32 v16, s[4:5], v5, v5, 1.0
	v_rcp_f32_e32 v23, v14
	v_div_scale_f32 v20, s[6:7], v4, v4, 1.0
	v_rcp_f32_e32 v24, v16
	v_rcp_f32_e32 v25, v20
	v_fma_f32 v26, -v12, v22, 1.0
	v_div_scale_f32 v13, vcc, 1.0, v3, 1.0
	v_fma_f32 v27, -v14, v23, 1.0
	v_fmac_f32_e32 v22, v26, v22
	v_div_scale_f32 v15, s[0:1], 1.0, v2, 1.0
	v_fma_f32 v28, -v16, v24, 1.0
	v_fmac_f32_e32 v23, v27, v23
	v_mul_f32_e32 v26, v13, v22
	v_div_scale_f32 v17, s[4:5], 1.0, v5, 1.0
	v_fma_f32 v29, -v20, v25, 1.0
	v_fmac_f32_e32 v24, v28, v24
	v_mul_f32_e32 v27, v15, v23
	v_fma_f32 v30, -v12, v26, v13
	v_div_scale_f32 v21, s[6:7], 1.0, v4, 1.0
	v_fmac_f32_e32 v25, v29, v25
	v_mul_f32_e32 v28, v17, v24
	v_fma_f32 v31, -v14, v27, v15
	v_fmac_f32_e32 v26, v30, v22
	v_mul_f32_e32 v29, v21, v25
	v_fma_f32 v32, -v16, v28, v17
	v_fmac_f32_e32 v27, v31, v23
	v_fma_f32 v12, -v12, v26, v13
	v_fma_f32 v33, -v20, v29, v21
	v_fmac_f32_e32 v28, v32, v24
	v_fma_f32 v13, -v14, v27, v15
	v_div_fmas_f32 v12, v12, v22, v26
	s_mov_b64 vcc, s[0:1]
	v_fmac_f32_e32 v29, v33, v25
	v_fma_f32 v14, -v16, v28, v17
	v_div_fixup_f32 v3, v12, v3, 1.0
	v_div_fmas_f32 v12, v13, v23, v27
	s_mov_b64 vcc, s[4:5]
	v_fma_f32 v15, -v20, v29, v21
	v_div_fixup_f32 v2, v12, v2, 1.0
	v_div_fmas_f32 v12, v14, v24, v28
	s_mov_b64 vcc, s[6:7]
	v_div_fixup_f32 v5, v12, v5, 1.0
	v_div_fmas_f32 v12, v15, v25, v29
	v_div_fixup_f32 v4, v12, v4, 1.0
	s_waitcnt vmcnt(0) lgkmcnt(0)
	v_lshlrev_b32_e32 v12, 16, v10
	v_and_b32_e32 v13, 0xffff0000, v10
	v_lshlrev_b32_e32 v10, 16, v11
	v_and_b32_e32 v11, 0xffff0000, v11
	v_pk_fma_f32 v[2:3], v[2:3], v[12:13], v[6:7]
	v_pk_fma_f32 v[4:5], v[4:5], v[10:11], v[8:9]
	flat_store_dwordx4 v[18:19], v[2:5] offset:192
	s_add_i32 s2, s2, s40
	s_add_i32 s41, s41, s40
	s_cmpk_gt_i32 s2, 0x7ff
	s_cbranch_scc0 .LBB0_1444
